# GEMM K-loops: the two k-step MFMAs of each accumulator issued back to back (a0k0 a0k1 a1k0 a1k1 ...) instead of k-major order; same math
# speedup vs baseline: 1.0098x; 1.0095x over previous
; #define PG8_STAGE(bufoff, gbase, voff) do { _Pragma("unroll") for (int _i = 0; _i < 2; ++_i) \
;         __builtin_amdgcn_global_load_lds((const unsigned*)((const char*)(gbase) + (voff)[_i]), (PG8_LAS unsigned*)(lds + (bufoff) + ldsw + _i * 8192), 16, 0, 0); } while (0)
; #define PG8_LDA(dst, b, h) do { _Pragma("unroll") for (int m = 0; m < 4; ++m) _Pragma("unroll") for (int k = 0; k < 2; ++k) dst[m][k] = *(const PG8_LAS bf16x8*)(lds + PG8_SA(b, h) + aoff + m * 2048 + k * 1024); } while (0)
; #define PG8_LDB(dst, b, h) do { _Pragma("unroll") for (int n = 0; n < 2; ++n) _Pragma("unroll") for (int k = 0; k < 2; ++k) dst[n][k] = *(const PG8_LAS bf16x8*)(lds + PG8_SB(b, h) + boff + n * 2048 + k * 1024); } while (0)
; #define PG8_WAIT_V(n) asm volatile("s_waitcnt vmcnt(" #n ")" ::: "memory")
; #define PG8_WAIT_L(n) asm volatile("s_waitcnt lgkmcnt(" #n ")" ::: "memory")
; #define PG8_BAR __builtin_amdgcn_s_barrier()
; #define PG8_SCHED __builtin_amdgcn_sched_barrier(0)
; template <class Epi, class Sched, bool ALIGN_EPI = false, bool SP2 = false, bool I8 = false>
; __device__ __forceinline__ void gemm_phase(PG8_LAS unsigned char* lds, const Gemm g, const Sched& S, const Epi& E) {
;     ...
;         const bool has_next = S.next(ui + 1, nxt);
;         const char* nA = has_next ? (const char*)g.A + (size_t)nxt.pm * tstep : cA; const char* nB = has_next ? (const char*)g.Bt + (size_t)nxt.pn * tstep : cB;
;         for (int t = 0; t < nt; t += 2) {
;             const bool last = (t == nt - 2);
;             const char* a1 = cA + (size_t)(t + 1) * kstep;
;             const char* a2 = last ? nA : cA + (size_t)(t + 2) * kstep; const char* b2 = last ? nB : cB + (size_t)(t + 2) * kstep;
;             const char* a3 = a2 + kstep; const char* b3 = b2 + kstep;
;             if (last && has_next) S.a_ready(nxt);
;             if constexpr (SP2) {
;             PG8_LDB(B0, 0, 0); PG8_LDB(B1, 0, 1); PG8_SCHED; PG8_LDA(At, 0, 0); PG8_STAGE(PG8_SA(1, 1), a1 + hstep, voffA);
;             PG8_WAIT_V(8); PG8_WAIT_L(0); PG8_BAR; PG8_MMA(0, 0, At, B0); PG8_MMA(0, 1, At, B1); PG8_BAR; PG8_SCHED;
;             PG8_LDA(At, 0, 1); PG8_STAGE(PG8_SB(0, 0), b2, voffB); PG8_STAGE(PG8_SB(0, 1), b2 + hstep, voffB); PG8_STAGE(PG8_SA(0, 0), a2, voffA);
;             PG8_WAIT_V(8); PG8_WAIT_L(0); PG8_BAR; PG8_MMA(1, 0, At, B0); PG8_MMA(1, 1, At, B1); PG8_BAR; PG8_SCHED;
.LBB0_207:
	s_ashr_i32 s19, s18, 31
	s_lshl_b64 s[22:23], s[18:19], 20
	s_add_u32 s22, s28, s22
	s_addc_u32 s23, s34, s23
	s_and_b64 s[24:25], s[6:7], exec
	s_cselect_b32 s19, s23, s27
	s_cselect_b32 s64, s22, s26
	s_ashr_i32 s17, s16, 31
	s_lshl_b64 s[24:25], s[16:17], 20
	s_add_u32 s24, s35, s24
	s_addc_u32 s25, s42, s25
	s_and_b64 s[40:41], s[6:7], exec
	s_cselect_b32 s17, s25, s37
	s_cselect_b32 s65, s24, s36
	s_add_u32 s26, s26, 0x80080
	s_addc_u32 s27, s27, 0
	s_add_u32 s72, s36, 0x100
	s_addc_u32 s73, s37, 0
	s_mov_b32 s76, -2
	s_add_u32 s36, s26, 0xfff80080
	s_addc_u32 s37, s27, -1
	s_add_i32 s50, 0, 0x10000
	s_cmp_eq_u32 s76, 28
	s_cselect_b32 s41, s19, s37
	s_cselect_b32 s40, s64, s36
	s_cselect_b32 s37, s17, s73
	s_cselect_b32 s36, s65, s72
	s_add_i32 s56, 0, 0x14000
	v_add_u32_e32 v136, s50, v175
	v_add_u32_e32 v172, s56, v175
	ds_read_b128 v[116:119], v136
	ds_read_b128 v[124:127], v136 offset:1024
	ds_read_b128 v[132:135], v136 offset:2048
	ds_read_b128 v[136:139], v136 offset:3072
	ds_read_b128 v[160:163], v172
	ds_read_b128 v[164:167], v172 offset:1024
	ds_read_b128 v[168:171], v172 offset:2048
	ds_read_b128 v[178:181], v172 offset:3072
	v_lshl_add_u64 v[172:173], s[26:27], 0, v[156:157]
	s_add_i32 m0, s44, 0xc000
	ds_read_b128 v[182:185], v177
	ds_read_b128 v[186:189], v177 offset:1024
	ds_read_b128 v[204:207], v177 offset:2048
	ds_read_b128 v[208:211], v177 offset:3072
	ds_read_b128 v[212:215], v177 offset:4096
	ds_read_b128 v[216:219], v177 offset:5120
	ds_read_b128 v[220:223], v177 offset:6144
	ds_read_b128 v[224:227], v177 offset:7168
	global_load_lds_dwordx4 v[172:173], off
	v_lshl_add_u64 v[172:173], s[26:27], 0, v[158:159]
	s_add_i32 m0, s44, 0xe000
	s_nop 0
	global_load_lds_dwordx4 v[172:173], off
	s_waitcnt vmcnt(8)
	s_waitcnt lgkmcnt(0)
	s_barrier
	s_setprio 1
	s_waitcnt lgkmcnt(0)
	v_mfma_i32_16x16x64_i8 v[144:147], v[116:119], v[182:185], 0
	v_mfma_i32_16x16x64_i8 v[144:147], v[124:127], v[186:189], v[144:147]
	v_mfma_i32_16x16x64_i8 v[140:143], v[132:135], v[182:185], 0
	v_mfma_i32_16x16x64_i8 v[140:143], v[136:139], v[186:189], v[140:143]
	v_mfma_i32_16x16x64_i8 v[112:115], v[116:119], v[204:207], 0
	v_mfma_i32_16x16x64_i8 v[112:115], v[124:127], v[208:211], v[112:115]
	v_mfma_i32_16x16x64_i8 v[108:111], v[132:135], v[204:207], 0
	v_mfma_i32_16x16x64_i8 v[108:111], v[136:139], v[208:211], v[108:111]
	v_mfma_i32_16x16x64_i8 v[96:99], v[116:119], v[212:215], 0
	v_mfma_i32_16x16x64_i8 v[96:99], v[124:127], v[216:219], v[96:99]
	v_mfma_i32_16x16x64_i8 v[92:95], v[132:135], v[212:215], 0
	v_mfma_i32_16x16x64_i8 v[92:95], v[136:139], v[216:219], v[92:95]
	v_mfma_i32_16x16x64_i8 v[80:83], v[116:119], v[220:223], 0
	v_mfma_i32_16x16x64_i8 v[80:83], v[124:127], v[224:227], v[80:83]
	v_mfma_i32_16x16x64_i8 v[76:79], v[132:135], v[220:223], 0
	v_mfma_i32_16x16x64_i8 v[76:79], v[136:139], v[224:227], v[76:79]
	s_setprio 0
	s_setprio 1
	v_mfma_i32_16x16x64_i8 v[128:131], v[160:163], v[182:185], 0
	v_mfma_i32_16x16x64_i8 v[128:131], v[164:167], v[186:189], v[128:131]
	v_mfma_i32_16x16x64_i8 v[120:123], v[168:171], v[182:185], 0
	v_mfma_i32_16x16x64_i8 v[120:123], v[178:181], v[186:189], v[120:123]
	v_mfma_i32_16x16x64_i8 v[104:107], v[160:163], v[204:207], 0
	v_mfma_i32_16x16x64_i8 v[104:107], v[164:167], v[208:211], v[104:107]
	v_mfma_i32_16x16x64_i8 v[100:103], v[168:171], v[204:207], 0
	v_mfma_i32_16x16x64_i8 v[100:103], v[178:181], v[208:211], v[100:103]
	v_mfma_i32_16x16x64_i8 v[88:91], v[160:163], v[212:215], 0
	v_mfma_i32_16x16x64_i8 v[88:91], v[164:167], v[216:219], v[88:91]
	v_mfma_i32_16x16x64_i8 v[84:87], v[168:171], v[212:215], 0
	v_mfma_i32_16x16x64_i8 v[84:87], v[178:181], v[216:219], v[84:87]
	v_mfma_i32_16x16x64_i8 v[72:75], v[160:163], v[220:223], 0
	v_mfma_i32_16x16x64_i8 v[72:75], v[164:167], v[224:227], v[72:75]
	v_mfma_i32_16x16x64_i8 v[68:71], v[168:171], v[220:223], 0
	v_mfma_i32_16x16x64_i8 v[68:71], v[178:181], v[224:227], v[68:71]
	s_setprio 0
	s_barrier
	s_add_i32 s50, s50, s43
	v_lshl_add_u64 v[172:173], s[36:37], 0, v[2:3]
	s_mov_b32 m0, s50
	ds_read_b128 v[182:185], v177 offset:16384
	ds_read_b128 v[186:189], v177 offset:17408
	ds_read_b128 v[204:207], v177 offset:18432
	ds_read_b128 v[208:211], v177 offset:19456
	ds_read_b128 v[212:215], v177 offset:20480
	ds_read_b128 v[216:219], v177 offset:21504
	ds_read_b128 v[220:223], v177 offset:22528
	ds_read_b128 v[224:227], v177 offset:23552
	global_load_lds_dwordx4 v[172:173], off
	s_add_i32 m0, s50, 0x2000
	s_add_u32 s50, s36, 0x80000
	v_lshl_add_u64 v[190:191], s[36:37], 0, v[148:149]
	s_addc_u32 s51, s37, 0
	s_add_i32 s56, s56, s43
	global_load_lds_dwordx4 v[190:191], off
	v_lshl_add_u64 v[228:229], s[50:51], 0, v[2:3]
	s_mov_b32 m0, s56
	v_lshl_add_u64 v[240:241], s[40:41], 0, v[150:151]
	global_load_lds_dwordx4 v[228:229], off
	v_lshl_add_u64 v[228:229], s[50:51], 0, v[148:149]
	s_add_i32 m0, s56, 0x2000
	s_nop 0
	global_load_lds_dwordx4 v[228:229], off
	v_lshl_add_u64 v[228:229], s[40:41], 0, v[152:153]
	s_mov_b32 m0, s44
	s_nop 0
	global_load_lds_dwordx4 v[228:229], off
	s_mov_b32 m0, s45
	s_nop 0
	global_load_lds_dwordx4 v[240:241], off
	s_waitcnt vmcnt(8)
	s_waitcnt lgkmcnt(0)
	s_barrier
; #define PG8_STAGE(bufoff, gbase, voff) do { _Pragma("unroll") for (int _i = 0; _i < 2; ++_i) \
;         __builtin_amdgcn_global_load_lds((const unsigned*)((const char*)(gbase) + (voff)[_i]), (PG8_LAS unsigned*)(lds + (bufoff) + ldsw + _i * 8192), 16, 0, 0); } while (0)
; #define PG8_LDA(dst, b, h) do { _Pragma("unroll") for (int m = 0; m < 4; ++m) _Pragma("unroll") for (int k = 0; k < 2; ++k) dst[m][k] = *(const PG8_LAS bf16x8*)(lds + PG8_SA(b, h) + aoff + m * 2048 + k * 1024); } while (0)
; #define PG8_LDB(dst, b, h) do { _Pragma("unroll") for (int n = 0; n < 2; ++n) _Pragma("unroll") for (int k = 0; k < 2; ++k) dst[n][k] = *(const PG8_LAS bf16x8*)(lds + PG8_SB(b, h) + boff + n * 2048 + k * 1024); } while (0)
; #define PG8_WAIT_V(n) asm volatile("s_waitcnt vmcnt(" #n ")" ::: "memory")
; #define PG8_WAIT_L(n) asm volatile("s_waitcnt lgkmcnt(" #n ")" ::: "memory")
; #define PG8_BAR __builtin_amdgcn_s_barrier()
; #define PG8_SCHED __builtin_amdgcn_sched_barrier(0)
; template <class Epi, class Sched, bool ALIGN_EPI = false, bool SP2 = false, bool I8 = false>
; __device__ __forceinline__ void gemm_phase(PG8_LAS unsigned char* lds, const Gemm g, const Sched& S, const Epi& E) {
;     ...
;             PG8_WAIT_V(8); PG8_WAIT_L(0); PG8_BAR; PG8_MMA(1, 0, At, B0); PG8_MMA(1, 1, At, B1); PG8_BAR; PG8_SCHED;
;             PG8_LDB(B0, 1, 0); PG8_LDB(B1, 1, 1); PG8_SCHED; PG8_LDA(At, 1, 0); PG8_STAGE(PG8_SA(0, 1), a2 + hstep, voffA);
;             PG8_WAIT_V(8); PG8_WAIT_L(0); PG8_BAR; PG8_MMA(0, 0, At, B0); PG8_MMA(0, 1, At, B1); PG8_BAR; PG8_SCHED;
	s_setprio 1
	s_waitcnt lgkmcnt(0)
	v_mfma_i32_16x16x64_i8 v[64:67], v[116:119], v[182:185], 0
	v_mfma_i32_16x16x64_i8 v[64:67], v[124:127], v[186:189], v[64:67]
	v_mfma_i32_16x16x64_i8 v[60:63], v[132:135], v[182:185], 0
	v_mfma_i32_16x16x64_i8 v[60:63], v[136:139], v[186:189], v[60:63]
	v_mfma_i32_16x16x64_i8 v[48:51], v[116:119], v[204:207], 0
	v_mfma_i32_16x16x64_i8 v[48:51], v[124:127], v[208:211], v[48:51]
	v_mfma_i32_16x16x64_i8 v[44:47], v[132:135], v[204:207], 0
	v_mfma_i32_16x16x64_i8 v[44:47], v[136:139], v[208:211], v[44:47]
	v_mfma_i32_16x16x64_i8 v[32:35], v[116:119], v[212:215], 0
	v_mfma_i32_16x16x64_i8 v[32:35], v[124:127], v[216:219], v[32:35]
	v_mfma_i32_16x16x64_i8 v[28:31], v[132:135], v[212:215], 0
	v_mfma_i32_16x16x64_i8 v[28:31], v[136:139], v[216:219], v[28:31]
	v_mfma_i32_16x16x64_i8 v[16:19], v[116:119], v[220:223], 0
	v_mfma_i32_16x16x64_i8 v[16:19], v[124:127], v[224:227], v[16:19]
	v_mfma_i32_16x16x64_i8 v[12:15], v[132:135], v[220:223], 0
	v_mfma_i32_16x16x64_i8 v[12:15], v[136:139], v[224:227], v[12:15]
	s_setprio 0
	s_setprio 1
	v_mfma_i32_16x16x64_i8 v[56:59], v[160:163], v[182:185], 0
	v_mfma_i32_16x16x64_i8 v[56:59], v[164:167], v[186:189], v[56:59]
	v_mfma_i32_16x16x64_i8 v[52:55], v[168:171], v[182:185], 0
	v_mfma_i32_16x16x64_i8 v[52:55], v[178:181], v[186:189], v[52:55]
	v_mfma_i32_16x16x64_i8 v[40:43], v[160:163], v[204:207], 0
	v_mfma_i32_16x16x64_i8 v[40:43], v[164:167], v[208:211], v[40:43]
	v_mfma_i32_16x16x64_i8 v[36:39], v[168:171], v[204:207], 0
	v_mfma_i32_16x16x64_i8 v[36:39], v[178:181], v[208:211], v[36:39]
	v_mfma_i32_16x16x64_i8 v[24:27], v[160:163], v[212:215], 0
	v_mfma_i32_16x16x64_i8 v[24:27], v[164:167], v[216:219], v[24:27]
	v_mfma_i32_16x16x64_i8 v[20:23], v[168:171], v[212:215], 0
	v_mfma_i32_16x16x64_i8 v[20:23], v[178:181], v[216:219], v[20:23]
	v_mfma_i32_16x16x64_i8 v[8:11], v[160:163], v[220:223], 0
	v_mfma_i32_16x16x64_i8 v[8:11], v[164:167], v[224:227], v[8:11]
	v_mfma_i32_16x16x64_i8 v[4:7], v[168:171], v[220:223], 0
	v_mfma_i32_16x16x64_i8 v[4:7], v[178:181], v[224:227], v[4:7]
	s_setprio 0
	s_barrier
	s_add_i32 s50, 0, 0x18000
	s_add_i32 s51, 0, 0x1c000
	v_add_u32_e32 v136, s50, v175
	v_add_u32_e32 v178, s51, v175
	ds_read_b128 v[116:119], v136
	ds_read_b128 v[124:127], v136 offset:1024
	ds_read_b128 v[132:135], v136 offset:2048
	ds_read_b128 v[136:139], v136 offset:3072
	ds_read_b128 v[160:163], v178
	ds_read_b128 v[164:167], v178 offset:1024
	ds_read_b128 v[168:171], v178 offset:2048
	ds_read_b128 v[178:181], v178 offset:3072
	s_add_u32 s40, s40, 0x80000
	s_addc_u32 s41, s41, 0
	s_mov_b32 m0, s46
	v_lshl_add_u64 v[242:243], s[40:41], 0, v[152:153]
	ds_read_b128 v[182:185], v177 offset:32768
	ds_read_b128 v[186:189], v177 offset:33792
	ds_read_b128 v[204:207], v177 offset:34816
	ds_read_b128 v[208:211], v177 offset:35840
	ds_read_b128 v[212:215], v177 offset:36864
	ds_read_b128 v[216:219], v177 offset:37888
	ds_read_b128 v[220:223], v177 offset:38912
	ds_read_b128 v[224:227], v177 offset:39936
	global_load_lds_dwordx4 v[242:243], off
	v_lshl_add_u64 v[242:243], s[40:41], 0, v[150:151]
	s_mov_b32 m0, s47
	s_nop 0
	global_load_lds_dwordx4 v[242:243], off
	s_waitcnt vmcnt(8)
	s_waitcnt lgkmcnt(0)
	s_barrier
	s_setprio 1
	s_waitcnt lgkmcnt(0)
	v_mfma_i32_16x16x64_i8 v[144:147], v[116:119], v[182:185], v[144:147]
	v_mfma_i32_16x16x64_i8 v[144:147], v[124:127], v[186:189], v[144:147]
	v_mfma_i32_16x16x64_i8 v[140:143], v[132:135], v[182:185], v[140:143]
	v_mfma_i32_16x16x64_i8 v[140:143], v[136:139], v[186:189], v[140:143]
	v_mfma_i32_16x16x64_i8 v[112:115], v[116:119], v[204:207], v[112:115]
	v_mfma_i32_16x16x64_i8 v[112:115], v[124:127], v[208:211], v[112:115]
	v_mfma_i32_16x16x64_i8 v[108:111], v[132:135], v[204:207], v[108:111]
	v_mfma_i32_16x16x64_i8 v[108:111], v[136:139], v[208:211], v[108:111]
	v_mfma_i32_16x16x64_i8 v[96:99], v[116:119], v[212:215], v[96:99]
	v_mfma_i32_16x16x64_i8 v[96:99], v[124:127], v[216:219], v[96:99]
	v_mfma_i32_16x16x64_i8 v[92:95], v[132:135], v[212:215], v[92:95]
	v_mfma_i32_16x16x64_i8 v[92:95], v[136:139], v[216:219], v[92:95]
	v_mfma_i32_16x16x64_i8 v[80:83], v[116:119], v[220:223], v[80:83]
	v_mfma_i32_16x16x64_i8 v[80:83], v[124:127], v[224:227], v[80:83]
	v_mfma_i32_16x16x64_i8 v[76:79], v[132:135], v[220:223], v[76:79]
	v_mfma_i32_16x16x64_i8 v[76:79], v[136:139], v[224:227], v[76:79]
	s_setprio 0
	s_setprio 1
	v_mfma_i32_16x16x64_i8 v[128:131], v[160:163], v[182:185], v[128:131]
	v_mfma_i32_16x16x64_i8 v[128:131], v[164:167], v[186:189], v[128:131]
	v_mfma_i32_16x16x64_i8 v[120:123], v[168:171], v[182:185], v[120:123]
	v_mfma_i32_16x16x64_i8 v[120:123], v[178:181], v[186:189], v[120:123]
	v_mfma_i32_16x16x64_i8 v[104:107], v[160:163], v[204:207], v[104:107]
	v_mfma_i32_16x16x64_i8 v[104:107], v[164:167], v[208:211], v[104:107]
	v_mfma_i32_16x16x64_i8 v[100:103], v[168:171], v[204:207], v[100:103]
	v_mfma_i32_16x16x64_i8 v[100:103], v[178:181], v[208:211], v[100:103]
	v_mfma_i32_16x16x64_i8 v[88:91], v[160:163], v[212:215], v[88:91]
	v_mfma_i32_16x16x64_i8 v[88:91], v[164:167], v[216:219], v[88:91]
	v_mfma_i32_16x16x64_i8 v[84:87], v[168:171], v[212:215], v[84:87]
	v_mfma_i32_16x16x64_i8 v[84:87], v[178:181], v[216:219], v[84:87]
	v_mfma_i32_16x16x64_i8 v[72:75], v[160:163], v[220:223], v[72:75]
	v_mfma_i32_16x16x64_i8 v[72:75], v[164:167], v[224:227], v[72:75]
	v_mfma_i32_16x16x64_i8 v[68:71], v[168:171], v[220:223], v[68:71]
	v_mfma_i32_16x16x64_i8 v[68:71], v[178:181], v[224:227], v[68:71]
	s_setprio 0
	s_barrier
; #define PG8_STAGE(bufoff, gbase, voff) do { _Pragma("unroll") for (int _i = 0; _i < 2; ++_i) \
;         __builtin_amdgcn_global_load_lds((const unsigned*)((const char*)(gbase) + (voff)[_i]), (PG8_LAS unsigned*)(lds + (bufoff) + ldsw + _i * 8192), 16, 0, 0); } while (0)
; #define PG8_LDA(dst, b, h) do { _Pragma("unroll") for (int m = 0; m < 4; ++m) _Pragma("unroll") for (int k = 0; k < 2; ++k) dst[m][k] = *(const PG8_LAS bf16x8*)(lds + PG8_SA(b, h) + aoff + m * 2048 + k * 1024); } while (0)
; #define PG8_LDB(dst, b, h) do { _Pragma("unroll") for (int n = 0; n < 2; ++n) _Pragma("unroll") for (int k = 0; k < 2; ++k) dst[n][k] = *(const PG8_LAS bf16x8*)(lds + PG8_SB(b, h) + boff + n * 2048 + k * 1024); } while (0)
; template <class Epi, class Sched, bool ALIGN_EPI = false, bool SP2 = false, bool I8 = false>
; __device__ __forceinline__ void gemm_phase(PG8_LAS unsigned char* lds, const Gemm g, const Sched& S, const Epi& E) {
;     ...
;             const bool last = (t == nt - 2);
;             const char* a1 = cA + (size_t)(t + 1) * kstep;
;             const char* a2 = last ? nA : cA + (size_t)(t + 2) * kstep; const char* b2 = last ? nB : cB + (size_t)(t + 2) * kstep;
;             const char* a3 = a2 + kstep; const char* b3 = b2 + kstep;
;             if (last && has_next) S.a_ready(nxt);
;             if constexpr (SP2) {
;             PG8_LDB(B0, 0, 0); PG8_LDB(B1, 0, 1); PG8_SCHED; PG8_LDA(At, 0, 0); PG8_STAGE(PG8_SA(1, 1), a1 + hstep, voffA);
;             PG8_WAIT_V(8); PG8_WAIT_L(0); PG8_BAR; PG8_MMA(0, 0, At, B0); PG8_MMA(0, 1, At, B1); PG8_BAR; PG8_SCHED;
;             PG8_LDA(At, 0, 1); PG8_STAGE(PG8_SB(0, 0), b2, voffB); PG8_STAGE(PG8_SB(0, 1), b2 + hstep, voffB); PG8_STAGE(PG8_SA(0, 0), a2, voffA);
;             PG8_WAIT_V(8); PG8_WAIT_L(0); PG8_BAR; PG8_MMA(1, 0, At, B0); PG8_MMA(1, 1, At, B1); PG8_BAR; PG8_SCHED;
;             PG8_LDB(B0, 1, 0); PG8_LDB(B1, 1, 1); PG8_SCHED; PG8_LDA(At, 1, 0); PG8_STAGE(PG8_SA(0, 1), a2 + hstep, voffA);
;             PG8_WAIT_V(8); PG8_WAIT_L(0); PG8_BAR; PG8_MMA(0, 0, At, B0); PG8_MMA(0, 1, At, B1); PG8_BAR; PG8_SCHED;
;             PG8_LDA(At, 1, 1); PG8_STAGE(PG8_SB(1, 0), b3, voffB); PG8_STAGE(PG8_SB(1, 1), b3 + hstep, voffB); PG8_STAGE(PG8_SA(1, 0), a3, voffA);
;             PG8_WAIT_V(8); PG8_WAIT_L(0); PG8_BAR; PG8_MMA(1, 0, At, B0); PG8_MMA(1, 1, At, B1); PG8_BAR; PG8_SCHED;
	s_add_i32 s40, s50, s43
	v_lshl_add_u64 v[172:173], v[172:173], 0, s[84:85]
	s_mov_b32 m0, s40
	ds_read_b128 v[182:185], v177 offset:49152
	ds_read_b128 v[186:189], v177 offset:50176
	ds_read_b128 v[204:207], v177 offset:51200
	ds_read_b128 v[208:211], v177 offset:52224
	ds_read_b128 v[212:215], v177 offset:53248
	ds_read_b128 v[216:219], v177 offset:54272
	ds_read_b128 v[220:223], v177 offset:55296
	ds_read_b128 v[224:227], v177 offset:56320
	global_load_lds_dwordx4 v[172:173], off
	s_add_i32 m0, s40, 0x2000
	s_add_u32 s36, s36, 0x80080
	v_lshl_add_u64 v[172:173], v[190:191], 0, s[84:85]
	s_addc_u32 s37, s37, 0
	s_add_i32 s40, s51, s43
	global_load_lds_dwordx4 v[172:173], off
	v_lshl_add_u64 v[172:173], s[36:37], 0, v[2:3]
	s_mov_b32 m0, s40
	s_nop 0
	global_load_lds_dwordx4 v[172:173], off
	v_lshl_add_u64 v[172:173], s[36:37], 0, v[148:149]
	s_add_i32 m0, s40, 0x2000
	s_nop 0
	global_load_lds_dwordx4 v[172:173], off
	v_lshl_add_u64 v[172:173], v[228:229], 0, s[84:85]
	s_mov_b32 m0, s52
	s_nop 0
	global_load_lds_dwordx4 v[172:173], off
	v_lshl_add_u64 v[172:173], v[240:241], 0, s[84:85]
	s_mov_b32 m0, s53
	s_nop 0
	global_load_lds_dwordx4 v[172:173], off
	s_waitcnt vmcnt(8)
	s_waitcnt lgkmcnt(0)
	s_barrier
	s_setprio 1
	s_waitcnt lgkmcnt(0)
	v_mfma_i32_16x16x64_i8 v[64:67], v[116:119], v[182:185], v[64:67]
	v_mfma_i32_16x16x64_i8 v[64:67], v[124:127], v[186:189], v[64:67]
	v_mfma_i32_16x16x64_i8 v[60:63], v[132:135], v[182:185], v[60:63]
	v_mfma_i32_16x16x64_i8 v[60:63], v[136:139], v[186:189], v[60:63]
	v_mfma_i32_16x16x64_i8 v[48:51], v[116:119], v[204:207], v[48:51]
	v_mfma_i32_16x16x64_i8 v[48:51], v[124:127], v[208:211], v[48:51]
	v_mfma_i32_16x16x64_i8 v[44:47], v[132:135], v[204:207], v[44:47]
	v_mfma_i32_16x16x64_i8 v[44:47], v[136:139], v[208:211], v[44:47]
	v_mfma_i32_16x16x64_i8 v[32:35], v[116:119], v[212:215], v[32:35]
	v_mfma_i32_16x16x64_i8 v[32:35], v[124:127], v[216:219], v[32:35]
	v_mfma_i32_16x16x64_i8 v[28:31], v[132:135], v[212:215], v[28:31]
	v_mfma_i32_16x16x64_i8 v[28:31], v[136:139], v[216:219], v[28:31]
	v_mfma_i32_16x16x64_i8 v[16:19], v[116:119], v[220:223], v[16:19]
	v_mfma_i32_16x16x64_i8 v[16:19], v[124:127], v[224:227], v[16:19]
	v_mfma_i32_16x16x64_i8 v[12:15], v[132:135], v[220:223], v[12:15]
	v_mfma_i32_16x16x64_i8 v[12:15], v[136:139], v[224:227], v[12:15]
	s_setprio 0
	s_setprio 1
	v_mfma_i32_16x16x64_i8 v[56:59], v[160:163], v[182:185], v[56:59]
	v_mfma_i32_16x16x64_i8 v[56:59], v[164:167], v[186:189], v[56:59]
	v_mfma_i32_16x16x64_i8 v[52:55], v[168:171], v[182:185], v[52:55]
	v_mfma_i32_16x16x64_i8 v[52:55], v[178:181], v[186:189], v[52:55]
	v_mfma_i32_16x16x64_i8 v[40:43], v[160:163], v[204:207], v[40:43]
	v_mfma_i32_16x16x64_i8 v[40:43], v[164:167], v[208:211], v[40:43]
	v_mfma_i32_16x16x64_i8 v[36:39], v[168:171], v[204:207], v[36:39]
	v_mfma_i32_16x16x64_i8 v[36:39], v[178:181], v[208:211], v[36:39]
	v_mfma_i32_16x16x64_i8 v[24:27], v[160:163], v[212:215], v[24:27]
	v_mfma_i32_16x16x64_i8 v[24:27], v[164:167], v[216:219], v[24:27]
	v_mfma_i32_16x16x64_i8 v[20:23], v[168:171], v[212:215], v[20:23]
	v_mfma_i32_16x16x64_i8 v[20:23], v[178:181], v[216:219], v[20:23]
	v_mfma_i32_16x16x64_i8 v[8:11], v[160:163], v[220:223], v[8:11]
	v_mfma_i32_16x16x64_i8 v[8:11], v[164:167], v[224:227], v[8:11]
	v_mfma_i32_16x16x64_i8 v[4:7], v[168:171], v[220:223], v[4:7]
	v_mfma_i32_16x16x64_i8 v[4:7], v[178:181], v[224:227], v[4:7]
	s_setprio 0
	s_barrier
	s_add_i32 s76, s76, 2
	s_add_u32 s26, s26, 0x100
	s_addc_u32 s27, s27, 0
	s_add_u32 s72, s72, 0x100
	s_addc_u32 s73, s73, 0
	s_cmp_gt_u32 s76, 29
	s_cbranch_scc1 .Lkloop_exit_0
.LBB0_208:
	s_add_u32 s36, s26, 0xfff80080
	s_addc_u32 s37, s27, -1
	s_add_i32 s50, 0, 0x10000
	s_cmp_eq_u32 s76, 28
	s_cselect_b32 s41, s19, s37
	s_cselect_b32 s40, s64, s36
	s_cselect_b32 s37, s17, s73
	s_cselect_b32 s36, s65, s72
	s_add_i32 s56, 0, 0x14000
	v_add_u32_e32 v136, s50, v175
	v_add_u32_e32 v172, s56, v175
	ds_read_b128 v[116:119], v136
	ds_read_b128 v[124:127], v136 offset:1024
	ds_read_b128 v[132:135], v136 offset:2048
	ds_read_b128 v[136:139], v136 offset:3072
	ds_read_b128 v[160:163], v172
	ds_read_b128 v[164:167], v172 offset:1024
	ds_read_b128 v[168:171], v172 offset:2048
	ds_read_b128 v[178:181], v172 offset:3072
	v_lshl_add_u64 v[172:173], s[26:27], 0, v[156:157]
	s_add_i32 m0, s44, 0xc000
	ds_read_b128 v[182:185], v177
	ds_read_b128 v[186:189], v177 offset:1024
	ds_read_b128 v[204:207], v177 offset:2048
	ds_read_b128 v[208:211], v177 offset:3072
	ds_read_b128 v[212:215], v177 offset:4096
	ds_read_b128 v[216:219], v177 offset:5120
	ds_read_b128 v[220:223], v177 offset:6144
	ds_read_b128 v[224:227], v177 offset:7168
	global_load_lds_dwordx4 v[172:173], off
	v_lshl_add_u64 v[172:173], s[26:27], 0, v[158:159]
	s_add_i32 m0, s44, 0xe000
	s_nop 0
	global_load_lds_dwordx4 v[172:173], off
	s_waitcnt vmcnt(8)
	s_waitcnt lgkmcnt(0)
	s_barrier
; #define PG8_STAGE(bufoff, gbase, voff) do { _Pragma("unroll") for (int _i = 0; _i < 2; ++_i) \
;         __builtin_amdgcn_global_load_lds((const unsigned*)((const char*)(gbase) + (voff)[_i]), (PG8_LAS unsigned*)(lds + (bufoff) + ldsw + _i * 8192), 16, 0, 0); } while (0)
; #define PG8_LDA(dst, b, h) do { _Pragma("unroll") for (int m = 0; m < 4; ++m) _Pragma("unroll") for (int k = 0; k < 2; ++k) dst[m][k] = *(const PG8_LAS bf16x8*)(lds + PG8_SA(b, h) + aoff + m * 2048 + k * 1024); } while (0)
; #define PG8_LDB(dst, b, h) do { _Pragma("unroll") for (int n = 0; n < 2; ++n) _Pragma("unroll") for (int k = 0; k < 2; ++k) dst[n][k] = *(const PG8_LAS bf16x8*)(lds + PG8_SB(b, h) + boff + n * 2048 + k * 1024); } while (0)
; #define PG8_WAIT_V(n) asm volatile("s_waitcnt vmcnt(" #n ")" ::: "memory")
; #define PG8_WAIT_L(n) asm volatile("s_waitcnt lgkmcnt(" #n ")" ::: "memory")
; #define PG8_BAR __builtin_amdgcn_s_barrier()
; #define PG8_SCHED __builtin_amdgcn_sched_barrier(0)
; template <class Epi, class Sched, bool ALIGN_EPI = false, bool SP2 = false, bool I8 = false>
; __device__ __forceinline__ void gemm_phase(PG8_LAS unsigned char* lds, const Gemm g, const Sched& S, const Epi& E) {
;     ...
;             PG8_LDB(B0, 0, 0); PG8_LDB(B1, 0, 1); PG8_SCHED; PG8_LDA(At, 0, 0); PG8_STAGE(PG8_SA(1, 1), a1 + hstep, voffA);
;             PG8_WAIT_V(8); PG8_WAIT_L(0); PG8_BAR; PG8_MMA(0, 0, At, B0); PG8_MMA(0, 1, At, B1); PG8_BAR; PG8_SCHED;
;             PG8_LDA(At, 0, 1); PG8_STAGE(PG8_SB(0, 0), b2, voffB); PG8_STAGE(PG8_SB(0, 1), b2 + hstep, voffB); PG8_STAGE(PG8_SA(0, 0), a2, voffA);
;             PG8_WAIT_V(8); PG8_WAIT_L(0); PG8_BAR; PG8_MMA(1, 0, At, B0); PG8_MMA(1, 1, At, B1); PG8_BAR; PG8_SCHED;
	s_setprio 1
	s_waitcnt lgkmcnt(0)
	v_mfma_i32_16x16x64_i8 v[144:147], v[116:119], v[182:185], v[144:147]
	v_mfma_i32_16x16x64_i8 v[144:147], v[124:127], v[186:189], v[144:147]
	v_mfma_i32_16x16x64_i8 v[140:143], v[132:135], v[182:185], v[140:143]
	v_mfma_i32_16x16x64_i8 v[140:143], v[136:139], v[186:189], v[140:143]
	v_mfma_i32_16x16x64_i8 v[112:115], v[116:119], v[204:207], v[112:115]
	v_mfma_i32_16x16x64_i8 v[112:115], v[124:127], v[208:211], v[112:115]
	v_mfma_i32_16x16x64_i8 v[108:111], v[132:135], v[204:207], v[108:111]
	v_mfma_i32_16x16x64_i8 v[108:111], v[136:139], v[208:211], v[108:111]
	v_mfma_i32_16x16x64_i8 v[96:99], v[116:119], v[212:215], v[96:99]
	v_mfma_i32_16x16x64_i8 v[96:99], v[124:127], v[216:219], v[96:99]
	v_mfma_i32_16x16x64_i8 v[92:95], v[132:135], v[212:215], v[92:95]
	v_mfma_i32_16x16x64_i8 v[92:95], v[136:139], v[216:219], v[92:95]
	v_mfma_i32_16x16x64_i8 v[80:83], v[116:119], v[220:223], v[80:83]
	v_mfma_i32_16x16x64_i8 v[80:83], v[124:127], v[224:227], v[80:83]
	v_mfma_i32_16x16x64_i8 v[76:79], v[132:135], v[220:223], v[76:79]
	v_mfma_i32_16x16x64_i8 v[76:79], v[136:139], v[224:227], v[76:79]
	s_setprio 0
	s_setprio 1
	v_mfma_i32_16x16x64_i8 v[128:131], v[160:163], v[182:185], v[128:131]
	v_mfma_i32_16x16x64_i8 v[128:131], v[164:167], v[186:189], v[128:131]
	v_mfma_i32_16x16x64_i8 v[120:123], v[168:171], v[182:185], v[120:123]
	v_mfma_i32_16x16x64_i8 v[120:123], v[178:181], v[186:189], v[120:123]
	v_mfma_i32_16x16x64_i8 v[104:107], v[160:163], v[204:207], v[104:107]
	v_mfma_i32_16x16x64_i8 v[104:107], v[164:167], v[208:211], v[104:107]
	v_mfma_i32_16x16x64_i8 v[100:103], v[168:171], v[204:207], v[100:103]
	v_mfma_i32_16x16x64_i8 v[100:103], v[178:181], v[208:211], v[100:103]
	v_mfma_i32_16x16x64_i8 v[88:91], v[160:163], v[212:215], v[88:91]
	v_mfma_i32_16x16x64_i8 v[88:91], v[164:167], v[216:219], v[88:91]
	v_mfma_i32_16x16x64_i8 v[84:87], v[168:171], v[212:215], v[84:87]
	v_mfma_i32_16x16x64_i8 v[84:87], v[178:181], v[216:219], v[84:87]
	v_mfma_i32_16x16x64_i8 v[72:75], v[160:163], v[220:223], v[72:75]
	v_mfma_i32_16x16x64_i8 v[72:75], v[164:167], v[224:227], v[72:75]
	v_mfma_i32_16x16x64_i8 v[68:71], v[168:171], v[220:223], v[68:71]
	v_mfma_i32_16x16x64_i8 v[68:71], v[178:181], v[224:227], v[68:71]
	s_setprio 0
	s_barrier
	s_add_i32 s50, s50, s43
	v_lshl_add_u64 v[172:173], s[36:37], 0, v[2:3]
	s_mov_b32 m0, s50
	ds_read_b128 v[182:185], v177 offset:16384
	ds_read_b128 v[186:189], v177 offset:17408
	ds_read_b128 v[204:207], v177 offset:18432
	ds_read_b128 v[208:211], v177 offset:19456
	ds_read_b128 v[212:215], v177 offset:20480
	ds_read_b128 v[216:219], v177 offset:21504
	ds_read_b128 v[220:223], v177 offset:22528
	ds_read_b128 v[224:227], v177 offset:23552
	global_load_lds_dwordx4 v[172:173], off
	s_add_i32 m0, s50, 0x2000
	s_add_u32 s50, s36, 0x80000
	v_lshl_add_u64 v[190:191], s[36:37], 0, v[148:149]
	s_addc_u32 s51, s37, 0
	s_add_i32 s56, s56, s43
	global_load_lds_dwordx4 v[190:191], off
	v_lshl_add_u64 v[228:229], s[50:51], 0, v[2:3]
	s_mov_b32 m0, s56
	v_lshl_add_u64 v[240:241], s[40:41], 0, v[150:151]
	global_load_lds_dwordx4 v[228:229], off
	v_lshl_add_u64 v[228:229], s[50:51], 0, v[148:149]
	s_add_i32 m0, s56, 0x2000
	s_nop 0
	global_load_lds_dwordx4 v[228:229], off
	v_lshl_add_u64 v[228:229], s[40:41], 0, v[152:153]
	s_mov_b32 m0, s44
	s_nop 0
	global_load_lds_dwordx4 v[228:229], off
	s_mov_b32 m0, s45
	s_nop 0
	global_load_lds_dwordx4 v[240:241], off
	s_waitcnt vmcnt(8)
	s_waitcnt lgkmcnt(0)
	s_barrier
	s_setprio 1
	s_waitcnt lgkmcnt(0)
	v_mfma_i32_16x16x64_i8 v[64:67], v[116:119], v[182:185], v[64:67]
	v_mfma_i32_16x16x64_i8 v[64:67], v[124:127], v[186:189], v[64:67]
	v_mfma_i32_16x16x64_i8 v[60:63], v[132:135], v[182:185], v[60:63]
	v_mfma_i32_16x16x64_i8 v[60:63], v[136:139], v[186:189], v[60:63]
	v_mfma_i32_16x16x64_i8 v[48:51], v[116:119], v[204:207], v[48:51]
	v_mfma_i32_16x16x64_i8 v[48:51], v[124:127], v[208:211], v[48:51]
	v_mfma_i32_16x16x64_i8 v[44:47], v[132:135], v[204:207], v[44:47]
	v_mfma_i32_16x16x64_i8 v[44:47], v[136:139], v[208:211], v[44:47]
	v_mfma_i32_16x16x64_i8 v[32:35], v[116:119], v[212:215], v[32:35]
	v_mfma_i32_16x16x64_i8 v[32:35], v[124:127], v[216:219], v[32:35]
	v_mfma_i32_16x16x64_i8 v[28:31], v[132:135], v[212:215], v[28:31]
	v_mfma_i32_16x16x64_i8 v[28:31], v[136:139], v[216:219], v[28:31]
	v_mfma_i32_16x16x64_i8 v[16:19], v[116:119], v[220:223], v[16:19]
	v_mfma_i32_16x16x64_i8 v[16:19], v[124:127], v[224:227], v[16:19]
	v_mfma_i32_16x16x64_i8 v[12:15], v[132:135], v[220:223], v[12:15]
	v_mfma_i32_16x16x64_i8 v[12:15], v[136:139], v[224:227], v[12:15]
	s_setprio 0
	s_setprio 1
	v_mfma_i32_16x16x64_i8 v[56:59], v[160:163], v[182:185], v[56:59]
	v_mfma_i32_16x16x64_i8 v[56:59], v[164:167], v[186:189], v[56:59]
	v_mfma_i32_16x16x64_i8 v[52:55], v[168:171], v[182:185], v[52:55]
	v_mfma_i32_16x16x64_i8 v[52:55], v[178:181], v[186:189], v[52:55]
	v_mfma_i32_16x16x64_i8 v[40:43], v[160:163], v[204:207], v[40:43]
	v_mfma_i32_16x16x64_i8 v[40:43], v[164:167], v[208:211], v[40:43]
	v_mfma_i32_16x16x64_i8 v[36:39], v[168:171], v[204:207], v[36:39]
	v_mfma_i32_16x16x64_i8 v[36:39], v[178:181], v[208:211], v[36:39]
	v_mfma_i32_16x16x64_i8 v[24:27], v[160:163], v[212:215], v[24:27]
	v_mfma_i32_16x16x64_i8 v[24:27], v[164:167], v[216:219], v[24:27]
	v_mfma_i32_16x16x64_i8 v[20:23], v[168:171], v[212:215], v[20:23]
	v_mfma_i32_16x16x64_i8 v[20:23], v[178:181], v[216:219], v[20:23]
	v_mfma_i32_16x16x64_i8 v[8:11], v[160:163], v[220:223], v[8:11]
	v_mfma_i32_16x16x64_i8 v[8:11], v[164:167], v[224:227], v[8:11]
	v_mfma_i32_16x16x64_i8 v[4:7], v[168:171], v[220:223], v[4:7]
	v_mfma_i32_16x16x64_i8 v[4:7], v[178:181], v[224:227], v[4:7]
	s_setprio 0
	s_barrier
; #define PG8_STAGE(bufoff, gbase, voff) do { _Pragma("unroll") for (int _i = 0; _i < 2; ++_i) \
;         __builtin_amdgcn_global_load_lds((const unsigned*)((const char*)(gbase) + (voff)[_i]), (PG8_LAS unsigned*)(lds + (bufoff) + ldsw + _i * 8192), 16, 0, 0); } while (0)
; #define PG8_LDA(dst, b, h) do { _Pragma("unroll") for (int m = 0; m < 4; ++m) _Pragma("unroll") for (int k = 0; k < 2; ++k) dst[m][k] = *(const PG8_LAS bf16x8*)(lds + PG8_SA(b, h) + aoff + m * 2048 + k * 1024); } while (0)
; #define PG8_LDB(dst, b, h) do { _Pragma("unroll") for (int n = 0; n < 2; ++n) _Pragma("unroll") for (int k = 0; k < 2; ++k) dst[n][k] = *(const PG8_LAS bf16x8*)(lds + PG8_SB(b, h) + boff + n * 2048 + k * 1024); } while (0)
; #define PG8_WAIT_V(n) asm volatile("s_waitcnt vmcnt(" #n ")" ::: "memory")
; #define PG8_WAIT_L(n) asm volatile("s_waitcnt lgkmcnt(" #n ")" ::: "memory")
; #define PG8_BAR __builtin_amdgcn_s_barrier()
; #define PG8_SCHED __builtin_amdgcn_sched_barrier(0)
; template <class Epi, class Sched, bool ALIGN_EPI = false, bool SP2 = false, bool I8 = false>
; __device__ __forceinline__ void gemm_phase(PG8_LAS unsigned char* lds, const Gemm g, const Sched& S, const Epi& E) {
;     ...
;             PG8_LDB(B0, 1, 0); PG8_LDB(B1, 1, 1); PG8_SCHED; PG8_LDA(At, 1, 0); PG8_STAGE(PG8_SA(0, 1), a2 + hstep, voffA);
;             PG8_WAIT_V(8); PG8_WAIT_L(0); PG8_BAR; PG8_MMA(0, 0, At, B0); PG8_MMA(0, 1, At, B1); PG8_BAR; PG8_SCHED;
;             PG8_LDA(At, 1, 1); PG8_STAGE(PG8_SB(1, 0), b3, voffB); PG8_STAGE(PG8_SB(1, 1), b3 + hstep, voffB); PG8_STAGE(PG8_SA(1, 0), a3, voffA);
;             PG8_WAIT_V(8); PG8_WAIT_L(0); PG8_BAR; PG8_MMA(1, 0, At, B0); PG8_MMA(1, 1, At, B1); PG8_BAR; PG8_SCHED;
	s_add_i32 s50, 0, 0x18000
	s_add_i32 s51, 0, 0x1c000
	v_add_u32_e32 v136, s50, v175
	v_add_u32_e32 v178, s51, v175
	ds_read_b128 v[116:119], v136
	ds_read_b128 v[124:127], v136 offset:1024
	ds_read_b128 v[132:135], v136 offset:2048
	ds_read_b128 v[136:139], v136 offset:3072
	ds_read_b128 v[160:163], v178
	ds_read_b128 v[164:167], v178 offset:1024
	ds_read_b128 v[168:171], v178 offset:2048
	ds_read_b128 v[178:181], v178 offset:3072
	s_add_u32 s40, s40, 0x80000
	s_addc_u32 s41, s41, 0
	s_mov_b32 m0, s46
	v_lshl_add_u64 v[242:243], s[40:41], 0, v[152:153]
	ds_read_b128 v[182:185], v177 offset:32768
	ds_read_b128 v[186:189], v177 offset:33792
	ds_read_b128 v[204:207], v177 offset:34816
	ds_read_b128 v[208:211], v177 offset:35840
	ds_read_b128 v[212:215], v177 offset:36864
	ds_read_b128 v[216:219], v177 offset:37888
	ds_read_b128 v[220:223], v177 offset:38912
	ds_read_b128 v[224:227], v177 offset:39936
	global_load_lds_dwordx4 v[242:243], off
	v_lshl_add_u64 v[242:243], s[40:41], 0, v[150:151]
	s_mov_b32 m0, s47
	s_nop 0
	global_load_lds_dwordx4 v[242:243], off
	s_waitcnt vmcnt(8)
	s_waitcnt lgkmcnt(0)
	s_barrier
	s_setprio 1
	s_waitcnt lgkmcnt(0)
	v_mfma_i32_16x16x64_i8 v[144:147], v[116:119], v[182:185], v[144:147]
	v_mfma_i32_16x16x64_i8 v[144:147], v[124:127], v[186:189], v[144:147]
	v_mfma_i32_16x16x64_i8 v[140:143], v[132:135], v[182:185], v[140:143]
	v_mfma_i32_16x16x64_i8 v[140:143], v[136:139], v[186:189], v[140:143]
	v_mfma_i32_16x16x64_i8 v[112:115], v[116:119], v[204:207], v[112:115]
	v_mfma_i32_16x16x64_i8 v[112:115], v[124:127], v[208:211], v[112:115]
	v_mfma_i32_16x16x64_i8 v[108:111], v[132:135], v[204:207], v[108:111]
	v_mfma_i32_16x16x64_i8 v[108:111], v[136:139], v[208:211], v[108:111]
	v_mfma_i32_16x16x64_i8 v[96:99], v[116:119], v[212:215], v[96:99]
	v_mfma_i32_16x16x64_i8 v[96:99], v[124:127], v[216:219], v[96:99]
	v_mfma_i32_16x16x64_i8 v[92:95], v[132:135], v[212:215], v[92:95]
	v_mfma_i32_16x16x64_i8 v[92:95], v[136:139], v[216:219], v[92:95]
	v_mfma_i32_16x16x64_i8 v[80:83], v[116:119], v[220:223], v[80:83]
	v_mfma_i32_16x16x64_i8 v[80:83], v[124:127], v[224:227], v[80:83]
	v_mfma_i32_16x16x64_i8 v[76:79], v[132:135], v[220:223], v[76:79]
	v_mfma_i32_16x16x64_i8 v[76:79], v[136:139], v[224:227], v[76:79]
	s_setprio 0
	s_setprio 1
	v_mfma_i32_16x16x64_i8 v[128:131], v[160:163], v[182:185], v[128:131]
	v_mfma_i32_16x16x64_i8 v[128:131], v[164:167], v[186:189], v[128:131]
	v_mfma_i32_16x16x64_i8 v[120:123], v[168:171], v[182:185], v[120:123]
	v_mfma_i32_16x16x64_i8 v[120:123], v[178:181], v[186:189], v[120:123]
	v_mfma_i32_16x16x64_i8 v[104:107], v[160:163], v[204:207], v[104:107]
	v_mfma_i32_16x16x64_i8 v[104:107], v[164:167], v[208:211], v[104:107]
	v_mfma_i32_16x16x64_i8 v[100:103], v[168:171], v[204:207], v[100:103]
	v_mfma_i32_16x16x64_i8 v[100:103], v[178:181], v[208:211], v[100:103]
	v_mfma_i32_16x16x64_i8 v[88:91], v[160:163], v[212:215], v[88:91]
	v_mfma_i32_16x16x64_i8 v[88:91], v[164:167], v[216:219], v[88:91]
	v_mfma_i32_16x16x64_i8 v[84:87], v[168:171], v[212:215], v[84:87]
	v_mfma_i32_16x16x64_i8 v[84:87], v[178:181], v[216:219], v[84:87]
	v_mfma_i32_16x16x64_i8 v[72:75], v[160:163], v[220:223], v[72:75]
	v_mfma_i32_16x16x64_i8 v[72:75], v[164:167], v[224:227], v[72:75]
	v_mfma_i32_16x16x64_i8 v[68:71], v[168:171], v[220:223], v[68:71]
	v_mfma_i32_16x16x64_i8 v[68:71], v[178:181], v[224:227], v[68:71]
	s_setprio 0
	s_barrier
	s_add_i32 s40, s50, s43
	v_lshl_add_u64 v[172:173], v[172:173], 0, s[84:85]
	s_mov_b32 m0, s40
	ds_read_b128 v[182:185], v177 offset:49152
	ds_read_b128 v[186:189], v177 offset:50176
	ds_read_b128 v[204:207], v177 offset:51200
	ds_read_b128 v[208:211], v177 offset:52224
	ds_read_b128 v[212:215], v177 offset:53248
	ds_read_b128 v[216:219], v177 offset:54272
	ds_read_b128 v[220:223], v177 offset:55296
	ds_read_b128 v[224:227], v177 offset:56320
	global_load_lds_dwordx4 v[172:173], off
	s_add_i32 m0, s40, 0x2000
	s_add_u32 s36, s36, 0x80080
	v_lshl_add_u64 v[172:173], v[190:191], 0, s[84:85]
	s_addc_u32 s37, s37, 0
	s_add_i32 s40, s51, s43
	global_load_lds_dwordx4 v[172:173], off
	v_lshl_add_u64 v[172:173], s[36:37], 0, v[2:3]
	s_mov_b32 m0, s40
	s_nop 0
	global_load_lds_dwordx4 v[172:173], off
	v_lshl_add_u64 v[172:173], s[36:37], 0, v[148:149]
	s_add_i32 m0, s40, 0x2000
	s_nop 0
	global_load_lds_dwordx4 v[172:173], off
	v_lshl_add_u64 v[172:173], v[228:229], 0, s[84:85]
	s_mov_b32 m0, s52
	s_nop 0
	global_load_lds_dwordx4 v[172:173], off
	v_lshl_add_u64 v[172:173], v[240:241], 0, s[84:85]
	s_mov_b32 m0, s53
	s_nop 0
	global_load_lds_dwordx4 v[172:173], off
	s_waitcnt vmcnt(8)
	s_waitcnt lgkmcnt(0)
	s_barrier
	s_setprio 1
	s_waitcnt lgkmcnt(0)
	v_mfma_i32_16x16x64_i8 v[64:67], v[116:119], v[182:185], v[64:67]
	v_mfma_i32_16x16x64_i8 v[64:67], v[124:127], v[186:189], v[64:67]
	v_mfma_i32_16x16x64_i8 v[60:63], v[132:135], v[182:185], v[60:63]
	v_mfma_i32_16x16x64_i8 v[60:63], v[136:139], v[186:189], v[60:63]
	v_mfma_i32_16x16x64_i8 v[48:51], v[116:119], v[204:207], v[48:51]
	v_mfma_i32_16x16x64_i8 v[48:51], v[124:127], v[208:211], v[48:51]
	v_mfma_i32_16x16x64_i8 v[44:47], v[132:135], v[204:207], v[44:47]
	v_mfma_i32_16x16x64_i8 v[44:47], v[136:139], v[208:211], v[44:47]
	v_mfma_i32_16x16x64_i8 v[32:35], v[116:119], v[212:215], v[32:35]
	v_mfma_i32_16x16x64_i8 v[32:35], v[124:127], v[216:219], v[32:35]
	v_mfma_i32_16x16x64_i8 v[28:31], v[132:135], v[212:215], v[28:31]
	v_mfma_i32_16x16x64_i8 v[28:31], v[136:139], v[216:219], v[28:31]
	v_mfma_i32_16x16x64_i8 v[16:19], v[116:119], v[220:223], v[16:19]
	v_mfma_i32_16x16x64_i8 v[16:19], v[124:127], v[224:227], v[16:19]
	v_mfma_i32_16x16x64_i8 v[12:15], v[132:135], v[220:223], v[12:15]
	v_mfma_i32_16x16x64_i8 v[12:15], v[136:139], v[224:227], v[12:15]
	s_setprio 0
	s_setprio 1
	v_mfma_i32_16x16x64_i8 v[56:59], v[160:163], v[182:185], v[56:59]
	v_mfma_i32_16x16x64_i8 v[56:59], v[164:167], v[186:189], v[56:59]
	v_mfma_i32_16x16x64_i8 v[52:55], v[168:171], v[182:185], v[52:55]
	v_mfma_i32_16x16x64_i8 v[52:55], v[178:181], v[186:189], v[52:55]
	v_mfma_i32_16x16x64_i8 v[40:43], v[160:163], v[204:207], v[40:43]
	v_mfma_i32_16x16x64_i8 v[40:43], v[164:167], v[208:211], v[40:43]
	v_mfma_i32_16x16x64_i8 v[36:39], v[168:171], v[204:207], v[36:39]
	v_mfma_i32_16x16x64_i8 v[36:39], v[178:181], v[208:211], v[36:39]
	v_mfma_i32_16x16x64_i8 v[24:27], v[160:163], v[212:215], v[24:27]
	v_mfma_i32_16x16x64_i8 v[24:27], v[164:167], v[216:219], v[24:27]
	v_mfma_i32_16x16x64_i8 v[20:23], v[168:171], v[212:215], v[20:23]
	v_mfma_i32_16x16x64_i8 v[20:23], v[178:181], v[216:219], v[20:23]
	v_mfma_i32_16x16x64_i8 v[8:11], v[160:163], v[220:223], v[8:11]
	v_mfma_i32_16x16x64_i8 v[8:11], v[164:167], v[224:227], v[8:11]
	v_mfma_i32_16x16x64_i8 v[4:7], v[168:171], v[220:223], v[4:7]
	v_mfma_i32_16x16x64_i8 v[4:7], v[178:181], v[224:227], v[4:7]
	s_setprio 0
	s_barrier
	s_add_i32 s76, s76, 2
	s_add_u32 s26, s26, 0x100
	s_addc_u32 s27, s27, 0
	s_add_u32 s72, s72, 0x100
	s_addc_u32 s73, s73, 0
	s_cmp_gt_u32 s76, 29
	s_cbranch_scc0 .LBB0_208

; #define PG8_STAGE(bufoff, gbase, voff) do { _Pragma("unroll") for (int _i = 0; _i < 2; ++_i) \
;         __builtin_amdgcn_global_load_lds((const unsigned*)((const char*)(gbase) + (voff)[_i]), (PG8_LAS unsigned*)(lds + (bufoff) + ldsw + _i * 8192), 16, 0, 0); } while (0)
; #define PG8_LDA(dst, b, h) do { _Pragma("unroll") for (int m = 0; m < 4; ++m) _Pragma("unroll") for (int k = 0; k < 2; ++k) dst[m][k] = *(const PG8_LAS bf16x8*)(lds + PG8_SA(b, h) + aoff + m * 2048 + k * 1024); } while (0)
; #define PG8_LDB(dst, b, h) do { _Pragma("unroll") for (int n = 0; n < 2; ++n) _Pragma("unroll") for (int k = 0; k < 2; ++k) dst[n][k] = *(const PG8_LAS bf16x8*)(lds + PG8_SB(b, h) + boff + n * 2048 + k * 1024); } while (0)
; #define PG8_WAIT_V(n) asm volatile("s_waitcnt vmcnt(" #n ")" ::: "memory")
; #define PG8_WAIT_L(n) asm volatile("s_waitcnt lgkmcnt(" #n ")" ::: "memory")
; #define PG8_BAR __builtin_amdgcn_s_barrier()
; #define PG8_SCHED __builtin_amdgcn_sched_barrier(0)
; template <class Epi, class Sched, bool ALIGN_EPI = false, bool SP2 = false, bool I8 = false>
; __device__ __forceinline__ void gemm_phase(PG8_LAS unsigned char* lds, const Gemm g, const Sched& S, const Epi& E) {
;     ...
;         const bool has_next = S.next(ui + 1, nxt);
;         const char* nA = has_next ? (const char*)g.A + (size_t)nxt.pm * tstep : cA; const char* nB = has_next ? (const char*)g.Bt + (size_t)nxt.pn * tstep : cB;
;         for (int t = 0; t < nt; t += 2) {
;             const bool last = (t == nt - 2);
;             const char* a1 = cA + (size_t)(t + 1) * kstep;
;             const char* a2 = last ? nA : cA + (size_t)(t + 2) * kstep; const char* b2 = last ? nB : cB + (size_t)(t + 2) * kstep;
;             const char* a3 = a2 + kstep; const char* b3 = b2 + kstep;
;             if (last && has_next) S.a_ready(nxt);
;             if constexpr (SP2) {
;             PG8_LDB(B0, 0, 0); PG8_LDB(B1, 0, 1); PG8_SCHED; PG8_LDA(At, 0, 0); PG8_STAGE(PG8_SA(1, 1), a1 + hstep, voffA);
;             PG8_WAIT_V(8); PG8_WAIT_L(0); PG8_BAR; PG8_MMA(0, 0, At, B0); PG8_MMA(0, 1, At, B1); PG8_BAR; PG8_SCHED;
;             PG8_LDA(At, 0, 1); PG8_STAGE(PG8_SB(0, 0), b2, voffB); PG8_STAGE(PG8_SB(0, 1), b2 + hstep, voffB); PG8_STAGE(PG8_SA(0, 0), a2, voffA);
;             PG8_WAIT_V(8); PG8_WAIT_L(0); PG8_BAR; PG8_MMA(1, 0, At, B0); PG8_MMA(1, 1, At, B1); PG8_BAR; PG8_SCHED;
.LBB0_229:
	s_ashr_i32 s37, s36, 31
	s_lshl_b64 s[34:35], s[36:37], 21
	s_add_u32 s40, s42, s34
	s_addc_u32 s41, s43, s35
	s_and_b64 s[34:35], s[8:9], exec
	s_cselect_b32 s11, s41, s13
	s_cselect_b32 s34, s40, s12
	s_ashr_i32 s27, s26, 31
	s_lshl_b64 s[50:51], s[26:27], 21
	s_add_u32 s54, s44, s50
	s_addc_u32 s55, s45, s51
	s_and_b64 s[50:51], s[8:9], exec
	s_cselect_b32 s27, s55, s73
	s_cselect_b32 s35, s54, s72
	s_add_u32 s12, s12, 0x100080
	s_addc_u32 s13, s13, 0
	s_add_u32 s37, s72, 0x100
	s_addc_u32 s61, s73, 0
	s_mov_b32 s97, -2
	s_add_u32 s50, s12, 0xfff00080
	s_addc_u32 s51, s13, -1
	s_add_i32 s56, 0, 0x10000
	s_cmp_eq_u32 s97, 60
	s_cselect_b32 s77, s11, s51
	s_cselect_b32 s76, s34, s50
	s_cselect_b32 s73, s27, s61
	s_cselect_b32 s72, s35, s37
	s_add_i32 s57, 0, 0x14000
	v_add_u32_e32 v156, s56, v171
	v_add_u32_e32 v168, s57, v171
	s_waitcnt vmcnt(0)
	ds_read_b128 v[112:115], v156
	ds_read_b128 v[120:123], v156 offset:1024
	ds_read_b128 v[152:155], v156 offset:2048
	ds_read_b128 v[156:159], v156 offset:3072
	ds_read_b128 v[160:163], v168
	ds_read_b128 v[164:167], v168 offset:1024
	s_waitcnt lgkmcnt(0)
	ds_read_b128 v[176:179], v168 offset:2048
	ds_read_b128 v[180:183], v168 offset:3072
	v_lshl_add_u64 v[168:169], s[12:13], 0, v[148:149]
	s_add_i32 m0, s47, 0xc000
	ds_read_b128 v[184:187], v173
	ds_read_b128 v[188:191], v173 offset:1024
	ds_read_b128 v[204:207], v173 offset:2048
	ds_read_b128 v[208:211], v173 offset:3072
	ds_read_b128 v[212:215], v173 offset:4096
	ds_read_b128 v[216:219], v173 offset:5120
	ds_read_b128 v[220:223], v173 offset:6144
	ds_read_b128 v[224:227], v173 offset:7168
	global_load_lds_dwordx4 v[168:169], off
	v_lshl_add_u64 v[168:169], s[12:13], 0, v[150:151]
	s_add_i32 m0, s47, 0xe000
	s_nop 0
	global_load_lds_dwordx4 v[168:169], off
	s_waitcnt vmcnt(8)
	s_waitcnt lgkmcnt(0)
	s_barrier
	s_setprio 1
	s_waitcnt lgkmcnt(0)
	v_mfma_f32_16x16x32_bf16 v[136:139], v[112:115], v[184:187], 0
	v_mfma_f32_16x16x32_bf16 v[136:139], v[120:123], v[188:191], v[136:139]
	v_mfma_f32_16x16x32_bf16 v[132:135], v[152:155], v[184:187], 0
	v_mfma_f32_16x16x32_bf16 v[132:135], v[156:159], v[188:191], v[132:135]
	v_mfma_f32_16x16x32_bf16 v[116:119], v[112:115], v[204:207], 0
	v_mfma_f32_16x16x32_bf16 v[116:119], v[120:123], v[208:211], v[116:119]
	v_mfma_f32_16x16x32_bf16 v[108:111], v[152:155], v[204:207], 0
	v_mfma_f32_16x16x32_bf16 v[108:111], v[156:159], v[208:211], v[108:111]
	v_mfma_f32_16x16x32_bf16 v[96:99], v[112:115], v[212:215], 0
	v_mfma_f32_16x16x32_bf16 v[96:99], v[120:123], v[216:219], v[96:99]
	v_mfma_f32_16x16x32_bf16 v[92:95], v[152:155], v[212:215], 0
	v_mfma_f32_16x16x32_bf16 v[92:95], v[156:159], v[216:219], v[92:95]
	v_mfma_f32_16x16x32_bf16 v[80:83], v[112:115], v[220:223], 0
	v_mfma_f32_16x16x32_bf16 v[80:83], v[120:123], v[224:227], v[80:83]
	v_mfma_f32_16x16x32_bf16 v[76:79], v[152:155], v[220:223], 0
	v_mfma_f32_16x16x32_bf16 v[76:79], v[156:159], v[224:227], v[76:79]
	s_setprio 0
	s_setprio 1
	v_mfma_f32_16x16x32_bf16 v[128:131], v[160:163], v[184:187], 0
	v_mfma_f32_16x16x32_bf16 v[128:131], v[164:167], v[188:191], v[128:131]
	v_mfma_f32_16x16x32_bf16 v[124:127], v[176:179], v[184:187], 0
	v_mfma_f32_16x16x32_bf16 v[124:127], v[180:183], v[188:191], v[124:127]
	v_mfma_f32_16x16x32_bf16 v[104:107], v[160:163], v[204:207], 0
	v_mfma_f32_16x16x32_bf16 v[104:107], v[164:167], v[208:211], v[104:107]
	v_mfma_f32_16x16x32_bf16 v[100:103], v[176:179], v[204:207], 0
	v_mfma_f32_16x16x32_bf16 v[100:103], v[180:183], v[208:211], v[100:103]
	v_mfma_f32_16x16x32_bf16 v[88:91], v[160:163], v[212:215], 0
	v_mfma_f32_16x16x32_bf16 v[88:91], v[164:167], v[216:219], v[88:91]
	v_mfma_f32_16x16x32_bf16 v[84:87], v[176:179], v[212:215], 0
	v_mfma_f32_16x16x32_bf16 v[84:87], v[180:183], v[216:219], v[84:87]
	v_mfma_f32_16x16x32_bf16 v[72:75], v[160:163], v[220:223], 0
	v_mfma_f32_16x16x32_bf16 v[72:75], v[164:167], v[224:227], v[72:75]
	v_mfma_f32_16x16x32_bf16 v[68:71], v[176:179], v[220:223], 0
	v_mfma_f32_16x16x32_bf16 v[68:71], v[180:183], v[224:227], v[68:71]
	s_setprio 0
	s_barrier
	s_add_i32 s50, s56, s46
	v_lshl_add_u64 v[168:169], s[72:73], 0, v[2:3]
	s_mov_b32 m0, s50
	ds_read_b128 v[184:187], v173 offset:16384
	ds_read_b128 v[188:191], v173 offset:17408
	ds_read_b128 v[204:207], v173 offset:18432
	ds_read_b128 v[208:211], v173 offset:19456
	ds_read_b128 v[212:215], v173 offset:20480
	ds_read_b128 v[216:219], v173 offset:21504
	ds_read_b128 v[220:223], v173 offset:22528
	ds_read_b128 v[224:227], v173 offset:23552
	global_load_lds_dwordx4 v[168:169], off
	s_add_i32 m0, s50, 0x2000
	s_add_u32 s50, s72, 0x100000
	v_lshl_add_u64 v[228:229], s[72:73], 0, v[144:145]
	s_addc_u32 s51, s73, 0
	s_add_i32 s56, s57, s46
	global_load_lds_dwordx4 v[228:229], off
	v_lshl_add_u64 v[240:241], s[50:51], 0, v[2:3]
	s_mov_b32 m0, s56
	v_lshl_add_u64 v[242:243], s[76:77], 0, v[142:143]
	global_load_lds_dwordx4 v[240:241], off
	v_lshl_add_u64 v[240:241], s[50:51], 0, v[144:145]
	s_add_i32 m0, s56, 0x2000
	s_nop 0
	global_load_lds_dwordx4 v[240:241], off
	v_lshl_add_u64 v[240:241], s[76:77], 0, v[140:141]
	s_mov_b32 m0, s47
	s_nop 0
	global_load_lds_dwordx4 v[240:241], off
	s_mov_b32 m0, s52
	s_nop 0
	global_load_lds_dwordx4 v[242:243], off
	s_waitcnt vmcnt(8)
	s_waitcnt lgkmcnt(0)
	s_barrier
; #define PG8_STAGE(bufoff, gbase, voff) do { _Pragma("unroll") for (int _i = 0; _i < 2; ++_i) \
;         __builtin_amdgcn_global_load_lds((const unsigned*)((const char*)(gbase) + (voff)[_i]), (PG8_LAS unsigned*)(lds + (bufoff) + ldsw + _i * 8192), 16, 0, 0); } while (0)
; #define PG8_LDA(dst, b, h) do { _Pragma("unroll") for (int m = 0; m < 4; ++m) _Pragma("unroll") for (int k = 0; k < 2; ++k) dst[m][k] = *(const PG8_LAS bf16x8*)(lds + PG8_SA(b, h) + aoff + m * 2048 + k * 1024); } while (0)
; #define PG8_LDB(dst, b, h) do { _Pragma("unroll") for (int n = 0; n < 2; ++n) _Pragma("unroll") for (int k = 0; k < 2; ++k) dst[n][k] = *(const PG8_LAS bf16x8*)(lds + PG8_SB(b, h) + boff + n * 2048 + k * 1024); } while (0)
; #define PG8_WAIT_V(n) asm volatile("s_waitcnt vmcnt(" #n ")" ::: "memory")
; #define PG8_WAIT_L(n) asm volatile("s_waitcnt lgkmcnt(" #n ")" ::: "memory")
; #define PG8_BAR __builtin_amdgcn_s_barrier()
; #define PG8_SCHED __builtin_amdgcn_sched_barrier(0)
; template <class Epi, class Sched, bool ALIGN_EPI = false, bool SP2 = false, bool I8 = false>
; __device__ __forceinline__ void gemm_phase(PG8_LAS unsigned char* lds, const Gemm g, const Sched& S, const Epi& E) {
;     ...
;             PG8_WAIT_V(8); PG8_WAIT_L(0); PG8_BAR; PG8_MMA(1, 0, At, B0); PG8_MMA(1, 1, At, B1); PG8_BAR; PG8_SCHED;
;             PG8_LDB(B0, 1, 0); PG8_LDB(B1, 1, 1); PG8_SCHED; PG8_LDA(At, 1, 0); PG8_STAGE(PG8_SA(0, 1), a2 + hstep, voffA);
;             PG8_WAIT_V(8); PG8_WAIT_L(0); PG8_BAR; PG8_MMA(0, 0, At, B0); PG8_MMA(0, 1, At, B1); PG8_BAR; PG8_SCHED;
	s_setprio 1
	s_waitcnt lgkmcnt(0)
	v_mfma_f32_16x16x32_bf16 v[64:67], v[112:115], v[184:187], 0
	v_mfma_f32_16x16x32_bf16 v[64:67], v[120:123], v[188:191], v[64:67]
	v_mfma_f32_16x16x32_bf16 v[60:63], v[152:155], v[184:187], 0
	v_mfma_f32_16x16x32_bf16 v[60:63], v[156:159], v[188:191], v[60:63]
	v_mfma_f32_16x16x32_bf16 v[48:51], v[112:115], v[204:207], 0
	v_mfma_f32_16x16x32_bf16 v[48:51], v[120:123], v[208:211], v[48:51]
	v_mfma_f32_16x16x32_bf16 v[44:47], v[152:155], v[204:207], 0
	v_mfma_f32_16x16x32_bf16 v[44:47], v[156:159], v[208:211], v[44:47]
	v_mfma_f32_16x16x32_bf16 v[32:35], v[112:115], v[212:215], 0
	v_mfma_f32_16x16x32_bf16 v[32:35], v[120:123], v[216:219], v[32:35]
	v_mfma_f32_16x16x32_bf16 v[28:31], v[152:155], v[212:215], 0
	v_mfma_f32_16x16x32_bf16 v[28:31], v[156:159], v[216:219], v[28:31]
	v_mfma_f32_16x16x32_bf16 v[16:19], v[112:115], v[220:223], 0
	v_mfma_f32_16x16x32_bf16 v[16:19], v[120:123], v[224:227], v[16:19]
	v_mfma_f32_16x16x32_bf16 v[12:15], v[152:155], v[220:223], 0
	v_mfma_f32_16x16x32_bf16 v[12:15], v[156:159], v[224:227], v[12:15]
	s_setprio 0
	s_setprio 1
	v_mfma_f32_16x16x32_bf16 v[56:59], v[160:163], v[184:187], 0
	v_mfma_f32_16x16x32_bf16 v[56:59], v[164:167], v[188:191], v[56:59]
	v_mfma_f32_16x16x32_bf16 v[52:55], v[176:179], v[184:187], 0
	v_mfma_f32_16x16x32_bf16 v[52:55], v[180:183], v[188:191], v[52:55]
	v_mfma_f32_16x16x32_bf16 v[40:43], v[160:163], v[204:207], 0
	v_mfma_f32_16x16x32_bf16 v[40:43], v[164:167], v[208:211], v[40:43]
	v_mfma_f32_16x16x32_bf16 v[36:39], v[176:179], v[204:207], 0
	v_mfma_f32_16x16x32_bf16 v[36:39], v[180:183], v[208:211], v[36:39]
	v_mfma_f32_16x16x32_bf16 v[24:27], v[160:163], v[212:215], 0
	v_mfma_f32_16x16x32_bf16 v[24:27], v[164:167], v[216:219], v[24:27]
	v_mfma_f32_16x16x32_bf16 v[20:23], v[176:179], v[212:215], 0
	v_mfma_f32_16x16x32_bf16 v[20:23], v[180:183], v[216:219], v[20:23]
	v_mfma_f32_16x16x32_bf16 v[8:11], v[160:163], v[220:223], 0
	v_mfma_f32_16x16x32_bf16 v[8:11], v[164:167], v[224:227], v[8:11]
	v_mfma_f32_16x16x32_bf16 v[4:7], v[176:179], v[220:223], 0
	v_mfma_f32_16x16x32_bf16 v[4:7], v[180:183], v[224:227], v[4:7]
	s_setprio 0
	s_barrier
	s_add_i32 s56, 0, 0x18000
	s_add_i32 s57, 0, 0x1c000
	v_add_u32_e32 v156, s56, v171
	v_add_u32_e32 v175, s57, v171
	ds_read_b128 v[112:115], v156
	ds_read_b128 v[120:123], v156 offset:1024
	ds_read_b128 v[152:155], v156 offset:2048
	ds_read_b128 v[156:159], v156 offset:3072
	ds_read_b128 v[160:163], v175
	ds_read_b128 v[164:167], v175 offset:1024
	ds_read_b128 v[176:179], v175 offset:2048
	ds_read_b128 v[180:183], v175 offset:3072
	s_add_u32 s50, s76, 0x100000
	s_addc_u32 s51, s77, 0
	s_mov_b32 m0, s53
	v_lshl_add_u64 v[244:245], s[50:51], 0, v[140:141]
	ds_read_b128 v[184:187], v173 offset:32768
	ds_read_b128 v[188:191], v173 offset:33792
	ds_read_b128 v[204:207], v173 offset:34816
	ds_read_b128 v[208:211], v173 offset:35840
	ds_read_b128 v[212:215], v173 offset:36864
	ds_read_b128 v[216:219], v173 offset:37888
	ds_read_b128 v[220:223], v173 offset:38912
	ds_read_b128 v[224:227], v173 offset:39936
	global_load_lds_dwordx4 v[244:245], off
	v_lshl_add_u64 v[244:245], s[50:51], 0, v[142:143]
	s_mov_b32 m0, s64
	s_nop 0
	global_load_lds_dwordx4 v[244:245], off
	s_waitcnt vmcnt(8)
	s_waitcnt lgkmcnt(0)
	s_barrier
	s_setprio 1
	s_waitcnt lgkmcnt(0)
	v_mfma_f32_16x16x32_bf16 v[136:139], v[112:115], v[184:187], v[136:139]
	v_mfma_f32_16x16x32_bf16 v[136:139], v[120:123], v[188:191], v[136:139]
	v_mfma_f32_16x16x32_bf16 v[132:135], v[152:155], v[184:187], v[132:135]
	v_mfma_f32_16x16x32_bf16 v[132:135], v[156:159], v[188:191], v[132:135]
	v_mfma_f32_16x16x32_bf16 v[116:119], v[112:115], v[204:207], v[116:119]
	v_mfma_f32_16x16x32_bf16 v[116:119], v[120:123], v[208:211], v[116:119]
	v_mfma_f32_16x16x32_bf16 v[108:111], v[152:155], v[204:207], v[108:111]
	v_mfma_f32_16x16x32_bf16 v[108:111], v[156:159], v[208:211], v[108:111]
	v_mfma_f32_16x16x32_bf16 v[96:99], v[112:115], v[212:215], v[96:99]
	v_mfma_f32_16x16x32_bf16 v[96:99], v[120:123], v[216:219], v[96:99]
	v_mfma_f32_16x16x32_bf16 v[92:95], v[152:155], v[212:215], v[92:95]
	v_mfma_f32_16x16x32_bf16 v[92:95], v[156:159], v[216:219], v[92:95]
	v_mfma_f32_16x16x32_bf16 v[80:83], v[112:115], v[220:223], v[80:83]
	v_mfma_f32_16x16x32_bf16 v[80:83], v[120:123], v[224:227], v[80:83]
	v_mfma_f32_16x16x32_bf16 v[76:79], v[152:155], v[220:223], v[76:79]
	v_mfma_f32_16x16x32_bf16 v[76:79], v[156:159], v[224:227], v[76:79]
	s_setprio 0
	s_setprio 1
	v_mfma_f32_16x16x32_bf16 v[128:131], v[160:163], v[184:187], v[128:131]
	v_mfma_f32_16x16x32_bf16 v[128:131], v[164:167], v[188:191], v[128:131]
	v_mfma_f32_16x16x32_bf16 v[124:127], v[176:179], v[184:187], v[124:127]
	v_mfma_f32_16x16x32_bf16 v[124:127], v[180:183], v[188:191], v[124:127]
	v_mfma_f32_16x16x32_bf16 v[104:107], v[160:163], v[204:207], v[104:107]
	v_mfma_f32_16x16x32_bf16 v[104:107], v[164:167], v[208:211], v[104:107]
	v_mfma_f32_16x16x32_bf16 v[100:103], v[176:179], v[204:207], v[100:103]
	v_mfma_f32_16x16x32_bf16 v[100:103], v[180:183], v[208:211], v[100:103]
	v_mfma_f32_16x16x32_bf16 v[88:91], v[160:163], v[212:215], v[88:91]
	v_mfma_f32_16x16x32_bf16 v[88:91], v[164:167], v[216:219], v[88:91]
	v_mfma_f32_16x16x32_bf16 v[84:87], v[176:179], v[212:215], v[84:87]
	v_mfma_f32_16x16x32_bf16 v[84:87], v[180:183], v[216:219], v[84:87]
	v_mfma_f32_16x16x32_bf16 v[72:75], v[160:163], v[220:223], v[72:75]
	v_mfma_f32_16x16x32_bf16 v[72:75], v[164:167], v[224:227], v[72:75]
	v_mfma_f32_16x16x32_bf16 v[68:71], v[176:179], v[220:223], v[68:71]
	v_mfma_f32_16x16x32_bf16 v[68:71], v[180:183], v[224:227], v[68:71]
	s_setprio 0
	s_barrier
; #define PG8_STAGE(bufoff, gbase, voff) do { _Pragma("unroll") for (int _i = 0; _i < 2; ++_i) \
;         __builtin_amdgcn_global_load_lds((const unsigned*)((const char*)(gbase) + (voff)[_i]), (PG8_LAS unsigned*)(lds + (bufoff) + ldsw + _i * 8192), 16, 0, 0); } while (0)
; #define PG8_LDA(dst, b, h) do { _Pragma("unroll") for (int m = 0; m < 4; ++m) _Pragma("unroll") for (int k = 0; k < 2; ++k) dst[m][k] = *(const PG8_LAS bf16x8*)(lds + PG8_SA(b, h) + aoff + m * 2048 + k * 1024); } while (0)
; #define PG8_LDB(dst, b, h) do { _Pragma("unroll") for (int n = 0; n < 2; ++n) _Pragma("unroll") for (int k = 0; k < 2; ++k) dst[n][k] = *(const PG8_LAS bf16x8*)(lds + PG8_SB(b, h) + boff + n * 2048 + k * 1024); } while (0)
; template <class Epi, class Sched, bool ALIGN_EPI = false, bool SP2 = false, bool I8 = false>
; __device__ __forceinline__ void gemm_phase(PG8_LAS unsigned char* lds, const Gemm g, const Sched& S, const Epi& E) {
;     ...
;             const bool last = (t == nt - 2);
;             const char* a1 = cA + (size_t)(t + 1) * kstep;
;             const char* a2 = last ? nA : cA + (size_t)(t + 2) * kstep; const char* b2 = last ? nB : cB + (size_t)(t + 2) * kstep;
;             const char* a3 = a2 + kstep; const char* b3 = b2 + kstep;
;             if (last && has_next) S.a_ready(nxt);
;             if constexpr (SP2) {
;             PG8_LDB(B0, 0, 0); PG8_LDB(B1, 0, 1); PG8_SCHED; PG8_LDA(At, 0, 0); PG8_STAGE(PG8_SA(1, 1), a1 + hstep, voffA);
;             PG8_WAIT_V(8); PG8_WAIT_L(0); PG8_BAR; PG8_MMA(0, 0, At, B0); PG8_MMA(0, 1, At, B1); PG8_BAR; PG8_SCHED;
;             PG8_LDA(At, 0, 1); PG8_STAGE(PG8_SB(0, 0), b2, voffB); PG8_STAGE(PG8_SB(0, 1), b2 + hstep, voffB); PG8_STAGE(PG8_SA(0, 0), a2, voffA);
;             PG8_WAIT_V(8); PG8_WAIT_L(0); PG8_BAR; PG8_MMA(1, 0, At, B0); PG8_MMA(1, 1, At, B1); PG8_BAR; PG8_SCHED;
;             PG8_LDB(B0, 1, 0); PG8_LDB(B1, 1, 1); PG8_SCHED; PG8_LDA(At, 1, 0); PG8_STAGE(PG8_SA(0, 1), a2 + hstep, voffA);
;             PG8_WAIT_V(8); PG8_WAIT_L(0); PG8_BAR; PG8_MMA(0, 0, At, B0); PG8_MMA(0, 1, At, B1); PG8_BAR; PG8_SCHED;
;             PG8_LDA(At, 1, 1); PG8_STAGE(PG8_SB(1, 0), b3, voffB); PG8_STAGE(PG8_SB(1, 1), b3 + hstep, voffB); PG8_STAGE(PG8_SA(1, 0), a3, voffA);
;             PG8_WAIT_V(8); PG8_WAIT_L(0); PG8_BAR; PG8_MMA(1, 0, At, B0); PG8_MMA(1, 1, At, B1); PG8_BAR; PG8_SCHED;
	s_add_i32 s50, s56, s46
	v_lshl_add_u64 v[168:169], v[168:169], 0, s[84:85]
	s_mov_b32 m0, s50
	ds_read_b128 v[184:187], v173 offset:49152
	ds_read_b128 v[188:191], v173 offset:50176
	ds_read_b128 v[204:207], v173 offset:51200
	ds_read_b128 v[208:211], v173 offset:52224
	ds_read_b128 v[212:215], v173 offset:53248
	ds_read_b128 v[216:219], v173 offset:54272
	ds_read_b128 v[220:223], v173 offset:55296
	ds_read_b128 v[224:227], v173 offset:56320
	global_load_lds_dwordx4 v[168:169], off
	s_add_i32 m0, s50, 0x2000
	s_add_u32 s50, s72, 0x100080
	v_lshl_add_u64 v[168:169], v[228:229], 0, s[84:85]
	s_addc_u32 s51, s73, 0
	s_add_i32 s56, s57, s46
	global_load_lds_dwordx4 v[168:169], off
	v_lshl_add_u64 v[168:169], s[50:51], 0, v[2:3]
	s_mov_b32 m0, s56
	s_nop 0
	global_load_lds_dwordx4 v[168:169], off
	v_lshl_add_u64 v[168:169], s[50:51], 0, v[144:145]
	s_add_i32 m0, s56, 0x2000
	s_nop 0
	global_load_lds_dwordx4 v[168:169], off
	v_lshl_add_u64 v[168:169], v[240:241], 0, s[84:85]
	s_mov_b32 m0, s28
	s_nop 0
	global_load_lds_dwordx4 v[168:169], off
	v_lshl_add_u64 v[168:169], v[242:243], 0, s[84:85]
	s_mov_b32 m0, s65
	s_nop 0
	global_load_lds_dwordx4 v[168:169], off
	s_waitcnt vmcnt(8)
	s_waitcnt lgkmcnt(0)
	s_barrier
	s_setprio 1
	s_waitcnt lgkmcnt(0)
	v_mfma_f32_16x16x32_bf16 v[64:67], v[112:115], v[184:187], v[64:67]
	v_mfma_f32_16x16x32_bf16 v[64:67], v[120:123], v[188:191], v[64:67]
	v_mfma_f32_16x16x32_bf16 v[60:63], v[152:155], v[184:187], v[60:63]
	v_mfma_f32_16x16x32_bf16 v[60:63], v[156:159], v[188:191], v[60:63]
	v_mfma_f32_16x16x32_bf16 v[48:51], v[112:115], v[204:207], v[48:51]
	v_mfma_f32_16x16x32_bf16 v[48:51], v[120:123], v[208:211], v[48:51]
	v_mfma_f32_16x16x32_bf16 v[44:47], v[152:155], v[204:207], v[44:47]
	v_mfma_f32_16x16x32_bf16 v[44:47], v[156:159], v[208:211], v[44:47]
	v_mfma_f32_16x16x32_bf16 v[32:35], v[112:115], v[212:215], v[32:35]
	v_mfma_f32_16x16x32_bf16 v[32:35], v[120:123], v[216:219], v[32:35]
	v_mfma_f32_16x16x32_bf16 v[28:31], v[152:155], v[212:215], v[28:31]
	v_mfma_f32_16x16x32_bf16 v[28:31], v[156:159], v[216:219], v[28:31]
	v_mfma_f32_16x16x32_bf16 v[16:19], v[112:115], v[220:223], v[16:19]
	v_mfma_f32_16x16x32_bf16 v[16:19], v[120:123], v[224:227], v[16:19]
	v_mfma_f32_16x16x32_bf16 v[12:15], v[152:155], v[220:223], v[12:15]
	v_mfma_f32_16x16x32_bf16 v[12:15], v[156:159], v[224:227], v[12:15]
	s_setprio 0
	s_setprio 1
	v_mfma_f32_16x16x32_bf16 v[56:59], v[160:163], v[184:187], v[56:59]
	v_mfma_f32_16x16x32_bf16 v[56:59], v[164:167], v[188:191], v[56:59]
	v_mfma_f32_16x16x32_bf16 v[52:55], v[176:179], v[184:187], v[52:55]
	v_mfma_f32_16x16x32_bf16 v[52:55], v[180:183], v[188:191], v[52:55]
	v_mfma_f32_16x16x32_bf16 v[40:43], v[160:163], v[204:207], v[40:43]
	v_mfma_f32_16x16x32_bf16 v[40:43], v[164:167], v[208:211], v[40:43]
	v_mfma_f32_16x16x32_bf16 v[36:39], v[176:179], v[204:207], v[36:39]
	v_mfma_f32_16x16x32_bf16 v[36:39], v[180:183], v[208:211], v[36:39]
	v_mfma_f32_16x16x32_bf16 v[24:27], v[160:163], v[212:215], v[24:27]
	v_mfma_f32_16x16x32_bf16 v[24:27], v[164:167], v[216:219], v[24:27]
	v_mfma_f32_16x16x32_bf16 v[20:23], v[176:179], v[212:215], v[20:23]
	v_mfma_f32_16x16x32_bf16 v[20:23], v[180:183], v[216:219], v[20:23]
	v_mfma_f32_16x16x32_bf16 v[8:11], v[160:163], v[220:223], v[8:11]
	v_mfma_f32_16x16x32_bf16 v[8:11], v[164:167], v[224:227], v[8:11]
	v_mfma_f32_16x16x32_bf16 v[4:7], v[176:179], v[220:223], v[4:7]
	v_mfma_f32_16x16x32_bf16 v[4:7], v[180:183], v[224:227], v[4:7]
	s_setprio 0
	s_barrier
	s_add_i32 s97, s97, 2
	s_add_u32 s12, s12, 0x100
	s_addc_u32 s13, s13, 0
	s_add_u32 s37, s37, 0x100
	s_addc_u32 s61, s61, 0
	s_cmp_gt_u32 s97, 61
	s_cbranch_scc1 .Lkloop_exit_1
.LBB0_230:
	s_add_u32 s50, s12, 0xfff00080
	s_addc_u32 s51, s13, -1
	s_add_i32 s56, 0, 0x10000
	s_cmp_eq_u32 s97, 60
	s_cselect_b32 s77, s11, s51
	s_cselect_b32 s76, s34, s50
	s_cselect_b32 s73, s27, s61
	s_cselect_b32 s72, s35, s37
	s_add_i32 s57, 0, 0x14000
	v_add_u32_e32 v156, s56, v171
	v_add_u32_e32 v168, s57, v171
	s_waitcnt vmcnt(0)
	ds_read_b128 v[112:115], v156
	ds_read_b128 v[120:123], v156 offset:1024
	ds_read_b128 v[152:155], v156 offset:2048
	ds_read_b128 v[156:159], v156 offset:3072
	ds_read_b128 v[160:163], v168
	ds_read_b128 v[164:167], v168 offset:1024
	s_waitcnt lgkmcnt(0)
	ds_read_b128 v[176:179], v168 offset:2048
	ds_read_b128 v[180:183], v168 offset:3072
	v_lshl_add_u64 v[168:169], s[12:13], 0, v[148:149]
	s_add_i32 m0, s47, 0xc000
	ds_read_b128 v[184:187], v173
	ds_read_b128 v[188:191], v173 offset:1024
	ds_read_b128 v[204:207], v173 offset:2048
	ds_read_b128 v[208:211], v173 offset:3072
	ds_read_b128 v[212:215], v173 offset:4096
	ds_read_b128 v[216:219], v173 offset:5120
	ds_read_b128 v[220:223], v173 offset:6144
	ds_read_b128 v[224:227], v173 offset:7168
	global_load_lds_dwordx4 v[168:169], off
	v_lshl_add_u64 v[168:169], s[12:13], 0, v[150:151]
	s_add_i32 m0, s47, 0xe000
	s_nop 0
	global_load_lds_dwordx4 v[168:169], off
	s_waitcnt vmcnt(8)
	s_waitcnt lgkmcnt(0)
	s_barrier
; #define PG8_STAGE(bufoff, gbase, voff) do { _Pragma("unroll") for (int _i = 0; _i < 2; ++_i) \
;         __builtin_amdgcn_global_load_lds((const unsigned*)((const char*)(gbase) + (voff)[_i]), (PG8_LAS unsigned*)(lds + (bufoff) + ldsw + _i * 8192), 16, 0, 0); } while (0)
; #define PG8_LDA(dst, b, h) do { _Pragma("unroll") for (int m = 0; m < 4; ++m) _Pragma("unroll") for (int k = 0; k < 2; ++k) dst[m][k] = *(const PG8_LAS bf16x8*)(lds + PG8_SA(b, h) + aoff + m * 2048 + k * 1024); } while (0)
; #define PG8_LDB(dst, b, h) do { _Pragma("unroll") for (int n = 0; n < 2; ++n) _Pragma("unroll") for (int k = 0; k < 2; ++k) dst[n][k] = *(const PG8_LAS bf16x8*)(lds + PG8_SB(b, h) + boff + n * 2048 + k * 1024); } while (0)
; #define PG8_WAIT_V(n) asm volatile("s_waitcnt vmcnt(" #n ")" ::: "memory")
; #define PG8_WAIT_L(n) asm volatile("s_waitcnt lgkmcnt(" #n ")" ::: "memory")
; #define PG8_BAR __builtin_amdgcn_s_barrier()
; #define PG8_SCHED __builtin_amdgcn_sched_barrier(0)
; template <class Epi, class Sched, bool ALIGN_EPI = false, bool SP2 = false, bool I8 = false>
; __device__ __forceinline__ void gemm_phase(PG8_LAS unsigned char* lds, const Gemm g, const Sched& S, const Epi& E) {
;     ...
;             PG8_LDB(B0, 0, 0); PG8_LDB(B1, 0, 1); PG8_SCHED; PG8_LDA(At, 0, 0); PG8_STAGE(PG8_SA(1, 1), a1 + hstep, voffA);
;             PG8_WAIT_V(8); PG8_WAIT_L(0); PG8_BAR; PG8_MMA(0, 0, At, B0); PG8_MMA(0, 1, At, B1); PG8_BAR; PG8_SCHED;
;             PG8_LDA(At, 0, 1); PG8_STAGE(PG8_SB(0, 0), b2, voffB); PG8_STAGE(PG8_SB(0, 1), b2 + hstep, voffB); PG8_STAGE(PG8_SA(0, 0), a2, voffA);
;             PG8_WAIT_V(8); PG8_WAIT_L(0); PG8_BAR; PG8_MMA(1, 0, At, B0); PG8_MMA(1, 1, At, B1); PG8_BAR; PG8_SCHED;
	s_setprio 1
	s_waitcnt lgkmcnt(0)
	v_mfma_f32_16x16x32_bf16 v[136:139], v[112:115], v[184:187], v[136:139]
	v_mfma_f32_16x16x32_bf16 v[136:139], v[120:123], v[188:191], v[136:139]
	v_mfma_f32_16x16x32_bf16 v[132:135], v[152:155], v[184:187], v[132:135]
	v_mfma_f32_16x16x32_bf16 v[132:135], v[156:159], v[188:191], v[132:135]
	v_mfma_f32_16x16x32_bf16 v[116:119], v[112:115], v[204:207], v[116:119]
	v_mfma_f32_16x16x32_bf16 v[116:119], v[120:123], v[208:211], v[116:119]
	v_mfma_f32_16x16x32_bf16 v[108:111], v[152:155], v[204:207], v[108:111]
	v_mfma_f32_16x16x32_bf16 v[108:111], v[156:159], v[208:211], v[108:111]
	v_mfma_f32_16x16x32_bf16 v[96:99], v[112:115], v[212:215], v[96:99]
	v_mfma_f32_16x16x32_bf16 v[96:99], v[120:123], v[216:219], v[96:99]
	v_mfma_f32_16x16x32_bf16 v[92:95], v[152:155], v[212:215], v[92:95]
	v_mfma_f32_16x16x32_bf16 v[92:95], v[156:159], v[216:219], v[92:95]
	v_mfma_f32_16x16x32_bf16 v[80:83], v[112:115], v[220:223], v[80:83]
	v_mfma_f32_16x16x32_bf16 v[80:83], v[120:123], v[224:227], v[80:83]
	v_mfma_f32_16x16x32_bf16 v[76:79], v[152:155], v[220:223], v[76:79]
	v_mfma_f32_16x16x32_bf16 v[76:79], v[156:159], v[224:227], v[76:79]
	s_setprio 0
	s_setprio 1
	v_mfma_f32_16x16x32_bf16 v[128:131], v[160:163], v[184:187], v[128:131]
	v_mfma_f32_16x16x32_bf16 v[128:131], v[164:167], v[188:191], v[128:131]
	v_mfma_f32_16x16x32_bf16 v[124:127], v[176:179], v[184:187], v[124:127]
	v_mfma_f32_16x16x32_bf16 v[124:127], v[180:183], v[188:191], v[124:127]
	v_mfma_f32_16x16x32_bf16 v[104:107], v[160:163], v[204:207], v[104:107]
	v_mfma_f32_16x16x32_bf16 v[104:107], v[164:167], v[208:211], v[104:107]
	v_mfma_f32_16x16x32_bf16 v[100:103], v[176:179], v[204:207], v[100:103]
	v_mfma_f32_16x16x32_bf16 v[100:103], v[180:183], v[208:211], v[100:103]
	v_mfma_f32_16x16x32_bf16 v[88:91], v[160:163], v[212:215], v[88:91]
	v_mfma_f32_16x16x32_bf16 v[88:91], v[164:167], v[216:219], v[88:91]
	v_mfma_f32_16x16x32_bf16 v[84:87], v[176:179], v[212:215], v[84:87]
	v_mfma_f32_16x16x32_bf16 v[84:87], v[180:183], v[216:219], v[84:87]
	v_mfma_f32_16x16x32_bf16 v[72:75], v[160:163], v[220:223], v[72:75]
	v_mfma_f32_16x16x32_bf16 v[72:75], v[164:167], v[224:227], v[72:75]
	v_mfma_f32_16x16x32_bf16 v[68:71], v[176:179], v[220:223], v[68:71]
	v_mfma_f32_16x16x32_bf16 v[68:71], v[180:183], v[224:227], v[68:71]
	s_setprio 0
	s_barrier
	s_add_i32 s50, s56, s46
	v_lshl_add_u64 v[168:169], s[72:73], 0, v[2:3]
	s_mov_b32 m0, s50
	ds_read_b128 v[184:187], v173 offset:16384
	ds_read_b128 v[188:191], v173 offset:17408
	ds_read_b128 v[204:207], v173 offset:18432
	ds_read_b128 v[208:211], v173 offset:19456
	ds_read_b128 v[212:215], v173 offset:20480
	ds_read_b128 v[216:219], v173 offset:21504
	ds_read_b128 v[220:223], v173 offset:22528
	ds_read_b128 v[224:227], v173 offset:23552
	global_load_lds_dwordx4 v[168:169], off
	s_add_i32 m0, s50, 0x2000
	s_add_u32 s50, s72, 0x100000
	v_lshl_add_u64 v[228:229], s[72:73], 0, v[144:145]
	s_addc_u32 s51, s73, 0
	s_add_i32 s56, s57, s46
	global_load_lds_dwordx4 v[228:229], off
	v_lshl_add_u64 v[240:241], s[50:51], 0, v[2:3]
	s_mov_b32 m0, s56
	v_lshl_add_u64 v[242:243], s[76:77], 0, v[142:143]
	global_load_lds_dwordx4 v[240:241], off
	v_lshl_add_u64 v[240:241], s[50:51], 0, v[144:145]
	s_add_i32 m0, s56, 0x2000
	s_nop 0
	global_load_lds_dwordx4 v[240:241], off
	v_lshl_add_u64 v[240:241], s[76:77], 0, v[140:141]
	s_mov_b32 m0, s47
	s_nop 0
	global_load_lds_dwordx4 v[240:241], off
	s_mov_b32 m0, s52
	s_nop 0
	global_load_lds_dwordx4 v[242:243], off
	s_waitcnt vmcnt(8)
	s_waitcnt lgkmcnt(0)
	s_barrier
	s_setprio 1
	s_waitcnt lgkmcnt(0)
	v_mfma_f32_16x16x32_bf16 v[64:67], v[112:115], v[184:187], v[64:67]
	v_mfma_f32_16x16x32_bf16 v[64:67], v[120:123], v[188:191], v[64:67]
	v_mfma_f32_16x16x32_bf16 v[60:63], v[152:155], v[184:187], v[60:63]
	v_mfma_f32_16x16x32_bf16 v[60:63], v[156:159], v[188:191], v[60:63]
	v_mfma_f32_16x16x32_bf16 v[48:51], v[112:115], v[204:207], v[48:51]
	v_mfma_f32_16x16x32_bf16 v[48:51], v[120:123], v[208:211], v[48:51]
	v_mfma_f32_16x16x32_bf16 v[44:47], v[152:155], v[204:207], v[44:47]
	v_mfma_f32_16x16x32_bf16 v[44:47], v[156:159], v[208:211], v[44:47]
	v_mfma_f32_16x16x32_bf16 v[32:35], v[112:115], v[212:215], v[32:35]
	v_mfma_f32_16x16x32_bf16 v[32:35], v[120:123], v[216:219], v[32:35]
	v_mfma_f32_16x16x32_bf16 v[28:31], v[152:155], v[212:215], v[28:31]
	v_mfma_f32_16x16x32_bf16 v[28:31], v[156:159], v[216:219], v[28:31]
	v_mfma_f32_16x16x32_bf16 v[16:19], v[112:115], v[220:223], v[16:19]
	v_mfma_f32_16x16x32_bf16 v[16:19], v[120:123], v[224:227], v[16:19]
	v_mfma_f32_16x16x32_bf16 v[12:15], v[152:155], v[220:223], v[12:15]
	v_mfma_f32_16x16x32_bf16 v[12:15], v[156:159], v[224:227], v[12:15]
	s_setprio 0
	s_setprio 1
	v_mfma_f32_16x16x32_bf16 v[56:59], v[160:163], v[184:187], v[56:59]
	v_mfma_f32_16x16x32_bf16 v[56:59], v[164:167], v[188:191], v[56:59]
	v_mfma_f32_16x16x32_bf16 v[52:55], v[176:179], v[184:187], v[52:55]
	v_mfma_f32_16x16x32_bf16 v[52:55], v[180:183], v[188:191], v[52:55]
	v_mfma_f32_16x16x32_bf16 v[40:43], v[160:163], v[204:207], v[40:43]
	v_mfma_f32_16x16x32_bf16 v[40:43], v[164:167], v[208:211], v[40:43]
	v_mfma_f32_16x16x32_bf16 v[36:39], v[176:179], v[204:207], v[36:39]
	v_mfma_f32_16x16x32_bf16 v[36:39], v[180:183], v[208:211], v[36:39]
	v_mfma_f32_16x16x32_bf16 v[24:27], v[160:163], v[212:215], v[24:27]
	v_mfma_f32_16x16x32_bf16 v[24:27], v[164:167], v[216:219], v[24:27]
	v_mfma_f32_16x16x32_bf16 v[20:23], v[176:179], v[212:215], v[20:23]
	v_mfma_f32_16x16x32_bf16 v[20:23], v[180:183], v[216:219], v[20:23]
	v_mfma_f32_16x16x32_bf16 v[8:11], v[160:163], v[220:223], v[8:11]
	v_mfma_f32_16x16x32_bf16 v[8:11], v[164:167], v[224:227], v[8:11]
	v_mfma_f32_16x16x32_bf16 v[4:7], v[176:179], v[220:223], v[4:7]
	v_mfma_f32_16x16x32_bf16 v[4:7], v[180:183], v[224:227], v[4:7]
	s_setprio 0
	s_barrier
; #define PG8_STAGE(bufoff, gbase, voff) do { _Pragma("unroll") for (int _i = 0; _i < 2; ++_i) \
;         __builtin_amdgcn_global_load_lds((const unsigned*)((const char*)(gbase) + (voff)[_i]), (PG8_LAS unsigned*)(lds + (bufoff) + ldsw + _i * 8192), 16, 0, 0); } while (0)
; #define PG8_LDA(dst, b, h) do { _Pragma("unroll") for (int m = 0; m < 4; ++m) _Pragma("unroll") for (int k = 0; k < 2; ++k) dst[m][k] = *(const PG8_LAS bf16x8*)(lds + PG8_SA(b, h) + aoff + m * 2048 + k * 1024); } while (0)
; #define PG8_LDB(dst, b, h) do { _Pragma("unroll") for (int n = 0; n < 2; ++n) _Pragma("unroll") for (int k = 0; k < 2; ++k) dst[n][k] = *(const PG8_LAS bf16x8*)(lds + PG8_SB(b, h) + boff + n * 2048 + k * 1024); } while (0)
; #define PG8_WAIT_V(n) asm volatile("s_waitcnt vmcnt(" #n ")" ::: "memory")
; #define PG8_WAIT_L(n) asm volatile("s_waitcnt lgkmcnt(" #n ")" ::: "memory")
; #define PG8_BAR __builtin_amdgcn_s_barrier()
; #define PG8_SCHED __builtin_amdgcn_sched_barrier(0)
; template <class Epi, class Sched, bool ALIGN_EPI = false, bool SP2 = false, bool I8 = false>
; __device__ __forceinline__ void gemm_phase(PG8_LAS unsigned char* lds, const Gemm g, const Sched& S, const Epi& E) {
;     ...
;             PG8_LDB(B0, 1, 0); PG8_LDB(B1, 1, 1); PG8_SCHED; PG8_LDA(At, 1, 0); PG8_STAGE(PG8_SA(0, 1), a2 + hstep, voffA);
;             PG8_WAIT_V(8); PG8_WAIT_L(0); PG8_BAR; PG8_MMA(0, 0, At, B0); PG8_MMA(0, 1, At, B1); PG8_BAR; PG8_SCHED;
	s_add_i32 s56, 0, 0x18000
	s_add_i32 s57, 0, 0x1c000
	v_add_u32_e32 v156, s56, v171
	v_add_u32_e32 v175, s57, v171
	ds_read_b128 v[112:115], v156
	ds_read_b128 v[120:123], v156 offset:1024
	ds_read_b128 v[152:155], v156 offset:2048
	ds_read_b128 v[156:159], v156 offset:3072
	ds_read_b128 v[160:163], v175
	ds_read_b128 v[164:167], v175 offset:1024
	ds_read_b128 v[176:179], v175 offset:2048
	ds_read_b128 v[180:183], v175 offset:3072
	s_add_u32 s50, s76, 0x100000
	s_addc_u32 s51, s77, 0
	s_mov_b32 m0, s53
	v_lshl_add_u64 v[244:245], s[50:51], 0, v[140:141]
	ds_read_b128 v[184:187], v173 offset:32768
	ds_read_b128 v[188:191], v173 offset:33792
	ds_read_b128 v[204:207], v173 offset:34816
	ds_read_b128 v[208:211], v173 offset:35840
	ds_read_b128 v[212:215], v173 offset:36864
	ds_read_b128 v[216:219], v173 offset:37888
	ds_read_b128 v[220:223], v173 offset:38912
	ds_read_b128 v[224:227], v173 offset:39936
	global_load_lds_dwordx4 v[244:245], off
	v_lshl_add_u64 v[244:245], s[50:51], 0, v[142:143]
	s_mov_b32 m0, s64
	s_nop 0
	global_load_lds_dwordx4 v[244:245], off
	s_waitcnt vmcnt(8)
	s_waitcnt lgkmcnt(0)
	s_barrier
	s_setprio 1
	s_waitcnt lgkmcnt(0)
	v_mfma_f32_16x16x32_bf16 v[136:139], v[112:115], v[184:187], v[136:139]
	v_mfma_f32_16x16x32_bf16 v[136:139], v[120:123], v[188:191], v[136:139]
	v_mfma_f32_16x16x32_bf16 v[132:135], v[152:155], v[184:187], v[132:135]
	v_mfma_f32_16x16x32_bf16 v[132:135], v[156:159], v[188:191], v[132:135]
	v_mfma_f32_16x16x32_bf16 v[116:119], v[112:115], v[204:207], v[116:119]
	v_mfma_f32_16x16x32_bf16 v[116:119], v[120:123], v[208:211], v[116:119]
	v_mfma_f32_16x16x32_bf16 v[108:111], v[152:155], v[204:207], v[108:111]
	v_mfma_f32_16x16x32_bf16 v[108:111], v[156:159], v[208:211], v[108:111]
	v_mfma_f32_16x16x32_bf16 v[96:99], v[112:115], v[212:215], v[96:99]
	v_mfma_f32_16x16x32_bf16 v[96:99], v[120:123], v[216:219], v[96:99]
	v_mfma_f32_16x16x32_bf16 v[92:95], v[152:155], v[212:215], v[92:95]
	v_mfma_f32_16x16x32_bf16 v[92:95], v[156:159], v[216:219], v[92:95]
	v_mfma_f32_16x16x32_bf16 v[80:83], v[112:115], v[220:223], v[80:83]
	v_mfma_f32_16x16x32_bf16 v[80:83], v[120:123], v[224:227], v[80:83]
	v_mfma_f32_16x16x32_bf16 v[76:79], v[152:155], v[220:223], v[76:79]
	v_mfma_f32_16x16x32_bf16 v[76:79], v[156:159], v[224:227], v[76:79]
	s_setprio 0
	s_setprio 1
	v_mfma_f32_16x16x32_bf16 v[128:131], v[160:163], v[184:187], v[128:131]
	v_mfma_f32_16x16x32_bf16 v[128:131], v[164:167], v[188:191], v[128:131]
	v_mfma_f32_16x16x32_bf16 v[124:127], v[176:179], v[184:187], v[124:127]
	v_mfma_f32_16x16x32_bf16 v[124:127], v[180:183], v[188:191], v[124:127]
	v_mfma_f32_16x16x32_bf16 v[104:107], v[160:163], v[204:207], v[104:107]
	v_mfma_f32_16x16x32_bf16 v[104:107], v[164:167], v[208:211], v[104:107]
	v_mfma_f32_16x16x32_bf16 v[100:103], v[176:179], v[204:207], v[100:103]
	v_mfma_f32_16x16x32_bf16 v[100:103], v[180:183], v[208:211], v[100:103]
	v_mfma_f32_16x16x32_bf16 v[88:91], v[160:163], v[212:215], v[88:91]
	v_mfma_f32_16x16x32_bf16 v[88:91], v[164:167], v[216:219], v[88:91]
	v_mfma_f32_16x16x32_bf16 v[84:87], v[176:179], v[212:215], v[84:87]
	v_mfma_f32_16x16x32_bf16 v[84:87], v[180:183], v[216:219], v[84:87]
	v_mfma_f32_16x16x32_bf16 v[72:75], v[160:163], v[220:223], v[72:75]
	v_mfma_f32_16x16x32_bf16 v[72:75], v[164:167], v[224:227], v[72:75]
	v_mfma_f32_16x16x32_bf16 v[68:71], v[176:179], v[220:223], v[68:71]
	v_mfma_f32_16x16x32_bf16 v[68:71], v[180:183], v[224:227], v[68:71]
	s_setprio 0
	s_barrier
; #define PG8_STAGE(bufoff, gbase, voff) do { _Pragma("unroll") for (int _i = 0; _i < 2; ++_i) \
;         __builtin_amdgcn_global_load_lds((const unsigned*)((const char*)(gbase) + (voff)[_i]), (PG8_LAS unsigned*)(lds + (bufoff) + ldsw + _i * 8192), 16, 0, 0); } while (0)
; #define PG8_LDA(dst, b, h) do { _Pragma("unroll") for (int m = 0; m < 4; ++m) _Pragma("unroll") for (int k = 0; k < 2; ++k) dst[m][k] = *(const PG8_LAS bf16x8*)(lds + PG8_SA(b, h) + aoff + m * 2048 + k * 1024); } while (0)
; #define PG8_WAIT_V(n) asm volatile("s_waitcnt vmcnt(" #n ")" ::: "memory")
; #define PG8_WAIT_L(n) asm volatile("s_waitcnt lgkmcnt(" #n ")" ::: "memory")
; #define PG8_BAR __builtin_amdgcn_s_barrier()
; #define PG8_SCHED __builtin_amdgcn_sched_barrier(0)
; template <class Epi, class Sched, bool ALIGN_EPI = false, bool SP2 = false, bool I8 = false>
; __device__ __forceinline__ void gemm_phase(PG8_LAS unsigned char* lds, const Gemm g, const Sched& S, const Epi& E) {
;     ...
;             PG8_LDA(At, 1, 1); PG8_STAGE(PG8_SB(1, 0), b3, voffB); PG8_STAGE(PG8_SB(1, 1), b3 + hstep, voffB); PG8_STAGE(PG8_SA(1, 0), a3, voffA);
;             PG8_WAIT_V(8); PG8_WAIT_L(0); PG8_BAR; PG8_MMA(1, 0, At, B0); PG8_MMA(1, 1, At, B1); PG8_BAR; PG8_SCHED;
	s_add_i32 s50, s56, s46
	v_lshl_add_u64 v[168:169], v[168:169], 0, s[84:85]
	s_mov_b32 m0, s50
	ds_read_b128 v[184:187], v173 offset:49152
	ds_read_b128 v[188:191], v173 offset:50176
	ds_read_b128 v[204:207], v173 offset:51200
	ds_read_b128 v[208:211], v173 offset:52224
	ds_read_b128 v[212:215], v173 offset:53248
	ds_read_b128 v[216:219], v173 offset:54272
	ds_read_b128 v[220:223], v173 offset:55296
	ds_read_b128 v[224:227], v173 offset:56320
	global_load_lds_dwordx4 v[168:169], off
	s_add_i32 m0, s50, 0x2000
	s_add_u32 s50, s72, 0x100080
	v_lshl_add_u64 v[168:169], v[228:229], 0, s[84:85]
	s_addc_u32 s51, s73, 0
	s_add_i32 s56, s57, s46
	global_load_lds_dwordx4 v[168:169], off
	v_lshl_add_u64 v[168:169], s[50:51], 0, v[2:3]
	s_mov_b32 m0, s56
	s_nop 0
	global_load_lds_dwordx4 v[168:169], off
	v_lshl_add_u64 v[168:169], s[50:51], 0, v[144:145]
	s_add_i32 m0, s56, 0x2000
	s_nop 0
	global_load_lds_dwordx4 v[168:169], off
	v_lshl_add_u64 v[168:169], v[240:241], 0, s[84:85]
	s_mov_b32 m0, s28
	s_nop 0
	global_load_lds_dwordx4 v[168:169], off
	v_lshl_add_u64 v[168:169], v[242:243], 0, s[84:85]
	s_mov_b32 m0, s65
	s_nop 0
	global_load_lds_dwordx4 v[168:169], off
	s_waitcnt vmcnt(8)
	s_waitcnt lgkmcnt(0)
	s_barrier
	s_setprio 1
	s_waitcnt lgkmcnt(0)
	v_mfma_f32_16x16x32_bf16 v[64:67], v[112:115], v[184:187], v[64:67]
	v_mfma_f32_16x16x32_bf16 v[64:67], v[120:123], v[188:191], v[64:67]
	v_mfma_f32_16x16x32_bf16 v[60:63], v[152:155], v[184:187], v[60:63]
	v_mfma_f32_16x16x32_bf16 v[60:63], v[156:159], v[188:191], v[60:63]
	v_mfma_f32_16x16x32_bf16 v[48:51], v[112:115], v[204:207], v[48:51]
	v_mfma_f32_16x16x32_bf16 v[48:51], v[120:123], v[208:211], v[48:51]
	v_mfma_f32_16x16x32_bf16 v[44:47], v[152:155], v[204:207], v[44:47]
	v_mfma_f32_16x16x32_bf16 v[44:47], v[156:159], v[208:211], v[44:47]
	v_mfma_f32_16x16x32_bf16 v[32:35], v[112:115], v[212:215], v[32:35]
	v_mfma_f32_16x16x32_bf16 v[32:35], v[120:123], v[216:219], v[32:35]
	v_mfma_f32_16x16x32_bf16 v[28:31], v[152:155], v[212:215], v[28:31]
	v_mfma_f32_16x16x32_bf16 v[28:31], v[156:159], v[216:219], v[28:31]
	v_mfma_f32_16x16x32_bf16 v[16:19], v[112:115], v[220:223], v[16:19]
	v_mfma_f32_16x16x32_bf16 v[16:19], v[120:123], v[224:227], v[16:19]
	v_mfma_f32_16x16x32_bf16 v[12:15], v[152:155], v[220:223], v[12:15]
	v_mfma_f32_16x16x32_bf16 v[12:15], v[156:159], v[224:227], v[12:15]
	s_setprio 0
	s_setprio 1
	v_mfma_f32_16x16x32_bf16 v[56:59], v[160:163], v[184:187], v[56:59]
	v_mfma_f32_16x16x32_bf16 v[56:59], v[164:167], v[188:191], v[56:59]
	v_mfma_f32_16x16x32_bf16 v[52:55], v[176:179], v[184:187], v[52:55]
	v_mfma_f32_16x16x32_bf16 v[52:55], v[180:183], v[188:191], v[52:55]
	v_mfma_f32_16x16x32_bf16 v[40:43], v[160:163], v[204:207], v[40:43]
	v_mfma_f32_16x16x32_bf16 v[40:43], v[164:167], v[208:211], v[40:43]
	v_mfma_f32_16x16x32_bf16 v[36:39], v[176:179], v[204:207], v[36:39]
	v_mfma_f32_16x16x32_bf16 v[36:39], v[180:183], v[208:211], v[36:39]
	v_mfma_f32_16x16x32_bf16 v[24:27], v[160:163], v[212:215], v[24:27]
	v_mfma_f32_16x16x32_bf16 v[24:27], v[164:167], v[216:219], v[24:27]
	v_mfma_f32_16x16x32_bf16 v[20:23], v[176:179], v[212:215], v[20:23]
	v_mfma_f32_16x16x32_bf16 v[20:23], v[180:183], v[216:219], v[20:23]
	v_mfma_f32_16x16x32_bf16 v[8:11], v[160:163], v[220:223], v[8:11]
	v_mfma_f32_16x16x32_bf16 v[8:11], v[164:167], v[224:227], v[8:11]
	v_mfma_f32_16x16x32_bf16 v[4:7], v[176:179], v[220:223], v[4:7]
	v_mfma_f32_16x16x32_bf16 v[4:7], v[180:183], v[224:227], v[4:7]
	s_setprio 0
	s_barrier
	s_add_i32 s97, s97, 2
	s_add_u32 s12, s12, 0x100
	s_addc_u32 s13, s13, 0
	s_add_u32 s37, s37, 0x100
	s_addc_u32 s61, s61, 0
	s_cmp_gt_u32 s97, 61
	s_cbranch_scc0 .LBB0_230

; #define PG8_STAGE(bufoff, gbase, voff) do { _Pragma("unroll") for (int _i = 0; _i < 2; ++_i) \
;         __builtin_amdgcn_global_load_lds((const unsigned*)((const char*)(gbase) + (voff)[_i]), (PG8_LAS unsigned*)(lds + (bufoff) + ldsw + _i * 8192), 16, 0, 0); } while (0)
; #define PG8_LDA(dst, b, h) do { _Pragma("unroll") for (int m = 0; m < 4; ++m) _Pragma("unroll") for (int k = 0; k < 2; ++k) dst[m][k] = *(const PG8_LAS bf16x8*)(lds + PG8_SA(b, h) + aoff + m * 2048 + k * 1024); } while (0)
; #define PG8_LDB(dst, b, h) do { _Pragma("unroll") for (int n = 0; n < 2; ++n) _Pragma("unroll") for (int k = 0; k < 2; ++k) dst[n][k] = *(const PG8_LAS bf16x8*)(lds + PG8_SB(b, h) + boff + n * 2048 + k * 1024); } while (0)
; #define PG8_WAIT_V(n) asm volatile("s_waitcnt vmcnt(" #n ")" ::: "memory")
; #define PG8_WAIT_L(n) asm volatile("s_waitcnt lgkmcnt(" #n ")" ::: "memory")
; #define PG8_BAR __builtin_amdgcn_s_barrier()
; #define PG8_SCHED __builtin_amdgcn_sched_barrier(0)
; template <class Epi, class Sched, bool ALIGN_EPI = false, bool SP2 = false, bool I8 = false>
; __device__ __forceinline__ void gemm_phase(PG8_LAS unsigned char* lds, const Gemm g, const Sched& S, const Epi& E) {
;     ...
;         const bool has_next = S.next(ui + 1, nxt);
;         const char* nA = has_next ? (const char*)g.A + (size_t)nxt.pm * tstep : cA; const char* nB = has_next ? (const char*)g.Bt + (size_t)nxt.pn * tstep : cB;
;         for (int t = 0; t < nt; t += 2) {
;             const bool last = (t == nt - 2);
;             const char* a1 = cA + (size_t)(t + 1) * kstep;
;             const char* a2 = last ? nA : cA + (size_t)(t + 2) * kstep; const char* b2 = last ? nB : cB + (size_t)(t + 2) * kstep;
;             const char* a3 = a2 + kstep; const char* b3 = b2 + kstep;
;             if (last && has_next) S.a_ready(nxt);
;             if constexpr (SP2) {
;             PG8_LDB(B0, 0, 0); PG8_LDB(B1, 0, 1); PG8_SCHED; PG8_LDA(At, 0, 0); PG8_STAGE(PG8_SA(1, 1), a1 + hstep, voffA);
;             PG8_WAIT_V(8); PG8_WAIT_L(0); PG8_BAR; PG8_MMA(0, 0, At, B0); PG8_MMA(0, 1, At, B1); PG8_BAR; PG8_SCHED;
;             PG8_LDA(At, 0, 1); PG8_STAGE(PG8_SB(0, 0), b2, voffB); PG8_STAGE(PG8_SB(0, 1), b2 + hstep, voffB); PG8_STAGE(PG8_SA(0, 0), a2, voffA);
;             PG8_WAIT_V(8); PG8_WAIT_L(0); PG8_BAR; PG8_MMA(1, 0, At, B0); PG8_MMA(1, 1, At, B1); PG8_BAR; PG8_SCHED;
.LBB0_1455:
	s_ashr_i32 s17, s16, 31
	s_lshl_b64 s[20:21], s[16:17], 21
	s_add_u32 s20, s28, s20
	s_addc_u32 s21, s34, s21
	s_and_b64 s[22:23], s[8:9], exec
	s_cselect_b32 s17, s21, s25
	s_cselect_b32 s51, s20, s24
	s_ashr_i32 s19, s18, 31
	s_lshl_b64 s[22:23], s[18:19], 21
	s_add_u32 s22, s35, s22
	s_addc_u32 s23, s39, s23
	s_and_b64 s[36:37], s[8:9], exec
	s_cselect_b32 s19, s23, s27
	s_cselect_b32 s52, s22, s26
	s_add_u32 s24, s24, 0x100080
	s_addc_u32 s25, s25, 0
	s_add_u32 s53, s26, 0x100
	s_addc_u32 s54, s27, 0
	s_mov_b32 s55, -2
	s_waitcnt vmcnt(0)
	s_add_u32 s26, s24, 0xfff00080
	s_addc_u32 s27, s25, -1
	s_add_i32 s56, 0, 0x10000
	s_cmp_eq_u32 s55, 60
	s_cselect_b32 s37, s17, s27
	s_cselect_b32 s36, s51, s26
	s_cselect_b32 s27, s19, s54
	s_cselect_b32 s26, s52, s53
	s_add_i32 s58, 0, 0x14000
	v_add_u32_e32 v144, s56, v240
	v_add_u32_e32 v160, s58, v240
	ds_read_b128 v[124:127], v144
	ds_read_b128 v[128:131], v144 offset:1024
	ds_read_b128 v[132:135], v144 offset:2048
	ds_read_b128 v[144:147], v144 offset:3072
	ds_read_b128 v[148:151], v160
	ds_read_b128 v[152:155], v160 offset:1024
	ds_read_b128 v[156:159], v160 offset:2048
	ds_read_b128 v[160:163], v160 offset:3072
	v_lshl_add_u64 v[218:219], s[24:25], 0, v[210:211]
	s_add_i32 m0, s41, 0xc000
	ds_read_b128 v[164:167], v242
	ds_read_b128 v[168:171], v242 offset:1024
	ds_read_b128 v[172:175], v242 offset:2048
	ds_read_b128 v[176:179], v242 offset:3072
	ds_read_b128 v[180:183], v242 offset:4096
	ds_read_b128 v[184:187], v242 offset:5120
	ds_read_b128 v[188:191], v242 offset:6144
	ds_read_b128 v[214:217], v242 offset:7168
	global_load_lds_dwordx4 v[218:219], off
	v_lshl_add_u64 v[218:219], s[24:25], 0, v[212:213]
	s_add_i32 m0, s41, 0xe000
	s_nop 0
	global_load_lds_dwordx4 v[218:219], off
	s_waitcnt vmcnt(8)
	s_waitcnt lgkmcnt(0)
	s_barrier
	s_setprio 1
	s_waitcnt lgkmcnt(0)
	v_mfma_f32_16x16x32_bf16 v[140:143], v[124:127], v[164:167], 0
	v_mfma_f32_16x16x32_bf16 v[140:143], v[128:131], v[168:171], v[140:143]
	v_mfma_f32_16x16x32_bf16 v[136:139], v[132:135], v[164:167], 0
	v_mfma_f32_16x16x32_bf16 v[136:139], v[144:147], v[168:171], v[136:139]
	v_mfma_f32_16x16x32_bf16 v[112:115], v[124:127], v[172:175], 0
	v_mfma_f32_16x16x32_bf16 v[112:115], v[128:131], v[176:179], v[112:115]
	v_mfma_f32_16x16x32_bf16 v[108:111], v[132:135], v[172:175], 0
	v_mfma_f32_16x16x32_bf16 v[108:111], v[144:147], v[176:179], v[108:111]
	v_mfma_f32_16x16x32_bf16 v[96:99], v[124:127], v[180:183], 0
	v_mfma_f32_16x16x32_bf16 v[96:99], v[128:131], v[184:187], v[96:99]
	v_mfma_f32_16x16x32_bf16 v[92:95], v[132:135], v[180:183], 0
	v_mfma_f32_16x16x32_bf16 v[92:95], v[144:147], v[184:187], v[92:95]
	v_mfma_f32_16x16x32_bf16 v[80:83], v[124:127], v[188:191], 0
	v_mfma_f32_16x16x32_bf16 v[80:83], v[128:131], v[214:217], v[80:83]
	v_mfma_f32_16x16x32_bf16 v[76:79], v[132:135], v[188:191], 0
	v_mfma_f32_16x16x32_bf16 v[76:79], v[144:147], v[214:217], v[76:79]
	s_setprio 0
	s_setprio 1
	v_mfma_f32_16x16x32_bf16 v[120:123], v[148:151], v[164:167], 0
	v_mfma_f32_16x16x32_bf16 v[120:123], v[152:155], v[168:171], v[120:123]
	v_mfma_f32_16x16x32_bf16 v[116:119], v[156:159], v[164:167], 0
	v_mfma_f32_16x16x32_bf16 v[116:119], v[160:163], v[168:171], v[116:119]
	v_mfma_f32_16x16x32_bf16 v[104:107], v[148:151], v[172:175], 0
	v_mfma_f32_16x16x32_bf16 v[104:107], v[152:155], v[176:179], v[104:107]
	v_mfma_f32_16x16x32_bf16 v[100:103], v[156:159], v[172:175], 0
	v_mfma_f32_16x16x32_bf16 v[100:103], v[160:163], v[176:179], v[100:103]
	v_mfma_f32_16x16x32_bf16 v[88:91], v[148:151], v[180:183], 0
	v_mfma_f32_16x16x32_bf16 v[88:91], v[152:155], v[184:187], v[88:91]
	v_mfma_f32_16x16x32_bf16 v[84:87], v[156:159], v[180:183], 0
	v_mfma_f32_16x16x32_bf16 v[84:87], v[160:163], v[184:187], v[84:87]
	v_mfma_f32_16x16x32_bf16 v[72:75], v[148:151], v[188:191], 0
	v_mfma_f32_16x16x32_bf16 v[72:75], v[152:155], v[214:217], v[72:75]
	v_mfma_f32_16x16x32_bf16 v[68:71], v[156:159], v[188:191], 0
	v_mfma_f32_16x16x32_bf16 v[68:71], v[160:163], v[214:217], v[68:71]
	s_setprio 0
	s_barrier
	s_add_i32 s56, s56, s40
	v_lshl_add_u64 v[218:219], s[26:27], 0, v[2:3]
	s_mov_b32 m0, s56
	ds_read_b128 v[164:167], v242 offset:16384
	ds_read_b128 v[168:171], v242 offset:17408
	ds_read_b128 v[172:175], v242 offset:18432
	ds_read_b128 v[176:179], v242 offset:19456
	ds_read_b128 v[180:183], v242 offset:20480
	ds_read_b128 v[184:187], v242 offset:21504
	ds_read_b128 v[188:191], v242 offset:22528
	ds_read_b128 v[214:217], v242 offset:23552
	global_load_lds_dwordx4 v[218:219], off
	s_add_i32 m0, s56, 0x2000
	s_add_u32 s56, s26, 0x100000
	v_lshl_add_u64 v[220:221], s[26:27], 0, v[204:205]
	s_addc_u32 s57, s27, 0
	s_add_i32 s58, s58, s40
	global_load_lds_dwordx4 v[220:221], off
	v_lshl_add_u64 v[222:223], s[56:57], 0, v[2:3]
	s_mov_b32 m0, s58
	v_lshl_add_u64 v[224:225], s[36:37], 0, v[206:207]
	global_load_lds_dwordx4 v[222:223], off
	v_lshl_add_u64 v[222:223], s[56:57], 0, v[204:205]
	s_add_i32 m0, s58, 0x2000
	s_nop 0
	global_load_lds_dwordx4 v[222:223], off
	v_lshl_add_u64 v[222:223], s[36:37], 0, v[208:209]
	s_mov_b32 m0, s41
	s_nop 0
	global_load_lds_dwordx4 v[222:223], off
	s_mov_b32 m0, s42
	s_nop 0
	global_load_lds_dwordx4 v[224:225], off
	s_waitcnt vmcnt(8)
	s_waitcnt lgkmcnt(0)
	s_barrier
; #define PG8_STAGE(bufoff, gbase, voff) do { _Pragma("unroll") for (int _i = 0; _i < 2; ++_i) \
;         __builtin_amdgcn_global_load_lds((const unsigned*)((const char*)(gbase) + (voff)[_i]), (PG8_LAS unsigned*)(lds + (bufoff) + ldsw + _i * 8192), 16, 0, 0); } while (0)
; #define PG8_LDA(dst, b, h) do { _Pragma("unroll") for (int m = 0; m < 4; ++m) _Pragma("unroll") for (int k = 0; k < 2; ++k) dst[m][k] = *(const PG8_LAS bf16x8*)(lds + PG8_SA(b, h) + aoff + m * 2048 + k * 1024); } while (0)
; #define PG8_LDB(dst, b, h) do { _Pragma("unroll") for (int n = 0; n < 2; ++n) _Pragma("unroll") for (int k = 0; k < 2; ++k) dst[n][k] = *(const PG8_LAS bf16x8*)(lds + PG8_SB(b, h) + boff + n * 2048 + k * 1024); } while (0)
; #define PG8_WAIT_V(n) asm volatile("s_waitcnt vmcnt(" #n ")" ::: "memory")
; #define PG8_WAIT_L(n) asm volatile("s_waitcnt lgkmcnt(" #n ")" ::: "memory")
; #define PG8_BAR __builtin_amdgcn_s_barrier()
; #define PG8_SCHED __builtin_amdgcn_sched_barrier(0)
; template <class Epi, class Sched, bool ALIGN_EPI = false, bool SP2 = false, bool I8 = false>
; __device__ __forceinline__ void gemm_phase(PG8_LAS unsigned char* lds, const Gemm g, const Sched& S, const Epi& E) {
;     ...
;             PG8_WAIT_V(8); PG8_WAIT_L(0); PG8_BAR; PG8_MMA(1, 0, At, B0); PG8_MMA(1, 1, At, B1); PG8_BAR; PG8_SCHED;
;             PG8_LDB(B0, 1, 0); PG8_LDB(B1, 1, 1); PG8_SCHED; PG8_LDA(At, 1, 0); PG8_STAGE(PG8_SA(0, 1), a2 + hstep, voffA);
;             PG8_WAIT_V(8); PG8_WAIT_L(0); PG8_BAR; PG8_MMA(0, 0, At, B0); PG8_MMA(0, 1, At, B1); PG8_BAR; PG8_SCHED;
	s_setprio 1
	s_waitcnt lgkmcnt(0)
	v_mfma_f32_16x16x32_bf16 v[64:67], v[124:127], v[164:167], 0
	v_mfma_f32_16x16x32_bf16 v[64:67], v[128:131], v[168:171], v[64:67]
	v_mfma_f32_16x16x32_bf16 v[60:63], v[132:135], v[164:167], 0
	v_mfma_f32_16x16x32_bf16 v[60:63], v[144:147], v[168:171], v[60:63]
	v_mfma_f32_16x16x32_bf16 v[48:51], v[124:127], v[172:175], 0
	v_mfma_f32_16x16x32_bf16 v[48:51], v[128:131], v[176:179], v[48:51]
	v_mfma_f32_16x16x32_bf16 v[44:47], v[132:135], v[172:175], 0
	v_mfma_f32_16x16x32_bf16 v[44:47], v[144:147], v[176:179], v[44:47]
	v_mfma_f32_16x16x32_bf16 v[32:35], v[124:127], v[180:183], 0
	v_mfma_f32_16x16x32_bf16 v[32:35], v[128:131], v[184:187], v[32:35]
	v_mfma_f32_16x16x32_bf16 v[28:31], v[132:135], v[180:183], 0
	v_mfma_f32_16x16x32_bf16 v[28:31], v[144:147], v[184:187], v[28:31]
	v_mfma_f32_16x16x32_bf16 v[16:19], v[124:127], v[188:191], 0
	v_mfma_f32_16x16x32_bf16 v[16:19], v[128:131], v[214:217], v[16:19]
	v_mfma_f32_16x16x32_bf16 v[12:15], v[132:135], v[188:191], 0
	v_mfma_f32_16x16x32_bf16 v[12:15], v[144:147], v[214:217], v[12:15]
	s_setprio 0
	s_setprio 1
	v_mfma_f32_16x16x32_bf16 v[56:59], v[148:151], v[164:167], 0
	v_mfma_f32_16x16x32_bf16 v[56:59], v[152:155], v[168:171], v[56:59]
	v_mfma_f32_16x16x32_bf16 v[52:55], v[156:159], v[164:167], 0
	v_mfma_f32_16x16x32_bf16 v[52:55], v[160:163], v[168:171], v[52:55]
	v_mfma_f32_16x16x32_bf16 v[40:43], v[148:151], v[172:175], 0
	v_mfma_f32_16x16x32_bf16 v[40:43], v[152:155], v[176:179], v[40:43]
	v_mfma_f32_16x16x32_bf16 v[36:39], v[156:159], v[172:175], 0
	v_mfma_f32_16x16x32_bf16 v[36:39], v[160:163], v[176:179], v[36:39]
	v_mfma_f32_16x16x32_bf16 v[24:27], v[148:151], v[180:183], 0
	v_mfma_f32_16x16x32_bf16 v[24:27], v[152:155], v[184:187], v[24:27]
	v_mfma_f32_16x16x32_bf16 v[20:23], v[156:159], v[180:183], 0
	v_mfma_f32_16x16x32_bf16 v[20:23], v[160:163], v[184:187], v[20:23]
	v_mfma_f32_16x16x32_bf16 v[8:11], v[148:151], v[188:191], 0
	v_mfma_f32_16x16x32_bf16 v[8:11], v[152:155], v[214:217], v[8:11]
	v_mfma_f32_16x16x32_bf16 v[4:7], v[156:159], v[188:191], 0
	v_mfma_f32_16x16x32_bf16 v[4:7], v[160:163], v[214:217], v[4:7]
	s_setprio 0
	s_barrier
	s_add_i32 s56, 0, 0x18000
	s_add_i32 s57, 0, 0x1c000
	v_add_u32_e32 v144, s56, v240
	v_add_u32_e32 v160, s57, v240
	ds_read_b128 v[124:127], v144
	ds_read_b128 v[128:131], v144 offset:1024
	ds_read_b128 v[132:135], v144 offset:2048
	ds_read_b128 v[144:147], v144 offset:3072
	ds_read_b128 v[148:151], v160
	ds_read_b128 v[152:155], v160 offset:1024
	ds_read_b128 v[156:159], v160 offset:2048
	ds_read_b128 v[160:163], v160 offset:3072
	s_add_u32 s36, s36, 0x100000
	s_addc_u32 s37, s37, 0
	s_mov_b32 m0, s43
	v_lshl_add_u64 v[226:227], s[36:37], 0, v[208:209]
	ds_read_b128 v[164:167], v242 offset:32768
	ds_read_b128 v[168:171], v242 offset:33792
	ds_read_b128 v[172:175], v242 offset:34816
	ds_read_b128 v[176:179], v242 offset:35840
	ds_read_b128 v[180:183], v242 offset:36864
	ds_read_b128 v[184:187], v242 offset:37888
	ds_read_b128 v[188:191], v242 offset:38912
	ds_read_b128 v[214:217], v242 offset:39936
	global_load_lds_dwordx4 v[226:227], off
	v_lshl_add_u64 v[226:227], s[36:37], 0, v[206:207]
	s_mov_b32 m0, s44
	s_nop 0
	global_load_lds_dwordx4 v[226:227], off
	s_waitcnt vmcnt(8)
	s_waitcnt lgkmcnt(0)
	s_barrier
	s_setprio 1
	s_waitcnt lgkmcnt(0)
	v_mfma_f32_16x16x32_bf16 v[140:143], v[124:127], v[164:167], v[140:143]
	v_mfma_f32_16x16x32_bf16 v[140:143], v[128:131], v[168:171], v[140:143]
	v_mfma_f32_16x16x32_bf16 v[136:139], v[132:135], v[164:167], v[136:139]
	v_mfma_f32_16x16x32_bf16 v[136:139], v[144:147], v[168:171], v[136:139]
	v_mfma_f32_16x16x32_bf16 v[112:115], v[124:127], v[172:175], v[112:115]
	v_mfma_f32_16x16x32_bf16 v[112:115], v[128:131], v[176:179], v[112:115]
	v_mfma_f32_16x16x32_bf16 v[108:111], v[132:135], v[172:175], v[108:111]
	v_mfma_f32_16x16x32_bf16 v[108:111], v[144:147], v[176:179], v[108:111]
	v_mfma_f32_16x16x32_bf16 v[96:99], v[124:127], v[180:183], v[96:99]
	v_mfma_f32_16x16x32_bf16 v[96:99], v[128:131], v[184:187], v[96:99]
	v_mfma_f32_16x16x32_bf16 v[92:95], v[132:135], v[180:183], v[92:95]
	v_mfma_f32_16x16x32_bf16 v[92:95], v[144:147], v[184:187], v[92:95]
	v_mfma_f32_16x16x32_bf16 v[80:83], v[124:127], v[188:191], v[80:83]
	v_mfma_f32_16x16x32_bf16 v[80:83], v[128:131], v[214:217], v[80:83]
	v_mfma_f32_16x16x32_bf16 v[76:79], v[132:135], v[188:191], v[76:79]
	v_mfma_f32_16x16x32_bf16 v[76:79], v[144:147], v[214:217], v[76:79]
	s_setprio 0
	s_setprio 1
	v_mfma_f32_16x16x32_bf16 v[120:123], v[148:151], v[164:167], v[120:123]
	v_mfma_f32_16x16x32_bf16 v[120:123], v[152:155], v[168:171], v[120:123]
	v_mfma_f32_16x16x32_bf16 v[116:119], v[156:159], v[164:167], v[116:119]
	v_mfma_f32_16x16x32_bf16 v[116:119], v[160:163], v[168:171], v[116:119]
	v_mfma_f32_16x16x32_bf16 v[104:107], v[148:151], v[172:175], v[104:107]
	v_mfma_f32_16x16x32_bf16 v[104:107], v[152:155], v[176:179], v[104:107]
	v_mfma_f32_16x16x32_bf16 v[100:103], v[156:159], v[172:175], v[100:103]
	v_mfma_f32_16x16x32_bf16 v[100:103], v[160:163], v[176:179], v[100:103]
	v_mfma_f32_16x16x32_bf16 v[88:91], v[148:151], v[180:183], v[88:91]
	v_mfma_f32_16x16x32_bf16 v[88:91], v[152:155], v[184:187], v[88:91]
	v_mfma_f32_16x16x32_bf16 v[84:87], v[156:159], v[180:183], v[84:87]
	v_mfma_f32_16x16x32_bf16 v[84:87], v[160:163], v[184:187], v[84:87]
	v_mfma_f32_16x16x32_bf16 v[72:75], v[148:151], v[188:191], v[72:75]
	v_mfma_f32_16x16x32_bf16 v[72:75], v[152:155], v[214:217], v[72:75]
	v_mfma_f32_16x16x32_bf16 v[68:71], v[156:159], v[188:191], v[68:71]
	v_mfma_f32_16x16x32_bf16 v[68:71], v[160:163], v[214:217], v[68:71]
	s_setprio 0
	s_barrier
; #define PG8_STAGE(bufoff, gbase, voff) do { _Pragma("unroll") for (int _i = 0; _i < 2; ++_i) \
;         __builtin_amdgcn_global_load_lds((const unsigned*)((const char*)(gbase) + (voff)[_i]), (PG8_LAS unsigned*)(lds + (bufoff) + ldsw + _i * 8192), 16, 0, 0); } while (0)
; #define PG8_LDA(dst, b, h) do { _Pragma("unroll") for (int m = 0; m < 4; ++m) _Pragma("unroll") for (int k = 0; k < 2; ++k) dst[m][k] = *(const PG8_LAS bf16x8*)(lds + PG8_SA(b, h) + aoff + m * 2048 + k * 1024); } while (0)
; #define PG8_LDB(dst, b, h) do { _Pragma("unroll") for (int n = 0; n < 2; ++n) _Pragma("unroll") for (int k = 0; k < 2; ++k) dst[n][k] = *(const PG8_LAS bf16x8*)(lds + PG8_SB(b, h) + boff + n * 2048 + k * 1024); } while (0)
; template <class Epi, class Sched, bool ALIGN_EPI = false, bool SP2 = false, bool I8 = false>
; __device__ __forceinline__ void gemm_phase(PG8_LAS unsigned char* lds, const Gemm g, const Sched& S, const Epi& E) {
;     ...
;             const bool last = (t == nt - 2);
;             const char* a1 = cA + (size_t)(t + 1) * kstep;
;             const char* a2 = last ? nA : cA + (size_t)(t + 2) * kstep; const char* b2 = last ? nB : cB + (size_t)(t + 2) * kstep;
;             const char* a3 = a2 + kstep; const char* b3 = b2 + kstep;
;             if (last && has_next) S.a_ready(nxt);
;             if constexpr (SP2) {
;             PG8_LDB(B0, 0, 0); PG8_LDB(B1, 0, 1); PG8_SCHED; PG8_LDA(At, 0, 0); PG8_STAGE(PG8_SA(1, 1), a1 + hstep, voffA);
;             PG8_WAIT_V(8); PG8_WAIT_L(0); PG8_BAR; PG8_MMA(0, 0, At, B0); PG8_MMA(0, 1, At, B1); PG8_BAR; PG8_SCHED;
;             PG8_LDA(At, 0, 1); PG8_STAGE(PG8_SB(0, 0), b2, voffB); PG8_STAGE(PG8_SB(0, 1), b2 + hstep, voffB); PG8_STAGE(PG8_SA(0, 0), a2, voffA);
;             PG8_WAIT_V(8); PG8_WAIT_L(0); PG8_BAR; PG8_MMA(1, 0, At, B0); PG8_MMA(1, 1, At, B1); PG8_BAR; PG8_SCHED;
;             PG8_LDB(B0, 1, 0); PG8_LDB(B1, 1, 1); PG8_SCHED; PG8_LDA(At, 1, 0); PG8_STAGE(PG8_SA(0, 1), a2 + hstep, voffA);
;             PG8_WAIT_V(8); PG8_WAIT_L(0); PG8_BAR; PG8_MMA(0, 0, At, B0); PG8_MMA(0, 1, At, B1); PG8_BAR; PG8_SCHED;
;             PG8_LDA(At, 1, 1); PG8_STAGE(PG8_SB(1, 0), b3, voffB); PG8_STAGE(PG8_SB(1, 1), b3 + hstep, voffB); PG8_STAGE(PG8_SA(1, 0), a3, voffA);
;             PG8_WAIT_V(8); PG8_WAIT_L(0); PG8_BAR; PG8_MMA(1, 0, At, B0); PG8_MMA(1, 1, At, B1); PG8_BAR; PG8_SCHED;
	s_add_i32 s36, s56, s40
	v_lshl_add_u64 v[218:219], v[218:219], 0, s[84:85]
	s_mov_b32 m0, s36
	ds_read_b128 v[164:167], v242 offset:49152
	ds_read_b128 v[168:171], v242 offset:50176
	ds_read_b128 v[172:175], v242 offset:51200
	ds_read_b128 v[176:179], v242 offset:52224
	ds_read_b128 v[180:183], v242 offset:53248
	ds_read_b128 v[184:187], v242 offset:54272
	ds_read_b128 v[188:191], v242 offset:55296
	ds_read_b128 v[214:217], v242 offset:56320
	global_load_lds_dwordx4 v[218:219], off
	s_add_i32 m0, s36, 0x2000
	s_add_u32 s26, s26, 0x100080
	v_lshl_add_u64 v[218:219], v[220:221], 0, s[84:85]
	s_addc_u32 s27, s27, 0
	s_add_i32 s36, s57, s40
	global_load_lds_dwordx4 v[218:219], off
	v_lshl_add_u64 v[218:219], s[26:27], 0, v[2:3]
	s_mov_b32 m0, s36
	s_nop 0
	global_load_lds_dwordx4 v[218:219], off
	v_lshl_add_u64 v[218:219], s[26:27], 0, v[204:205]
	s_add_i32 m0, s36, 0x2000
	s_nop 0
	global_load_lds_dwordx4 v[218:219], off
	v_lshl_add_u64 v[218:219], v[222:223], 0, s[84:85]
	s_mov_b32 m0, s45
	s_nop 0
	global_load_lds_dwordx4 v[218:219], off
	v_lshl_add_u64 v[218:219], v[224:225], 0, s[84:85]
	s_mov_b32 m0, s46
	s_nop 0
	global_load_lds_dwordx4 v[218:219], off
	s_waitcnt vmcnt(8)
	s_waitcnt lgkmcnt(0)
	s_barrier
	s_setprio 1
	s_waitcnt lgkmcnt(0)
	v_mfma_f32_16x16x32_bf16 v[64:67], v[124:127], v[164:167], v[64:67]
	v_mfma_f32_16x16x32_bf16 v[64:67], v[128:131], v[168:171], v[64:67]
	v_mfma_f32_16x16x32_bf16 v[60:63], v[132:135], v[164:167], v[60:63]
	v_mfma_f32_16x16x32_bf16 v[60:63], v[144:147], v[168:171], v[60:63]
	v_mfma_f32_16x16x32_bf16 v[48:51], v[124:127], v[172:175], v[48:51]
	v_mfma_f32_16x16x32_bf16 v[48:51], v[128:131], v[176:179], v[48:51]
	v_mfma_f32_16x16x32_bf16 v[44:47], v[132:135], v[172:175], v[44:47]
	v_mfma_f32_16x16x32_bf16 v[44:47], v[144:147], v[176:179], v[44:47]
	v_mfma_f32_16x16x32_bf16 v[32:35], v[124:127], v[180:183], v[32:35]
	v_mfma_f32_16x16x32_bf16 v[32:35], v[128:131], v[184:187], v[32:35]
	v_mfma_f32_16x16x32_bf16 v[28:31], v[132:135], v[180:183], v[28:31]
	v_mfma_f32_16x16x32_bf16 v[28:31], v[144:147], v[184:187], v[28:31]
	v_mfma_f32_16x16x32_bf16 v[16:19], v[124:127], v[188:191], v[16:19]
	v_mfma_f32_16x16x32_bf16 v[16:19], v[128:131], v[214:217], v[16:19]
	v_mfma_f32_16x16x32_bf16 v[12:15], v[132:135], v[188:191], v[12:15]
	v_mfma_f32_16x16x32_bf16 v[12:15], v[144:147], v[214:217], v[12:15]
	s_setprio 0
	s_setprio 1
	v_mfma_f32_16x16x32_bf16 v[56:59], v[148:151], v[164:167], v[56:59]
	v_mfma_f32_16x16x32_bf16 v[56:59], v[152:155], v[168:171], v[56:59]
	v_mfma_f32_16x16x32_bf16 v[52:55], v[156:159], v[164:167], v[52:55]
	v_mfma_f32_16x16x32_bf16 v[52:55], v[160:163], v[168:171], v[52:55]
	v_mfma_f32_16x16x32_bf16 v[40:43], v[148:151], v[172:175], v[40:43]
	v_mfma_f32_16x16x32_bf16 v[40:43], v[152:155], v[176:179], v[40:43]
	v_mfma_f32_16x16x32_bf16 v[36:39], v[156:159], v[172:175], v[36:39]
	v_mfma_f32_16x16x32_bf16 v[36:39], v[160:163], v[176:179], v[36:39]
	v_mfma_f32_16x16x32_bf16 v[24:27], v[148:151], v[180:183], v[24:27]
	v_mfma_f32_16x16x32_bf16 v[24:27], v[152:155], v[184:187], v[24:27]
	v_mfma_f32_16x16x32_bf16 v[20:23], v[156:159], v[180:183], v[20:23]
	v_mfma_f32_16x16x32_bf16 v[20:23], v[160:163], v[184:187], v[20:23]
	v_mfma_f32_16x16x32_bf16 v[8:11], v[148:151], v[188:191], v[8:11]
	v_mfma_f32_16x16x32_bf16 v[8:11], v[152:155], v[214:217], v[8:11]
	v_mfma_f32_16x16x32_bf16 v[4:7], v[156:159], v[188:191], v[4:7]
	v_mfma_f32_16x16x32_bf16 v[4:7], v[160:163], v[214:217], v[4:7]
	s_setprio 0
	s_barrier
	s_add_i32 s55, s55, 2
	s_add_u32 s24, s24, 0x100
	s_addc_u32 s25, s25, 0
	s_add_u32 s53, s53, 0x100
	s_addc_u32 s54, s54, 0
	s_cmp_gt_u32 s55, 61
	s_cbranch_scc1 .Lkloop_exit_2
.LBB0_1456:
	s_add_u32 s26, s24, 0xfff00080
	s_addc_u32 s27, s25, -1
	s_add_i32 s56, 0, 0x10000
	s_cmp_eq_u32 s55, 60
	s_cselect_b32 s37, s17, s27
	s_cselect_b32 s36, s51, s26
	s_cselect_b32 s27, s19, s54
	s_cselect_b32 s26, s52, s53
	s_add_i32 s58, 0, 0x14000
	v_add_u32_e32 v144, s56, v240
	v_add_u32_e32 v160, s58, v240
	ds_read_b128 v[124:127], v144
	ds_read_b128 v[128:131], v144 offset:1024
	ds_read_b128 v[132:135], v144 offset:2048
	ds_read_b128 v[144:147], v144 offset:3072
	ds_read_b128 v[148:151], v160
	ds_read_b128 v[152:155], v160 offset:1024
	ds_read_b128 v[156:159], v160 offset:2048
	ds_read_b128 v[160:163], v160 offset:3072
	v_lshl_add_u64 v[218:219], s[24:25], 0, v[210:211]
	s_add_i32 m0, s41, 0xc000
	ds_read_b128 v[164:167], v242
	ds_read_b128 v[168:171], v242 offset:1024
	ds_read_b128 v[172:175], v242 offset:2048
	ds_read_b128 v[176:179], v242 offset:3072
	ds_read_b128 v[180:183], v242 offset:4096
	ds_read_b128 v[184:187], v242 offset:5120
	ds_read_b128 v[188:191], v242 offset:6144
	ds_read_b128 v[214:217], v242 offset:7168
	global_load_lds_dwordx4 v[218:219], off
	v_lshl_add_u64 v[218:219], s[24:25], 0, v[212:213]
	s_add_i32 m0, s41, 0xe000
	s_nop 0
	global_load_lds_dwordx4 v[218:219], off
	s_waitcnt vmcnt(8)
	s_waitcnt lgkmcnt(0)
	s_barrier
; #define PG8_STAGE(bufoff, gbase, voff) do { _Pragma("unroll") for (int _i = 0; _i < 2; ++_i) \
;         __builtin_amdgcn_global_load_lds((const unsigned*)((const char*)(gbase) + (voff)[_i]), (PG8_LAS unsigned*)(lds + (bufoff) + ldsw + _i * 8192), 16, 0, 0); } while (0)
; #define PG8_LDA(dst, b, h) do { _Pragma("unroll") for (int m = 0; m < 4; ++m) _Pragma("unroll") for (int k = 0; k < 2; ++k) dst[m][k] = *(const PG8_LAS bf16x8*)(lds + PG8_SA(b, h) + aoff + m * 2048 + k * 1024); } while (0)
; #define PG8_LDB(dst, b, h) do { _Pragma("unroll") for (int n = 0; n < 2; ++n) _Pragma("unroll") for (int k = 0; k < 2; ++k) dst[n][k] = *(const PG8_LAS bf16x8*)(lds + PG8_SB(b, h) + boff + n * 2048 + k * 1024); } while (0)
; #define PG8_WAIT_V(n) asm volatile("s_waitcnt vmcnt(" #n ")" ::: "memory")
; #define PG8_WAIT_L(n) asm volatile("s_waitcnt lgkmcnt(" #n ")" ::: "memory")
; #define PG8_BAR __builtin_amdgcn_s_barrier()
; #define PG8_SCHED __builtin_amdgcn_sched_barrier(0)
; template <class Epi, class Sched, bool ALIGN_EPI = false, bool SP2 = false, bool I8 = false>
; __device__ __forceinline__ void gemm_phase(PG8_LAS unsigned char* lds, const Gemm g, const Sched& S, const Epi& E) {
;     ...
;             PG8_LDB(B0, 0, 0); PG8_LDB(B1, 0, 1); PG8_SCHED; PG8_LDA(At, 0, 0); PG8_STAGE(PG8_SA(1, 1), a1 + hstep, voffA);
;             PG8_WAIT_V(8); PG8_WAIT_L(0); PG8_BAR; PG8_MMA(0, 0, At, B0); PG8_MMA(0, 1, At, B1); PG8_BAR; PG8_SCHED;
;             PG8_LDA(At, 0, 1); PG8_STAGE(PG8_SB(0, 0), b2, voffB); PG8_STAGE(PG8_SB(0, 1), b2 + hstep, voffB); PG8_STAGE(PG8_SA(0, 0), a2, voffA);
;             PG8_WAIT_V(8); PG8_WAIT_L(0); PG8_BAR; PG8_MMA(1, 0, At, B0); PG8_MMA(1, 1, At, B1); PG8_BAR; PG8_SCHED;
	s_setprio 1
	s_waitcnt lgkmcnt(0)
	v_mfma_f32_16x16x32_bf16 v[140:143], v[124:127], v[164:167], v[140:143]
	v_mfma_f32_16x16x32_bf16 v[140:143], v[128:131], v[168:171], v[140:143]
	v_mfma_f32_16x16x32_bf16 v[136:139], v[132:135], v[164:167], v[136:139]
	v_mfma_f32_16x16x32_bf16 v[136:139], v[144:147], v[168:171], v[136:139]
	v_mfma_f32_16x16x32_bf16 v[112:115], v[124:127], v[172:175], v[112:115]
	v_mfma_f32_16x16x32_bf16 v[112:115], v[128:131], v[176:179], v[112:115]
	v_mfma_f32_16x16x32_bf16 v[108:111], v[132:135], v[172:175], v[108:111]
	v_mfma_f32_16x16x32_bf16 v[108:111], v[144:147], v[176:179], v[108:111]
	v_mfma_f32_16x16x32_bf16 v[96:99], v[124:127], v[180:183], v[96:99]
	v_mfma_f32_16x16x32_bf16 v[96:99], v[128:131], v[184:187], v[96:99]
	v_mfma_f32_16x16x32_bf16 v[92:95], v[132:135], v[180:183], v[92:95]
	v_mfma_f32_16x16x32_bf16 v[92:95], v[144:147], v[184:187], v[92:95]
	v_mfma_f32_16x16x32_bf16 v[80:83], v[124:127], v[188:191], v[80:83]
	v_mfma_f32_16x16x32_bf16 v[80:83], v[128:131], v[214:217], v[80:83]
	v_mfma_f32_16x16x32_bf16 v[76:79], v[132:135], v[188:191], v[76:79]
	v_mfma_f32_16x16x32_bf16 v[76:79], v[144:147], v[214:217], v[76:79]
	s_setprio 0
	s_setprio 1
	v_mfma_f32_16x16x32_bf16 v[120:123], v[148:151], v[164:167], v[120:123]
	v_mfma_f32_16x16x32_bf16 v[120:123], v[152:155], v[168:171], v[120:123]
	v_mfma_f32_16x16x32_bf16 v[116:119], v[156:159], v[164:167], v[116:119]
	v_mfma_f32_16x16x32_bf16 v[116:119], v[160:163], v[168:171], v[116:119]
	v_mfma_f32_16x16x32_bf16 v[104:107], v[148:151], v[172:175], v[104:107]
	v_mfma_f32_16x16x32_bf16 v[104:107], v[152:155], v[176:179], v[104:107]
	v_mfma_f32_16x16x32_bf16 v[100:103], v[156:159], v[172:175], v[100:103]
	v_mfma_f32_16x16x32_bf16 v[100:103], v[160:163], v[176:179], v[100:103]
	v_mfma_f32_16x16x32_bf16 v[88:91], v[148:151], v[180:183], v[88:91]
	v_mfma_f32_16x16x32_bf16 v[88:91], v[152:155], v[184:187], v[88:91]
	v_mfma_f32_16x16x32_bf16 v[84:87], v[156:159], v[180:183], v[84:87]
	v_mfma_f32_16x16x32_bf16 v[84:87], v[160:163], v[184:187], v[84:87]
	v_mfma_f32_16x16x32_bf16 v[72:75], v[148:151], v[188:191], v[72:75]
	v_mfma_f32_16x16x32_bf16 v[72:75], v[152:155], v[214:217], v[72:75]
	v_mfma_f32_16x16x32_bf16 v[68:71], v[156:159], v[188:191], v[68:71]
	v_mfma_f32_16x16x32_bf16 v[68:71], v[160:163], v[214:217], v[68:71]
	s_setprio 0
	s_barrier
	s_add_i32 s56, s56, s40
	v_lshl_add_u64 v[218:219], s[26:27], 0, v[2:3]
	s_mov_b32 m0, s56
	ds_read_b128 v[164:167], v242 offset:16384
	ds_read_b128 v[168:171], v242 offset:17408
	ds_read_b128 v[172:175], v242 offset:18432
	ds_read_b128 v[176:179], v242 offset:19456
	ds_read_b128 v[180:183], v242 offset:20480
	ds_read_b128 v[184:187], v242 offset:21504
	ds_read_b128 v[188:191], v242 offset:22528
	ds_read_b128 v[214:217], v242 offset:23552
	global_load_lds_dwordx4 v[218:219], off
	s_add_i32 m0, s56, 0x2000
	s_add_u32 s56, s26, 0x100000
	v_lshl_add_u64 v[220:221], s[26:27], 0, v[204:205]
	s_addc_u32 s57, s27, 0
	s_add_i32 s58, s58, s40
	global_load_lds_dwordx4 v[220:221], off
	v_lshl_add_u64 v[222:223], s[56:57], 0, v[2:3]
	s_mov_b32 m0, s58
	v_lshl_add_u64 v[224:225], s[36:37], 0, v[206:207]
	global_load_lds_dwordx4 v[222:223], off
	v_lshl_add_u64 v[222:223], s[56:57], 0, v[204:205]
	s_add_i32 m0, s58, 0x2000
	s_nop 0
	global_load_lds_dwordx4 v[222:223], off
	v_lshl_add_u64 v[222:223], s[36:37], 0, v[208:209]
	s_mov_b32 m0, s41
	s_nop 0
	global_load_lds_dwordx4 v[222:223], off
	s_mov_b32 m0, s42
	s_nop 0
	global_load_lds_dwordx4 v[224:225], off
	s_waitcnt vmcnt(8)
	s_waitcnt lgkmcnt(0)
	s_barrier
	s_setprio 1
	s_waitcnt lgkmcnt(0)
	v_mfma_f32_16x16x32_bf16 v[64:67], v[124:127], v[164:167], v[64:67]
	v_mfma_f32_16x16x32_bf16 v[64:67], v[128:131], v[168:171], v[64:67]
	v_mfma_f32_16x16x32_bf16 v[60:63], v[132:135], v[164:167], v[60:63]
	v_mfma_f32_16x16x32_bf16 v[60:63], v[144:147], v[168:171], v[60:63]
	v_mfma_f32_16x16x32_bf16 v[48:51], v[124:127], v[172:175], v[48:51]
	v_mfma_f32_16x16x32_bf16 v[48:51], v[128:131], v[176:179], v[48:51]
	v_mfma_f32_16x16x32_bf16 v[44:47], v[132:135], v[172:175], v[44:47]
	v_mfma_f32_16x16x32_bf16 v[44:47], v[144:147], v[176:179], v[44:47]
	v_mfma_f32_16x16x32_bf16 v[32:35], v[124:127], v[180:183], v[32:35]
	v_mfma_f32_16x16x32_bf16 v[32:35], v[128:131], v[184:187], v[32:35]
	v_mfma_f32_16x16x32_bf16 v[28:31], v[132:135], v[180:183], v[28:31]
	v_mfma_f32_16x16x32_bf16 v[28:31], v[144:147], v[184:187], v[28:31]
	v_mfma_f32_16x16x32_bf16 v[16:19], v[124:127], v[188:191], v[16:19]
	v_mfma_f32_16x16x32_bf16 v[16:19], v[128:131], v[214:217], v[16:19]
	v_mfma_f32_16x16x32_bf16 v[12:15], v[132:135], v[188:191], v[12:15]
	v_mfma_f32_16x16x32_bf16 v[12:15], v[144:147], v[214:217], v[12:15]
	s_setprio 0
	s_setprio 1
	v_mfma_f32_16x16x32_bf16 v[56:59], v[148:151], v[164:167], v[56:59]
	v_mfma_f32_16x16x32_bf16 v[56:59], v[152:155], v[168:171], v[56:59]
	v_mfma_f32_16x16x32_bf16 v[52:55], v[156:159], v[164:167], v[52:55]
	v_mfma_f32_16x16x32_bf16 v[52:55], v[160:163], v[168:171], v[52:55]
	v_mfma_f32_16x16x32_bf16 v[40:43], v[148:151], v[172:175], v[40:43]
	v_mfma_f32_16x16x32_bf16 v[40:43], v[152:155], v[176:179], v[40:43]
	v_mfma_f32_16x16x32_bf16 v[36:39], v[156:159], v[172:175], v[36:39]
	v_mfma_f32_16x16x32_bf16 v[36:39], v[160:163], v[176:179], v[36:39]
	v_mfma_f32_16x16x32_bf16 v[24:27], v[148:151], v[180:183], v[24:27]
	v_mfma_f32_16x16x32_bf16 v[24:27], v[152:155], v[184:187], v[24:27]
	v_mfma_f32_16x16x32_bf16 v[20:23], v[156:159], v[180:183], v[20:23]
	v_mfma_f32_16x16x32_bf16 v[20:23], v[160:163], v[184:187], v[20:23]
	v_mfma_f32_16x16x32_bf16 v[8:11], v[148:151], v[188:191], v[8:11]
	v_mfma_f32_16x16x32_bf16 v[8:11], v[152:155], v[214:217], v[8:11]
	v_mfma_f32_16x16x32_bf16 v[4:7], v[156:159], v[188:191], v[4:7]
	v_mfma_f32_16x16x32_bf16 v[4:7], v[160:163], v[214:217], v[4:7]
	s_setprio 0
	s_barrier
; #define PG8_STAGE(bufoff, gbase, voff) do { _Pragma("unroll") for (int _i = 0; _i < 2; ++_i) \
;         __builtin_amdgcn_global_load_lds((const unsigned*)((const char*)(gbase) + (voff)[_i]), (PG8_LAS unsigned*)(lds + (bufoff) + ldsw + _i * 8192), 16, 0, 0); } while (0)
; #define PG8_LDA(dst, b, h) do { _Pragma("unroll") for (int m = 0; m < 4; ++m) _Pragma("unroll") for (int k = 0; k < 2; ++k) dst[m][k] = *(const PG8_LAS bf16x8*)(lds + PG8_SA(b, h) + aoff + m * 2048 + k * 1024); } while (0)
; #define PG8_LDB(dst, b, h) do { _Pragma("unroll") for (int n = 0; n < 2; ++n) _Pragma("unroll") for (int k = 0; k < 2; ++k) dst[n][k] = *(const PG8_LAS bf16x8*)(lds + PG8_SB(b, h) + boff + n * 2048 + k * 1024); } while (0)
; #define PG8_WAIT_V(n) asm volatile("s_waitcnt vmcnt(" #n ")" ::: "memory")
; #define PG8_WAIT_L(n) asm volatile("s_waitcnt lgkmcnt(" #n ")" ::: "memory")
; #define PG8_BAR __builtin_amdgcn_s_barrier()
; #define PG8_SCHED __builtin_amdgcn_sched_barrier(0)
; template <class Epi, class Sched, bool ALIGN_EPI = false, bool SP2 = false, bool I8 = false>
; __device__ __forceinline__ void gemm_phase(PG8_LAS unsigned char* lds, const Gemm g, const Sched& S, const Epi& E) {
;     ...
;             PG8_LDB(B0, 1, 0); PG8_LDB(B1, 1, 1); PG8_SCHED; PG8_LDA(At, 1, 0); PG8_STAGE(PG8_SA(0, 1), a2 + hstep, voffA);
;             PG8_WAIT_V(8); PG8_WAIT_L(0); PG8_BAR; PG8_MMA(0, 0, At, B0); PG8_MMA(0, 1, At, B1); PG8_BAR; PG8_SCHED;
	s_add_i32 s56, 0, 0x18000
	s_add_i32 s57, 0, 0x1c000
	v_add_u32_e32 v144, s56, v240
	v_add_u32_e32 v160, s57, v240
	ds_read_b128 v[124:127], v144
	ds_read_b128 v[128:131], v144 offset:1024
	ds_read_b128 v[132:135], v144 offset:2048
	ds_read_b128 v[144:147], v144 offset:3072
	ds_read_b128 v[148:151], v160
	ds_read_b128 v[152:155], v160 offset:1024
	ds_read_b128 v[156:159], v160 offset:2048
	ds_read_b128 v[160:163], v160 offset:3072
	s_add_u32 s36, s36, 0x100000
	s_addc_u32 s37, s37, 0
	s_mov_b32 m0, s43
	v_lshl_add_u64 v[226:227], s[36:37], 0, v[208:209]
	ds_read_b128 v[164:167], v242 offset:32768
	ds_read_b128 v[168:171], v242 offset:33792
	ds_read_b128 v[172:175], v242 offset:34816
	ds_read_b128 v[176:179], v242 offset:35840
	ds_read_b128 v[180:183], v242 offset:36864
	ds_read_b128 v[184:187], v242 offset:37888
	ds_read_b128 v[188:191], v242 offset:38912
	ds_read_b128 v[214:217], v242 offset:39936
	global_load_lds_dwordx4 v[226:227], off
	v_lshl_add_u64 v[226:227], s[36:37], 0, v[206:207]
	s_mov_b32 m0, s44
	s_nop 0
	global_load_lds_dwordx4 v[226:227], off
	s_waitcnt vmcnt(8)
	s_waitcnt lgkmcnt(0)
	s_barrier
	s_setprio 1
	s_waitcnt lgkmcnt(0)
	v_mfma_f32_16x16x32_bf16 v[140:143], v[124:127], v[164:167], v[140:143]
	v_mfma_f32_16x16x32_bf16 v[140:143], v[128:131], v[168:171], v[140:143]
	v_mfma_f32_16x16x32_bf16 v[136:139], v[132:135], v[164:167], v[136:139]
	v_mfma_f32_16x16x32_bf16 v[136:139], v[144:147], v[168:171], v[136:139]
	v_mfma_f32_16x16x32_bf16 v[112:115], v[124:127], v[172:175], v[112:115]
	v_mfma_f32_16x16x32_bf16 v[112:115], v[128:131], v[176:179], v[112:115]
	v_mfma_f32_16x16x32_bf16 v[108:111], v[132:135], v[172:175], v[108:111]
	v_mfma_f32_16x16x32_bf16 v[108:111], v[144:147], v[176:179], v[108:111]
	v_mfma_f32_16x16x32_bf16 v[96:99], v[124:127], v[180:183], v[96:99]
	v_mfma_f32_16x16x32_bf16 v[96:99], v[128:131], v[184:187], v[96:99]
	v_mfma_f32_16x16x32_bf16 v[92:95], v[132:135], v[180:183], v[92:95]
	v_mfma_f32_16x16x32_bf16 v[92:95], v[144:147], v[184:187], v[92:95]
	v_mfma_f32_16x16x32_bf16 v[80:83], v[124:127], v[188:191], v[80:83]
	v_mfma_f32_16x16x32_bf16 v[80:83], v[128:131], v[214:217], v[80:83]
	v_mfma_f32_16x16x32_bf16 v[76:79], v[132:135], v[188:191], v[76:79]
	v_mfma_f32_16x16x32_bf16 v[76:79], v[144:147], v[214:217], v[76:79]
	s_setprio 0
	s_setprio 1
	v_mfma_f32_16x16x32_bf16 v[120:123], v[148:151], v[164:167], v[120:123]
	v_mfma_f32_16x16x32_bf16 v[120:123], v[152:155], v[168:171], v[120:123]
	v_mfma_f32_16x16x32_bf16 v[116:119], v[156:159], v[164:167], v[116:119]
	v_mfma_f32_16x16x32_bf16 v[116:119], v[160:163], v[168:171], v[116:119]
	v_mfma_f32_16x16x32_bf16 v[104:107], v[148:151], v[172:175], v[104:107]
	v_mfma_f32_16x16x32_bf16 v[104:107], v[152:155], v[176:179], v[104:107]
	v_mfma_f32_16x16x32_bf16 v[100:103], v[156:159], v[172:175], v[100:103]
	v_mfma_f32_16x16x32_bf16 v[100:103], v[160:163], v[176:179], v[100:103]
	v_mfma_f32_16x16x32_bf16 v[88:91], v[148:151], v[180:183], v[88:91]
	v_mfma_f32_16x16x32_bf16 v[88:91], v[152:155], v[184:187], v[88:91]
	v_mfma_f32_16x16x32_bf16 v[84:87], v[156:159], v[180:183], v[84:87]
	v_mfma_f32_16x16x32_bf16 v[84:87], v[160:163], v[184:187], v[84:87]
	v_mfma_f32_16x16x32_bf16 v[72:75], v[148:151], v[188:191], v[72:75]
	v_mfma_f32_16x16x32_bf16 v[72:75], v[152:155], v[214:217], v[72:75]
	v_mfma_f32_16x16x32_bf16 v[68:71], v[156:159], v[188:191], v[68:71]
	v_mfma_f32_16x16x32_bf16 v[68:71], v[160:163], v[214:217], v[68:71]
	s_setprio 0
	s_barrier
; #define PG8_STAGE(bufoff, gbase, voff) do { _Pragma("unroll") for (int _i = 0; _i < 2; ++_i) \
;         __builtin_amdgcn_global_load_lds((const unsigned*)((const char*)(gbase) + (voff)[_i]), (PG8_LAS unsigned*)(lds + (bufoff) + ldsw + _i * 8192), 16, 0, 0); } while (0)
; #define PG8_LDA(dst, b, h) do { _Pragma("unroll") for (int m = 0; m < 4; ++m) _Pragma("unroll") for (int k = 0; k < 2; ++k) dst[m][k] = *(const PG8_LAS bf16x8*)(lds + PG8_SA(b, h) + aoff + m * 2048 + k * 1024); } while (0)
; #define PG8_WAIT_V(n) asm volatile("s_waitcnt vmcnt(" #n ")" ::: "memory")
; #define PG8_WAIT_L(n) asm volatile("s_waitcnt lgkmcnt(" #n ")" ::: "memory")
; #define PG8_BAR __builtin_amdgcn_s_barrier()
; #define PG8_SCHED __builtin_amdgcn_sched_barrier(0)
; template <class Epi, class Sched, bool ALIGN_EPI = false, bool SP2 = false, bool I8 = false>
; __device__ __forceinline__ void gemm_phase(PG8_LAS unsigned char* lds, const Gemm g, const Sched& S, const Epi& E) {
;     ...
;             PG8_LDA(At, 1, 1); PG8_STAGE(PG8_SB(1, 0), b3, voffB); PG8_STAGE(PG8_SB(1, 1), b3 + hstep, voffB); PG8_STAGE(PG8_SA(1, 0), a3, voffA);
;             PG8_WAIT_V(8); PG8_WAIT_L(0); PG8_BAR; PG8_MMA(1, 0, At, B0); PG8_MMA(1, 1, At, B1); PG8_BAR; PG8_SCHED;
	s_add_i32 s36, s56, s40
	v_lshl_add_u64 v[218:219], v[218:219], 0, s[84:85]
	s_mov_b32 m0, s36
	ds_read_b128 v[164:167], v242 offset:49152
	ds_read_b128 v[168:171], v242 offset:50176
	ds_read_b128 v[172:175], v242 offset:51200
	ds_read_b128 v[176:179], v242 offset:52224
	ds_read_b128 v[180:183], v242 offset:53248
	ds_read_b128 v[184:187], v242 offset:54272
	ds_read_b128 v[188:191], v242 offset:55296
	ds_read_b128 v[214:217], v242 offset:56320
	global_load_lds_dwordx4 v[218:219], off
	s_add_i32 m0, s36, 0x2000
	s_add_u32 s26, s26, 0x100080
	v_lshl_add_u64 v[218:219], v[220:221], 0, s[84:85]
	s_addc_u32 s27, s27, 0
	s_add_i32 s36, s57, s40
	global_load_lds_dwordx4 v[218:219], off
	v_lshl_add_u64 v[218:219], s[26:27], 0, v[2:3]
	s_mov_b32 m0, s36
	s_nop 0
	global_load_lds_dwordx4 v[218:219], off
	v_lshl_add_u64 v[218:219], s[26:27], 0, v[204:205]
	s_add_i32 m0, s36, 0x2000
	s_nop 0
	global_load_lds_dwordx4 v[218:219], off
	v_lshl_add_u64 v[218:219], v[222:223], 0, s[84:85]
	s_mov_b32 m0, s45
	s_nop 0
	global_load_lds_dwordx4 v[218:219], off
	v_lshl_add_u64 v[218:219], v[224:225], 0, s[84:85]
	s_mov_b32 m0, s46
	s_nop 0
	global_load_lds_dwordx4 v[218:219], off
	s_waitcnt vmcnt(8)
	s_waitcnt lgkmcnt(0)
	s_barrier
	s_setprio 1
	s_waitcnt lgkmcnt(0)
	v_mfma_f32_16x16x32_bf16 v[64:67], v[124:127], v[164:167], v[64:67]
	v_mfma_f32_16x16x32_bf16 v[64:67], v[128:131], v[168:171], v[64:67]
	v_mfma_f32_16x16x32_bf16 v[60:63], v[132:135], v[164:167], v[60:63]
	v_mfma_f32_16x16x32_bf16 v[60:63], v[144:147], v[168:171], v[60:63]
	v_mfma_f32_16x16x32_bf16 v[48:51], v[124:127], v[172:175], v[48:51]
	v_mfma_f32_16x16x32_bf16 v[48:51], v[128:131], v[176:179], v[48:51]
	v_mfma_f32_16x16x32_bf16 v[44:47], v[132:135], v[172:175], v[44:47]
	v_mfma_f32_16x16x32_bf16 v[44:47], v[144:147], v[176:179], v[44:47]
	v_mfma_f32_16x16x32_bf16 v[32:35], v[124:127], v[180:183], v[32:35]
	v_mfma_f32_16x16x32_bf16 v[32:35], v[128:131], v[184:187], v[32:35]
	v_mfma_f32_16x16x32_bf16 v[28:31], v[132:135], v[180:183], v[28:31]
	v_mfma_f32_16x16x32_bf16 v[28:31], v[144:147], v[184:187], v[28:31]
	v_mfma_f32_16x16x32_bf16 v[16:19], v[124:127], v[188:191], v[16:19]
	v_mfma_f32_16x16x32_bf16 v[16:19], v[128:131], v[214:217], v[16:19]
	v_mfma_f32_16x16x32_bf16 v[12:15], v[132:135], v[188:191], v[12:15]
	v_mfma_f32_16x16x32_bf16 v[12:15], v[144:147], v[214:217], v[12:15]
	s_setprio 0
	s_setprio 1
	v_mfma_f32_16x16x32_bf16 v[56:59], v[148:151], v[164:167], v[56:59]
	v_mfma_f32_16x16x32_bf16 v[56:59], v[152:155], v[168:171], v[56:59]
	v_mfma_f32_16x16x32_bf16 v[52:55], v[156:159], v[164:167], v[52:55]
	v_mfma_f32_16x16x32_bf16 v[52:55], v[160:163], v[168:171], v[52:55]
	v_mfma_f32_16x16x32_bf16 v[40:43], v[148:151], v[172:175], v[40:43]
	v_mfma_f32_16x16x32_bf16 v[40:43], v[152:155], v[176:179], v[40:43]
	v_mfma_f32_16x16x32_bf16 v[36:39], v[156:159], v[172:175], v[36:39]
	v_mfma_f32_16x16x32_bf16 v[36:39], v[160:163], v[176:179], v[36:39]
	v_mfma_f32_16x16x32_bf16 v[24:27], v[148:151], v[180:183], v[24:27]
	v_mfma_f32_16x16x32_bf16 v[24:27], v[152:155], v[184:187], v[24:27]
	v_mfma_f32_16x16x32_bf16 v[20:23], v[156:159], v[180:183], v[20:23]
	v_mfma_f32_16x16x32_bf16 v[20:23], v[160:163], v[184:187], v[20:23]
	v_mfma_f32_16x16x32_bf16 v[8:11], v[148:151], v[188:191], v[8:11]
	v_mfma_f32_16x16x32_bf16 v[8:11], v[152:155], v[214:217], v[8:11]
	v_mfma_f32_16x16x32_bf16 v[4:7], v[156:159], v[188:191], v[4:7]
	v_mfma_f32_16x16x32_bf16 v[4:7], v[160:163], v[214:217], v[4:7]
	s_setprio 0
	s_barrier
	s_add_i32 s55, s55, 2
	s_add_u32 s24, s24, 0x100
	s_addc_u32 s25, s25, 0
	s_add_u32 s53, s53, 0x100
	s_addc_u32 s54, s54, 0
	s_cmp_gt_u32 s55, 61
	s_cbranch_scc0 .LBB0_1456

; #define PG8_STAGE(bufoff, gbase, voff) do { _Pragma("unroll") for (int _i = 0; _i < 2; ++_i) \
;         __builtin_amdgcn_global_load_lds((const unsigned*)((const char*)(gbase) + (voff)[_i]), (PG8_LAS unsigned*)(lds + (bufoff) + ldsw + _i * 8192), 16, 0, 0); } while (0)
; #define PG8_LDA(dst, b, h) do { _Pragma("unroll") for (int m = 0; m < 4; ++m) _Pragma("unroll") for (int k = 0; k < 2; ++k) dst[m][k] = *(const PG8_LAS bf16x8*)(lds + PG8_SA(b, h) + aoff + m * 2048 + k * 1024); } while (0)
; #define PG8_LDB(dst, b, h) do { _Pragma("unroll") for (int n = 0; n < 2; ++n) _Pragma("unroll") for (int k = 0; k < 2; ++k) dst[n][k] = *(const PG8_LAS bf16x8*)(lds + PG8_SB(b, h) + boff + n * 2048 + k * 1024); } while (0)
; #define PG8_WAIT_V(n) asm volatile("s_waitcnt vmcnt(" #n ")" ::: "memory")
; #define PG8_WAIT_L(n) asm volatile("s_waitcnt lgkmcnt(" #n ")" ::: "memory")
; #define PG8_BAR __builtin_amdgcn_s_barrier()
; #define PG8_SCHED __builtin_amdgcn_sched_barrier(0)
; template <class Epi, class Sched, bool ALIGN_EPI = false, bool SP2 = false, bool I8 = false>
; __device__ __forceinline__ void gemm_phase(PG8_LAS unsigned char* lds, const Gemm g, const Sched& S, const Epi& E) {
;     ...
;         const bool has_next = S.next(ui + 1, nxt);
;         const char* nA = has_next ? (const char*)g.A + (size_t)nxt.pm * tstep : cA; const char* nB = has_next ? (const char*)g.Bt + (size_t)nxt.pn * tstep : cB;
;         for (int t = 0; t < nt; t += 2) {
;             const bool last = (t == nt - 2);
;             const char* a1 = cA + (size_t)(t + 1) * kstep;
;             const char* a2 = last ? nA : cA + (size_t)(t + 2) * kstep; const char* b2 = last ? nB : cB + (size_t)(t + 2) * kstep;
;             const char* a3 = a2 + kstep; const char* b3 = b2 + kstep;
;             if (last && has_next) S.a_ready(nxt);
;             if constexpr (SP2) {
;             PG8_LDB(B0, 0, 0); PG8_LDB(B1, 0, 1); PG8_SCHED; PG8_LDA(At, 0, 0); PG8_STAGE(PG8_SA(1, 1), a1 + hstep, voffA);
;             PG8_WAIT_V(8); PG8_WAIT_L(0); PG8_BAR; PG8_MMA(0, 0, At, B0); PG8_MMA(0, 1, At, B1); PG8_BAR; PG8_SCHED;
;             PG8_LDA(At, 0, 1); PG8_STAGE(PG8_SB(0, 0), b2, voffB); PG8_STAGE(PG8_SB(0, 1), b2 + hstep, voffB); PG8_STAGE(PG8_SA(0, 0), a2, voffA);
;             PG8_WAIT_V(8); PG8_WAIT_L(0); PG8_BAR; PG8_MMA(1, 0, At, B0); PG8_MMA(1, 1, At, B1); PG8_BAR; PG8_SCHED;
.LBB0_1590:
	s_ashr_i32 s25, s24, 31
	s_lshl_b64 s[26:27], s[24:25], 20
	s_add_u32 s26, s28, s26
	s_addc_u32 s27, s42, s27
	s_and_b64 s[36:37], s[10:11], exec
	s_cselect_b32 s25, s27, s41
	s_cselect_b32 s57, s26, s40
	s_ashr_i32 s23, s22, 31
	s_lshl_b64 s[36:37], s[22:23], 20
	s_add_u32 s36, s43, s36
	s_addc_u32 s37, s46, s37
	s_and_b64 s[48:49], s[10:11], exec
	s_cselect_b32 s23, s37, s45
	s_cselect_b32 s58, s36, s44
	s_add_u32 s40, s40, 0x80080
	s_addc_u32 s41, s41, 0
	s_add_u32 s59, s44, 0x100
	s_addc_u32 s60, s45, 0
	s_mov_b32 s61, -2
	s_add_u32 s44, s40, 0xfff80080
	s_addc_u32 s45, s41, -1
	s_add_i32 s64, 0, 0x10000
	s_cmp_eq_u32 s61, 28
	s_cselect_b32 s49, s25, s45
	s_cselect_b32 s48, s57, s44
	s_cselect_b32 s45, s23, s60
	s_cselect_b32 s44, s58, s59
	s_add_i32 s67, 0, 0x14000
	v_add_u32_e32 v144, s64, v167
	v_add_u32_e32 v158, s67, v167
	ds_read_b128 v[36:39], v144
	ds_read_b128 v[44:47], v144 offset:1024
	ds_read_b128 v[140:143], v144 offset:2048
	ds_read_b128 v[144:147], v144 offset:3072
	ds_read_b128 v[160:163], v158
	ds_read_b128 v[172:175], v158 offset:1024
	ds_read_b128 v[176:179], v158 offset:2048
	ds_read_b128 v[180:183], v158 offset:3072
	v_lshl_add_u64 v[164:165], s[40:41], 0, v[154:155]
	s_add_i32 m0, s50, 0xc000
	ds_read_b128 v[184:187], v171
	ds_read_b128 v[188:191], v171 offset:1024
	ds_read_b128 v[204:207], v171 offset:2048
	ds_read_b128 v[208:211], v171 offset:3072
	ds_read_b128 v[212:215], v171 offset:4096
	ds_read_b128 v[216:219], v171 offset:5120
	ds_read_b128 v[220:223], v171 offset:6144
	ds_read_b128 v[224:227], v171 offset:7168
	global_load_lds_dwordx4 v[164:165], off
	v_lshl_add_u64 v[164:165], s[40:41], 0, v[156:157]
	s_add_i32 m0, s50, 0xe000
	s_nop 0
	global_load_lds_dwordx4 v[164:165], off
	s_waitcnt vmcnt(8)
	s_waitcnt lgkmcnt(0)
	s_barrier
	s_setprio 1
	s_waitcnt lgkmcnt(0)
	v_mfma_i32_16x16x64_i8 v[136:139], v[36:39], v[184:187], 0
	v_mfma_i32_16x16x64_i8 v[136:139], v[44:47], v[188:191], v[136:139]
	v_mfma_i32_16x16x64_i8 v[128:131], v[140:143], v[184:187], 0
	v_mfma_i32_16x16x64_i8 v[128:131], v[144:147], v[188:191], v[128:131]
	v_mfma_i32_16x16x64_i8 v[120:123], v[36:39], v[204:207], 0
	v_mfma_i32_16x16x64_i8 v[120:123], v[44:47], v[208:211], v[120:123]
	v_mfma_i32_16x16x64_i8 v[112:115], v[140:143], v[204:207], 0
	v_mfma_i32_16x16x64_i8 v[112:115], v[144:147], v[208:211], v[112:115]
	v_mfma_i32_16x16x64_i8 v[104:107], v[36:39], v[212:215], 0
	v_mfma_i32_16x16x64_i8 v[104:107], v[44:47], v[216:219], v[104:107]
	v_mfma_i32_16x16x64_i8 v[96:99], v[140:143], v[212:215], 0
	v_mfma_i32_16x16x64_i8 v[96:99], v[144:147], v[216:219], v[96:99]
	v_mfma_i32_16x16x64_i8 v[88:91], v[36:39], v[220:223], 0
	v_mfma_i32_16x16x64_i8 v[88:91], v[44:47], v[224:227], v[88:91]
	v_mfma_i32_16x16x64_i8 v[80:83], v[140:143], v[220:223], 0
	v_mfma_i32_16x16x64_i8 v[80:83], v[144:147], v[224:227], v[80:83]
	s_setprio 0
	s_setprio 1
	v_mfma_i32_16x16x64_i8 v[132:135], v[160:163], v[184:187], 0
	v_mfma_i32_16x16x64_i8 v[132:135], v[172:175], v[188:191], v[132:135]
	v_mfma_i32_16x16x64_i8 v[124:127], v[176:179], v[184:187], 0
	v_mfma_i32_16x16x64_i8 v[124:127], v[180:183], v[188:191], v[124:127]
	v_mfma_i32_16x16x64_i8 v[116:119], v[160:163], v[204:207], 0
	v_mfma_i32_16x16x64_i8 v[116:119], v[172:175], v[208:211], v[116:119]
	v_mfma_i32_16x16x64_i8 v[108:111], v[176:179], v[204:207], 0
	v_mfma_i32_16x16x64_i8 v[108:111], v[180:183], v[208:211], v[108:111]
	v_mfma_i32_16x16x64_i8 v[100:103], v[160:163], v[212:215], 0
	v_mfma_i32_16x16x64_i8 v[100:103], v[172:175], v[216:219], v[100:103]
	v_mfma_i32_16x16x64_i8 v[92:95], v[176:179], v[212:215], 0
	v_mfma_i32_16x16x64_i8 v[92:95], v[180:183], v[216:219], v[92:95]
	v_mfma_i32_16x16x64_i8 v[84:87], v[160:163], v[220:223], 0
	v_mfma_i32_16x16x64_i8 v[84:87], v[172:175], v[224:227], v[84:87]
	v_mfma_i32_16x16x64_i8 v[76:79], v[176:179], v[220:223], 0
	v_mfma_i32_16x16x64_i8 v[76:79], v[180:183], v[224:227], v[76:79]
	s_setprio 0
	s_barrier
	s_add_i32 s64, s64, s47
	v_lshl_add_u64 v[164:165], s[44:45], 0, v[2:3]
	s_mov_b32 m0, s64
	ds_read_b128 v[184:187], v171 offset:16384
	ds_read_b128 v[188:191], v171 offset:17408
	ds_read_b128 v[204:207], v171 offset:18432
	ds_read_b128 v[208:211], v171 offset:19456
	ds_read_b128 v[212:215], v171 offset:20480
	ds_read_b128 v[216:219], v171 offset:21504
	ds_read_b128 v[220:223], v171 offset:22528
	ds_read_b128 v[224:227], v171 offset:23552
	global_load_lds_dwordx4 v[164:165], off
	s_add_i32 m0, s64, 0x2000
	s_add_u32 s64, s44, 0x80000
	v_lshl_add_u64 v[228:229], s[44:45], 0, v[148:149]
	s_addc_u32 s65, s45, 0
	s_add_i32 s67, s67, s47
	global_load_lds_dwordx4 v[228:229], off
	v_lshl_add_u64 v[240:241], s[64:65], 0, v[2:3]
	s_mov_b32 m0, s67
	v_lshl_add_u64 v[242:243], s[48:49], 0, v[150:151]
	global_load_lds_dwordx4 v[240:241], off
	v_lshl_add_u64 v[240:241], s[64:65], 0, v[148:149]
	s_add_i32 m0, s67, 0x2000
	s_nop 0
	global_load_lds_dwordx4 v[240:241], off
	v_lshl_add_u64 v[240:241], s[48:49], 0, v[152:153]
	s_mov_b32 m0, s50
	s_nop 0
	global_load_lds_dwordx4 v[240:241], off
	s_mov_b32 m0, s51
	s_nop 0
	global_load_lds_dwordx4 v[242:243], off
	s_waitcnt vmcnt(8)
	s_waitcnt lgkmcnt(0)
	s_barrier
; #define PG8_STAGE(bufoff, gbase, voff) do { _Pragma("unroll") for (int _i = 0; _i < 2; ++_i) \
;         __builtin_amdgcn_global_load_lds((const unsigned*)((const char*)(gbase) + (voff)[_i]), (PG8_LAS unsigned*)(lds + (bufoff) + ldsw + _i * 8192), 16, 0, 0); } while (0)
; #define PG8_LDA(dst, b, h) do { _Pragma("unroll") for (int m = 0; m < 4; ++m) _Pragma("unroll") for (int k = 0; k < 2; ++k) dst[m][k] = *(const PG8_LAS bf16x8*)(lds + PG8_SA(b, h) + aoff + m * 2048 + k * 1024); } while (0)
; #define PG8_LDB(dst, b, h) do { _Pragma("unroll") for (int n = 0; n < 2; ++n) _Pragma("unroll") for (int k = 0; k < 2; ++k) dst[n][k] = *(const PG8_LAS bf16x8*)(lds + PG8_SB(b, h) + boff + n * 2048 + k * 1024); } while (0)
; #define PG8_WAIT_V(n) asm volatile("s_waitcnt vmcnt(" #n ")" ::: "memory")
; #define PG8_WAIT_L(n) asm volatile("s_waitcnt lgkmcnt(" #n ")" ::: "memory")
; #define PG8_BAR __builtin_amdgcn_s_barrier()
; #define PG8_SCHED __builtin_amdgcn_sched_barrier(0)
; template <class Epi, class Sched, bool ALIGN_EPI = false, bool SP2 = false, bool I8 = false>
; __device__ __forceinline__ void gemm_phase(PG8_LAS unsigned char* lds, const Gemm g, const Sched& S, const Epi& E) {
;     ...
;             PG8_WAIT_V(8); PG8_WAIT_L(0); PG8_BAR; PG8_MMA(1, 0, At, B0); PG8_MMA(1, 1, At, B1); PG8_BAR; PG8_SCHED;
;             PG8_LDB(B0, 1, 0); PG8_LDB(B1, 1, 1); PG8_SCHED; PG8_LDA(At, 1, 0); PG8_STAGE(PG8_SA(0, 1), a2 + hstep, voffA);
;             PG8_WAIT_V(8); PG8_WAIT_L(0); PG8_BAR; PG8_MMA(0, 0, At, B0); PG8_MMA(0, 1, At, B1); PG8_BAR; PG8_SCHED;
	s_setprio 1
	s_waitcnt lgkmcnt(0)
	v_mfma_i32_16x16x64_i8 v[72:75], v[36:39], v[184:187], 0
	v_mfma_i32_16x16x64_i8 v[72:75], v[44:47], v[188:191], v[72:75]
	v_mfma_i32_16x16x64_i8 v[64:67], v[140:143], v[184:187], 0
	v_mfma_i32_16x16x64_i8 v[64:67], v[144:147], v[188:191], v[64:67]
	v_mfma_i32_16x16x64_i8 v[56:59], v[36:39], v[204:207], 0
	v_mfma_i32_16x16x64_i8 v[56:59], v[44:47], v[208:211], v[56:59]
	v_mfma_i32_16x16x64_i8 v[48:51], v[140:143], v[204:207], 0
	v_mfma_i32_16x16x64_i8 v[48:51], v[144:147], v[208:211], v[48:51]
	v_mfma_i32_16x16x64_i8 v[32:35], v[36:39], v[212:215], 0
	v_mfma_i32_16x16x64_i8 v[32:35], v[44:47], v[216:219], v[32:35]
	v_mfma_i32_16x16x64_i8 v[24:27], v[140:143], v[212:215], 0
	v_mfma_i32_16x16x64_i8 v[24:27], v[144:147], v[216:219], v[24:27]
	v_mfma_i32_16x16x64_i8 v[16:19], v[36:39], v[220:223], 0
	v_mfma_i32_16x16x64_i8 v[16:19], v[44:47], v[224:227], v[16:19]
	v_mfma_i32_16x16x64_i8 v[8:11], v[140:143], v[220:223], 0
	v_mfma_i32_16x16x64_i8 v[8:11], v[144:147], v[224:227], v[8:11]
	s_setprio 0
	s_setprio 1
	v_mfma_i32_16x16x64_i8 v[52:55], v[160:163], v[204:207], 0
	v_mfma_i32_16x16x64_i8 v[52:55], v[172:175], v[208:211], v[52:55]
	v_mfma_i32_16x16x64_i8 v[40:43], v[176:179], v[204:207], 0
	v_mfma_i32_16x16x64_i8 v[40:43], v[180:183], v[208:211], v[40:43]
	v_mfma_i32_16x16x64_i8 v[28:31], v[160:163], v[212:215], 0
	v_mfma_i32_16x16x64_i8 v[28:31], v[172:175], v[216:219], v[28:31]
	v_mfma_i32_16x16x64_i8 v[20:23], v[176:179], v[212:215], 0
	v_mfma_i32_16x16x64_i8 v[20:23], v[180:183], v[216:219], v[20:23]
	v_mfma_i32_16x16x64_i8 v[12:15], v[160:163], v[220:223], 0
	v_mfma_i32_16x16x64_i8 v[12:15], v[172:175], v[224:227], v[12:15]
	v_mfma_i32_16x16x64_i8 v[4:7], v[176:179], v[220:223], 0
	v_mfma_i32_16x16x64_i8 v[4:7], v[180:183], v[224:227], v[4:7]
	v_mfma_i32_16x16x64_i8 v[36:39], v[160:163], v[184:187], 0
	v_mfma_i32_16x16x64_i8 v[36:39], v[172:175], v[188:191], v[36:39]
	v_mfma_i32_16x16x64_i8 v[44:47], v[176:179], v[184:187], 0
	v_mfma_i32_16x16x64_i8 v[44:47], v[180:183], v[188:191], v[44:47]
	s_setprio 0
	s_barrier
	s_add_i32 s64, 0, 0x18000
	s_add_i32 s65, 0, 0x1c000
	v_add_u32_e32 v144, s64, v167
	v_add_u32_e32 v158, s65, v167
	ds_read_b128 v[60:63], v144
	ds_read_b128 v[68:71], v144 offset:1024
	ds_read_b128 v[140:143], v144 offset:2048
	ds_read_b128 v[144:147], v144 offset:3072
	ds_read_b128 v[160:163], v158
	ds_read_b128 v[172:175], v158 offset:1024
	ds_read_b128 v[176:179], v158 offset:2048
	ds_read_b128 v[180:183], v158 offset:3072
	s_add_u32 s48, s48, 0x80000
	s_addc_u32 s49, s49, 0
	s_mov_b32 m0, s52
	v_lshl_add_u64 v[244:245], s[48:49], 0, v[152:153]
	ds_read_b128 v[184:187], v171 offset:32768
	ds_read_b128 v[188:191], v171 offset:33792
	ds_read_b128 v[204:207], v171 offset:34816
	ds_read_b128 v[208:211], v171 offset:35840
	ds_read_b128 v[212:215], v171 offset:36864
	ds_read_b128 v[216:219], v171 offset:37888
	ds_read_b128 v[220:223], v171 offset:38912
	ds_read_b128 v[224:227], v171 offset:39936
	global_load_lds_dwordx4 v[244:245], off
	v_lshl_add_u64 v[244:245], s[48:49], 0, v[150:151]
	s_mov_b32 m0, s53
	s_nop 0
	global_load_lds_dwordx4 v[244:245], off
	s_waitcnt vmcnt(8)
	s_waitcnt lgkmcnt(0)
	s_barrier
	s_setprio 1
	s_waitcnt lgkmcnt(0)
	v_mfma_i32_16x16x64_i8 v[136:139], v[60:63], v[184:187], v[136:139]
	v_mfma_i32_16x16x64_i8 v[136:139], v[68:71], v[188:191], v[136:139]
	v_mfma_i32_16x16x64_i8 v[128:131], v[140:143], v[184:187], v[128:131]
	v_mfma_i32_16x16x64_i8 v[128:131], v[144:147], v[188:191], v[128:131]
	v_mfma_i32_16x16x64_i8 v[120:123], v[60:63], v[204:207], v[120:123]
	v_mfma_i32_16x16x64_i8 v[120:123], v[68:71], v[208:211], v[120:123]
	v_mfma_i32_16x16x64_i8 v[112:115], v[140:143], v[204:207], v[112:115]
	v_mfma_i32_16x16x64_i8 v[112:115], v[144:147], v[208:211], v[112:115]
	v_mfma_i32_16x16x64_i8 v[104:107], v[60:63], v[212:215], v[104:107]
	v_mfma_i32_16x16x64_i8 v[104:107], v[68:71], v[216:219], v[104:107]
	v_mfma_i32_16x16x64_i8 v[96:99], v[140:143], v[212:215], v[96:99]
	v_mfma_i32_16x16x64_i8 v[96:99], v[144:147], v[216:219], v[96:99]
	v_mfma_i32_16x16x64_i8 v[88:91], v[60:63], v[220:223], v[88:91]
	v_mfma_i32_16x16x64_i8 v[88:91], v[68:71], v[224:227], v[88:91]
	v_mfma_i32_16x16x64_i8 v[80:83], v[140:143], v[220:223], v[80:83]
	v_mfma_i32_16x16x64_i8 v[80:83], v[144:147], v[224:227], v[80:83]
	s_setprio 0
	s_setprio 1
	v_mfma_i32_16x16x64_i8 v[132:135], v[160:163], v[184:187], v[132:135]
	v_mfma_i32_16x16x64_i8 v[132:135], v[172:175], v[188:191], v[132:135]
	v_mfma_i32_16x16x64_i8 v[124:127], v[176:179], v[184:187], v[124:127]
	v_mfma_i32_16x16x64_i8 v[124:127], v[180:183], v[188:191], v[124:127]
	v_mfma_i32_16x16x64_i8 v[116:119], v[160:163], v[204:207], v[116:119]
	v_mfma_i32_16x16x64_i8 v[116:119], v[172:175], v[208:211], v[116:119]
	v_mfma_i32_16x16x64_i8 v[108:111], v[176:179], v[204:207], v[108:111]
	v_mfma_i32_16x16x64_i8 v[108:111], v[180:183], v[208:211], v[108:111]
	v_mfma_i32_16x16x64_i8 v[100:103], v[160:163], v[212:215], v[100:103]
	v_mfma_i32_16x16x64_i8 v[100:103], v[172:175], v[216:219], v[100:103]
	v_mfma_i32_16x16x64_i8 v[92:95], v[176:179], v[212:215], v[92:95]
	v_mfma_i32_16x16x64_i8 v[92:95], v[180:183], v[216:219], v[92:95]
	v_mfma_i32_16x16x64_i8 v[84:87], v[160:163], v[220:223], v[84:87]
	v_mfma_i32_16x16x64_i8 v[84:87], v[172:175], v[224:227], v[84:87]
	v_mfma_i32_16x16x64_i8 v[76:79], v[176:179], v[220:223], v[76:79]
	v_mfma_i32_16x16x64_i8 v[76:79], v[180:183], v[224:227], v[76:79]
	s_setprio 0
	s_barrier
; #define PG8_STAGE(bufoff, gbase, voff) do { _Pragma("unroll") for (int _i = 0; _i < 2; ++_i) \
;         __builtin_amdgcn_global_load_lds((const unsigned*)((const char*)(gbase) + (voff)[_i]), (PG8_LAS unsigned*)(lds + (bufoff) + ldsw + _i * 8192), 16, 0, 0); } while (0)
; #define PG8_LDA(dst, b, h) do { _Pragma("unroll") for (int m = 0; m < 4; ++m) _Pragma("unroll") for (int k = 0; k < 2; ++k) dst[m][k] = *(const PG8_LAS bf16x8*)(lds + PG8_SA(b, h) + aoff + m * 2048 + k * 1024); } while (0)
; #define PG8_WAIT_V(n) asm volatile("s_waitcnt vmcnt(" #n ")" ::: "memory")
; #define PG8_WAIT_L(n) asm volatile("s_waitcnt lgkmcnt(" #n ")" ::: "memory")
; #define PG8_BAR __builtin_amdgcn_s_barrier()
; template <class Epi, class Sched, bool ALIGN_EPI = false, bool SP2 = false, bool I8 = false>
; __device__ __forceinline__ void gemm_phase(PG8_LAS unsigned char* lds, const Gemm g, const Sched& S, const Epi& E) {
;     ...
;         for (int t = 0; t < nt; t += 2) {
;             const bool last = (t == nt - 2);
;             const char* a1 = cA + (size_t)(t + 1) * kstep;
;             const char* a2 = last ? nA : cA + (size_t)(t + 2) * kstep; const char* b2 = last ? nB : cB + (size_t)(t + 2) * kstep;
;             const char* a3 = a2 + kstep; const char* b3 = b2 + kstep;
;             if (last && has_next) S.a_ready(nxt);
;             if constexpr (SP2) {
;             PG8_LDB(B0, 0, 0); PG8_LDB(B1, 0, 1); PG8_SCHED; PG8_LDA(At, 0, 0); PG8_STAGE(PG8_SA(1, 1), a1 + hstep, voffA);
;             PG8_WAIT_V(8); PG8_WAIT_L(0); PG8_BAR; PG8_MMA(0, 0, At, B0); PG8_MMA(0, 1, At, B1); PG8_BAR; PG8_SCHED;
;             PG8_LDA(At, 0, 1); PG8_STAGE(PG8_SB(0, 0), b2, voffB); PG8_STAGE(PG8_SB(0, 1), b2 + hstep, voffB); PG8_STAGE(PG8_SA(0, 0), a2, voffA);
;             PG8_WAIT_V(8); PG8_WAIT_L(0); PG8_BAR; PG8_MMA(1, 0, At, B0); PG8_MMA(1, 1, At, B1); PG8_BAR; PG8_SCHED;
;             PG8_LDB(B0, 1, 0); PG8_LDB(B1, 1, 1); PG8_SCHED; PG8_LDA(At, 1, 0); PG8_STAGE(PG8_SA(0, 1), a2 + hstep, voffA);
;             PG8_WAIT_V(8); PG8_WAIT_L(0); PG8_BAR; PG8_MMA(0, 0, At, B0); PG8_MMA(0, 1, At, B1); PG8_BAR; PG8_SCHED;
;             PG8_LDA(At, 1, 1); PG8_STAGE(PG8_SB(1, 0), b3, voffB); PG8_STAGE(PG8_SB(1, 1), b3 + hstep, voffB); PG8_STAGE(PG8_SA(1, 0), a3, voffA);
;             PG8_WAIT_V(8); PG8_WAIT_L(0); PG8_BAR; PG8_MMA(1, 0, At, B0); PG8_MMA(1, 1, At, B1); PG8_BAR; PG8_SCHED;
	s_add_i32 s48, s64, s47
	v_lshl_add_u64 v[164:165], v[164:165], 0, s[84:85]
	s_mov_b32 m0, s48
	ds_read_b128 v[184:187], v171 offset:49152
	ds_read_b128 v[188:191], v171 offset:50176
	ds_read_b128 v[204:207], v171 offset:51200
	ds_read_b128 v[208:211], v171 offset:52224
	ds_read_b128 v[212:215], v171 offset:53248
	ds_read_b128 v[216:219], v171 offset:54272
	ds_read_b128 v[220:223], v171 offset:55296
	ds_read_b128 v[224:227], v171 offset:56320
	global_load_lds_dwordx4 v[164:165], off
	s_add_i32 m0, s48, 0x2000
	s_add_u32 s44, s44, 0x80080
	v_lshl_add_u64 v[164:165], v[228:229], 0, s[84:85]
	s_addc_u32 s45, s45, 0
	s_add_i32 s48, s65, s47
	global_load_lds_dwordx4 v[164:165], off
	v_lshl_add_u64 v[164:165], s[44:45], 0, v[2:3]
	s_mov_b32 m0, s48
	s_nop 0
	global_load_lds_dwordx4 v[164:165], off
	v_lshl_add_u64 v[164:165], s[44:45], 0, v[148:149]
	s_add_i32 m0, s48, 0x2000
	s_nop 0
	global_load_lds_dwordx4 v[164:165], off
	v_lshl_add_u64 v[164:165], v[240:241], 0, s[84:85]
	s_mov_b32 m0, s54
	s_nop 0
	global_load_lds_dwordx4 v[164:165], off
	v_lshl_add_u64 v[164:165], v[242:243], 0, s[84:85]
	s_mov_b32 m0, s55
	s_nop 0
	global_load_lds_dwordx4 v[164:165], off
	s_waitcnt vmcnt(8)
	s_waitcnt lgkmcnt(0)
	s_barrier
	s_setprio 1
	s_waitcnt lgkmcnt(0)
	v_mfma_i32_16x16x64_i8 v[72:75], v[60:63], v[184:187], v[72:75]
	v_mfma_i32_16x16x64_i8 v[72:75], v[68:71], v[188:191], v[72:75]
	v_mfma_i32_16x16x64_i8 v[64:67], v[140:143], v[184:187], v[64:67]
	v_mfma_i32_16x16x64_i8 v[64:67], v[144:147], v[188:191], v[64:67]
	v_mfma_i32_16x16x64_i8 v[56:59], v[60:63], v[204:207], v[56:59]
	v_mfma_i32_16x16x64_i8 v[56:59], v[68:71], v[208:211], v[56:59]
	v_mfma_i32_16x16x64_i8 v[48:51], v[140:143], v[204:207], v[48:51]
	v_mfma_i32_16x16x64_i8 v[48:51], v[144:147], v[208:211], v[48:51]
	v_mfma_i32_16x16x64_i8 v[32:35], v[60:63], v[212:215], v[32:35]
	v_mfma_i32_16x16x64_i8 v[32:35], v[68:71], v[216:219], v[32:35]
	v_mfma_i32_16x16x64_i8 v[24:27], v[140:143], v[212:215], v[24:27]
	v_mfma_i32_16x16x64_i8 v[24:27], v[144:147], v[216:219], v[24:27]
	v_mfma_i32_16x16x64_i8 v[16:19], v[60:63], v[220:223], v[16:19]
	v_mfma_i32_16x16x64_i8 v[16:19], v[68:71], v[224:227], v[16:19]
	v_mfma_i32_16x16x64_i8 v[8:11], v[140:143], v[220:223], v[8:11]
	v_mfma_i32_16x16x64_i8 v[8:11], v[144:147], v[224:227], v[8:11]
	s_setprio 0
	s_setprio 1
	v_mfma_i32_16x16x64_i8 v[36:39], v[160:163], v[184:187], v[36:39]
	v_mfma_i32_16x16x64_i8 v[68:71], v[172:175], v[188:191], v[36:39]
	v_mfma_i32_16x16x64_i8 v[36:39], v[176:179], v[184:187], v[44:47]
	v_mfma_i32_16x16x64_i8 v[60:63], v[180:183], v[188:191], v[36:39]
	v_mfma_i32_16x16x64_i8 v[36:39], v[160:163], v[204:207], v[52:55]
	v_mfma_i32_16x16x64_i8 v[52:55], v[172:175], v[208:211], v[36:39]
	v_mfma_i32_16x16x64_i8 v[36:39], v[176:179], v[204:207], v[40:43]
	v_mfma_i32_16x16x64_i8 v[40:43], v[180:183], v[208:211], v[36:39]
	v_mfma_i32_16x16x64_i8 v[28:31], v[160:163], v[212:215], v[28:31]
	v_mfma_i32_16x16x64_i8 v[28:31], v[172:175], v[216:219], v[28:31]
	v_mfma_i32_16x16x64_i8 v[20:23], v[176:179], v[212:215], v[20:23]
	v_mfma_i32_16x16x64_i8 v[20:23], v[180:183], v[216:219], v[20:23]
	v_mfma_i32_16x16x64_i8 v[12:15], v[160:163], v[220:223], v[12:15]
	v_mfma_i32_16x16x64_i8 v[12:15], v[172:175], v[224:227], v[12:15]
	v_mfma_i32_16x16x64_i8 v[4:7], v[176:179], v[220:223], v[4:7]
	v_mfma_i32_16x16x64_i8 v[4:7], v[180:183], v[224:227], v[4:7]
	s_setprio 0
	s_barrier
	s_add_i32 s61, s61, 2
	s_add_u32 s40, s40, 0x100
	s_addc_u32 s41, s41, 0
	s_add_u32 s59, s59, 0x100
	s_addc_u32 s60, s60, 0
	s_cmp_gt_u32 s61, 29
	s_cbranch_scc1 .Lkloop_exit_3
.LBB0_1591:
	s_add_u32 s44, s40, 0xfff80080
	s_addc_u32 s45, s41, -1
	s_add_i32 s64, 0, 0x10000
	s_cmp_eq_u32 s61, 28
	s_cselect_b32 s49, s25, s45
	s_cselect_b32 s48, s57, s44
	s_cselect_b32 s45, s23, s60
	s_cselect_b32 s44, s58, s59
	s_add_i32 s67, 0, 0x14000
	v_add_u32_e32 v144, s64, v167
	v_add_u32_e32 v158, s67, v167
	ds_read_b128 v[36:39], v144
	ds_read_b128 v[44:47], v144 offset:1024
	ds_read_b128 v[140:143], v144 offset:2048
	ds_read_b128 v[144:147], v144 offset:3072
	ds_read_b128 v[160:163], v158
	ds_read_b128 v[172:175], v158 offset:1024
	ds_read_b128 v[176:179], v158 offset:2048
	ds_read_b128 v[180:183], v158 offset:3072
	v_lshl_add_u64 v[164:165], s[40:41], 0, v[154:155]
	s_add_i32 m0, s50, 0xc000
	ds_read_b128 v[184:187], v171
	ds_read_b128 v[188:191], v171 offset:1024
	ds_read_b128 v[204:207], v171 offset:2048
	ds_read_b128 v[208:211], v171 offset:3072
	ds_read_b128 v[212:215], v171 offset:4096
	ds_read_b128 v[216:219], v171 offset:5120
	ds_read_b128 v[220:223], v171 offset:6144
	ds_read_b128 v[224:227], v171 offset:7168
	global_load_lds_dwordx4 v[164:165], off
	v_lshl_add_u64 v[164:165], s[40:41], 0, v[156:157]
	s_add_i32 m0, s50, 0xe000
	s_nop 0
	global_load_lds_dwordx4 v[164:165], off
	s_waitcnt vmcnt(8)
	s_waitcnt lgkmcnt(0)
	s_barrier
; #define PG8_STAGE(bufoff, gbase, voff) do { _Pragma("unroll") for (int _i = 0; _i < 2; ++_i) \
;         __builtin_amdgcn_global_load_lds((const unsigned*)((const char*)(gbase) + (voff)[_i]), (PG8_LAS unsigned*)(lds + (bufoff) + ldsw + _i * 8192), 16, 0, 0); } while (0)
; #define PG8_LDA(dst, b, h) do { _Pragma("unroll") for (int m = 0; m < 4; ++m) _Pragma("unroll") for (int k = 0; k < 2; ++k) dst[m][k] = *(const PG8_LAS bf16x8*)(lds + PG8_SA(b, h) + aoff + m * 2048 + k * 1024); } while (0)
; #define PG8_LDB(dst, b, h) do { _Pragma("unroll") for (int n = 0; n < 2; ++n) _Pragma("unroll") for (int k = 0; k < 2; ++k) dst[n][k] = *(const PG8_LAS bf16x8*)(lds + PG8_SB(b, h) + boff + n * 2048 + k * 1024); } while (0)
; #define PG8_WAIT_V(n) asm volatile("s_waitcnt vmcnt(" #n ")" ::: "memory")
; #define PG8_WAIT_L(n) asm volatile("s_waitcnt lgkmcnt(" #n ")" ::: "memory")
; #define PG8_BAR __builtin_amdgcn_s_barrier()
; #define PG8_SCHED __builtin_amdgcn_sched_barrier(0)
; template <class Epi, class Sched, bool ALIGN_EPI = false, bool SP2 = false, bool I8 = false>
; __device__ __forceinline__ void gemm_phase(PG8_LAS unsigned char* lds, const Gemm g, const Sched& S, const Epi& E) {
;     ...
;             PG8_LDB(B0, 0, 0); PG8_LDB(B1, 0, 1); PG8_SCHED; PG8_LDA(At, 0, 0); PG8_STAGE(PG8_SA(1, 1), a1 + hstep, voffA);
;             PG8_WAIT_V(8); PG8_WAIT_L(0); PG8_BAR; PG8_MMA(0, 0, At, B0); PG8_MMA(0, 1, At, B1); PG8_BAR; PG8_SCHED;
;             PG8_LDA(At, 0, 1); PG8_STAGE(PG8_SB(0, 0), b2, voffB); PG8_STAGE(PG8_SB(0, 1), b2 + hstep, voffB); PG8_STAGE(PG8_SA(0, 0), a2, voffA);
;             PG8_WAIT_V(8); PG8_WAIT_L(0); PG8_BAR; PG8_MMA(1, 0, At, B0); PG8_MMA(1, 1, At, B1); PG8_BAR; PG8_SCHED;
	s_setprio 1
	s_waitcnt lgkmcnt(0)
	v_mfma_i32_16x16x64_i8 v[136:139], v[36:39], v[184:187], v[136:139]
	v_mfma_i32_16x16x64_i8 v[136:139], v[44:47], v[188:191], v[136:139]
	v_mfma_i32_16x16x64_i8 v[128:131], v[140:143], v[184:187], v[128:131]
	v_mfma_i32_16x16x64_i8 v[128:131], v[144:147], v[188:191], v[128:131]
	v_mfma_i32_16x16x64_i8 v[120:123], v[36:39], v[204:207], v[120:123]
	v_mfma_i32_16x16x64_i8 v[120:123], v[44:47], v[208:211], v[120:123]
	v_mfma_i32_16x16x64_i8 v[112:115], v[140:143], v[204:207], v[112:115]
	v_mfma_i32_16x16x64_i8 v[112:115], v[144:147], v[208:211], v[112:115]
	v_mfma_i32_16x16x64_i8 v[104:107], v[36:39], v[212:215], v[104:107]
	v_mfma_i32_16x16x64_i8 v[104:107], v[44:47], v[216:219], v[104:107]
	v_mfma_i32_16x16x64_i8 v[96:99], v[140:143], v[212:215], v[96:99]
	v_mfma_i32_16x16x64_i8 v[96:99], v[144:147], v[216:219], v[96:99]
	v_mfma_i32_16x16x64_i8 v[88:91], v[36:39], v[220:223], v[88:91]
	v_mfma_i32_16x16x64_i8 v[88:91], v[44:47], v[224:227], v[88:91]
	v_mfma_i32_16x16x64_i8 v[80:83], v[140:143], v[220:223], v[80:83]
	v_mfma_i32_16x16x64_i8 v[80:83], v[144:147], v[224:227], v[80:83]
	s_setprio 0
	s_setprio 1
	v_mfma_i32_16x16x64_i8 v[132:135], v[160:163], v[184:187], v[132:135]
	v_mfma_i32_16x16x64_i8 v[132:135], v[172:175], v[188:191], v[132:135]
	v_mfma_i32_16x16x64_i8 v[124:127], v[176:179], v[184:187], v[124:127]
	v_mfma_i32_16x16x64_i8 v[124:127], v[180:183], v[188:191], v[124:127]
	v_mfma_i32_16x16x64_i8 v[116:119], v[160:163], v[204:207], v[116:119]
	v_mfma_i32_16x16x64_i8 v[116:119], v[172:175], v[208:211], v[116:119]
	v_mfma_i32_16x16x64_i8 v[108:111], v[176:179], v[204:207], v[108:111]
	v_mfma_i32_16x16x64_i8 v[108:111], v[180:183], v[208:211], v[108:111]
	v_mfma_i32_16x16x64_i8 v[100:103], v[160:163], v[212:215], v[100:103]
	v_mfma_i32_16x16x64_i8 v[100:103], v[172:175], v[216:219], v[100:103]
	v_mfma_i32_16x16x64_i8 v[92:95], v[176:179], v[212:215], v[92:95]
	v_mfma_i32_16x16x64_i8 v[92:95], v[180:183], v[216:219], v[92:95]
	v_mfma_i32_16x16x64_i8 v[84:87], v[160:163], v[220:223], v[84:87]
	v_mfma_i32_16x16x64_i8 v[84:87], v[172:175], v[224:227], v[84:87]
	v_mfma_i32_16x16x64_i8 v[76:79], v[176:179], v[220:223], v[76:79]
	v_mfma_i32_16x16x64_i8 v[76:79], v[180:183], v[224:227], v[76:79]
	s_setprio 0
	s_barrier
	s_add_i32 s64, s64, s47
	v_lshl_add_u64 v[164:165], s[44:45], 0, v[2:3]
	s_mov_b32 m0, s64
	ds_read_b128 v[184:187], v171 offset:16384
	ds_read_b128 v[188:191], v171 offset:17408
	ds_read_b128 v[204:207], v171 offset:18432
	ds_read_b128 v[208:211], v171 offset:19456
	ds_read_b128 v[212:215], v171 offset:20480
	ds_read_b128 v[216:219], v171 offset:21504
	ds_read_b128 v[220:223], v171 offset:22528
	ds_read_b128 v[224:227], v171 offset:23552
	global_load_lds_dwordx4 v[164:165], off
	s_add_i32 m0, s64, 0x2000
	s_add_u32 s64, s44, 0x80000
	v_lshl_add_u64 v[228:229], s[44:45], 0, v[148:149]
	s_addc_u32 s65, s45, 0
	s_add_i32 s67, s67, s47
	global_load_lds_dwordx4 v[228:229], off
	v_lshl_add_u64 v[240:241], s[64:65], 0, v[2:3]
	s_mov_b32 m0, s67
	v_lshl_add_u64 v[242:243], s[48:49], 0, v[150:151]
	global_load_lds_dwordx4 v[240:241], off
	v_lshl_add_u64 v[240:241], s[64:65], 0, v[148:149]
	s_add_i32 m0, s67, 0x2000
	s_nop 0
	global_load_lds_dwordx4 v[240:241], off
	v_lshl_add_u64 v[240:241], s[48:49], 0, v[152:153]
	s_mov_b32 m0, s50
	s_nop 0
	global_load_lds_dwordx4 v[240:241], off
	s_mov_b32 m0, s51
	s_nop 0
	global_load_lds_dwordx4 v[242:243], off
	s_waitcnt vmcnt(8)
	s_waitcnt lgkmcnt(0)
	s_barrier
	s_setprio 1
	s_waitcnt lgkmcnt(0)
	v_mfma_i32_16x16x64_i8 v[72:75], v[36:39], v[184:187], v[72:75]
	v_mfma_i32_16x16x64_i8 v[72:75], v[44:47], v[188:191], v[72:75]
	v_mfma_i32_16x16x64_i8 v[64:67], v[140:143], v[184:187], v[64:67]
	v_mfma_i32_16x16x64_i8 v[64:67], v[144:147], v[188:191], v[64:67]
	v_mfma_i32_16x16x64_i8 v[56:59], v[36:39], v[204:207], v[56:59]
	v_mfma_i32_16x16x64_i8 v[56:59], v[44:47], v[208:211], v[56:59]
	v_mfma_i32_16x16x64_i8 v[48:51], v[140:143], v[204:207], v[48:51]
	v_mfma_i32_16x16x64_i8 v[48:51], v[144:147], v[208:211], v[48:51]
	v_mfma_i32_16x16x64_i8 v[32:35], v[36:39], v[212:215], v[32:35]
	v_mfma_i32_16x16x64_i8 v[32:35], v[44:47], v[216:219], v[32:35]
	v_mfma_i32_16x16x64_i8 v[24:27], v[140:143], v[212:215], v[24:27]
	v_mfma_i32_16x16x64_i8 v[24:27], v[144:147], v[216:219], v[24:27]
	v_mfma_i32_16x16x64_i8 v[16:19], v[36:39], v[220:223], v[16:19]
	v_mfma_i32_16x16x64_i8 v[16:19], v[44:47], v[224:227], v[16:19]
	v_mfma_i32_16x16x64_i8 v[8:11], v[140:143], v[220:223], v[8:11]
	v_mfma_i32_16x16x64_i8 v[8:11], v[144:147], v[224:227], v[8:11]
	s_setprio 0
	s_setprio 1
	v_mfma_i32_16x16x64_i8 v[52:55], v[160:163], v[204:207], v[52:55]
	v_mfma_i32_16x16x64_i8 v[52:55], v[172:175], v[208:211], v[52:55]
	v_mfma_i32_16x16x64_i8 v[40:43], v[176:179], v[204:207], v[40:43]
	v_mfma_i32_16x16x64_i8 v[40:43], v[180:183], v[208:211], v[40:43]
	v_mfma_i32_16x16x64_i8 v[28:31], v[160:163], v[212:215], v[28:31]
	v_mfma_i32_16x16x64_i8 v[28:31], v[172:175], v[216:219], v[28:31]
	v_mfma_i32_16x16x64_i8 v[20:23], v[176:179], v[212:215], v[20:23]
	v_mfma_i32_16x16x64_i8 v[20:23], v[180:183], v[216:219], v[20:23]
	v_mfma_i32_16x16x64_i8 v[12:15], v[160:163], v[220:223], v[12:15]
	v_mfma_i32_16x16x64_i8 v[12:15], v[172:175], v[224:227], v[12:15]
	v_mfma_i32_16x16x64_i8 v[4:7], v[176:179], v[220:223], v[4:7]
	v_mfma_i32_16x16x64_i8 v[4:7], v[180:183], v[224:227], v[4:7]
	v_mfma_i32_16x16x64_i8 v[36:39], v[160:163], v[184:187], v[68:71]
	v_mfma_i32_16x16x64_i8 v[36:39], v[172:175], v[188:191], v[36:39]
	v_mfma_i32_16x16x64_i8 v[44:47], v[176:179], v[184:187], v[60:63]
	v_mfma_i32_16x16x64_i8 v[44:47], v[180:183], v[188:191], v[44:47]
	s_setprio 0
	s_barrier
; #define PG8_STAGE(bufoff, gbase, voff) do { _Pragma("unroll") for (int _i = 0; _i < 2; ++_i) \
;         __builtin_amdgcn_global_load_lds((const unsigned*)((const char*)(gbase) + (voff)[_i]), (PG8_LAS unsigned*)(lds + (bufoff) + ldsw + _i * 8192), 16, 0, 0); } while (0)
; #define PG8_LDA(dst, b, h) do { _Pragma("unroll") for (int m = 0; m < 4; ++m) _Pragma("unroll") for (int k = 0; k < 2; ++k) dst[m][k] = *(const PG8_LAS bf16x8*)(lds + PG8_SA(b, h) + aoff + m * 2048 + k * 1024); } while (0)
; #define PG8_LDB(dst, b, h) do { _Pragma("unroll") for (int n = 0; n < 2; ++n) _Pragma("unroll") for (int k = 0; k < 2; ++k) dst[n][k] = *(const PG8_LAS bf16x8*)(lds + PG8_SB(b, h) + boff + n * 2048 + k * 1024); } while (0)
; #define PG8_WAIT_V(n) asm volatile("s_waitcnt vmcnt(" #n ")" ::: "memory")
; #define PG8_WAIT_L(n) asm volatile("s_waitcnt lgkmcnt(" #n ")" ::: "memory")
; #define PG8_BAR __builtin_amdgcn_s_barrier()
; #define PG8_SCHED __builtin_amdgcn_sched_barrier(0)
; template <class Epi, class Sched, bool ALIGN_EPI = false, bool SP2 = false, bool I8 = false>
; __device__ __forceinline__ void gemm_phase(PG8_LAS unsigned char* lds, const Gemm g, const Sched& S, const Epi& E) {
;     ...
;             PG8_LDB(B0, 1, 0); PG8_LDB(B1, 1, 1); PG8_SCHED; PG8_LDA(At, 1, 0); PG8_STAGE(PG8_SA(0, 1), a2 + hstep, voffA);
;             PG8_WAIT_V(8); PG8_WAIT_L(0); PG8_BAR; PG8_MMA(0, 0, At, B0); PG8_MMA(0, 1, At, B1); PG8_BAR; PG8_SCHED;
;             PG8_LDA(At, 1, 1); PG8_STAGE(PG8_SB(1, 0), b3, voffB); PG8_STAGE(PG8_SB(1, 1), b3 + hstep, voffB); PG8_STAGE(PG8_SA(1, 0), a3, voffA);
;             PG8_WAIT_V(8); PG8_WAIT_L(0); PG8_BAR; PG8_MMA(1, 0, At, B0); PG8_MMA(1, 1, At, B1); PG8_BAR; PG8_SCHED;
	s_add_i32 s64, 0, 0x18000
	s_add_i32 s65, 0, 0x1c000
	v_add_u32_e32 v144, s64, v167
	v_add_u32_e32 v158, s65, v167
	ds_read_b128 v[60:63], v144
	ds_read_b128 v[68:71], v144 offset:1024
	ds_read_b128 v[140:143], v144 offset:2048
	ds_read_b128 v[144:147], v144 offset:3072
	ds_read_b128 v[160:163], v158
	ds_read_b128 v[172:175], v158 offset:1024
	ds_read_b128 v[176:179], v158 offset:2048
	ds_read_b128 v[180:183], v158 offset:3072
	s_add_u32 s48, s48, 0x80000
	s_addc_u32 s49, s49, 0
	s_mov_b32 m0, s52
	v_lshl_add_u64 v[244:245], s[48:49], 0, v[152:153]
	ds_read_b128 v[184:187], v171 offset:32768
	ds_read_b128 v[188:191], v171 offset:33792
	ds_read_b128 v[204:207], v171 offset:34816
	ds_read_b128 v[208:211], v171 offset:35840
	ds_read_b128 v[212:215], v171 offset:36864
	ds_read_b128 v[216:219], v171 offset:37888
	ds_read_b128 v[220:223], v171 offset:38912
	ds_read_b128 v[224:227], v171 offset:39936
	global_load_lds_dwordx4 v[244:245], off
	v_lshl_add_u64 v[244:245], s[48:49], 0, v[150:151]
	s_mov_b32 m0, s53
	s_nop 0
	global_load_lds_dwordx4 v[244:245], off
	s_waitcnt vmcnt(8)
	s_waitcnt lgkmcnt(0)
	s_barrier
	s_setprio 1
	s_waitcnt lgkmcnt(0)
	v_mfma_i32_16x16x64_i8 v[136:139], v[60:63], v[184:187], v[136:139]
	v_mfma_i32_16x16x64_i8 v[136:139], v[68:71], v[188:191], v[136:139]
	v_mfma_i32_16x16x64_i8 v[128:131], v[140:143], v[184:187], v[128:131]
	v_mfma_i32_16x16x64_i8 v[128:131], v[144:147], v[188:191], v[128:131]
	v_mfma_i32_16x16x64_i8 v[120:123], v[60:63], v[204:207], v[120:123]
	v_mfma_i32_16x16x64_i8 v[120:123], v[68:71], v[208:211], v[120:123]
	v_mfma_i32_16x16x64_i8 v[112:115], v[140:143], v[204:207], v[112:115]
	v_mfma_i32_16x16x64_i8 v[112:115], v[144:147], v[208:211], v[112:115]
	v_mfma_i32_16x16x64_i8 v[104:107], v[60:63], v[212:215], v[104:107]
	v_mfma_i32_16x16x64_i8 v[104:107], v[68:71], v[216:219], v[104:107]
	v_mfma_i32_16x16x64_i8 v[96:99], v[140:143], v[212:215], v[96:99]
	v_mfma_i32_16x16x64_i8 v[96:99], v[144:147], v[216:219], v[96:99]
	v_mfma_i32_16x16x64_i8 v[88:91], v[60:63], v[220:223], v[88:91]
	v_mfma_i32_16x16x64_i8 v[88:91], v[68:71], v[224:227], v[88:91]
	v_mfma_i32_16x16x64_i8 v[80:83], v[140:143], v[220:223], v[80:83]
	v_mfma_i32_16x16x64_i8 v[80:83], v[144:147], v[224:227], v[80:83]
	s_setprio 0
	s_setprio 1
	v_mfma_i32_16x16x64_i8 v[132:135], v[160:163], v[184:187], v[132:135]
	v_mfma_i32_16x16x64_i8 v[132:135], v[172:175], v[188:191], v[132:135]
	v_mfma_i32_16x16x64_i8 v[124:127], v[176:179], v[184:187], v[124:127]
	v_mfma_i32_16x16x64_i8 v[124:127], v[180:183], v[188:191], v[124:127]
	v_mfma_i32_16x16x64_i8 v[116:119], v[160:163], v[204:207], v[116:119]
	v_mfma_i32_16x16x64_i8 v[116:119], v[172:175], v[208:211], v[116:119]
	v_mfma_i32_16x16x64_i8 v[108:111], v[176:179], v[204:207], v[108:111]
	v_mfma_i32_16x16x64_i8 v[108:111], v[180:183], v[208:211], v[108:111]
	v_mfma_i32_16x16x64_i8 v[100:103], v[160:163], v[212:215], v[100:103]
	v_mfma_i32_16x16x64_i8 v[100:103], v[172:175], v[216:219], v[100:103]
	v_mfma_i32_16x16x64_i8 v[92:95], v[176:179], v[212:215], v[92:95]
	v_mfma_i32_16x16x64_i8 v[92:95], v[180:183], v[216:219], v[92:95]
	v_mfma_i32_16x16x64_i8 v[84:87], v[160:163], v[220:223], v[84:87]
	v_mfma_i32_16x16x64_i8 v[84:87], v[172:175], v[224:227], v[84:87]
	v_mfma_i32_16x16x64_i8 v[76:79], v[176:179], v[220:223], v[76:79]
	v_mfma_i32_16x16x64_i8 v[76:79], v[180:183], v[224:227], v[76:79]
	s_setprio 0
	s_barrier
	s_add_i32 s48, s64, s47
	v_lshl_add_u64 v[164:165], v[164:165], 0, s[84:85]
	s_mov_b32 m0, s48
	ds_read_b128 v[184:187], v171 offset:49152
	ds_read_b128 v[188:191], v171 offset:50176
	ds_read_b128 v[204:207], v171 offset:51200
	ds_read_b128 v[208:211], v171 offset:52224
	ds_read_b128 v[212:215], v171 offset:53248
	ds_read_b128 v[216:219], v171 offset:54272
	ds_read_b128 v[220:223], v171 offset:55296
	ds_read_b128 v[224:227], v171 offset:56320
	global_load_lds_dwordx4 v[164:165], off
	s_add_i32 m0, s48, 0x2000
	s_add_u32 s44, s44, 0x80080
	v_lshl_add_u64 v[164:165], v[228:229], 0, s[84:85]
	s_addc_u32 s45, s45, 0
	s_add_i32 s48, s65, s47
	global_load_lds_dwordx4 v[164:165], off
	v_lshl_add_u64 v[164:165], s[44:45], 0, v[2:3]
	s_mov_b32 m0, s48
	s_nop 0
	global_load_lds_dwordx4 v[164:165], off
	v_lshl_add_u64 v[164:165], s[44:45], 0, v[148:149]
	s_add_i32 m0, s48, 0x2000
	s_nop 0
	global_load_lds_dwordx4 v[164:165], off
	v_lshl_add_u64 v[164:165], v[240:241], 0, s[84:85]
	s_mov_b32 m0, s54
	s_nop 0
	global_load_lds_dwordx4 v[164:165], off
	v_lshl_add_u64 v[164:165], v[242:243], 0, s[84:85]
	s_mov_b32 m0, s55
	s_nop 0
	global_load_lds_dwordx4 v[164:165], off
	s_waitcnt vmcnt(8)
	s_waitcnt lgkmcnt(0)
	s_barrier
	s_setprio 1
	s_waitcnt lgkmcnt(0)
	v_mfma_i32_16x16x64_i8 v[72:75], v[60:63], v[184:187], v[72:75]
	v_mfma_i32_16x16x64_i8 v[72:75], v[68:71], v[188:191], v[72:75]
	v_mfma_i32_16x16x64_i8 v[64:67], v[140:143], v[184:187], v[64:67]
	v_mfma_i32_16x16x64_i8 v[64:67], v[144:147], v[188:191], v[64:67]
	v_mfma_i32_16x16x64_i8 v[56:59], v[60:63], v[204:207], v[56:59]
	v_mfma_i32_16x16x64_i8 v[56:59], v[68:71], v[208:211], v[56:59]
	v_mfma_i32_16x16x64_i8 v[48:51], v[140:143], v[204:207], v[48:51]
	v_mfma_i32_16x16x64_i8 v[48:51], v[144:147], v[208:211], v[48:51]
	v_mfma_i32_16x16x64_i8 v[32:35], v[60:63], v[212:215], v[32:35]
	v_mfma_i32_16x16x64_i8 v[32:35], v[68:71], v[216:219], v[32:35]
	v_mfma_i32_16x16x64_i8 v[24:27], v[140:143], v[212:215], v[24:27]
	v_mfma_i32_16x16x64_i8 v[24:27], v[144:147], v[216:219], v[24:27]
	v_mfma_i32_16x16x64_i8 v[16:19], v[60:63], v[220:223], v[16:19]
	v_mfma_i32_16x16x64_i8 v[16:19], v[68:71], v[224:227], v[16:19]
	v_mfma_i32_16x16x64_i8 v[8:11], v[140:143], v[220:223], v[8:11]
	v_mfma_i32_16x16x64_i8 v[8:11], v[144:147], v[224:227], v[8:11]
	s_setprio 0
	s_setprio 1
	v_mfma_i32_16x16x64_i8 v[36:39], v[160:163], v[184:187], v[36:39]
	v_mfma_i32_16x16x64_i8 v[68:71], v[172:175], v[188:191], v[36:39]
	v_mfma_i32_16x16x64_i8 v[36:39], v[176:179], v[184:187], v[44:47]
	v_mfma_i32_16x16x64_i8 v[60:63], v[180:183], v[188:191], v[36:39]
	v_mfma_i32_16x16x64_i8 v[36:39], v[160:163], v[204:207], v[52:55]
	v_mfma_i32_16x16x64_i8 v[52:55], v[172:175], v[208:211], v[36:39]
	v_mfma_i32_16x16x64_i8 v[36:39], v[176:179], v[204:207], v[40:43]
	v_mfma_i32_16x16x64_i8 v[40:43], v[180:183], v[208:211], v[36:39]
	v_mfma_i32_16x16x64_i8 v[28:31], v[160:163], v[212:215], v[28:31]
	v_mfma_i32_16x16x64_i8 v[28:31], v[172:175], v[216:219], v[28:31]
	v_mfma_i32_16x16x64_i8 v[20:23], v[176:179], v[212:215], v[20:23]
	v_mfma_i32_16x16x64_i8 v[20:23], v[180:183], v[216:219], v[20:23]
	v_mfma_i32_16x16x64_i8 v[12:15], v[160:163], v[220:223], v[12:15]
	v_mfma_i32_16x16x64_i8 v[12:15], v[172:175], v[224:227], v[12:15]
	v_mfma_i32_16x16x64_i8 v[4:7], v[176:179], v[220:223], v[4:7]
	v_mfma_i32_16x16x64_i8 v[4:7], v[180:183], v[224:227], v[4:7]
	s_setprio 0
	s_barrier
	s_add_i32 s61, s61, 2
	s_add_u32 s40, s40, 0x100
	s_addc_u32 s41, s41, 0
	s_add_u32 s59, s59, 0x100
	s_addc_u32 s60, s60, 0
	s_cmp_gt_u32 s61, 29
	s_cbranch_scc0 .LBB0_1591

; #define PG8_STAGE(bufoff, gbase, voff) do { _Pragma("unroll") for (int _i = 0; _i < 2; ++_i) \
;         __builtin_amdgcn_global_load_lds((const unsigned*)((const char*)(gbase) + (voff)[_i]), (PG8_LAS unsigned*)(lds + (bufoff) + ldsw + _i * 8192), 16, 0, 0); } while (0)
; #define PG8_LDA(dst, b, h) do { _Pragma("unroll") for (int m = 0; m < 4; ++m) _Pragma("unroll") for (int k = 0; k < 2; ++k) dst[m][k] = *(const PG8_LAS bf16x8*)(lds + PG8_SA(b, h) + aoff + m * 2048 + k * 1024); } while (0)
; #define PG8_LDB(dst, b, h) do { _Pragma("unroll") for (int n = 0; n < 2; ++n) _Pragma("unroll") for (int k = 0; k < 2; ++k) dst[n][k] = *(const PG8_LAS bf16x8*)(lds + PG8_SB(b, h) + boff + n * 2048 + k * 1024); } while (0)
; #define PG8_WAIT_V(n) asm volatile("s_waitcnt vmcnt(" #n ")" ::: "memory")
; #define PG8_WAIT_L(n) asm volatile("s_waitcnt lgkmcnt(" #n ")" ::: "memory")
; #define PG8_BAR __builtin_amdgcn_s_barrier()
; #define PG8_SCHED __builtin_amdgcn_sched_barrier(0)
; template <class Epi, class Sched, bool ALIGN_EPI = false, bool SP2 = false, bool I8 = false>
; __device__ __forceinline__ void gemm_phase(PG8_LAS unsigned char* lds, const Gemm g, const Sched& S, const Epi& E) {
;     ...
;         const bool has_next = S.next(ui + 1, nxt);
;         const char* nA = has_next ? (const char*)g.A + (size_t)nxt.pm * tstep : cA; const char* nB = has_next ? (const char*)g.Bt + (size_t)nxt.pn * tstep : cB;
;         for (int t = 0; t < nt; t += 2) {
;             const bool last = (t == nt - 2);
;             const char* a1 = cA + (size_t)(t + 1) * kstep;
;             const char* a2 = last ? nA : cA + (size_t)(t + 2) * kstep; const char* b2 = last ? nB : cB + (size_t)(t + 2) * kstep;
;             const char* a3 = a2 + kstep; const char* b3 = b2 + kstep;
;             if (last && has_next) S.a_ready(nxt);
;             if constexpr (SP2) {
;             PG8_LDB(B0, 0, 0); PG8_LDB(B1, 0, 1); PG8_SCHED; PG8_LDA(At, 0, 0); PG8_STAGE(PG8_SA(1, 1), a1 + hstep, voffA);
;             PG8_WAIT_V(8); PG8_WAIT_L(0); PG8_BAR; PG8_MMA(0, 0, At, B0); PG8_MMA(0, 1, At, B1); PG8_BAR; PG8_SCHED;
;     ...
; #pragma unroll
;         for (int a = 0; a < 2; ++a)
; #pragma unroll
;             for (int b = 0; b < 2; ++b)
; #pragma unroll
;                 for (int m = 0; m < 4; ++m)
; #pragma unroll
;                     for (int n = 0; n < 2; ++n) acc[a][b][m][n] = (acc_t){0, 0, 0, 0};
.LBB0_1621:
	v_mov_b32_e32 v127, 0
	s_andn2_b64 vcc, exec, s[26:27]
	v_mov_b32_e32 v126, v127
	v_mov_b32_e32 v125, v127
	v_mov_b32_e32 v124, v127
	v_mov_b32_e32 v131, v127
	v_mov_b32_e32 v130, v127
	v_mov_b32_e32 v129, v127
	v_mov_b32_e32 v128, v127
	v_mov_b32_e32 v115, v127
	v_mov_b32_e32 v114, v127
	v_mov_b32_e32 v113, v127
	v_mov_b32_e32 v112, v127
	v_mov_b32_e32 v111, v127
	v_mov_b32_e32 v110, v127
	v_mov_b32_e32 v109, v127
	v_mov_b32_e32 v108, v127
	v_mov_b32_e32 v99, v127
	v_mov_b32_e32 v98, v127
	v_mov_b32_e32 v97, v127
	v_mov_b32_e32 v96, v127
	v_mov_b32_e32 v95, v127
	v_mov_b32_e32 v94, v127
	v_mov_b32_e32 v93, v127
	v_mov_b32_e32 v92, v127
	v_mov_b32_e32 v83, v127
	v_mov_b32_e32 v82, v127
	v_mov_b32_e32 v81, v127
	v_mov_b32_e32 v80, v127
	v_mov_b32_e32 v79, v127
	v_mov_b32_e32 v78, v127
	v_mov_b32_e32 v77, v127
	v_mov_b32_e32 v76, v127
	v_mov_b32_e32 v123, v127
	v_mov_b32_e32 v122, v127
	v_mov_b32_e32 v121, v127
	v_mov_b32_e32 v120, v127
	v_mov_b32_e32 v119, v127
	v_mov_b32_e32 v118, v127
	v_mov_b32_e32 v117, v127
	v_mov_b32_e32 v116, v127
	v_mov_b32_e32 v107, v127
	v_mov_b32_e32 v106, v127
	v_mov_b32_e32 v105, v127
	v_mov_b32_e32 v104, v127
	v_mov_b32_e32 v103, v127
	v_mov_b32_e32 v102, v127
	v_mov_b32_e32 v101, v127
	v_mov_b32_e32 v100, v127
	v_mov_b32_e32 v91, v127
	v_mov_b32_e32 v90, v127
	v_mov_b32_e32 v89, v127
	v_mov_b32_e32 v88, v127
	v_mov_b32_e32 v87, v127
	v_mov_b32_e32 v86, v127
	v_mov_b32_e32 v85, v127
	v_mov_b32_e32 v84, v127
	v_mov_b32_e32 v75, v127
	v_mov_b32_e32 v74, v127
	v_mov_b32_e32 v73, v127
	v_mov_b32_e32 v72, v127
	v_mov_b32_e32 v71, v127
	v_mov_b32_e32 v70, v127
	v_mov_b32_e32 v69, v127
	v_mov_b32_e32 v68, v127
	v_mov_b32_e32 v67, v127
	v_mov_b32_e32 v66, v127
	v_mov_b32_e32 v65, v127
	v_mov_b32_e32 v64, v127
	v_mov_b32_e32 v63, v127
	v_mov_b32_e32 v62, v127
	v_mov_b32_e32 v61, v127
	v_mov_b32_e32 v60, v127
	v_mov_b32_e32 v51, v127
	v_mov_b32_e32 v50, v127
	v_mov_b32_e32 v49, v127
	v_mov_b32_e32 v48, v127
	v_mov_b32_e32 v47, v127
	v_mov_b32_e32 v46, v127
	v_mov_b32_e32 v45, v127
	v_mov_b32_e32 v44, v127
	v_mov_b32_e32 v35, v127
	v_mov_b32_e32 v34, v127
	v_mov_b32_e32 v33, v127
	v_mov_b32_e32 v32, v127
	v_mov_b32_e32 v31, v127
	v_mov_b32_e32 v30, v127
	v_mov_b32_e32 v29, v127
	v_mov_b32_e32 v28, v127
	v_mov_b32_e32 v19, v127
	v_mov_b32_e32 v18, v127
	v_mov_b32_e32 v17, v127
	v_mov_b32_e32 v16, v127
	v_mov_b32_e32 v15, v127
	v_mov_b32_e32 v14, v127
	v_mov_b32_e32 v13, v127
	v_mov_b32_e32 v12, v127
	v_mov_b32_e32 v59, v127
	v_mov_b32_e32 v58, v127
	v_mov_b32_e32 v57, v127
	v_mov_b32_e32 v56, v127
	v_mov_b32_e32 v55, v127
	v_mov_b32_e32 v54, v127
	v_mov_b32_e32 v53, v127
	v_mov_b32_e32 v52, v127
	v_mov_b32_e32 v43, v127
	v_mov_b32_e32 v42, v127
	v_mov_b32_e32 v41, v127
	v_mov_b32_e32 v40, v127
	v_mov_b32_e32 v39, v127
	v_mov_b32_e32 v38, v127
	v_mov_b32_e32 v37, v127
	v_mov_b32_e32 v36, v127
	v_mov_b32_e32 v27, v127
	v_mov_b32_e32 v26, v127
	v_mov_b32_e32 v25, v127
	v_mov_b32_e32 v24, v127
	v_mov_b32_e32 v23, v127
	v_mov_b32_e32 v22, v127
	v_mov_b32_e32 v21, v127
	v_mov_b32_e32 v20, v127
	v_mov_b32_e32 v11, v127
	v_mov_b32_e32 v10, v127
	v_mov_b32_e32 v9, v127
	v_mov_b32_e32 v8, v127
	v_mov_b32_e32 v7, v127
	v_mov_b32_e32 v6, v127
	v_mov_b32_e32 v5, v127
	v_mov_b32_e32 v4, v127
	s_cbranch_vccnz .LBB0_1625
	s_add_u32 s44, s44, 0x80
	s_addc_u32 s45, s45, 0
	s_add_u32 s65, s48, 0x100
	s_addc_u32 s67, s49, 0
	s_mov_b32 s48, 0
	s_add_i32 s72, s48, 2
	s_add_u32 s73, s44, 0x80
	s_addc_u32 s49, s45, 0
	s_add_i32 s86, 0, 0x10000
	s_cmp_eq_u32 s57, s48
	s_cselect_b32 s49, s13, s49
	s_cselect_b32 s48, s12, s73
	s_cselect_b32 s77, s41, s67
	s_cselect_b32 s76, s40, s65
	s_add_i32 s73, 0, 0x14000
	v_add_u32_e32 v158, s86, v143
	v_add_u32_e32 v174, s73, v143
	ds_read_b128 v[146:149], v158
	ds_read_b128 v[150:153], v158 offset:1024
	ds_read_b128 v[154:157], v158 offset:2048
	ds_read_b128 v[158:161], v158 offset:3072
	ds_read_b128 v[162:165], v174
	ds_read_b128 v[166:169], v174 offset:1024
	ds_read_b128 v[170:173], v174 offset:2048
	ds_read_b128 v[174:177], v174 offset:3072
	v_lshl_add_u64 v[190:191], s[44:45], 0, v[138:139]
	s_add_i32 m0, s47, 0xc000
	ds_read_b128 v[178:181], v145
	ds_read_b128 v[182:185], v145 offset:1024
	ds_read_b128 v[186:189], v145 offset:2048
	ds_read_b128 v[204:207], v145 offset:3072
	ds_read_b128 v[208:211], v145 offset:4096
	ds_read_b128 v[212:215], v145 offset:5120
	ds_read_b128 v[216:219], v145 offset:6144
	ds_read_b128 v[220:223], v145 offset:7168
	global_load_lds_dwordx4 v[190:191], off
	v_lshl_add_u64 v[190:191], s[44:45], 0, v[140:141]
	s_add_i32 m0, s47, 0xe000
	s_nop 0
	global_load_lds_dwordx4 v[190:191], off
	s_waitcnt vmcnt(8)
	s_waitcnt lgkmcnt(0)
	s_barrier
; #define PG8_STAGE(bufoff, gbase, voff) do { _Pragma("unroll") for (int _i = 0; _i < 2; ++_i) \
;         __builtin_amdgcn_global_load_lds((const unsigned*)((const char*)(gbase) + (voff)[_i]), (PG8_LAS unsigned*)(lds + (bufoff) + ldsw + _i * 8192), 16, 0, 0); } while (0)
; #define PG8_LDA(dst, b, h) do { _Pragma("unroll") for (int m = 0; m < 4; ++m) _Pragma("unroll") for (int k = 0; k < 2; ++k) dst[m][k] = *(const PG8_LAS bf16x8*)(lds + PG8_SA(b, h) + aoff + m * 2048 + k * 1024); } while (0)
; #define PG8_LDB(dst, b, h) do { _Pragma("unroll") for (int n = 0; n < 2; ++n) _Pragma("unroll") for (int k = 0; k < 2; ++k) dst[n][k] = *(const PG8_LAS bf16x8*)(lds + PG8_SB(b, h) + boff + n * 2048 + k * 1024); } while (0)
; #define PG8_WAIT_V(n) asm volatile("s_waitcnt vmcnt(" #n ")" ::: "memory")
; #define PG8_WAIT_L(n) asm volatile("s_waitcnt lgkmcnt(" #n ")" ::: "memory")
; #define PG8_BAR __builtin_amdgcn_s_barrier()
; #define PG8_SCHED __builtin_amdgcn_sched_barrier(0)
; template <class Epi, class Sched, bool ALIGN_EPI = false, bool SP2 = false, bool I8 = false>
; __device__ __forceinline__ void gemm_phase(PG8_LAS unsigned char* lds, const Gemm g, const Sched& S, const Epi& E) {
;     ...
;             PG8_LDB(B0, 0, 0); PG8_LDB(B1, 0, 1); PG8_SCHED; PG8_LDA(At, 0, 0); PG8_STAGE(PG8_SA(1, 1), a1 + hstep, voffA);
;             PG8_WAIT_V(8); PG8_WAIT_L(0); PG8_BAR; PG8_MMA(0, 0, At, B0); PG8_MMA(0, 1, At, B1); PG8_BAR; PG8_SCHED;
;             PG8_LDA(At, 0, 1); PG8_STAGE(PG8_SB(0, 0), b2, voffB); PG8_STAGE(PG8_SB(0, 1), b2 + hstep, voffB); PG8_STAGE(PG8_SA(0, 0), a2, voffA);
;             PG8_WAIT_V(8); PG8_WAIT_L(0); PG8_BAR; PG8_MMA(1, 0, At, B0); PG8_MMA(1, 1, At, B1); PG8_BAR; PG8_SCHED;
	s_setprio 1
	s_waitcnt lgkmcnt(0)
	v_mfma_f32_16x16x32_bf16 v[124:127], v[146:149], v[178:181], 0
	v_mfma_f32_16x16x32_bf16 v[124:127], v[150:153], v[182:185], v[124:127]
	v_mfma_f32_16x16x32_bf16 v[128:131], v[154:157], v[178:181], 0
	v_mfma_f32_16x16x32_bf16 v[128:131], v[158:161], v[182:185], v[128:131]
	v_mfma_f32_16x16x32_bf16 v[112:115], v[146:149], v[186:189], 0
	v_mfma_f32_16x16x32_bf16 v[112:115], v[150:153], v[204:207], v[112:115]
	v_mfma_f32_16x16x32_bf16 v[108:111], v[154:157], v[186:189], 0
	v_mfma_f32_16x16x32_bf16 v[108:111], v[158:161], v[204:207], v[108:111]
	v_mfma_f32_16x16x32_bf16 v[96:99], v[146:149], v[208:211], 0
	v_mfma_f32_16x16x32_bf16 v[96:99], v[150:153], v[212:215], v[96:99]
	v_mfma_f32_16x16x32_bf16 v[92:95], v[154:157], v[208:211], 0
	v_mfma_f32_16x16x32_bf16 v[92:95], v[158:161], v[212:215], v[92:95]
	v_mfma_f32_16x16x32_bf16 v[80:83], v[146:149], v[216:219], 0
	v_mfma_f32_16x16x32_bf16 v[80:83], v[150:153], v[220:223], v[80:83]
	v_mfma_f32_16x16x32_bf16 v[76:79], v[154:157], v[216:219], 0
	v_mfma_f32_16x16x32_bf16 v[76:79], v[158:161], v[220:223], v[76:79]
	s_setprio 0
	s_setprio 1
	v_mfma_f32_16x16x32_bf16 v[120:123], v[162:165], v[178:181], 0
	v_mfma_f32_16x16x32_bf16 v[120:123], v[166:169], v[182:185], v[120:123]
	v_mfma_f32_16x16x32_bf16 v[116:119], v[170:173], v[178:181], 0
	v_mfma_f32_16x16x32_bf16 v[116:119], v[174:177], v[182:185], v[116:119]
	v_mfma_f32_16x16x32_bf16 v[104:107], v[162:165], v[186:189], 0
	v_mfma_f32_16x16x32_bf16 v[104:107], v[166:169], v[204:207], v[104:107]
	v_mfma_f32_16x16x32_bf16 v[100:103], v[170:173], v[186:189], 0
	v_mfma_f32_16x16x32_bf16 v[100:103], v[174:177], v[204:207], v[100:103]
	v_mfma_f32_16x16x32_bf16 v[88:91], v[162:165], v[208:211], 0
	v_mfma_f32_16x16x32_bf16 v[88:91], v[166:169], v[212:215], v[88:91]
	v_mfma_f32_16x16x32_bf16 v[84:87], v[170:173], v[208:211], 0
	v_mfma_f32_16x16x32_bf16 v[84:87], v[174:177], v[212:215], v[84:87]
	v_mfma_f32_16x16x32_bf16 v[72:75], v[162:165], v[216:219], 0
	v_mfma_f32_16x16x32_bf16 v[72:75], v[166:169], v[220:223], v[72:75]
	v_mfma_f32_16x16x32_bf16 v[68:71], v[170:173], v[216:219], 0
	v_mfma_f32_16x16x32_bf16 v[68:71], v[174:177], v[220:223], v[68:71]
	s_setprio 0
	s_barrier
	s_add_i32 s86, s86, s28
	v_lshl_add_u64 v[190:191], s[76:77], 0, v[2:3]
	s_mov_b32 m0, s86
	ds_read_b128 v[178:181], v145 offset:16384
	ds_read_b128 v[182:185], v145 offset:17408
	ds_read_b128 v[186:189], v145 offset:18432
	ds_read_b128 v[204:207], v145 offset:19456
	ds_read_b128 v[208:211], v145 offset:20480
	ds_read_b128 v[212:215], v145 offset:21504
	ds_read_b128 v[216:219], v145 offset:22528
	ds_read_b128 v[220:223], v145 offset:23552
	global_load_lds_dwordx4 v[190:191], off
	s_add_i32 m0, s86, 0x2000
	v_lshl_add_u64 v[224:225], s[76:77], 0, v[136:137]
	s_add_u32 s76, s76, s18
	s_addc_u32 s77, s77, s19
	s_add_i32 s73, s73, s28
	global_load_lds_dwordx4 v[224:225], off
	v_lshl_add_u64 v[226:227], s[76:77], 0, v[2:3]
	s_mov_b32 m0, s73
	v_lshl_add_u64 v[228:229], s[76:77], 0, v[136:137]
	global_load_lds_dwordx4 v[226:227], off
	s_add_i32 m0, s73, 0x2000
	v_lshl_add_u64 v[240:241], s[48:49], 0, v[132:133]
	global_load_lds_dwordx4 v[228:229], off
	s_mov_b32 m0, s47
	v_lshl_add_u64 v[242:243], s[48:49], 0, v[134:135]
	global_load_lds_dwordx4 v[240:241], off
	s_mov_b32 m0, s50
	s_nop 0
	global_load_lds_dwordx4 v[242:243], off
	s_waitcnt vmcnt(8)
	s_waitcnt lgkmcnt(0)
	s_barrier
	s_setprio 1
	s_waitcnt lgkmcnt(0)
	v_mfma_f32_16x16x32_bf16 v[64:67], v[146:149], v[178:181], 0
	v_mfma_f32_16x16x32_bf16 v[64:67], v[150:153], v[182:185], v[64:67]
	v_mfma_f32_16x16x32_bf16 v[60:63], v[154:157], v[178:181], 0
	v_mfma_f32_16x16x32_bf16 v[60:63], v[158:161], v[182:185], v[60:63]
	v_mfma_f32_16x16x32_bf16 v[48:51], v[146:149], v[186:189], 0
	v_mfma_f32_16x16x32_bf16 v[48:51], v[150:153], v[204:207], v[48:51]
	v_mfma_f32_16x16x32_bf16 v[44:47], v[154:157], v[186:189], 0
	v_mfma_f32_16x16x32_bf16 v[44:47], v[158:161], v[204:207], v[44:47]
	v_mfma_f32_16x16x32_bf16 v[32:35], v[146:149], v[208:211], 0
	v_mfma_f32_16x16x32_bf16 v[32:35], v[150:153], v[212:215], v[32:35]
	v_mfma_f32_16x16x32_bf16 v[28:31], v[154:157], v[208:211], 0
	v_mfma_f32_16x16x32_bf16 v[28:31], v[158:161], v[212:215], v[28:31]
	v_mfma_f32_16x16x32_bf16 v[16:19], v[146:149], v[216:219], 0
	v_mfma_f32_16x16x32_bf16 v[16:19], v[150:153], v[220:223], v[16:19]
	v_mfma_f32_16x16x32_bf16 v[12:15], v[154:157], v[216:219], 0
	v_mfma_f32_16x16x32_bf16 v[12:15], v[158:161], v[220:223], v[12:15]
	s_setprio 0
	s_setprio 1
	v_mfma_f32_16x16x32_bf16 v[56:59], v[162:165], v[178:181], 0
	v_mfma_f32_16x16x32_bf16 v[56:59], v[166:169], v[182:185], v[56:59]
	v_mfma_f32_16x16x32_bf16 v[52:55], v[170:173], v[178:181], 0
	v_mfma_f32_16x16x32_bf16 v[52:55], v[174:177], v[182:185], v[52:55]
	v_mfma_f32_16x16x32_bf16 v[40:43], v[162:165], v[186:189], 0
	v_mfma_f32_16x16x32_bf16 v[40:43], v[166:169], v[204:207], v[40:43]
	v_mfma_f32_16x16x32_bf16 v[36:39], v[170:173], v[186:189], 0
	v_mfma_f32_16x16x32_bf16 v[36:39], v[174:177], v[204:207], v[36:39]
	v_mfma_f32_16x16x32_bf16 v[24:27], v[162:165], v[208:211], 0
	v_mfma_f32_16x16x32_bf16 v[24:27], v[166:169], v[212:215], v[24:27]
	v_mfma_f32_16x16x32_bf16 v[20:23], v[170:173], v[208:211], 0
	v_mfma_f32_16x16x32_bf16 v[20:23], v[174:177], v[212:215], v[20:23]
	v_mfma_f32_16x16x32_bf16 v[8:11], v[162:165], v[216:219], 0
	v_mfma_f32_16x16x32_bf16 v[8:11], v[166:169], v[220:223], v[8:11]
	v_mfma_f32_16x16x32_bf16 v[4:7], v[170:173], v[216:219], 0
	v_mfma_f32_16x16x32_bf16 v[4:7], v[174:177], v[220:223], v[4:7]
	s_setprio 0
	s_barrier
; #define PG8_STAGE(bufoff, gbase, voff) do { _Pragma("unroll") for (int _i = 0; _i < 2; ++_i) \
;         __builtin_amdgcn_global_load_lds((const unsigned*)((const char*)(gbase) + (voff)[_i]), (PG8_LAS unsigned*)(lds + (bufoff) + ldsw + _i * 8192), 16, 0, 0); } while (0)
; #define PG8_LDA(dst, b, h) do { _Pragma("unroll") for (int m = 0; m < 4; ++m) _Pragma("unroll") for (int k = 0; k < 2; ++k) dst[m][k] = *(const PG8_LAS bf16x8*)(lds + PG8_SA(b, h) + aoff + m * 2048 + k * 1024); } while (0)
; #define PG8_LDB(dst, b, h) do { _Pragma("unroll") for (int n = 0; n < 2; ++n) _Pragma("unroll") for (int k = 0; k < 2; ++k) dst[n][k] = *(const PG8_LAS bf16x8*)(lds + PG8_SB(b, h) + boff + n * 2048 + k * 1024); } while (0)
; #define PG8_WAIT_V(n) asm volatile("s_waitcnt vmcnt(" #n ")" ::: "memory")
; #define PG8_WAIT_L(n) asm volatile("s_waitcnt lgkmcnt(" #n ")" ::: "memory")
; #define PG8_BAR __builtin_amdgcn_s_barrier()
; #define PG8_SCHED __builtin_amdgcn_sched_barrier(0)
; template <class Epi, class Sched, bool ALIGN_EPI = false, bool SP2 = false, bool I8 = false>
; __device__ __forceinline__ void gemm_phase(PG8_LAS unsigned char* lds, const Gemm g, const Sched& S, const Epi& E) {
;     ...
;             PG8_LDB(B0, 1, 0); PG8_LDB(B1, 1, 1); PG8_SCHED; PG8_LDA(At, 1, 0); PG8_STAGE(PG8_SA(0, 1), a2 + hstep, voffA);
;             PG8_WAIT_V(8); PG8_WAIT_L(0); PG8_BAR; PG8_MMA(0, 0, At, B0); PG8_MMA(0, 1, At, B1); PG8_BAR; PG8_SCHED;
;             PG8_LDA(At, 1, 1); PG8_STAGE(PG8_SB(1, 0), b3, voffB); PG8_STAGE(PG8_SB(1, 1), b3 + hstep, voffB); PG8_STAGE(PG8_SA(1, 0), a3, voffA);
;             PG8_WAIT_V(8); PG8_WAIT_L(0); PG8_BAR; PG8_MMA(1, 0, At, B0); PG8_MMA(1, 1, At, B1); PG8_BAR; PG8_SCHED;
	s_add_i32 s73, 0, 0x18000
	s_add_i32 s76, 0, 0x1c000
	v_add_u32_e32 v158, s73, v143
	v_add_u32_e32 v174, s76, v143
	ds_read_b128 v[146:149], v158
	ds_read_b128 v[150:153], v158 offset:1024
	ds_read_b128 v[154:157], v158 offset:2048
	ds_read_b128 v[158:161], v158 offset:3072
	ds_read_b128 v[162:165], v174
	ds_read_b128 v[166:169], v174 offset:1024
	ds_read_b128 v[170:173], v174 offset:2048
	ds_read_b128 v[174:177], v174 offset:3072
	s_add_u32 s48, s48, s18
	s_addc_u32 s49, s49, s19
	s_mov_b32 m0, s51
	v_lshl_add_u64 v[244:245], s[48:49], 0, v[132:133]
	ds_read_b128 v[178:181], v145 offset:32768
	ds_read_b128 v[182:185], v145 offset:33792
	ds_read_b128 v[186:189], v145 offset:34816
	ds_read_b128 v[204:207], v145 offset:35840
	ds_read_b128 v[208:211], v145 offset:36864
	ds_read_b128 v[212:215], v145 offset:37888
	ds_read_b128 v[216:219], v145 offset:38912
	ds_read_b128 v[220:223], v145 offset:39936
	global_load_lds_dwordx4 v[244:245], off
	v_lshl_add_u64 v[244:245], s[48:49], 0, v[134:135]
	s_mov_b32 m0, s52
	s_nop 0
	global_load_lds_dwordx4 v[244:245], off
	s_waitcnt vmcnt(8)
	s_waitcnt lgkmcnt(0)
	s_barrier
	s_setprio 1
	s_waitcnt lgkmcnt(0)
	v_mfma_f32_16x16x32_bf16 v[124:127], v[146:149], v[178:181], v[124:127]
	v_mfma_f32_16x16x32_bf16 v[124:127], v[150:153], v[182:185], v[124:127]
	v_mfma_f32_16x16x32_bf16 v[128:131], v[154:157], v[178:181], v[128:131]
	v_mfma_f32_16x16x32_bf16 v[128:131], v[158:161], v[182:185], v[128:131]
	v_mfma_f32_16x16x32_bf16 v[112:115], v[146:149], v[186:189], v[112:115]
	v_mfma_f32_16x16x32_bf16 v[112:115], v[150:153], v[204:207], v[112:115]
	v_mfma_f32_16x16x32_bf16 v[108:111], v[154:157], v[186:189], v[108:111]
	v_mfma_f32_16x16x32_bf16 v[108:111], v[158:161], v[204:207], v[108:111]
	v_mfma_f32_16x16x32_bf16 v[96:99], v[146:149], v[208:211], v[96:99]
	v_mfma_f32_16x16x32_bf16 v[96:99], v[150:153], v[212:215], v[96:99]
	v_mfma_f32_16x16x32_bf16 v[92:95], v[154:157], v[208:211], v[92:95]
	v_mfma_f32_16x16x32_bf16 v[92:95], v[158:161], v[212:215], v[92:95]
	v_mfma_f32_16x16x32_bf16 v[80:83], v[146:149], v[216:219], v[80:83]
	v_mfma_f32_16x16x32_bf16 v[80:83], v[150:153], v[220:223], v[80:83]
	v_mfma_f32_16x16x32_bf16 v[76:79], v[154:157], v[216:219], v[76:79]
	v_mfma_f32_16x16x32_bf16 v[76:79], v[158:161], v[220:223], v[76:79]
	s_setprio 0
	s_setprio 1
	v_mfma_f32_16x16x32_bf16 v[120:123], v[162:165], v[178:181], v[120:123]
	v_mfma_f32_16x16x32_bf16 v[120:123], v[166:169], v[182:185], v[120:123]
	v_mfma_f32_16x16x32_bf16 v[116:119], v[170:173], v[178:181], v[116:119]
	v_mfma_f32_16x16x32_bf16 v[116:119], v[174:177], v[182:185], v[116:119]
	v_mfma_f32_16x16x32_bf16 v[104:107], v[162:165], v[186:189], v[104:107]
	v_mfma_f32_16x16x32_bf16 v[104:107], v[166:169], v[204:207], v[104:107]
	v_mfma_f32_16x16x32_bf16 v[100:103], v[170:173], v[186:189], v[100:103]
	v_mfma_f32_16x16x32_bf16 v[100:103], v[174:177], v[204:207], v[100:103]
	v_mfma_f32_16x16x32_bf16 v[88:91], v[162:165], v[208:211], v[88:91]
	v_mfma_f32_16x16x32_bf16 v[88:91], v[166:169], v[212:215], v[88:91]
	v_mfma_f32_16x16x32_bf16 v[84:87], v[170:173], v[208:211], v[84:87]
	v_mfma_f32_16x16x32_bf16 v[84:87], v[174:177], v[212:215], v[84:87]
	v_mfma_f32_16x16x32_bf16 v[72:75], v[162:165], v[216:219], v[72:75]
	v_mfma_f32_16x16x32_bf16 v[72:75], v[166:169], v[220:223], v[72:75]
	v_mfma_f32_16x16x32_bf16 v[68:71], v[170:173], v[216:219], v[68:71]
	v_mfma_f32_16x16x32_bf16 v[68:71], v[174:177], v[220:223], v[68:71]
	s_setprio 0
	s_barrier
	s_add_i32 s48, s73, s28
	v_lshl_add_u64 v[190:191], v[190:191], 0, s[84:85]
	s_mov_b32 m0, s48
	ds_read_b128 v[178:181], v145 offset:49152
	ds_read_b128 v[182:185], v145 offset:50176
	ds_read_b128 v[186:189], v145 offset:51200
	ds_read_b128 v[204:207], v145 offset:52224
	ds_read_b128 v[208:211], v145 offset:53248
	ds_read_b128 v[212:215], v145 offset:54272
	ds_read_b128 v[216:219], v145 offset:55296
	ds_read_b128 v[220:223], v145 offset:56320
	global_load_lds_dwordx4 v[190:191], off
	v_lshl_add_u64 v[190:191], v[224:225], 0, s[84:85]
	s_add_i32 m0, s48, 0x2000
	s_add_i32 s48, s76, s28
	global_load_lds_dwordx4 v[190:191], off
	v_lshl_add_u64 v[190:191], v[226:227], 0, s[84:85]
	s_mov_b32 m0, s48
	s_nop 0
	global_load_lds_dwordx4 v[190:191], off
	v_lshl_add_u64 v[190:191], v[228:229], 0, s[84:85]
	s_add_i32 m0, s48, 0x2000
	s_nop 0
	global_load_lds_dwordx4 v[190:191], off
	v_lshl_add_u64 v[190:191], v[240:241], 0, s[84:85]
	s_mov_b32 m0, s55
	s_nop 0
	global_load_lds_dwordx4 v[190:191], off
	v_lshl_add_u64 v[190:191], v[242:243], 0, s[84:85]
	s_mov_b32 m0, s56
	s_nop 0
	global_load_lds_dwordx4 v[190:191], off
	s_waitcnt vmcnt(8)
	s_waitcnt lgkmcnt(0)
	s_barrier
; #define PG8_STAGE(bufoff, gbase, voff) do { _Pragma("unroll") for (int _i = 0; _i < 2; ++_i) \
;         __builtin_amdgcn_global_load_lds((const unsigned*)((const char*)(gbase) + (voff)[_i]), (PG8_LAS unsigned*)(lds + (bufoff) + ldsw + _i * 8192), 16, 0, 0); } while (0)
; #define PG8_LDA(dst, b, h) do { _Pragma("unroll") for (int m = 0; m < 4; ++m) _Pragma("unroll") for (int k = 0; k < 2; ++k) dst[m][k] = *(const PG8_LAS bf16x8*)(lds + PG8_SA(b, h) + aoff + m * 2048 + k * 1024); } while (0)
; #define PG8_WAIT_V(n) asm volatile("s_waitcnt vmcnt(" #n ")" ::: "memory")
; #define PG8_WAIT_L(n) asm volatile("s_waitcnt lgkmcnt(" #n ")" ::: "memory")
; #define PG8_BAR __builtin_amdgcn_s_barrier()
; template <class Epi, class Sched, bool ALIGN_EPI = false, bool SP2 = false, bool I8 = false>
; __device__ __forceinline__ void gemm_phase(PG8_LAS unsigned char* lds, const Gemm g, const Sched& S, const Epi& E) {
;     ...
;         for (int t = 0; t < nt; t += 2) {
;             const bool last = (t == nt - 2);
;             const char* a1 = cA + (size_t)(t + 1) * kstep;
;             const char* a2 = last ? nA : cA + (size_t)(t + 2) * kstep; const char* b2 = last ? nB : cB + (size_t)(t + 2) * kstep;
;             const char* a3 = a2 + kstep; const char* b3 = b2 + kstep;
;             if (last && has_next) S.a_ready(nxt);
;             if constexpr (SP2) {
;             PG8_LDB(B0, 0, 0); PG8_LDB(B1, 0, 1); PG8_SCHED; PG8_LDA(At, 0, 0); PG8_STAGE(PG8_SA(1, 1), a1 + hstep, voffA);
;             PG8_WAIT_V(8); PG8_WAIT_L(0); PG8_BAR; PG8_MMA(0, 0, At, B0); PG8_MMA(0, 1, At, B1); PG8_BAR; PG8_SCHED;
;             PG8_LDA(At, 0, 1); PG8_STAGE(PG8_SB(0, 0), b2, voffB); PG8_STAGE(PG8_SB(0, 1), b2 + hstep, voffB); PG8_STAGE(PG8_SA(0, 0), a2, voffA);
;             PG8_WAIT_V(8); PG8_WAIT_L(0); PG8_BAR; PG8_MMA(1, 0, At, B0); PG8_MMA(1, 1, At, B1); PG8_BAR; PG8_SCHED;
;             PG8_LDB(B0, 1, 0); PG8_LDB(B1, 1, 1); PG8_SCHED; PG8_LDA(At, 1, 0); PG8_STAGE(PG8_SA(0, 1), a2 + hstep, voffA);
;             PG8_WAIT_V(8); PG8_WAIT_L(0); PG8_BAR; PG8_MMA(0, 0, At, B0); PG8_MMA(0, 1, At, B1); PG8_BAR; PG8_SCHED;
;             PG8_LDA(At, 1, 1); PG8_STAGE(PG8_SB(1, 0), b3, voffB); PG8_STAGE(PG8_SB(1, 1), b3 + hstep, voffB); PG8_STAGE(PG8_SA(1, 0), a3, voffA);
;             PG8_WAIT_V(8); PG8_WAIT_L(0); PG8_BAR; PG8_MMA(1, 0, At, B0); PG8_MMA(1, 1, At, B1); PG8_BAR; PG8_SCHED;
	s_setprio 1
	s_waitcnt lgkmcnt(0)
	v_mfma_f32_16x16x32_bf16 v[64:67], v[146:149], v[178:181], v[64:67]
	v_mfma_f32_16x16x32_bf16 v[64:67], v[150:153], v[182:185], v[64:67]
	v_mfma_f32_16x16x32_bf16 v[60:63], v[154:157], v[178:181], v[60:63]
	v_mfma_f32_16x16x32_bf16 v[60:63], v[158:161], v[182:185], v[60:63]
	v_mfma_f32_16x16x32_bf16 v[48:51], v[146:149], v[186:189], v[48:51]
	v_mfma_f32_16x16x32_bf16 v[48:51], v[150:153], v[204:207], v[48:51]
	v_mfma_f32_16x16x32_bf16 v[44:47], v[154:157], v[186:189], v[44:47]
	v_mfma_f32_16x16x32_bf16 v[44:47], v[158:161], v[204:207], v[44:47]
	v_mfma_f32_16x16x32_bf16 v[32:35], v[146:149], v[208:211], v[32:35]
	v_mfma_f32_16x16x32_bf16 v[32:35], v[150:153], v[212:215], v[32:35]
	v_mfma_f32_16x16x32_bf16 v[28:31], v[154:157], v[208:211], v[28:31]
	v_mfma_f32_16x16x32_bf16 v[28:31], v[158:161], v[212:215], v[28:31]
	v_mfma_f32_16x16x32_bf16 v[16:19], v[146:149], v[216:219], v[16:19]
	v_mfma_f32_16x16x32_bf16 v[16:19], v[150:153], v[220:223], v[16:19]
	v_mfma_f32_16x16x32_bf16 v[12:15], v[154:157], v[216:219], v[12:15]
	v_mfma_f32_16x16x32_bf16 v[12:15], v[158:161], v[220:223], v[12:15]
	s_setprio 0
	s_setprio 1
	v_mfma_f32_16x16x32_bf16 v[56:59], v[162:165], v[178:181], v[56:59]
	v_mfma_f32_16x16x32_bf16 v[56:59], v[166:169], v[182:185], v[56:59]
	v_mfma_f32_16x16x32_bf16 v[52:55], v[170:173], v[178:181], v[52:55]
	v_mfma_f32_16x16x32_bf16 v[52:55], v[174:177], v[182:185], v[52:55]
	v_mfma_f32_16x16x32_bf16 v[40:43], v[162:165], v[186:189], v[40:43]
	v_mfma_f32_16x16x32_bf16 v[40:43], v[166:169], v[204:207], v[40:43]
	v_mfma_f32_16x16x32_bf16 v[36:39], v[170:173], v[186:189], v[36:39]
	v_mfma_f32_16x16x32_bf16 v[36:39], v[174:177], v[204:207], v[36:39]
	v_mfma_f32_16x16x32_bf16 v[24:27], v[162:165], v[208:211], v[24:27]
	v_mfma_f32_16x16x32_bf16 v[24:27], v[166:169], v[212:215], v[24:27]
	v_mfma_f32_16x16x32_bf16 v[20:23], v[170:173], v[208:211], v[20:23]
	v_mfma_f32_16x16x32_bf16 v[20:23], v[174:177], v[212:215], v[20:23]
	v_mfma_f32_16x16x32_bf16 v[8:11], v[162:165], v[216:219], v[8:11]
	v_mfma_f32_16x16x32_bf16 v[8:11], v[166:169], v[220:223], v[8:11]
	v_mfma_f32_16x16x32_bf16 v[4:7], v[170:173], v[216:219], v[4:7]
	v_mfma_f32_16x16x32_bf16 v[4:7], v[174:177], v[220:223], v[4:7]
	s_setprio 0
	s_barrier
	s_add_u32 s44, s44, 0x100
	s_addc_u32 s45, s45, 0
	s_add_u32 s65, s65, 0x100
	s_addc_u32 s67, s67, 0
	s_cmp_ge_i32 s72, s53
	s_mov_b32 s48, s72
	s_cbranch_scc1 .Lkloop_exit_4
.LBB0_1623:
	s_add_i32 s72, s48, 2
	s_add_u32 s73, s44, 0x80
	s_addc_u32 s49, s45, 0
	s_add_i32 s86, 0, 0x10000
	s_cmp_eq_u32 s57, s48
	s_cselect_b32 s49, s13, s49
	s_cselect_b32 s48, s12, s73
	s_cselect_b32 s77, s41, s67
	s_cselect_b32 s76, s40, s65
	s_add_i32 s73, 0, 0x14000
	v_add_u32_e32 v158, s86, v143
	v_add_u32_e32 v174, s73, v143
	ds_read_b128 v[146:149], v158
	ds_read_b128 v[150:153], v158 offset:1024
	ds_read_b128 v[154:157], v158 offset:2048
	ds_read_b128 v[158:161], v158 offset:3072
	ds_read_b128 v[162:165], v174
	ds_read_b128 v[166:169], v174 offset:1024
	ds_read_b128 v[170:173], v174 offset:2048
	ds_read_b128 v[174:177], v174 offset:3072
	v_lshl_add_u64 v[190:191], s[44:45], 0, v[138:139]
	s_add_i32 m0, s47, 0xc000
	ds_read_b128 v[178:181], v145
	ds_read_b128 v[182:185], v145 offset:1024
	ds_read_b128 v[186:189], v145 offset:2048
	ds_read_b128 v[204:207], v145 offset:3072
	ds_read_b128 v[208:211], v145 offset:4096
	ds_read_b128 v[212:215], v145 offset:5120
	ds_read_b128 v[216:219], v145 offset:6144
	ds_read_b128 v[220:223], v145 offset:7168
	global_load_lds_dwordx4 v[190:191], off
	v_lshl_add_u64 v[190:191], s[44:45], 0, v[140:141]
	s_add_i32 m0, s47, 0xe000
	s_nop 0
	global_load_lds_dwordx4 v[190:191], off
	s_waitcnt vmcnt(8)
	s_waitcnt lgkmcnt(0)
	s_barrier
	s_setprio 1
	s_waitcnt lgkmcnt(0)
	v_mfma_f32_16x16x32_bf16 v[124:127], v[146:149], v[178:181], v[124:127]
	v_mfma_f32_16x16x32_bf16 v[124:127], v[150:153], v[182:185], v[124:127]
	v_mfma_f32_16x16x32_bf16 v[128:131], v[154:157], v[178:181], v[128:131]
	v_mfma_f32_16x16x32_bf16 v[128:131], v[158:161], v[182:185], v[128:131]
	v_mfma_f32_16x16x32_bf16 v[112:115], v[146:149], v[186:189], v[112:115]
	v_mfma_f32_16x16x32_bf16 v[112:115], v[150:153], v[204:207], v[112:115]
	v_mfma_f32_16x16x32_bf16 v[108:111], v[154:157], v[186:189], v[108:111]
	v_mfma_f32_16x16x32_bf16 v[108:111], v[158:161], v[204:207], v[108:111]
	v_mfma_f32_16x16x32_bf16 v[96:99], v[146:149], v[208:211], v[96:99]
	v_mfma_f32_16x16x32_bf16 v[96:99], v[150:153], v[212:215], v[96:99]
	v_mfma_f32_16x16x32_bf16 v[92:95], v[154:157], v[208:211], v[92:95]
	v_mfma_f32_16x16x32_bf16 v[92:95], v[158:161], v[212:215], v[92:95]
	v_mfma_f32_16x16x32_bf16 v[80:83], v[146:149], v[216:219], v[80:83]
	v_mfma_f32_16x16x32_bf16 v[80:83], v[150:153], v[220:223], v[80:83]
	v_mfma_f32_16x16x32_bf16 v[76:79], v[154:157], v[216:219], v[76:79]
	v_mfma_f32_16x16x32_bf16 v[76:79], v[158:161], v[220:223], v[76:79]
	s_setprio 0
	s_setprio 1
	v_mfma_f32_16x16x32_bf16 v[120:123], v[162:165], v[178:181], v[120:123]
	v_mfma_f32_16x16x32_bf16 v[120:123], v[166:169], v[182:185], v[120:123]
	v_mfma_f32_16x16x32_bf16 v[116:119], v[170:173], v[178:181], v[116:119]
	v_mfma_f32_16x16x32_bf16 v[116:119], v[174:177], v[182:185], v[116:119]
	v_mfma_f32_16x16x32_bf16 v[104:107], v[162:165], v[186:189], v[104:107]
	v_mfma_f32_16x16x32_bf16 v[104:107], v[166:169], v[204:207], v[104:107]
	v_mfma_f32_16x16x32_bf16 v[100:103], v[170:173], v[186:189], v[100:103]
	v_mfma_f32_16x16x32_bf16 v[100:103], v[174:177], v[204:207], v[100:103]
	v_mfma_f32_16x16x32_bf16 v[88:91], v[162:165], v[208:211], v[88:91]
	v_mfma_f32_16x16x32_bf16 v[88:91], v[166:169], v[212:215], v[88:91]
	v_mfma_f32_16x16x32_bf16 v[84:87], v[170:173], v[208:211], v[84:87]
	v_mfma_f32_16x16x32_bf16 v[84:87], v[174:177], v[212:215], v[84:87]
	v_mfma_f32_16x16x32_bf16 v[72:75], v[162:165], v[216:219], v[72:75]
	v_mfma_f32_16x16x32_bf16 v[72:75], v[166:169], v[220:223], v[72:75]
	v_mfma_f32_16x16x32_bf16 v[68:71], v[170:173], v[216:219], v[68:71]
	v_mfma_f32_16x16x32_bf16 v[68:71], v[174:177], v[220:223], v[68:71]
	s_setprio 0
	s_barrier
; #define PG8_STAGE(bufoff, gbase, voff) do { _Pragma("unroll") for (int _i = 0; _i < 2; ++_i) \
;         __builtin_amdgcn_global_load_lds((const unsigned*)((const char*)(gbase) + (voff)[_i]), (PG8_LAS unsigned*)(lds + (bufoff) + ldsw + _i * 8192), 16, 0, 0); } while (0)
; #define PG8_LDA(dst, b, h) do { _Pragma("unroll") for (int m = 0; m < 4; ++m) _Pragma("unroll") for (int k = 0; k < 2; ++k) dst[m][k] = *(const PG8_LAS bf16x8*)(lds + PG8_SA(b, h) + aoff + m * 2048 + k * 1024); } while (0)
; #define PG8_LDB(dst, b, h) do { _Pragma("unroll") for (int n = 0; n < 2; ++n) _Pragma("unroll") for (int k = 0; k < 2; ++k) dst[n][k] = *(const PG8_LAS bf16x8*)(lds + PG8_SB(b, h) + boff + n * 2048 + k * 1024); } while (0)
; #define PG8_WAIT_V(n) asm volatile("s_waitcnt vmcnt(" #n ")" ::: "memory")
; #define PG8_WAIT_L(n) asm volatile("s_waitcnt lgkmcnt(" #n ")" ::: "memory")
; #define PG8_BAR __builtin_amdgcn_s_barrier()
; #define PG8_SCHED __builtin_amdgcn_sched_barrier(0)
; template <class Epi, class Sched, bool ALIGN_EPI = false, bool SP2 = false, bool I8 = false>
; __device__ __forceinline__ void gemm_phase(PG8_LAS unsigned char* lds, const Gemm g, const Sched& S, const Epi& E) {
;     ...
;             PG8_WAIT_V(8); PG8_WAIT_L(0); PG8_BAR; PG8_MMA(0, 0, At, B0); PG8_MMA(0, 1, At, B1); PG8_BAR; PG8_SCHED;
;             PG8_LDA(At, 0, 1); PG8_STAGE(PG8_SB(0, 0), b2, voffB); PG8_STAGE(PG8_SB(0, 1), b2 + hstep, voffB); PG8_STAGE(PG8_SA(0, 0), a2, voffA);
;             PG8_WAIT_V(8); PG8_WAIT_L(0); PG8_BAR; PG8_MMA(1, 0, At, B0); PG8_MMA(1, 1, At, B1); PG8_BAR; PG8_SCHED;
;             PG8_LDB(B0, 1, 0); PG8_LDB(B1, 1, 1); PG8_SCHED; PG8_LDA(At, 1, 0); PG8_STAGE(PG8_SA(0, 1), a2 + hstep, voffA);
;             PG8_WAIT_V(8); PG8_WAIT_L(0); PG8_BAR; PG8_MMA(0, 0, At, B0); PG8_MMA(0, 1, At, B1); PG8_BAR; PG8_SCHED;
	s_add_i32 s86, s86, s28
	v_lshl_add_u64 v[190:191], s[76:77], 0, v[2:3]
	s_mov_b32 m0, s86
	ds_read_b128 v[178:181], v145 offset:16384
	ds_read_b128 v[182:185], v145 offset:17408
	ds_read_b128 v[186:189], v145 offset:18432
	ds_read_b128 v[204:207], v145 offset:19456
	ds_read_b128 v[208:211], v145 offset:20480
	ds_read_b128 v[212:215], v145 offset:21504
	ds_read_b128 v[216:219], v145 offset:22528
	ds_read_b128 v[220:223], v145 offset:23552
	global_load_lds_dwordx4 v[190:191], off
	s_add_i32 m0, s86, 0x2000
	v_lshl_add_u64 v[224:225], s[76:77], 0, v[136:137]
	s_add_u32 s76, s76, s18
	s_addc_u32 s77, s77, s19
	s_add_i32 s73, s73, s28
	global_load_lds_dwordx4 v[224:225], off
	v_lshl_add_u64 v[226:227], s[76:77], 0, v[2:3]
	s_mov_b32 m0, s73
	v_lshl_add_u64 v[228:229], s[76:77], 0, v[136:137]
	global_load_lds_dwordx4 v[226:227], off
	s_add_i32 m0, s73, 0x2000
	v_lshl_add_u64 v[240:241], s[48:49], 0, v[132:133]
	global_load_lds_dwordx4 v[228:229], off
	s_mov_b32 m0, s47
	v_lshl_add_u64 v[242:243], s[48:49], 0, v[134:135]
	global_load_lds_dwordx4 v[240:241], off
	s_mov_b32 m0, s50
	s_nop 0
	global_load_lds_dwordx4 v[242:243], off
	s_waitcnt vmcnt(8)
	s_waitcnt lgkmcnt(0)
	s_barrier
	s_setprio 1
	s_waitcnt lgkmcnt(0)
	v_mfma_f32_16x16x32_bf16 v[64:67], v[146:149], v[178:181], v[64:67]
	v_mfma_f32_16x16x32_bf16 v[64:67], v[150:153], v[182:185], v[64:67]
	v_mfma_f32_16x16x32_bf16 v[60:63], v[154:157], v[178:181], v[60:63]
	v_mfma_f32_16x16x32_bf16 v[60:63], v[158:161], v[182:185], v[60:63]
	v_mfma_f32_16x16x32_bf16 v[48:51], v[146:149], v[186:189], v[48:51]
	v_mfma_f32_16x16x32_bf16 v[48:51], v[150:153], v[204:207], v[48:51]
	v_mfma_f32_16x16x32_bf16 v[44:47], v[154:157], v[186:189], v[44:47]
	v_mfma_f32_16x16x32_bf16 v[44:47], v[158:161], v[204:207], v[44:47]
	v_mfma_f32_16x16x32_bf16 v[32:35], v[146:149], v[208:211], v[32:35]
	v_mfma_f32_16x16x32_bf16 v[32:35], v[150:153], v[212:215], v[32:35]
	v_mfma_f32_16x16x32_bf16 v[28:31], v[154:157], v[208:211], v[28:31]
	v_mfma_f32_16x16x32_bf16 v[28:31], v[158:161], v[212:215], v[28:31]
	v_mfma_f32_16x16x32_bf16 v[16:19], v[146:149], v[216:219], v[16:19]
	v_mfma_f32_16x16x32_bf16 v[16:19], v[150:153], v[220:223], v[16:19]
	v_mfma_f32_16x16x32_bf16 v[12:15], v[154:157], v[216:219], v[12:15]
	v_mfma_f32_16x16x32_bf16 v[12:15], v[158:161], v[220:223], v[12:15]
	s_setprio 0
	s_setprio 1
	v_mfma_f32_16x16x32_bf16 v[56:59], v[162:165], v[178:181], v[56:59]
	v_mfma_f32_16x16x32_bf16 v[56:59], v[166:169], v[182:185], v[56:59]
	v_mfma_f32_16x16x32_bf16 v[52:55], v[170:173], v[178:181], v[52:55]
	v_mfma_f32_16x16x32_bf16 v[52:55], v[174:177], v[182:185], v[52:55]
	v_mfma_f32_16x16x32_bf16 v[40:43], v[162:165], v[186:189], v[40:43]
	v_mfma_f32_16x16x32_bf16 v[40:43], v[166:169], v[204:207], v[40:43]
	v_mfma_f32_16x16x32_bf16 v[36:39], v[170:173], v[186:189], v[36:39]
	v_mfma_f32_16x16x32_bf16 v[36:39], v[174:177], v[204:207], v[36:39]
	v_mfma_f32_16x16x32_bf16 v[24:27], v[162:165], v[208:211], v[24:27]
	v_mfma_f32_16x16x32_bf16 v[24:27], v[166:169], v[212:215], v[24:27]
	v_mfma_f32_16x16x32_bf16 v[20:23], v[170:173], v[208:211], v[20:23]
	v_mfma_f32_16x16x32_bf16 v[20:23], v[174:177], v[212:215], v[20:23]
	v_mfma_f32_16x16x32_bf16 v[8:11], v[162:165], v[216:219], v[8:11]
	v_mfma_f32_16x16x32_bf16 v[8:11], v[166:169], v[220:223], v[8:11]
	v_mfma_f32_16x16x32_bf16 v[4:7], v[170:173], v[216:219], v[4:7]
	v_mfma_f32_16x16x32_bf16 v[4:7], v[174:177], v[220:223], v[4:7]
	s_setprio 0
	s_barrier
	s_add_i32 s73, 0, 0x18000
	s_add_i32 s76, 0, 0x1c000
	v_add_u32_e32 v158, s73, v143
	v_add_u32_e32 v174, s76, v143
	ds_read_b128 v[146:149], v158
	ds_read_b128 v[150:153], v158 offset:1024
	ds_read_b128 v[154:157], v158 offset:2048
	ds_read_b128 v[158:161], v158 offset:3072
	ds_read_b128 v[162:165], v174
	ds_read_b128 v[166:169], v174 offset:1024
	ds_read_b128 v[170:173], v174 offset:2048
	ds_read_b128 v[174:177], v174 offset:3072
	s_add_u32 s48, s48, s18
	s_addc_u32 s49, s49, s19
	s_mov_b32 m0, s51
	v_lshl_add_u64 v[244:245], s[48:49], 0, v[132:133]
	ds_read_b128 v[178:181], v145 offset:32768
	ds_read_b128 v[182:185], v145 offset:33792
	ds_read_b128 v[186:189], v145 offset:34816
	ds_read_b128 v[204:207], v145 offset:35840
	ds_read_b128 v[208:211], v145 offset:36864
	ds_read_b128 v[212:215], v145 offset:37888
	ds_read_b128 v[216:219], v145 offset:38912
	ds_read_b128 v[220:223], v145 offset:39936
	global_load_lds_dwordx4 v[244:245], off
	v_lshl_add_u64 v[244:245], s[48:49], 0, v[134:135]
	s_mov_b32 m0, s52
	s_nop 0
	global_load_lds_dwordx4 v[244:245], off
	s_waitcnt vmcnt(8)
	s_waitcnt lgkmcnt(0)
	s_barrier
; #define PG8_STAGE(bufoff, gbase, voff) do { _Pragma("unroll") for (int _i = 0; _i < 2; ++_i) \
;         __builtin_amdgcn_global_load_lds((const unsigned*)((const char*)(gbase) + (voff)[_i]), (PG8_LAS unsigned*)(lds + (bufoff) + ldsw + _i * 8192), 16, 0, 0); } while (0)
; #define PG8_LDA(dst, b, h) do { _Pragma("unroll") for (int m = 0; m < 4; ++m) _Pragma("unroll") for (int k = 0; k < 2; ++k) dst[m][k] = *(const PG8_LAS bf16x8*)(lds + PG8_SA(b, h) + aoff + m * 2048 + k * 1024); } while (0)
; #define PG8_WAIT_V(n) asm volatile("s_waitcnt vmcnt(" #n ")" ::: "memory")
; #define PG8_WAIT_L(n) asm volatile("s_waitcnt lgkmcnt(" #n ")" ::: "memory")
; #define PG8_BAR __builtin_amdgcn_s_barrier()
; #define PG8_SCHED __builtin_amdgcn_sched_barrier(0)
; template <class Epi, class Sched, bool ALIGN_EPI = false, bool SP2 = false, bool I8 = false>
; __device__ __forceinline__ void gemm_phase(PG8_LAS unsigned char* lds, const Gemm g, const Sched& S, const Epi& E) {
;     ...
;             PG8_WAIT_V(8); PG8_WAIT_L(0); PG8_BAR; PG8_MMA(0, 0, At, B0); PG8_MMA(0, 1, At, B1); PG8_BAR; PG8_SCHED;
;             PG8_LDA(At, 1, 1); PG8_STAGE(PG8_SB(1, 0), b3, voffB); PG8_STAGE(PG8_SB(1, 1), b3 + hstep, voffB); PG8_STAGE(PG8_SA(1, 0), a3, voffA);
;             PG8_WAIT_V(8); PG8_WAIT_L(0); PG8_BAR; PG8_MMA(1, 0, At, B0); PG8_MMA(1, 1, At, B1); PG8_BAR; PG8_SCHED;
	s_setprio 1
	s_waitcnt lgkmcnt(0)
	v_mfma_f32_16x16x32_bf16 v[124:127], v[146:149], v[178:181], v[124:127]
	v_mfma_f32_16x16x32_bf16 v[124:127], v[150:153], v[182:185], v[124:127]
	v_mfma_f32_16x16x32_bf16 v[128:131], v[154:157], v[178:181], v[128:131]
	v_mfma_f32_16x16x32_bf16 v[128:131], v[158:161], v[182:185], v[128:131]
	v_mfma_f32_16x16x32_bf16 v[112:115], v[146:149], v[186:189], v[112:115]
	v_mfma_f32_16x16x32_bf16 v[112:115], v[150:153], v[204:207], v[112:115]
	v_mfma_f32_16x16x32_bf16 v[108:111], v[154:157], v[186:189], v[108:111]
	v_mfma_f32_16x16x32_bf16 v[108:111], v[158:161], v[204:207], v[108:111]
	v_mfma_f32_16x16x32_bf16 v[96:99], v[146:149], v[208:211], v[96:99]
	v_mfma_f32_16x16x32_bf16 v[96:99], v[150:153], v[212:215], v[96:99]
	v_mfma_f32_16x16x32_bf16 v[92:95], v[154:157], v[208:211], v[92:95]
	v_mfma_f32_16x16x32_bf16 v[92:95], v[158:161], v[212:215], v[92:95]
	v_mfma_f32_16x16x32_bf16 v[80:83], v[146:149], v[216:219], v[80:83]
	v_mfma_f32_16x16x32_bf16 v[80:83], v[150:153], v[220:223], v[80:83]
	v_mfma_f32_16x16x32_bf16 v[76:79], v[154:157], v[216:219], v[76:79]
	v_mfma_f32_16x16x32_bf16 v[76:79], v[158:161], v[220:223], v[76:79]
	s_setprio 0
	s_setprio 1
	v_mfma_f32_16x16x32_bf16 v[120:123], v[162:165], v[178:181], v[120:123]
	v_mfma_f32_16x16x32_bf16 v[120:123], v[166:169], v[182:185], v[120:123]
	v_mfma_f32_16x16x32_bf16 v[116:119], v[170:173], v[178:181], v[116:119]
	v_mfma_f32_16x16x32_bf16 v[116:119], v[174:177], v[182:185], v[116:119]
	v_mfma_f32_16x16x32_bf16 v[104:107], v[162:165], v[186:189], v[104:107]
	v_mfma_f32_16x16x32_bf16 v[104:107], v[166:169], v[204:207], v[104:107]
	v_mfma_f32_16x16x32_bf16 v[100:103], v[170:173], v[186:189], v[100:103]
	v_mfma_f32_16x16x32_bf16 v[100:103], v[174:177], v[204:207], v[100:103]
	v_mfma_f32_16x16x32_bf16 v[88:91], v[162:165], v[208:211], v[88:91]
	v_mfma_f32_16x16x32_bf16 v[88:91], v[166:169], v[212:215], v[88:91]
	v_mfma_f32_16x16x32_bf16 v[84:87], v[170:173], v[208:211], v[84:87]
	v_mfma_f32_16x16x32_bf16 v[84:87], v[174:177], v[212:215], v[84:87]
	v_mfma_f32_16x16x32_bf16 v[72:75], v[162:165], v[216:219], v[72:75]
	v_mfma_f32_16x16x32_bf16 v[72:75], v[166:169], v[220:223], v[72:75]
	v_mfma_f32_16x16x32_bf16 v[68:71], v[170:173], v[216:219], v[68:71]
	v_mfma_f32_16x16x32_bf16 v[68:71], v[174:177], v[220:223], v[68:71]
	s_setprio 0
	s_barrier
	s_add_i32 s48, s73, s28
	v_lshl_add_u64 v[190:191], v[190:191], 0, s[84:85]
	s_mov_b32 m0, s48
	ds_read_b128 v[178:181], v145 offset:49152
	ds_read_b128 v[182:185], v145 offset:50176
	ds_read_b128 v[186:189], v145 offset:51200
	ds_read_b128 v[204:207], v145 offset:52224
	ds_read_b128 v[208:211], v145 offset:53248
	ds_read_b128 v[212:215], v145 offset:54272
	ds_read_b128 v[216:219], v145 offset:55296
	ds_read_b128 v[220:223], v145 offset:56320
	global_load_lds_dwordx4 v[190:191], off
	v_lshl_add_u64 v[190:191], v[224:225], 0, s[84:85]
	s_add_i32 m0, s48, 0x2000
	s_add_i32 s48, s76, s28
	global_load_lds_dwordx4 v[190:191], off
	v_lshl_add_u64 v[190:191], v[226:227], 0, s[84:85]
	s_mov_b32 m0, s48
	s_nop 0
	global_load_lds_dwordx4 v[190:191], off
	v_lshl_add_u64 v[190:191], v[228:229], 0, s[84:85]
	s_add_i32 m0, s48, 0x2000
	s_nop 0
	global_load_lds_dwordx4 v[190:191], off
	v_lshl_add_u64 v[190:191], v[240:241], 0, s[84:85]
	s_mov_b32 m0, s55
	s_nop 0
	global_load_lds_dwordx4 v[190:191], off
	v_lshl_add_u64 v[190:191], v[242:243], 0, s[84:85]
	s_mov_b32 m0, s56
	s_nop 0
	global_load_lds_dwordx4 v[190:191], off
	s_waitcnt vmcnt(8)
	s_waitcnt lgkmcnt(0)
	s_barrier
	s_setprio 1
	s_waitcnt lgkmcnt(0)
	v_mfma_f32_16x16x32_bf16 v[64:67], v[146:149], v[178:181], v[64:67]
	v_mfma_f32_16x16x32_bf16 v[64:67], v[150:153], v[182:185], v[64:67]
	v_mfma_f32_16x16x32_bf16 v[60:63], v[154:157], v[178:181], v[60:63]
	v_mfma_f32_16x16x32_bf16 v[60:63], v[158:161], v[182:185], v[60:63]
	v_mfma_f32_16x16x32_bf16 v[48:51], v[146:149], v[186:189], v[48:51]
	v_mfma_f32_16x16x32_bf16 v[48:51], v[150:153], v[204:207], v[48:51]
	v_mfma_f32_16x16x32_bf16 v[44:47], v[154:157], v[186:189], v[44:47]
	v_mfma_f32_16x16x32_bf16 v[44:47], v[158:161], v[204:207], v[44:47]
	v_mfma_f32_16x16x32_bf16 v[32:35], v[146:149], v[208:211], v[32:35]
	v_mfma_f32_16x16x32_bf16 v[32:35], v[150:153], v[212:215], v[32:35]
	v_mfma_f32_16x16x32_bf16 v[28:31], v[154:157], v[208:211], v[28:31]
	v_mfma_f32_16x16x32_bf16 v[28:31], v[158:161], v[212:215], v[28:31]
	v_mfma_f32_16x16x32_bf16 v[16:19], v[146:149], v[216:219], v[16:19]
	v_mfma_f32_16x16x32_bf16 v[16:19], v[150:153], v[220:223], v[16:19]
	v_mfma_f32_16x16x32_bf16 v[12:15], v[154:157], v[216:219], v[12:15]
	v_mfma_f32_16x16x32_bf16 v[12:15], v[158:161], v[220:223], v[12:15]
	s_setprio 0
	s_setprio 1
	v_mfma_f32_16x16x32_bf16 v[56:59], v[162:165], v[178:181], v[56:59]
	v_mfma_f32_16x16x32_bf16 v[56:59], v[166:169], v[182:185], v[56:59]
	v_mfma_f32_16x16x32_bf16 v[52:55], v[170:173], v[178:181], v[52:55]
	v_mfma_f32_16x16x32_bf16 v[52:55], v[174:177], v[182:185], v[52:55]
	v_mfma_f32_16x16x32_bf16 v[40:43], v[162:165], v[186:189], v[40:43]
	v_mfma_f32_16x16x32_bf16 v[40:43], v[166:169], v[204:207], v[40:43]
	v_mfma_f32_16x16x32_bf16 v[36:39], v[170:173], v[186:189], v[36:39]
	v_mfma_f32_16x16x32_bf16 v[36:39], v[174:177], v[204:207], v[36:39]
	v_mfma_f32_16x16x32_bf16 v[24:27], v[162:165], v[208:211], v[24:27]
	v_mfma_f32_16x16x32_bf16 v[24:27], v[166:169], v[212:215], v[24:27]
	v_mfma_f32_16x16x32_bf16 v[20:23], v[170:173], v[208:211], v[20:23]
	v_mfma_f32_16x16x32_bf16 v[20:23], v[174:177], v[212:215], v[20:23]
	v_mfma_f32_16x16x32_bf16 v[8:11], v[162:165], v[216:219], v[8:11]
	v_mfma_f32_16x16x32_bf16 v[8:11], v[166:169], v[220:223], v[8:11]
	v_mfma_f32_16x16x32_bf16 v[4:7], v[170:173], v[216:219], v[4:7]
	v_mfma_f32_16x16x32_bf16 v[4:7], v[174:177], v[220:223], v[4:7]
	s_setprio 0
	s_barrier
	s_add_u32 s44, s44, 0x100
	s_addc_u32 s45, s45, 0
	s_add_u32 s65, s65, 0x100
	s_addc_u32 s67, s67, 0
	s_cmp_ge_i32 s72, s53
	s_mov_b32 s48, s72
	s_cbranch_scc0 .LBB0_1623

; #define PG8_STAGE(bufoff, gbase, voff) do { _Pragma("unroll") for (int _i = 0; _i < 2; ++_i) \
;         __builtin_amdgcn_global_load_lds((const unsigned*)((const char*)(gbase) + (voff)[_i]), (PG8_LAS unsigned*)(lds + (bufoff) + ldsw + _i * 8192), 16, 0, 0); } while (0)
; #define PG8_LDA(dst, b, h) do { _Pragma("unroll") for (int m = 0; m < 4; ++m) _Pragma("unroll") for (int k = 0; k < 2; ++k) dst[m][k] = *(const PG8_LAS bf16x8*)(lds + PG8_SA(b, h) + aoff + m * 2048 + k * 1024); } while (0)
; #define PG8_LDB(dst, b, h) do { _Pragma("unroll") for (int n = 0; n < 2; ++n) _Pragma("unroll") for (int k = 0; k < 2; ++k) dst[n][k] = *(const PG8_LAS bf16x8*)(lds + PG8_SB(b, h) + boff + n * 2048 + k * 1024); } while (0)
; #define PG8_WAIT_V(n) asm volatile("s_waitcnt vmcnt(" #n ")" ::: "memory")
; #define PG8_WAIT_L(n) asm volatile("s_waitcnt lgkmcnt(" #n ")" ::: "memory")
; #define PG8_BAR __builtin_amdgcn_s_barrier()
; #define PG8_SCHED __builtin_amdgcn_sched_barrier(0)
; template <class Epi, class Sched, bool ALIGN_EPI = false, bool SP2 = false, bool I8 = false>
; __device__ __forceinline__ void gemm_phase(PG8_LAS unsigned char* lds, const Gemm g, const Sched& S, const Epi& E) {
;     ...
;         const bool has_next = S.next(ui + 1, nxt);
;         const char* nA = has_next ? (const char*)g.A + (size_t)nxt.pm * tstep : cA; const char* nB = has_next ? (const char*)g.Bt + (size_t)nxt.pn * tstep : cB;
;         for (int t = 0; t < nt; t += 2) {
;             const bool last = (t == nt - 2);
;             const char* a1 = cA + (size_t)(t + 1) * kstep;
;             const char* a2 = last ? nA : cA + (size_t)(t + 2) * kstep; const char* b2 = last ? nB : cB + (size_t)(t + 2) * kstep;
;             const char* a3 = a2 + kstep; const char* b3 = b2 + kstep;
;             if (last && has_next) S.a_ready(nxt);
;             if constexpr (SP2) {
;             PG8_LDB(B0, 0, 0); PG8_LDB(B1, 0, 1); PG8_SCHED; PG8_LDA(At, 0, 0); PG8_STAGE(PG8_SA(1, 1), a1 + hstep, voffA);
;             PG8_WAIT_V(8); PG8_WAIT_L(0); PG8_BAR; PG8_MMA(0, 0, At, B0); PG8_MMA(0, 1, At, B1); PG8_BAR; PG8_SCHED;
;             PG8_LDA(At, 0, 1); PG8_STAGE(PG8_SB(0, 0), b2, voffB); PG8_STAGE(PG8_SB(0, 1), b2 + hstep, voffB); PG8_STAGE(PG8_SA(0, 0), a2, voffA);
;             PG8_WAIT_V(8); PG8_WAIT_L(0); PG8_BAR; PG8_MMA(1, 0, At, B0); PG8_MMA(1, 1, At, B1); PG8_BAR; PG8_SCHED;
.LBB0_1699:
	s_add_u32 s53, s24, 0x100
	s_addc_u32 s54, s25, 0
	s_mov_b32 s55, -2
	s_add_u32 s24, s22, 0x100
	s_addc_u32 s25, s23, 0
	s_add_i32 s56, 0, 0x10000
	s_cmpk_eq_i32 s55, 0xa8
	s_cselect_b32 s37, s13, s25
	s_cselect_b32 s36, s12, s24
	s_cselect_b32 s27, s21, s54
	s_cselect_b32 s26, s20, s53
	s_add_i32 s57, 0, 0x14000
	v_add_u32_e32 v144, s56, v240
	v_add_u32_e32 v160, s57, v240
	ds_read_b128 v[124:127], v144
	ds_read_b128 v[128:131], v144 offset:1024
	ds_read_b128 v[132:135], v144 offset:2048
	ds_read_b128 v[144:147], v144 offset:3072
	ds_read_b128 v[148:151], v160
	ds_read_b128 v[152:155], v160 offset:1024
	ds_read_b128 v[156:159], v160 offset:2048
	ds_read_b128 v[160:163], v160 offset:3072
	v_lshl_add_u64 v[218:219], s[22:23], 0, v[210:211]
	s_add_i32 m0, s42, 0xc000
	ds_read_b128 v[164:167], v242
	ds_read_b128 v[168:171], v242 offset:1024
	ds_read_b128 v[172:175], v242 offset:2048
	ds_read_b128 v[176:179], v242 offset:3072
	ds_read_b128 v[180:183], v242 offset:4096
	ds_read_b128 v[184:187], v242 offset:5120
	ds_read_b128 v[188:191], v242 offset:6144
	ds_read_b128 v[214:217], v242 offset:7168
	global_load_lds_dwordx4 v[218:219], off
	v_lshl_add_u64 v[218:219], s[22:23], 0, v[212:213]
	s_add_i32 m0, s42, 0xe000
	s_nop 0
	global_load_lds_dwordx4 v[218:219], off
	s_waitcnt vmcnt(8)
	s_waitcnt lgkmcnt(0)
	s_barrier
	s_setprio 1
	s_waitcnt lgkmcnt(0)
	v_mfma_f32_16x16x32_bf16 v[140:143], v[124:127], v[164:167], 0
	v_mfma_f32_16x16x32_bf16 v[140:143], v[128:131], v[168:171], v[140:143]
	v_mfma_f32_16x16x32_bf16 v[136:139], v[132:135], v[164:167], 0
	v_mfma_f32_16x16x32_bf16 v[136:139], v[144:147], v[168:171], v[136:139]
	v_mfma_f32_16x16x32_bf16 v[112:115], v[124:127], v[172:175], 0
	v_mfma_f32_16x16x32_bf16 v[112:115], v[128:131], v[176:179], v[112:115]
	v_mfma_f32_16x16x32_bf16 v[108:111], v[132:135], v[172:175], 0
	v_mfma_f32_16x16x32_bf16 v[108:111], v[144:147], v[176:179], v[108:111]
	v_mfma_f32_16x16x32_bf16 v[96:99], v[124:127], v[180:183], 0
	v_mfma_f32_16x16x32_bf16 v[96:99], v[128:131], v[184:187], v[96:99]
	v_mfma_f32_16x16x32_bf16 v[92:95], v[132:135], v[180:183], 0
	v_mfma_f32_16x16x32_bf16 v[92:95], v[144:147], v[184:187], v[92:95]
	v_mfma_f32_16x16x32_bf16 v[80:83], v[124:127], v[188:191], 0
	v_mfma_f32_16x16x32_bf16 v[80:83], v[128:131], v[214:217], v[80:83]
	v_mfma_f32_16x16x32_bf16 v[76:79], v[132:135], v[188:191], 0
	v_mfma_f32_16x16x32_bf16 v[76:79], v[144:147], v[214:217], v[76:79]
	s_setprio 0
	s_setprio 1
	v_mfma_f32_16x16x32_bf16 v[120:123], v[148:151], v[164:167], 0
	v_mfma_f32_16x16x32_bf16 v[120:123], v[152:155], v[168:171], v[120:123]
	v_mfma_f32_16x16x32_bf16 v[116:119], v[156:159], v[164:167], 0
	v_mfma_f32_16x16x32_bf16 v[116:119], v[160:163], v[168:171], v[116:119]
	v_mfma_f32_16x16x32_bf16 v[104:107], v[148:151], v[172:175], 0
	v_mfma_f32_16x16x32_bf16 v[104:107], v[152:155], v[176:179], v[104:107]
	v_mfma_f32_16x16x32_bf16 v[100:103], v[156:159], v[172:175], 0
	v_mfma_f32_16x16x32_bf16 v[100:103], v[160:163], v[176:179], v[100:103]
	v_mfma_f32_16x16x32_bf16 v[88:91], v[148:151], v[180:183], 0
	v_mfma_f32_16x16x32_bf16 v[88:91], v[152:155], v[184:187], v[88:91]
	v_mfma_f32_16x16x32_bf16 v[84:87], v[156:159], v[180:183], 0
	v_mfma_f32_16x16x32_bf16 v[84:87], v[160:163], v[184:187], v[84:87]
	v_mfma_f32_16x16x32_bf16 v[72:75], v[148:151], v[188:191], 0
	v_mfma_f32_16x16x32_bf16 v[72:75], v[152:155], v[214:217], v[72:75]
	v_mfma_f32_16x16x32_bf16 v[68:71], v[156:159], v[188:191], 0
	v_mfma_f32_16x16x32_bf16 v[68:71], v[160:163], v[214:217], v[68:71]
	s_setprio 0
	s_barrier
	s_add_i32 s22, s56, s41
	v_lshl_add_u64 v[218:219], s[26:27], 0, v[2:3]
	s_mov_b32 m0, s22
	ds_read_b128 v[164:167], v242 offset:16384
	ds_read_b128 v[168:171], v242 offset:17408
	ds_read_b128 v[172:175], v242 offset:18432
	ds_read_b128 v[176:179], v242 offset:19456
	ds_read_b128 v[180:183], v242 offset:20480
	ds_read_b128 v[184:187], v242 offset:21504
	ds_read_b128 v[188:191], v242 offset:22528
	ds_read_b128 v[214:217], v242 offset:23552
	global_load_lds_dwordx4 v[218:219], off
	s_add_i32 m0, s22, 0x2000
	s_add_u32 s22, s26, 0x2b0000
	v_lshl_add_u64 v[220:221], s[26:27], 0, v[204:205]
	s_addc_u32 s23, s27, 0
	s_add_i32 s56, s57, s41
	global_load_lds_dwordx4 v[220:221], off
	v_lshl_add_u64 v[222:223], s[22:23], 0, v[2:3]
	s_mov_b32 m0, s56
	v_lshl_add_u64 v[224:225], s[36:37], 0, v[206:207]
	global_load_lds_dwordx4 v[222:223], off
	v_lshl_add_u64 v[222:223], s[22:23], 0, v[204:205]
	s_add_i32 m0, s56, 0x2000
	s_nop 0
	global_load_lds_dwordx4 v[222:223], off
	v_lshl_add_u64 v[222:223], s[36:37], 0, v[208:209]
	s_mov_b32 m0, s42
	s_nop 0
	global_load_lds_dwordx4 v[222:223], off
	s_mov_b32 m0, s43
	s_nop 0
	global_load_lds_dwordx4 v[224:225], off
	s_waitcnt vmcnt(8)
	s_waitcnt lgkmcnt(0)
	s_barrier
; #define PG8_STAGE(bufoff, gbase, voff) do { _Pragma("unroll") for (int _i = 0; _i < 2; ++_i) \
;         __builtin_amdgcn_global_load_lds((const unsigned*)((const char*)(gbase) + (voff)[_i]), (PG8_LAS unsigned*)(lds + (bufoff) + ldsw + _i * 8192), 16, 0, 0); } while (0)
; #define PG8_LDA(dst, b, h) do { _Pragma("unroll") for (int m = 0; m < 4; ++m) _Pragma("unroll") for (int k = 0; k < 2; ++k) dst[m][k] = *(const PG8_LAS bf16x8*)(lds + PG8_SA(b, h) + aoff + m * 2048 + k * 1024); } while (0)
; #define PG8_LDB(dst, b, h) do { _Pragma("unroll") for (int n = 0; n < 2; ++n) _Pragma("unroll") for (int k = 0; k < 2; ++k) dst[n][k] = *(const PG8_LAS bf16x8*)(lds + PG8_SB(b, h) + boff + n * 2048 + k * 1024); } while (0)
; #define PG8_WAIT_V(n) asm volatile("s_waitcnt vmcnt(" #n ")" ::: "memory")
; #define PG8_WAIT_L(n) asm volatile("s_waitcnt lgkmcnt(" #n ")" ::: "memory")
; #define PG8_BAR __builtin_amdgcn_s_barrier()
; #define PG8_SCHED __builtin_amdgcn_sched_barrier(0)
; template <class Epi, class Sched, bool ALIGN_EPI = false, bool SP2 = false, bool I8 = false>
; __device__ __forceinline__ void gemm_phase(PG8_LAS unsigned char* lds, const Gemm g, const Sched& S, const Epi& E) {
;     ...
;             PG8_WAIT_V(8); PG8_WAIT_L(0); PG8_BAR; PG8_MMA(0, 0, At, B0); PG8_MMA(0, 1, At, B1); PG8_BAR; PG8_SCHED;
;             PG8_LDA(At, 0, 1); PG8_STAGE(PG8_SB(0, 0), b2, voffB); PG8_STAGE(PG8_SB(0, 1), b2 + hstep, voffB); PG8_STAGE(PG8_SA(0, 0), a2, voffA);
;             PG8_WAIT_V(8); PG8_WAIT_L(0); PG8_BAR; PG8_MMA(1, 0, At, B0); PG8_MMA(1, 1, At, B1); PG8_BAR; PG8_SCHED;
;             PG8_LDB(B0, 1, 0); PG8_LDB(B1, 1, 1); PG8_SCHED; PG8_LDA(At, 1, 0); PG8_STAGE(PG8_SA(0, 1), a2 + hstep, voffA);
;             PG8_WAIT_V(8); PG8_WAIT_L(0); PG8_BAR; PG8_MMA(0, 0, At, B0); PG8_MMA(0, 1, At, B1); PG8_BAR; PG8_SCHED;
	s_setprio 1
	s_waitcnt lgkmcnt(0)
	v_mfma_f32_16x16x32_bf16 v[64:67], v[124:127], v[164:167], 0
	v_mfma_f32_16x16x32_bf16 v[64:67], v[128:131], v[168:171], v[64:67]
	v_mfma_f32_16x16x32_bf16 v[60:63], v[132:135], v[164:167], 0
	v_mfma_f32_16x16x32_bf16 v[60:63], v[144:147], v[168:171], v[60:63]
	v_mfma_f32_16x16x32_bf16 v[48:51], v[124:127], v[172:175], 0
	v_mfma_f32_16x16x32_bf16 v[48:51], v[128:131], v[176:179], v[48:51]
	v_mfma_f32_16x16x32_bf16 v[44:47], v[132:135], v[172:175], 0
	v_mfma_f32_16x16x32_bf16 v[44:47], v[144:147], v[176:179], v[44:47]
	v_mfma_f32_16x16x32_bf16 v[32:35], v[124:127], v[180:183], 0
	v_mfma_f32_16x16x32_bf16 v[32:35], v[128:131], v[184:187], v[32:35]
	v_mfma_f32_16x16x32_bf16 v[28:31], v[132:135], v[180:183], 0
	v_mfma_f32_16x16x32_bf16 v[28:31], v[144:147], v[184:187], v[28:31]
	v_mfma_f32_16x16x32_bf16 v[16:19], v[124:127], v[188:191], 0
	v_mfma_f32_16x16x32_bf16 v[16:19], v[128:131], v[214:217], v[16:19]
	v_mfma_f32_16x16x32_bf16 v[12:15], v[132:135], v[188:191], 0
	v_mfma_f32_16x16x32_bf16 v[12:15], v[144:147], v[214:217], v[12:15]
	s_setprio 0
	s_setprio 1
	v_mfma_f32_16x16x32_bf16 v[56:59], v[148:151], v[164:167], 0
	v_mfma_f32_16x16x32_bf16 v[56:59], v[152:155], v[168:171], v[56:59]
	v_mfma_f32_16x16x32_bf16 v[52:55], v[156:159], v[164:167], 0
	v_mfma_f32_16x16x32_bf16 v[52:55], v[160:163], v[168:171], v[52:55]
	v_mfma_f32_16x16x32_bf16 v[40:43], v[148:151], v[172:175], 0
	v_mfma_f32_16x16x32_bf16 v[40:43], v[152:155], v[176:179], v[40:43]
	v_mfma_f32_16x16x32_bf16 v[36:39], v[156:159], v[172:175], 0
	v_mfma_f32_16x16x32_bf16 v[36:39], v[160:163], v[176:179], v[36:39]
	v_mfma_f32_16x16x32_bf16 v[24:27], v[148:151], v[180:183], 0
	v_mfma_f32_16x16x32_bf16 v[24:27], v[152:155], v[184:187], v[24:27]
	v_mfma_f32_16x16x32_bf16 v[20:23], v[156:159], v[180:183], 0
	v_mfma_f32_16x16x32_bf16 v[20:23], v[160:163], v[184:187], v[20:23]
	v_mfma_f32_16x16x32_bf16 v[8:11], v[148:151], v[188:191], 0
	v_mfma_f32_16x16x32_bf16 v[8:11], v[152:155], v[214:217], v[8:11]
	v_mfma_f32_16x16x32_bf16 v[4:7], v[156:159], v[188:191], 0
	v_mfma_f32_16x16x32_bf16 v[4:7], v[160:163], v[214:217], v[4:7]
	s_setprio 0
	s_barrier
	s_add_i32 s56, 0, 0x18000
	s_add_i32 s57, 0, 0x1c000
	v_add_u32_e32 v144, s56, v240
	v_add_u32_e32 v160, s57, v240
	ds_read_b128 v[124:127], v144
	ds_read_b128 v[128:131], v144 offset:1024
	ds_read_b128 v[132:135], v144 offset:2048
	ds_read_b128 v[144:147], v144 offset:3072
	ds_read_b128 v[148:151], v160
	ds_read_b128 v[152:155], v160 offset:1024
	ds_read_b128 v[156:159], v160 offset:2048
	ds_read_b128 v[160:163], v160 offset:3072
	s_add_u32 s22, s36, 0x2b0000
	s_addc_u32 s23, s37, 0
	s_mov_b32 m0, s44
	v_lshl_add_u64 v[226:227], s[22:23], 0, v[208:209]
	ds_read_b128 v[164:167], v242 offset:32768
	ds_read_b128 v[168:171], v242 offset:33792
	ds_read_b128 v[172:175], v242 offset:34816
	ds_read_b128 v[176:179], v242 offset:35840
	ds_read_b128 v[180:183], v242 offset:36864
	ds_read_b128 v[184:187], v242 offset:37888
	ds_read_b128 v[188:191], v242 offset:38912
	ds_read_b128 v[214:217], v242 offset:39936
	global_load_lds_dwordx4 v[226:227], off
	v_lshl_add_u64 v[226:227], s[22:23], 0, v[206:207]
	s_mov_b32 m0, s45
	s_nop 0
	global_load_lds_dwordx4 v[226:227], off
	s_waitcnt vmcnt(8)
	s_waitcnt lgkmcnt(0)
	s_barrier
	s_setprio 1
	s_waitcnt lgkmcnt(0)
	v_mfma_f32_16x16x32_bf16 v[140:143], v[124:127], v[164:167], v[140:143]
	v_mfma_f32_16x16x32_bf16 v[140:143], v[128:131], v[168:171], v[140:143]
	v_mfma_f32_16x16x32_bf16 v[136:139], v[132:135], v[164:167], v[136:139]
	v_mfma_f32_16x16x32_bf16 v[136:139], v[144:147], v[168:171], v[136:139]
	v_mfma_f32_16x16x32_bf16 v[112:115], v[124:127], v[172:175], v[112:115]
	v_mfma_f32_16x16x32_bf16 v[112:115], v[128:131], v[176:179], v[112:115]
	v_mfma_f32_16x16x32_bf16 v[108:111], v[132:135], v[172:175], v[108:111]
	v_mfma_f32_16x16x32_bf16 v[108:111], v[144:147], v[176:179], v[108:111]
	v_mfma_f32_16x16x32_bf16 v[96:99], v[124:127], v[180:183], v[96:99]
	v_mfma_f32_16x16x32_bf16 v[96:99], v[128:131], v[184:187], v[96:99]
	v_mfma_f32_16x16x32_bf16 v[92:95], v[132:135], v[180:183], v[92:95]
	v_mfma_f32_16x16x32_bf16 v[92:95], v[144:147], v[184:187], v[92:95]
	v_mfma_f32_16x16x32_bf16 v[80:83], v[124:127], v[188:191], v[80:83]
	v_mfma_f32_16x16x32_bf16 v[80:83], v[128:131], v[214:217], v[80:83]
	v_mfma_f32_16x16x32_bf16 v[76:79], v[132:135], v[188:191], v[76:79]
	v_mfma_f32_16x16x32_bf16 v[76:79], v[144:147], v[214:217], v[76:79]
	s_setprio 0
	s_setprio 1
	v_mfma_f32_16x16x32_bf16 v[120:123], v[148:151], v[164:167], v[120:123]
	v_mfma_f32_16x16x32_bf16 v[120:123], v[152:155], v[168:171], v[120:123]
	v_mfma_f32_16x16x32_bf16 v[116:119], v[156:159], v[164:167], v[116:119]
	v_mfma_f32_16x16x32_bf16 v[116:119], v[160:163], v[168:171], v[116:119]
	v_mfma_f32_16x16x32_bf16 v[104:107], v[148:151], v[172:175], v[104:107]
	v_mfma_f32_16x16x32_bf16 v[104:107], v[152:155], v[176:179], v[104:107]
	v_mfma_f32_16x16x32_bf16 v[100:103], v[156:159], v[172:175], v[100:103]
	v_mfma_f32_16x16x32_bf16 v[100:103], v[160:163], v[176:179], v[100:103]
	v_mfma_f32_16x16x32_bf16 v[88:91], v[148:151], v[180:183], v[88:91]
	v_mfma_f32_16x16x32_bf16 v[88:91], v[152:155], v[184:187], v[88:91]
	v_mfma_f32_16x16x32_bf16 v[84:87], v[156:159], v[180:183], v[84:87]
	v_mfma_f32_16x16x32_bf16 v[84:87], v[160:163], v[184:187], v[84:87]
	v_mfma_f32_16x16x32_bf16 v[72:75], v[148:151], v[188:191], v[72:75]
	v_mfma_f32_16x16x32_bf16 v[72:75], v[152:155], v[214:217], v[72:75]
	v_mfma_f32_16x16x32_bf16 v[68:71], v[156:159], v[188:191], v[68:71]
	v_mfma_f32_16x16x32_bf16 v[68:71], v[160:163], v[214:217], v[68:71]
	s_setprio 0
	s_barrier
; #define PG8_STAGE(bufoff, gbase, voff) do { _Pragma("unroll") for (int _i = 0; _i < 2; ++_i) \
;         __builtin_amdgcn_global_load_lds((const unsigned*)((const char*)(gbase) + (voff)[_i]), (PG8_LAS unsigned*)(lds + (bufoff) + ldsw + _i * 8192), 16, 0, 0); } while (0)
; #define PG8_LDA(dst, b, h) do { _Pragma("unroll") for (int m = 0; m < 4; ++m) _Pragma("unroll") for (int k = 0; k < 2; ++k) dst[m][k] = *(const PG8_LAS bf16x8*)(lds + PG8_SA(b, h) + aoff + m * 2048 + k * 1024); } while (0)
; #define PG8_WAIT_V(n) asm volatile("s_waitcnt vmcnt(" #n ")" ::: "memory")
; #define PG8_WAIT_L(n) asm volatile("s_waitcnt lgkmcnt(" #n ")" ::: "memory")
; #define PG8_BAR __builtin_amdgcn_s_barrier()
; template <class Epi, class Sched, bool ALIGN_EPI = false, bool SP2 = false, bool I8 = false>
; __device__ __forceinline__ void gemm_phase(PG8_LAS unsigned char* lds, const Gemm g, const Sched& S, const Epi& E) {
;     ...
;         for (int t = 0; t < nt; t += 2) {
;             const bool last = (t == nt - 2);
;             const char* a1 = cA + (size_t)(t + 1) * kstep;
;             const char* a2 = last ? nA : cA + (size_t)(t + 2) * kstep; const char* b2 = last ? nB : cB + (size_t)(t + 2) * kstep;
;             const char* a3 = a2 + kstep; const char* b3 = b2 + kstep;
;             if (last && has_next) S.a_ready(nxt);
;             if constexpr (SP2) {
;             PG8_LDB(B0, 0, 0); PG8_LDB(B1, 0, 1); PG8_SCHED; PG8_LDA(At, 0, 0); PG8_STAGE(PG8_SA(1, 1), a1 + hstep, voffA);
;             PG8_WAIT_V(8); PG8_WAIT_L(0); PG8_BAR; PG8_MMA(0, 0, At, B0); PG8_MMA(0, 1, At, B1); PG8_BAR; PG8_SCHED;
;             PG8_LDA(At, 0, 1); PG8_STAGE(PG8_SB(0, 0), b2, voffB); PG8_STAGE(PG8_SB(0, 1), b2 + hstep, voffB); PG8_STAGE(PG8_SA(0, 0), a2, voffA);
;             PG8_WAIT_V(8); PG8_WAIT_L(0); PG8_BAR; PG8_MMA(1, 0, At, B0); PG8_MMA(1, 1, At, B1); PG8_BAR; PG8_SCHED;
;             PG8_LDB(B0, 1, 0); PG8_LDB(B1, 1, 1); PG8_SCHED; PG8_LDA(At, 1, 0); PG8_STAGE(PG8_SA(0, 1), a2 + hstep, voffA);
;             PG8_WAIT_V(8); PG8_WAIT_L(0); PG8_BAR; PG8_MMA(0, 0, At, B0); PG8_MMA(0, 1, At, B1); PG8_BAR; PG8_SCHED;
;             PG8_LDA(At, 1, 1); PG8_STAGE(PG8_SB(1, 0), b3, voffB); PG8_STAGE(PG8_SB(1, 1), b3 + hstep, voffB); PG8_STAGE(PG8_SA(1, 0), a3, voffA);
;             PG8_WAIT_V(8); PG8_WAIT_L(0); PG8_BAR; PG8_MMA(1, 0, At, B0); PG8_MMA(1, 1, At, B1); PG8_BAR; PG8_SCHED;
	s_add_i32 s22, s56, s41
	v_lshl_add_u64 v[218:219], v[218:219], 0, s[84:85]
	s_mov_b32 m0, s22
	ds_read_b128 v[164:167], v242 offset:49152
	ds_read_b128 v[168:171], v242 offset:50176
	ds_read_b128 v[172:175], v242 offset:51200
	ds_read_b128 v[176:179], v242 offset:52224
	ds_read_b128 v[180:183], v242 offset:53248
	ds_read_b128 v[184:187], v242 offset:54272
	ds_read_b128 v[188:191], v242 offset:55296
	ds_read_b128 v[214:217], v242 offset:56320
	global_load_lds_dwordx4 v[218:219], off
	s_add_i32 m0, s22, 0x2000
	s_add_u32 s22, s26, 0x2b0080
	v_lshl_add_u64 v[218:219], v[220:221], 0, s[84:85]
	s_addc_u32 s23, s27, 0
	s_add_i32 s26, s57, s41
	global_load_lds_dwordx4 v[218:219], off
	v_lshl_add_u64 v[218:219], s[22:23], 0, v[2:3]
	s_mov_b32 m0, s26
	s_nop 0
	global_load_lds_dwordx4 v[218:219], off
	v_lshl_add_u64 v[218:219], s[22:23], 0, v[204:205]
	s_add_i32 m0, s26, 0x2000
	s_nop 0
	global_load_lds_dwordx4 v[218:219], off
	v_lshl_add_u64 v[218:219], v[222:223], 0, s[84:85]
	s_mov_b32 m0, s46
	s_nop 0
	global_load_lds_dwordx4 v[218:219], off
	v_lshl_add_u64 v[218:219], v[224:225], 0, s[84:85]
	s_mov_b32 m0, s47
	s_nop 0
	global_load_lds_dwordx4 v[218:219], off
	s_waitcnt vmcnt(8)
	s_waitcnt lgkmcnt(0)
	s_barrier
	s_setprio 1
	s_waitcnt lgkmcnt(0)
	v_mfma_f32_16x16x32_bf16 v[64:67], v[124:127], v[164:167], v[64:67]
	v_mfma_f32_16x16x32_bf16 v[64:67], v[128:131], v[168:171], v[64:67]
	v_mfma_f32_16x16x32_bf16 v[60:63], v[132:135], v[164:167], v[60:63]
	v_mfma_f32_16x16x32_bf16 v[60:63], v[144:147], v[168:171], v[60:63]
	v_mfma_f32_16x16x32_bf16 v[48:51], v[124:127], v[172:175], v[48:51]
	v_mfma_f32_16x16x32_bf16 v[48:51], v[128:131], v[176:179], v[48:51]
	v_mfma_f32_16x16x32_bf16 v[44:47], v[132:135], v[172:175], v[44:47]
	v_mfma_f32_16x16x32_bf16 v[44:47], v[144:147], v[176:179], v[44:47]
	v_mfma_f32_16x16x32_bf16 v[32:35], v[124:127], v[180:183], v[32:35]
	v_mfma_f32_16x16x32_bf16 v[32:35], v[128:131], v[184:187], v[32:35]
	v_mfma_f32_16x16x32_bf16 v[28:31], v[132:135], v[180:183], v[28:31]
	v_mfma_f32_16x16x32_bf16 v[28:31], v[144:147], v[184:187], v[28:31]
	v_mfma_f32_16x16x32_bf16 v[16:19], v[124:127], v[188:191], v[16:19]
	v_mfma_f32_16x16x32_bf16 v[16:19], v[128:131], v[214:217], v[16:19]
	v_mfma_f32_16x16x32_bf16 v[12:15], v[132:135], v[188:191], v[12:15]
	v_mfma_f32_16x16x32_bf16 v[12:15], v[144:147], v[214:217], v[12:15]
	s_setprio 0
	s_setprio 1
	v_mfma_f32_16x16x32_bf16 v[56:59], v[148:151], v[164:167], v[56:59]
	v_mfma_f32_16x16x32_bf16 v[56:59], v[152:155], v[168:171], v[56:59]
	v_mfma_f32_16x16x32_bf16 v[52:55], v[156:159], v[164:167], v[52:55]
	v_mfma_f32_16x16x32_bf16 v[52:55], v[160:163], v[168:171], v[52:55]
	v_mfma_f32_16x16x32_bf16 v[40:43], v[148:151], v[172:175], v[40:43]
	v_mfma_f32_16x16x32_bf16 v[40:43], v[152:155], v[176:179], v[40:43]
	v_mfma_f32_16x16x32_bf16 v[36:39], v[156:159], v[172:175], v[36:39]
	v_mfma_f32_16x16x32_bf16 v[36:39], v[160:163], v[176:179], v[36:39]
	v_mfma_f32_16x16x32_bf16 v[24:27], v[148:151], v[180:183], v[24:27]
	v_mfma_f32_16x16x32_bf16 v[24:27], v[152:155], v[184:187], v[24:27]
	v_mfma_f32_16x16x32_bf16 v[20:23], v[156:159], v[180:183], v[20:23]
	v_mfma_f32_16x16x32_bf16 v[20:23], v[160:163], v[184:187], v[20:23]
	v_mfma_f32_16x16x32_bf16 v[8:11], v[148:151], v[188:191], v[8:11]
	v_mfma_f32_16x16x32_bf16 v[8:11], v[152:155], v[214:217], v[8:11]
	v_mfma_f32_16x16x32_bf16 v[4:7], v[156:159], v[188:191], v[4:7]
	v_mfma_f32_16x16x32_bf16 v[4:7], v[160:163], v[214:217], v[4:7]
	s_setprio 0
	s_barrier
	s_add_i32 s55, s55, 2
	s_add_u32 s53, s53, 0x100
	s_addc_u32 s54, s54, 0
	s_cmpk_gt_u32 s55, 0xa9
	s_mov_b64 s[22:23], s[24:25]
	s_cbranch_scc1 .Lkloop_exit_5
.LBB0_1700:
	s_add_u32 s24, s22, 0x100
	s_addc_u32 s25, s23, 0
	s_add_i32 s56, 0, 0x10000
	s_cmpk_eq_i32 s55, 0xa8
	s_cselect_b32 s37, s13, s25
	s_cselect_b32 s36, s12, s24
	s_cselect_b32 s27, s21, s54
	s_cselect_b32 s26, s20, s53
	s_add_i32 s57, 0, 0x14000
	v_add_u32_e32 v144, s56, v240
	v_add_u32_e32 v160, s57, v240
	ds_read_b128 v[124:127], v144
	ds_read_b128 v[128:131], v144 offset:1024
	ds_read_b128 v[132:135], v144 offset:2048
	ds_read_b128 v[144:147], v144 offset:3072
	ds_read_b128 v[148:151], v160
	ds_read_b128 v[152:155], v160 offset:1024
	ds_read_b128 v[156:159], v160 offset:2048
	ds_read_b128 v[160:163], v160 offset:3072
	v_lshl_add_u64 v[218:219], s[22:23], 0, v[210:211]
	s_add_i32 m0, s42, 0xc000
	ds_read_b128 v[164:167], v242
	ds_read_b128 v[168:171], v242 offset:1024
	ds_read_b128 v[172:175], v242 offset:2048
	ds_read_b128 v[176:179], v242 offset:3072
	ds_read_b128 v[180:183], v242 offset:4096
	ds_read_b128 v[184:187], v242 offset:5120
	ds_read_b128 v[188:191], v242 offset:6144
	ds_read_b128 v[214:217], v242 offset:7168
	global_load_lds_dwordx4 v[218:219], off
	v_lshl_add_u64 v[218:219], s[22:23], 0, v[212:213]
	s_add_i32 m0, s42, 0xe000
	s_nop 0
	global_load_lds_dwordx4 v[218:219], off
	s_waitcnt vmcnt(8)
	s_waitcnt lgkmcnt(0)
	s_barrier
; #define PG8_STAGE(bufoff, gbase, voff) do { _Pragma("unroll") for (int _i = 0; _i < 2; ++_i) \
;         __builtin_amdgcn_global_load_lds((const unsigned*)((const char*)(gbase) + (voff)[_i]), (PG8_LAS unsigned*)(lds + (bufoff) + ldsw + _i * 8192), 16, 0, 0); } while (0)
; #define PG8_LDA(dst, b, h) do { _Pragma("unroll") for (int m = 0; m < 4; ++m) _Pragma("unroll") for (int k = 0; k < 2; ++k) dst[m][k] = *(const PG8_LAS bf16x8*)(lds + PG8_SA(b, h) + aoff + m * 2048 + k * 1024); } while (0)
; #define PG8_LDB(dst, b, h) do { _Pragma("unroll") for (int n = 0; n < 2; ++n) _Pragma("unroll") for (int k = 0; k < 2; ++k) dst[n][k] = *(const PG8_LAS bf16x8*)(lds + PG8_SB(b, h) + boff + n * 2048 + k * 1024); } while (0)
; #define PG8_WAIT_V(n) asm volatile("s_waitcnt vmcnt(" #n ")" ::: "memory")
; #define PG8_WAIT_L(n) asm volatile("s_waitcnt lgkmcnt(" #n ")" ::: "memory")
; #define PG8_BAR __builtin_amdgcn_s_barrier()
; #define PG8_SCHED __builtin_amdgcn_sched_barrier(0)
; template <class Epi, class Sched, bool ALIGN_EPI = false, bool SP2 = false, bool I8 = false>
; __device__ __forceinline__ void gemm_phase(PG8_LAS unsigned char* lds, const Gemm g, const Sched& S, const Epi& E) {
;     ...
;             PG8_LDB(B0, 0, 0); PG8_LDB(B1, 0, 1); PG8_SCHED; PG8_LDA(At, 0, 0); PG8_STAGE(PG8_SA(1, 1), a1 + hstep, voffA);
;             PG8_WAIT_V(8); PG8_WAIT_L(0); PG8_BAR; PG8_MMA(0, 0, At, B0); PG8_MMA(0, 1, At, B1); PG8_BAR; PG8_SCHED;
;             PG8_LDA(At, 0, 1); PG8_STAGE(PG8_SB(0, 0), b2, voffB); PG8_STAGE(PG8_SB(0, 1), b2 + hstep, voffB); PG8_STAGE(PG8_SA(0, 0), a2, voffA);
;             PG8_WAIT_V(8); PG8_WAIT_L(0); PG8_BAR; PG8_MMA(1, 0, At, B0); PG8_MMA(1, 1, At, B1); PG8_BAR; PG8_SCHED;
	s_setprio 1
	s_waitcnt lgkmcnt(0)
	v_mfma_f32_16x16x32_bf16 v[140:143], v[124:127], v[164:167], v[140:143]
	v_mfma_f32_16x16x32_bf16 v[140:143], v[128:131], v[168:171], v[140:143]
	v_mfma_f32_16x16x32_bf16 v[136:139], v[132:135], v[164:167], v[136:139]
	v_mfma_f32_16x16x32_bf16 v[136:139], v[144:147], v[168:171], v[136:139]
	v_mfma_f32_16x16x32_bf16 v[112:115], v[124:127], v[172:175], v[112:115]
	v_mfma_f32_16x16x32_bf16 v[112:115], v[128:131], v[176:179], v[112:115]
	v_mfma_f32_16x16x32_bf16 v[108:111], v[132:135], v[172:175], v[108:111]
	v_mfma_f32_16x16x32_bf16 v[108:111], v[144:147], v[176:179], v[108:111]
	v_mfma_f32_16x16x32_bf16 v[96:99], v[124:127], v[180:183], v[96:99]
	v_mfma_f32_16x16x32_bf16 v[96:99], v[128:131], v[184:187], v[96:99]
	v_mfma_f32_16x16x32_bf16 v[92:95], v[132:135], v[180:183], v[92:95]
	v_mfma_f32_16x16x32_bf16 v[92:95], v[144:147], v[184:187], v[92:95]
	v_mfma_f32_16x16x32_bf16 v[80:83], v[124:127], v[188:191], v[80:83]
	v_mfma_f32_16x16x32_bf16 v[80:83], v[128:131], v[214:217], v[80:83]
	v_mfma_f32_16x16x32_bf16 v[76:79], v[132:135], v[188:191], v[76:79]
	v_mfma_f32_16x16x32_bf16 v[76:79], v[144:147], v[214:217], v[76:79]
	s_setprio 0
	s_setprio 1
	v_mfma_f32_16x16x32_bf16 v[120:123], v[148:151], v[164:167], v[120:123]
	v_mfma_f32_16x16x32_bf16 v[120:123], v[152:155], v[168:171], v[120:123]
	v_mfma_f32_16x16x32_bf16 v[116:119], v[156:159], v[164:167], v[116:119]
	v_mfma_f32_16x16x32_bf16 v[116:119], v[160:163], v[168:171], v[116:119]
	v_mfma_f32_16x16x32_bf16 v[104:107], v[148:151], v[172:175], v[104:107]
	v_mfma_f32_16x16x32_bf16 v[104:107], v[152:155], v[176:179], v[104:107]
	v_mfma_f32_16x16x32_bf16 v[100:103], v[156:159], v[172:175], v[100:103]
	v_mfma_f32_16x16x32_bf16 v[100:103], v[160:163], v[176:179], v[100:103]
	v_mfma_f32_16x16x32_bf16 v[88:91], v[148:151], v[180:183], v[88:91]
	v_mfma_f32_16x16x32_bf16 v[88:91], v[152:155], v[184:187], v[88:91]
	v_mfma_f32_16x16x32_bf16 v[84:87], v[156:159], v[180:183], v[84:87]
	v_mfma_f32_16x16x32_bf16 v[84:87], v[160:163], v[184:187], v[84:87]
	v_mfma_f32_16x16x32_bf16 v[72:75], v[148:151], v[188:191], v[72:75]
	v_mfma_f32_16x16x32_bf16 v[72:75], v[152:155], v[214:217], v[72:75]
	v_mfma_f32_16x16x32_bf16 v[68:71], v[156:159], v[188:191], v[68:71]
	v_mfma_f32_16x16x32_bf16 v[68:71], v[160:163], v[214:217], v[68:71]
	s_setprio 0
	s_barrier
	s_add_i32 s22, s56, s41
	v_lshl_add_u64 v[218:219], s[26:27], 0, v[2:3]
	s_mov_b32 m0, s22
	ds_read_b128 v[164:167], v242 offset:16384
	ds_read_b128 v[168:171], v242 offset:17408
	ds_read_b128 v[172:175], v242 offset:18432
	ds_read_b128 v[176:179], v242 offset:19456
	ds_read_b128 v[180:183], v242 offset:20480
	ds_read_b128 v[184:187], v242 offset:21504
	ds_read_b128 v[188:191], v242 offset:22528
	ds_read_b128 v[214:217], v242 offset:23552
	global_load_lds_dwordx4 v[218:219], off
	s_add_i32 m0, s22, 0x2000
	s_add_u32 s22, s26, 0x2b0000
	v_lshl_add_u64 v[220:221], s[26:27], 0, v[204:205]
	s_addc_u32 s23, s27, 0
	s_add_i32 s56, s57, s41
	global_load_lds_dwordx4 v[220:221], off
	v_lshl_add_u64 v[222:223], s[22:23], 0, v[2:3]
	s_mov_b32 m0, s56
	v_lshl_add_u64 v[224:225], s[36:37], 0, v[206:207]
	global_load_lds_dwordx4 v[222:223], off
	v_lshl_add_u64 v[222:223], s[22:23], 0, v[204:205]
	s_add_i32 m0, s56, 0x2000
	s_nop 0
	global_load_lds_dwordx4 v[222:223], off
	v_lshl_add_u64 v[222:223], s[36:37], 0, v[208:209]
	s_mov_b32 m0, s42
	s_nop 0
	global_load_lds_dwordx4 v[222:223], off
	s_mov_b32 m0, s43
	s_nop 0
	global_load_lds_dwordx4 v[224:225], off
	s_waitcnt vmcnt(8)
	s_waitcnt lgkmcnt(0)
	s_barrier
	s_setprio 1
	s_waitcnt lgkmcnt(0)
	v_mfma_f32_16x16x32_bf16 v[64:67], v[124:127], v[164:167], v[64:67]
	v_mfma_f32_16x16x32_bf16 v[64:67], v[128:131], v[168:171], v[64:67]
	v_mfma_f32_16x16x32_bf16 v[60:63], v[132:135], v[164:167], v[60:63]
	v_mfma_f32_16x16x32_bf16 v[60:63], v[144:147], v[168:171], v[60:63]
	v_mfma_f32_16x16x32_bf16 v[48:51], v[124:127], v[172:175], v[48:51]
	v_mfma_f32_16x16x32_bf16 v[48:51], v[128:131], v[176:179], v[48:51]
	v_mfma_f32_16x16x32_bf16 v[44:47], v[132:135], v[172:175], v[44:47]
	v_mfma_f32_16x16x32_bf16 v[44:47], v[144:147], v[176:179], v[44:47]
	v_mfma_f32_16x16x32_bf16 v[32:35], v[124:127], v[180:183], v[32:35]
	v_mfma_f32_16x16x32_bf16 v[32:35], v[128:131], v[184:187], v[32:35]
	v_mfma_f32_16x16x32_bf16 v[28:31], v[132:135], v[180:183], v[28:31]
	v_mfma_f32_16x16x32_bf16 v[28:31], v[144:147], v[184:187], v[28:31]
	v_mfma_f32_16x16x32_bf16 v[16:19], v[124:127], v[188:191], v[16:19]
	v_mfma_f32_16x16x32_bf16 v[16:19], v[128:131], v[214:217], v[16:19]
	v_mfma_f32_16x16x32_bf16 v[12:15], v[132:135], v[188:191], v[12:15]
	v_mfma_f32_16x16x32_bf16 v[12:15], v[144:147], v[214:217], v[12:15]
	s_setprio 0
	s_setprio 1
	v_mfma_f32_16x16x32_bf16 v[56:59], v[148:151], v[164:167], v[56:59]
	v_mfma_f32_16x16x32_bf16 v[56:59], v[152:155], v[168:171], v[56:59]
	v_mfma_f32_16x16x32_bf16 v[52:55], v[156:159], v[164:167], v[52:55]
	v_mfma_f32_16x16x32_bf16 v[52:55], v[160:163], v[168:171], v[52:55]
	v_mfma_f32_16x16x32_bf16 v[40:43], v[148:151], v[172:175], v[40:43]
	v_mfma_f32_16x16x32_bf16 v[40:43], v[152:155], v[176:179], v[40:43]
	v_mfma_f32_16x16x32_bf16 v[36:39], v[156:159], v[172:175], v[36:39]
	v_mfma_f32_16x16x32_bf16 v[36:39], v[160:163], v[176:179], v[36:39]
	v_mfma_f32_16x16x32_bf16 v[24:27], v[148:151], v[180:183], v[24:27]
	v_mfma_f32_16x16x32_bf16 v[24:27], v[152:155], v[184:187], v[24:27]
	v_mfma_f32_16x16x32_bf16 v[20:23], v[156:159], v[180:183], v[20:23]
	v_mfma_f32_16x16x32_bf16 v[20:23], v[160:163], v[184:187], v[20:23]
	v_mfma_f32_16x16x32_bf16 v[8:11], v[148:151], v[188:191], v[8:11]
	v_mfma_f32_16x16x32_bf16 v[8:11], v[152:155], v[214:217], v[8:11]
	v_mfma_f32_16x16x32_bf16 v[4:7], v[156:159], v[188:191], v[4:7]
	v_mfma_f32_16x16x32_bf16 v[4:7], v[160:163], v[214:217], v[4:7]
	s_setprio 0
	s_barrier
; #define PG8_STAGE(bufoff, gbase, voff) do { _Pragma("unroll") for (int _i = 0; _i < 2; ++_i) \
;         __builtin_amdgcn_global_load_lds((const unsigned*)((const char*)(gbase) + (voff)[_i]), (PG8_LAS unsigned*)(lds + (bufoff) + ldsw + _i * 8192), 16, 0, 0); } while (0)
; #define PG8_LDA(dst, b, h) do { _Pragma("unroll") for (int m = 0; m < 4; ++m) _Pragma("unroll") for (int k = 0; k < 2; ++k) dst[m][k] = *(const PG8_LAS bf16x8*)(lds + PG8_SA(b, h) + aoff + m * 2048 + k * 1024); } while (0)
; #define PG8_LDB(dst, b, h) do { _Pragma("unroll") for (int n = 0; n < 2; ++n) _Pragma("unroll") for (int k = 0; k < 2; ++k) dst[n][k] = *(const PG8_LAS bf16x8*)(lds + PG8_SB(b, h) + boff + n * 2048 + k * 1024); } while (0)
; #define PG8_WAIT_V(n) asm volatile("s_waitcnt vmcnt(" #n ")" ::: "memory")
; #define PG8_WAIT_L(n) asm volatile("s_waitcnt lgkmcnt(" #n ")" ::: "memory")
; #define PG8_BAR __builtin_amdgcn_s_barrier()
; #define PG8_SCHED __builtin_amdgcn_sched_barrier(0)
; template <class Epi, class Sched, bool ALIGN_EPI = false, bool SP2 = false, bool I8 = false>
; __device__ __forceinline__ void gemm_phase(PG8_LAS unsigned char* lds, const Gemm g, const Sched& S, const Epi& E) {
;     ...
;             PG8_LDB(B0, 1, 0); PG8_LDB(B1, 1, 1); PG8_SCHED; PG8_LDA(At, 1, 0); PG8_STAGE(PG8_SA(0, 1), a2 + hstep, voffA);
;             PG8_WAIT_V(8); PG8_WAIT_L(0); PG8_BAR; PG8_MMA(0, 0, At, B0); PG8_MMA(0, 1, At, B1); PG8_BAR; PG8_SCHED;
	s_add_i32 s56, 0, 0x18000
	s_add_i32 s57, 0, 0x1c000
	v_add_u32_e32 v144, s56, v240
	v_add_u32_e32 v160, s57, v240
	ds_read_b128 v[124:127], v144
	ds_read_b128 v[128:131], v144 offset:1024
	ds_read_b128 v[132:135], v144 offset:2048
	ds_read_b128 v[144:147], v144 offset:3072
	ds_read_b128 v[148:151], v160
	ds_read_b128 v[152:155], v160 offset:1024
	ds_read_b128 v[156:159], v160 offset:2048
	ds_read_b128 v[160:163], v160 offset:3072
	s_add_u32 s22, s36, 0x2b0000
	s_addc_u32 s23, s37, 0
	s_mov_b32 m0, s44
	v_lshl_add_u64 v[226:227], s[22:23], 0, v[208:209]
	ds_read_b128 v[164:167], v242 offset:32768
	ds_read_b128 v[168:171], v242 offset:33792
	ds_read_b128 v[172:175], v242 offset:34816
	ds_read_b128 v[176:179], v242 offset:35840
	ds_read_b128 v[180:183], v242 offset:36864
	ds_read_b128 v[184:187], v242 offset:37888
	ds_read_b128 v[188:191], v242 offset:38912
	ds_read_b128 v[214:217], v242 offset:39936
	global_load_lds_dwordx4 v[226:227], off
	v_lshl_add_u64 v[226:227], s[22:23], 0, v[206:207]
	s_mov_b32 m0, s45
	s_nop 0
	global_load_lds_dwordx4 v[226:227], off
	s_waitcnt vmcnt(8)
	s_waitcnt lgkmcnt(0)
	s_barrier
	s_setprio 1
	s_waitcnt lgkmcnt(0)
	v_mfma_f32_16x16x32_bf16 v[140:143], v[124:127], v[164:167], v[140:143]
	v_mfma_f32_16x16x32_bf16 v[140:143], v[128:131], v[168:171], v[140:143]
	v_mfma_f32_16x16x32_bf16 v[136:139], v[132:135], v[164:167], v[136:139]
	v_mfma_f32_16x16x32_bf16 v[136:139], v[144:147], v[168:171], v[136:139]
	v_mfma_f32_16x16x32_bf16 v[112:115], v[124:127], v[172:175], v[112:115]
	v_mfma_f32_16x16x32_bf16 v[112:115], v[128:131], v[176:179], v[112:115]
	v_mfma_f32_16x16x32_bf16 v[108:111], v[132:135], v[172:175], v[108:111]
	v_mfma_f32_16x16x32_bf16 v[108:111], v[144:147], v[176:179], v[108:111]
	v_mfma_f32_16x16x32_bf16 v[96:99], v[124:127], v[180:183], v[96:99]
	v_mfma_f32_16x16x32_bf16 v[96:99], v[128:131], v[184:187], v[96:99]
	v_mfma_f32_16x16x32_bf16 v[92:95], v[132:135], v[180:183], v[92:95]
	v_mfma_f32_16x16x32_bf16 v[92:95], v[144:147], v[184:187], v[92:95]
	v_mfma_f32_16x16x32_bf16 v[80:83], v[124:127], v[188:191], v[80:83]
	v_mfma_f32_16x16x32_bf16 v[80:83], v[128:131], v[214:217], v[80:83]
	v_mfma_f32_16x16x32_bf16 v[76:79], v[132:135], v[188:191], v[76:79]
	v_mfma_f32_16x16x32_bf16 v[76:79], v[144:147], v[214:217], v[76:79]
	s_setprio 0
	s_setprio 1
	v_mfma_f32_16x16x32_bf16 v[120:123], v[148:151], v[164:167], v[120:123]
	v_mfma_f32_16x16x32_bf16 v[120:123], v[152:155], v[168:171], v[120:123]
	v_mfma_f32_16x16x32_bf16 v[116:119], v[156:159], v[164:167], v[116:119]
	v_mfma_f32_16x16x32_bf16 v[116:119], v[160:163], v[168:171], v[116:119]
	v_mfma_f32_16x16x32_bf16 v[104:107], v[148:151], v[172:175], v[104:107]
	v_mfma_f32_16x16x32_bf16 v[104:107], v[152:155], v[176:179], v[104:107]
	v_mfma_f32_16x16x32_bf16 v[100:103], v[156:159], v[172:175], v[100:103]
	v_mfma_f32_16x16x32_bf16 v[100:103], v[160:163], v[176:179], v[100:103]
	v_mfma_f32_16x16x32_bf16 v[88:91], v[148:151], v[180:183], v[88:91]
	v_mfma_f32_16x16x32_bf16 v[88:91], v[152:155], v[184:187], v[88:91]
	v_mfma_f32_16x16x32_bf16 v[84:87], v[156:159], v[180:183], v[84:87]
	v_mfma_f32_16x16x32_bf16 v[84:87], v[160:163], v[184:187], v[84:87]
	v_mfma_f32_16x16x32_bf16 v[72:75], v[148:151], v[188:191], v[72:75]
	v_mfma_f32_16x16x32_bf16 v[72:75], v[152:155], v[214:217], v[72:75]
	v_mfma_f32_16x16x32_bf16 v[68:71], v[156:159], v[188:191], v[68:71]
	v_mfma_f32_16x16x32_bf16 v[68:71], v[160:163], v[214:217], v[68:71]
	s_setprio 0
	s_barrier
; #define PG8_STAGE(bufoff, gbase, voff) do { _Pragma("unroll") for (int _i = 0; _i < 2; ++_i) \
;         __builtin_amdgcn_global_load_lds((const unsigned*)((const char*)(gbase) + (voff)[_i]), (PG8_LAS unsigned*)(lds + (bufoff) + ldsw + _i * 8192), 16, 0, 0); } while (0)
; #define PG8_LDA(dst, b, h) do { _Pragma("unroll") for (int m = 0; m < 4; ++m) _Pragma("unroll") for (int k = 0; k < 2; ++k) dst[m][k] = *(const PG8_LAS bf16x8*)(lds + PG8_SA(b, h) + aoff + m * 2048 + k * 1024); } while (0)
; #define PG8_WAIT_V(n) asm volatile("s_waitcnt vmcnt(" #n ")" ::: "memory")
; #define PG8_WAIT_L(n) asm volatile("s_waitcnt lgkmcnt(" #n ")" ::: "memory")
; #define PG8_BAR __builtin_amdgcn_s_barrier()
; #define PG8_SCHED __builtin_amdgcn_sched_barrier(0)
; template <class Epi, class Sched, bool ALIGN_EPI = false, bool SP2 = false, bool I8 = false>
; __device__ __forceinline__ void gemm_phase(PG8_LAS unsigned char* lds, const Gemm g, const Sched& S, const Epi& E) {
;     ...
;             PG8_LDA(At, 1, 1); PG8_STAGE(PG8_SB(1, 0), b3, voffB); PG8_STAGE(PG8_SB(1, 1), b3 + hstep, voffB); PG8_STAGE(PG8_SA(1, 0), a3, voffA);
;             PG8_WAIT_V(8); PG8_WAIT_L(0); PG8_BAR; PG8_MMA(1, 0, At, B0); PG8_MMA(1, 1, At, B1); PG8_BAR; PG8_SCHED;
	s_add_i32 s22, s56, s41
	v_lshl_add_u64 v[218:219], v[218:219], 0, s[84:85]
	s_mov_b32 m0, s22
	ds_read_b128 v[164:167], v242 offset:49152
	ds_read_b128 v[168:171], v242 offset:50176
	ds_read_b128 v[172:175], v242 offset:51200
	ds_read_b128 v[176:179], v242 offset:52224
	ds_read_b128 v[180:183], v242 offset:53248
	ds_read_b128 v[184:187], v242 offset:54272
	ds_read_b128 v[188:191], v242 offset:55296
	ds_read_b128 v[214:217], v242 offset:56320
	global_load_lds_dwordx4 v[218:219], off
	s_add_i32 m0, s22, 0x2000
	s_add_u32 s22, s26, 0x2b0080
	v_lshl_add_u64 v[218:219], v[220:221], 0, s[84:85]
	s_addc_u32 s23, s27, 0
	s_add_i32 s26, s57, s41
	global_load_lds_dwordx4 v[218:219], off
	v_lshl_add_u64 v[218:219], s[22:23], 0, v[2:3]
	s_mov_b32 m0, s26
	s_nop 0
	global_load_lds_dwordx4 v[218:219], off
	v_lshl_add_u64 v[218:219], s[22:23], 0, v[204:205]
	s_add_i32 m0, s26, 0x2000
	s_nop 0
	global_load_lds_dwordx4 v[218:219], off
	v_lshl_add_u64 v[218:219], v[222:223], 0, s[84:85]
	s_mov_b32 m0, s46
	s_nop 0
	global_load_lds_dwordx4 v[218:219], off
	v_lshl_add_u64 v[218:219], v[224:225], 0, s[84:85]
	s_mov_b32 m0, s47
	s_nop 0
	global_load_lds_dwordx4 v[218:219], off
	s_waitcnt vmcnt(8)
	s_waitcnt lgkmcnt(0)
	s_barrier
	s_setprio 1
	s_waitcnt lgkmcnt(0)
	v_mfma_f32_16x16x32_bf16 v[64:67], v[124:127], v[164:167], v[64:67]
	v_mfma_f32_16x16x32_bf16 v[64:67], v[128:131], v[168:171], v[64:67]
	v_mfma_f32_16x16x32_bf16 v[60:63], v[132:135], v[164:167], v[60:63]
	v_mfma_f32_16x16x32_bf16 v[60:63], v[144:147], v[168:171], v[60:63]
	v_mfma_f32_16x16x32_bf16 v[48:51], v[124:127], v[172:175], v[48:51]
	v_mfma_f32_16x16x32_bf16 v[48:51], v[128:131], v[176:179], v[48:51]
	v_mfma_f32_16x16x32_bf16 v[44:47], v[132:135], v[172:175], v[44:47]
	v_mfma_f32_16x16x32_bf16 v[44:47], v[144:147], v[176:179], v[44:47]
	v_mfma_f32_16x16x32_bf16 v[32:35], v[124:127], v[180:183], v[32:35]
	v_mfma_f32_16x16x32_bf16 v[32:35], v[128:131], v[184:187], v[32:35]
	v_mfma_f32_16x16x32_bf16 v[28:31], v[132:135], v[180:183], v[28:31]
	v_mfma_f32_16x16x32_bf16 v[28:31], v[144:147], v[184:187], v[28:31]
	v_mfma_f32_16x16x32_bf16 v[16:19], v[124:127], v[188:191], v[16:19]
	v_mfma_f32_16x16x32_bf16 v[16:19], v[128:131], v[214:217], v[16:19]
	v_mfma_f32_16x16x32_bf16 v[12:15], v[132:135], v[188:191], v[12:15]
	v_mfma_f32_16x16x32_bf16 v[12:15], v[144:147], v[214:217], v[12:15]
	s_setprio 0
	s_setprio 1
	v_mfma_f32_16x16x32_bf16 v[56:59], v[148:151], v[164:167], v[56:59]
	v_mfma_f32_16x16x32_bf16 v[56:59], v[152:155], v[168:171], v[56:59]
	v_mfma_f32_16x16x32_bf16 v[52:55], v[156:159], v[164:167], v[52:55]
	v_mfma_f32_16x16x32_bf16 v[52:55], v[160:163], v[168:171], v[52:55]
	v_mfma_f32_16x16x32_bf16 v[40:43], v[148:151], v[172:175], v[40:43]
	v_mfma_f32_16x16x32_bf16 v[40:43], v[152:155], v[176:179], v[40:43]
	v_mfma_f32_16x16x32_bf16 v[36:39], v[156:159], v[172:175], v[36:39]
	v_mfma_f32_16x16x32_bf16 v[36:39], v[160:163], v[176:179], v[36:39]
	v_mfma_f32_16x16x32_bf16 v[24:27], v[148:151], v[180:183], v[24:27]
	v_mfma_f32_16x16x32_bf16 v[24:27], v[152:155], v[184:187], v[24:27]
	v_mfma_f32_16x16x32_bf16 v[20:23], v[156:159], v[180:183], v[20:23]
	v_mfma_f32_16x16x32_bf16 v[20:23], v[160:163], v[184:187], v[20:23]
	v_mfma_f32_16x16x32_bf16 v[8:11], v[148:151], v[188:191], v[8:11]
	v_mfma_f32_16x16x32_bf16 v[8:11], v[152:155], v[214:217], v[8:11]
	v_mfma_f32_16x16x32_bf16 v[4:7], v[156:159], v[188:191], v[4:7]
	v_mfma_f32_16x16x32_bf16 v[4:7], v[160:163], v[214:217], v[4:7]
	s_setprio 0
	s_barrier
	s_add_i32 s55, s55, 2
	s_add_u32 s53, s53, 0x100
	s_addc_u32 s54, s54, 0
	s_cmpk_gt_u32 s55, 0xa9
	s_mov_b64 s[22:23], s[24:25]
	s_cbranch_scc0 .LBB0_1700

; #define PG8_STAGE(bufoff, gbase, voff) do { _Pragma("unroll") for (int _i = 0; _i < 2; ++_i) \
;         __builtin_amdgcn_global_load_lds((const unsigned*)((const char*)(gbase) + (voff)[_i]), (PG8_LAS unsigned*)(lds + (bufoff) + ldsw + _i * 8192), 16, 0, 0); } while (0)
; #define PG8_LDA(dst, b, h) do { _Pragma("unroll") for (int m = 0; m < 4; ++m) _Pragma("unroll") for (int k = 0; k < 2; ++k) dst[m][k] = *(const PG8_LAS bf16x8*)(lds + PG8_SA(b, h) + aoff + m * 2048 + k * 1024); } while (0)
; #define PG8_LDB(dst, b, h) do { _Pragma("unroll") for (int n = 0; n < 2; ++n) _Pragma("unroll") for (int k = 0; k < 2; ++k) dst[n][k] = *(const PG8_LAS bf16x8*)(lds + PG8_SB(b, h) + boff + n * 2048 + k * 1024); } while (0)
; #define PG8_WAIT_V(n) asm volatile("s_waitcnt vmcnt(" #n ")" ::: "memory")
; #define PG8_WAIT_L(n) asm volatile("s_waitcnt lgkmcnt(" #n ")" ::: "memory")
; #define PG8_BAR __builtin_amdgcn_s_barrier()
; #define PG8_SCHED __builtin_amdgcn_sched_barrier(0)
; template <class Epi, class Sched, bool ALIGN_EPI = false, bool SP2 = false, bool I8 = false>
; __device__ __forceinline__ void gemm_phase(PG8_LAS unsigned char* lds, const Gemm g, const Sched& S, const Epi& E) {
;     ...
;         const bool has_next = S.next(ui + 1, nxt);
;         const char* nA = has_next ? (const char*)g.A + (size_t)nxt.pm * tstep : cA; const char* nB = has_next ? (const char*)g.Bt + (size_t)nxt.pn * tstep : cB;
;         for (int t = 0; t < nt; t += 2) {
;             const bool last = (t == nt - 2);
;             const char* a1 = cA + (size_t)(t + 1) * kstep;
;             const char* a2 = last ? nA : cA + (size_t)(t + 2) * kstep; const char* b2 = last ? nB : cB + (size_t)(t + 2) * kstep;
;             const char* a3 = a2 + kstep; const char* b3 = b2 + kstep;
;             if (last && has_next) S.a_ready(nxt);
;             if constexpr (SP2) {
;             PG8_LDB(B0, 0, 0); PG8_LDB(B1, 0, 1); PG8_SCHED; PG8_LDA(At, 0, 0); PG8_STAGE(PG8_SA(1, 1), a1 + hstep, voffA);
;             PG8_WAIT_V(8); PG8_WAIT_L(0); PG8_BAR; PG8_MMA(0, 0, At, B0); PG8_MMA(0, 1, At, B1); PG8_BAR; PG8_SCHED;
;             PG8_LDA(At, 0, 1); PG8_STAGE(PG8_SB(0, 0), b2, voffB); PG8_STAGE(PG8_SB(0, 1), b2 + hstep, voffB); PG8_STAGE(PG8_SA(0, 0), a2, voffA);
;             PG8_WAIT_V(8); PG8_WAIT_L(0); PG8_BAR; PG8_MMA(1, 0, At, B0); PG8_MMA(1, 1, At, B1); PG8_BAR; PG8_SCHED;
.LBB0_1842:
	s_ashr_i32 s45, s44, 31
	s_lshl_b64 s[34:35], s[44:45], 20
	s_add_u32 s50, s47, s34
	s_addc_u32 s51, s52, s35
	s_and_b64 s[34:35], s[8:9], exec
	s_cselect_b32 s11, s51, s55
	s_cselect_b32 s13, s50, s54
	s_ashr_i32 s49, s48, 31
	s_lshl_b64 s[34:35], s[48:49], 20
	s_add_u32 s56, s53, s34
	s_addc_u32 s57, s64, s35
	s_and_b64 s[34:35], s[8:9], exec
	s_cselect_b32 s34, s57, s59
	s_cselect_b32 s35, s56, s58
	s_add_u32 s54, s54, 0x80080
	s_addc_u32 s55, s55, 0
	s_add_u32 s45, s58, 0x100
	s_addc_u32 s49, s59, 0
	s_mov_b32 s86, -2
	s_waitcnt lgkmcnt(0)
	s_add_u32 s58, s54, 0xfff80080
	s_addc_u32 s59, s55, -1
	s_add_i32 s87, 0, 0x10000
	s_cmp_eq_u32 s86, 28
	s_cselect_b32 s61, s11, s59
	s_cselect_b32 s60, s13, s58
	s_cselect_b32 s59, s34, s49
	s_cselect_b32 s58, s35, s45
	s_add_i32 vcc_lo, 0, 0x14000
	v_add_u32_e32 v40, s87, v217
	v_add_u32_e32 v160, vcc_lo, v217
	ds_read_b128 v[28:31], v40
	ds_read_b128 v[32:35], v40 offset:1024
	ds_read_b128 v[36:39], v40 offset:2048
	ds_read_b128 v[40:43], v40 offset:3072
	ds_read_b128 v[140:143], v160
	ds_read_b128 v[144:147], v160 offset:1024
	ds_read_b128 v[156:159], v160 offset:2048
	ds_read_b128 v[160:163], v160 offset:3072
	v_lshl_add_u64 v[190:191], s[54:55], 0, v[186:187]
	s_add_i32 m0, s65, 0xc000
	ds_read_b128 v[164:167], v219
	ds_read_b128 v[168:171], v219 offset:1024
	ds_read_b128 v[172:175], v219 offset:2048
	ds_read_b128 v[176:179], v219 offset:3072
	ds_read_b128 v[204:207], v219 offset:4096
	ds_read_b128 v[208:211], v219 offset:5120
	ds_read_b128 v[212:215], v219 offset:6144
	ds_read_b128 v[220:223], v219 offset:7168
	global_load_lds_dwordx4 v[190:191], off
	v_lshl_add_u64 v[190:191], s[54:55], 0, v[188:189]
	s_add_i32 m0, s65, 0xe000
	s_nop 0
	global_load_lds_dwordx4 v[190:191], off
	s_waitcnt vmcnt(8)
	s_waitcnt lgkmcnt(0)
	s_barrier
	s_setprio 1
	s_waitcnt lgkmcnt(0)
	v_mfma_i32_16x16x64_i8 v[152:155], v[28:31], v[164:167], 0
	v_mfma_i32_16x16x64_i8 v[152:155], v[32:35], v[168:171], v[152:155]
	v_mfma_i32_16x16x64_i8 v[148:151], v[36:39], v[164:167], 0
	v_mfma_i32_16x16x64_i8 v[148:151], v[40:43], v[168:171], v[148:151]
	v_mfma_i32_16x16x64_i8 v[128:131], v[28:31], v[172:175], 0
	v_mfma_i32_16x16x64_i8 v[128:131], v[32:35], v[176:179], v[128:131]
	v_mfma_i32_16x16x64_i8 v[124:127], v[36:39], v[172:175], 0
	v_mfma_i32_16x16x64_i8 v[124:127], v[40:43], v[176:179], v[124:127]
	v_mfma_i32_16x16x64_i8 v[112:115], v[28:31], v[204:207], 0
	v_mfma_i32_16x16x64_i8 v[112:115], v[32:35], v[208:211], v[112:115]
	v_mfma_i32_16x16x64_i8 v[108:111], v[36:39], v[204:207], 0
	v_mfma_i32_16x16x64_i8 v[108:111], v[40:43], v[208:211], v[108:111]
	v_mfma_i32_16x16x64_i8 v[96:99], v[28:31], v[212:215], 0
	v_mfma_i32_16x16x64_i8 v[96:99], v[32:35], v[220:223], v[96:99]
	v_mfma_i32_16x16x64_i8 v[92:95], v[36:39], v[212:215], 0
	v_mfma_i32_16x16x64_i8 v[92:95], v[40:43], v[220:223], v[92:95]
	s_setprio 0
	s_setprio 1
	v_mfma_i32_16x16x64_i8 v[136:139], v[140:143], v[164:167], 0
	v_mfma_i32_16x16x64_i8 v[136:139], v[144:147], v[168:171], v[136:139]
	v_mfma_i32_16x16x64_i8 v[132:135], v[156:159], v[164:167], 0
	v_mfma_i32_16x16x64_i8 v[132:135], v[160:163], v[168:171], v[132:135]
	v_mfma_i32_16x16x64_i8 v[120:123], v[140:143], v[172:175], 0
	v_mfma_i32_16x16x64_i8 v[120:123], v[144:147], v[176:179], v[120:123]
	v_mfma_i32_16x16x64_i8 v[116:119], v[156:159], v[172:175], 0
	v_mfma_i32_16x16x64_i8 v[116:119], v[160:163], v[176:179], v[116:119]
	v_mfma_i32_16x16x64_i8 v[104:107], v[140:143], v[204:207], 0
	v_mfma_i32_16x16x64_i8 v[104:107], v[144:147], v[208:211], v[104:107]
	v_mfma_i32_16x16x64_i8 v[100:103], v[156:159], v[204:207], 0
	v_mfma_i32_16x16x64_i8 v[100:103], v[160:163], v[208:211], v[100:103]
	v_mfma_i32_16x16x64_i8 v[88:91], v[140:143], v[212:215], 0
	v_mfma_i32_16x16x64_i8 v[88:91], v[144:147], v[220:223], v[88:91]
	v_mfma_i32_16x16x64_i8 v[84:87], v[156:159], v[212:215], 0
	v_mfma_i32_16x16x64_i8 v[84:87], v[160:163], v[220:223], v[84:87]
	s_setprio 0
	s_barrier
	s_add_i32 s87, s87, s46
	v_lshl_add_u64 v[190:191], s[58:59], 0, v[2:3]
	s_mov_b32 m0, s87
	ds_read_b128 v[164:167], v219 offset:16384
	ds_read_b128 v[168:171], v219 offset:17408
	ds_read_b128 v[172:175], v219 offset:18432
	ds_read_b128 v[176:179], v219 offset:19456
	ds_read_b128 v[204:207], v219 offset:20480
	ds_read_b128 v[208:211], v219 offset:21504
	ds_read_b128 v[212:215], v219 offset:22528
	ds_read_b128 v[220:223], v219 offset:23552
	global_load_lds_dwordx4 v[190:191], off
	s_add_i32 m0, s87, 0x2000
	s_add_u32 s96, s58, 0x80000
	v_lshl_add_u64 v[224:225], s[58:59], 0, v[184:185]
	s_addc_u32 s97, s59, 0
	s_add_i32 s87, vcc_lo, s46
	global_load_lds_dwordx4 v[224:225], off
	v_lshl_add_u64 v[226:227], s[96:97], 0, v[2:3]
	s_mov_b32 m0, s87
	v_lshl_add_u64 v[228:229], s[60:61], 0, v[182:183]
	global_load_lds_dwordx4 v[226:227], off
	v_lshl_add_u64 v[226:227], s[96:97], 0, v[184:185]
	s_add_i32 m0, s87, 0x2000
	s_nop 0
	global_load_lds_dwordx4 v[226:227], off
	v_lshl_add_u64 v[226:227], s[60:61], 0, v[180:181]
	s_mov_b32 m0, s65
	s_nop 0
	global_load_lds_dwordx4 v[226:227], off
	s_mov_b32 m0, s67
	s_nop 0
	global_load_lds_dwordx4 v[228:229], off
	s_waitcnt vmcnt(8)
	s_waitcnt lgkmcnt(0)
	s_barrier
; #define PG8_STAGE(bufoff, gbase, voff) do { _Pragma("unroll") for (int _i = 0; _i < 2; ++_i) \
;         __builtin_amdgcn_global_load_lds((const unsigned*)((const char*)(gbase) + (voff)[_i]), (PG8_LAS unsigned*)(lds + (bufoff) + ldsw + _i * 8192), 16, 0, 0); } while (0)
; #define PG8_LDA(dst, b, h) do { _Pragma("unroll") for (int m = 0; m < 4; ++m) _Pragma("unroll") for (int k = 0; k < 2; ++k) dst[m][k] = *(const PG8_LAS bf16x8*)(lds + PG8_SA(b, h) + aoff + m * 2048 + k * 1024); } while (0)
; #define PG8_LDB(dst, b, h) do { _Pragma("unroll") for (int n = 0; n < 2; ++n) _Pragma("unroll") for (int k = 0; k < 2; ++k) dst[n][k] = *(const PG8_LAS bf16x8*)(lds + PG8_SB(b, h) + boff + n * 2048 + k * 1024); } while (0)
; #define PG8_WAIT_V(n) asm volatile("s_waitcnt vmcnt(" #n ")" ::: "memory")
; #define PG8_WAIT_L(n) asm volatile("s_waitcnt lgkmcnt(" #n ")" ::: "memory")
; #define PG8_BAR __builtin_amdgcn_s_barrier()
; #define PG8_SCHED __builtin_amdgcn_sched_barrier(0)
; template <class Epi, class Sched, bool ALIGN_EPI = false, bool SP2 = false, bool I8 = false>
; __device__ __forceinline__ void gemm_phase(PG8_LAS unsigned char* lds, const Gemm g, const Sched& S, const Epi& E) {
;     ...
;             PG8_WAIT_V(8); PG8_WAIT_L(0); PG8_BAR; PG8_MMA(0, 0, At, B0); PG8_MMA(0, 1, At, B1); PG8_BAR; PG8_SCHED;
;             PG8_LDA(At, 0, 1); PG8_STAGE(PG8_SB(0, 0), b2, voffB); PG8_STAGE(PG8_SB(0, 1), b2 + hstep, voffB); PG8_STAGE(PG8_SA(0, 0), a2, voffA);
;             PG8_WAIT_V(8); PG8_WAIT_L(0); PG8_BAR; PG8_MMA(1, 0, At, B0); PG8_MMA(1, 1, At, B1); PG8_BAR; PG8_SCHED;
;             PG8_LDB(B0, 1, 0); PG8_LDB(B1, 1, 1); PG8_SCHED; PG8_LDA(At, 1, 0); PG8_STAGE(PG8_SA(0, 1), a2 + hstep, voffA);
;             PG8_WAIT_V(8); PG8_WAIT_L(0); PG8_BAR; PG8_MMA(0, 0, At, B0); PG8_MMA(0, 1, At, B1); PG8_BAR; PG8_SCHED;
	s_setprio 1
	s_waitcnt lgkmcnt(0)
	v_mfma_i32_16x16x64_i8 v[80:83], v[28:31], v[164:167], 0
	v_mfma_i32_16x16x64_i8 v[80:83], v[32:35], v[168:171], v[80:83]
	v_mfma_i32_16x16x64_i8 v[76:79], v[36:39], v[164:167], 0
	v_mfma_i32_16x16x64_i8 v[76:79], v[40:43], v[168:171], v[76:79]
	v_mfma_i32_16x16x64_i8 v[64:67], v[28:31], v[172:175], 0
	v_mfma_i32_16x16x64_i8 v[64:67], v[32:35], v[176:179], v[64:67]
	v_mfma_i32_16x16x64_i8 v[60:63], v[36:39], v[172:175], 0
	v_mfma_i32_16x16x64_i8 v[60:63], v[40:43], v[176:179], v[60:63]
	v_mfma_i32_16x16x64_i8 v[48:51], v[28:31], v[204:207], 0
	v_mfma_i32_16x16x64_i8 v[48:51], v[32:35], v[208:211], v[48:51]
	v_mfma_i32_16x16x64_i8 v[44:47], v[36:39], v[204:207], 0
	v_mfma_i32_16x16x64_i8 v[44:47], v[40:43], v[208:211], v[44:47]
	v_mfma_i32_16x16x64_i8 v[16:19], v[28:31], v[212:215], 0
	v_mfma_i32_16x16x64_i8 v[16:19], v[32:35], v[220:223], v[16:19]
	v_mfma_i32_16x16x64_i8 v[12:15], v[36:39], v[212:215], 0
	v_mfma_i32_16x16x64_i8 v[12:15], v[40:43], v[220:223], v[12:15]
	s_setprio 0
	s_setprio 1
	v_mfma_i32_16x16x64_i8 v[24:27], v[140:143], v[204:207], 0
	v_mfma_i32_16x16x64_i8 v[24:27], v[144:147], v[208:211], v[24:27]
	v_mfma_i32_16x16x64_i8 v[20:23], v[156:159], v[204:207], 0
	v_mfma_i32_16x16x64_i8 v[20:23], v[160:163], v[208:211], v[20:23]
	v_mfma_i32_16x16x64_i8 v[8:11], v[140:143], v[212:215], 0
	v_mfma_i32_16x16x64_i8 v[8:11], v[144:147], v[220:223], v[8:11]
	v_mfma_i32_16x16x64_i8 v[4:7], v[156:159], v[212:215], 0
	v_mfma_i32_16x16x64_i8 v[4:7], v[160:163], v[220:223], v[4:7]
	v_mfma_i32_16x16x64_i8 v[28:31], v[140:143], v[164:167], 0
	v_mfma_i32_16x16x64_i8 v[28:31], v[144:147], v[168:171], v[28:31]
	v_mfma_i32_16x16x64_i8 v[32:35], v[156:159], v[164:167], 0
	v_mfma_i32_16x16x64_i8 v[32:35], v[160:163], v[168:171], v[32:35]
	v_mfma_i32_16x16x64_i8 v[36:39], v[140:143], v[172:175], 0
	v_mfma_i32_16x16x64_i8 v[36:39], v[144:147], v[176:179], v[36:39]
	v_mfma_i32_16x16x64_i8 v[40:43], v[156:159], v[172:175], 0
	v_mfma_i32_16x16x64_i8 v[40:43], v[160:163], v[176:179], v[40:43]
	s_setprio 0
	s_barrier
	s_add_i32 s87, 0, 0x18000
	s_add_i32 s96, 0, 0x1c000
	v_add_u32_e32 v72, s87, v217
	v_add_u32_e32 v160, s96, v217
	ds_read_b128 v[52:55], v72
	ds_read_b128 v[56:59], v72 offset:1024
	ds_read_b128 v[68:71], v72 offset:2048
	ds_read_b128 v[72:75], v72 offset:3072
	ds_read_b128 v[140:143], v160
	ds_read_b128 v[144:147], v160 offset:1024
	ds_read_b128 v[156:159], v160 offset:2048
	ds_read_b128 v[160:163], v160 offset:3072
	s_add_u32 s60, s60, 0x80000
	s_addc_u32 s61, s61, 0
	s_mov_b32 m0, s72
	v_lshl_add_u64 v[240:241], s[60:61], 0, v[180:181]
	ds_read_b128 v[164:167], v219 offset:32768
	ds_read_b128 v[168:171], v219 offset:33792
	ds_read_b128 v[172:175], v219 offset:34816
	ds_read_b128 v[176:179], v219 offset:35840
	ds_read_b128 v[204:207], v219 offset:36864
	ds_read_b128 v[208:211], v219 offset:37888
	ds_read_b128 v[212:215], v219 offset:38912
	ds_read_b128 v[220:223], v219 offset:39936
	global_load_lds_dwordx4 v[240:241], off
	v_lshl_add_u64 v[240:241], s[60:61], 0, v[182:183]
	s_mov_b32 m0, s73
	s_nop 0
	global_load_lds_dwordx4 v[240:241], off
	s_waitcnt vmcnt(8)
	s_waitcnt lgkmcnt(0)
	s_barrier
	s_setprio 1
	s_waitcnt lgkmcnt(0)
	v_mfma_i32_16x16x64_i8 v[152:155], v[52:55], v[164:167], v[152:155]
	v_mfma_i32_16x16x64_i8 v[152:155], v[56:59], v[168:171], v[152:155]
	v_mfma_i32_16x16x64_i8 v[148:151], v[68:71], v[164:167], v[148:151]
	v_mfma_i32_16x16x64_i8 v[148:151], v[72:75], v[168:171], v[148:151]
	v_mfma_i32_16x16x64_i8 v[128:131], v[52:55], v[172:175], v[128:131]
	v_mfma_i32_16x16x64_i8 v[128:131], v[56:59], v[176:179], v[128:131]
	v_mfma_i32_16x16x64_i8 v[124:127], v[68:71], v[172:175], v[124:127]
	v_mfma_i32_16x16x64_i8 v[124:127], v[72:75], v[176:179], v[124:127]
	v_mfma_i32_16x16x64_i8 v[112:115], v[52:55], v[204:207], v[112:115]
	v_mfma_i32_16x16x64_i8 v[112:115], v[56:59], v[208:211], v[112:115]
	v_mfma_i32_16x16x64_i8 v[108:111], v[68:71], v[204:207], v[108:111]
	v_mfma_i32_16x16x64_i8 v[108:111], v[72:75], v[208:211], v[108:111]
	v_mfma_i32_16x16x64_i8 v[96:99], v[52:55], v[212:215], v[96:99]
	v_mfma_i32_16x16x64_i8 v[96:99], v[56:59], v[220:223], v[96:99]
	v_mfma_i32_16x16x64_i8 v[92:95], v[68:71], v[212:215], v[92:95]
	v_mfma_i32_16x16x64_i8 v[92:95], v[72:75], v[220:223], v[92:95]
	s_setprio 0
	s_setprio 1
	v_mfma_i32_16x16x64_i8 v[136:139], v[140:143], v[164:167], v[136:139]
	v_mfma_i32_16x16x64_i8 v[136:139], v[144:147], v[168:171], v[136:139]
	v_mfma_i32_16x16x64_i8 v[132:135], v[156:159], v[164:167], v[132:135]
	v_mfma_i32_16x16x64_i8 v[132:135], v[160:163], v[168:171], v[132:135]
	v_mfma_i32_16x16x64_i8 v[120:123], v[140:143], v[172:175], v[120:123]
	v_mfma_i32_16x16x64_i8 v[120:123], v[144:147], v[176:179], v[120:123]
	v_mfma_i32_16x16x64_i8 v[116:119], v[156:159], v[172:175], v[116:119]
	v_mfma_i32_16x16x64_i8 v[116:119], v[160:163], v[176:179], v[116:119]
	v_mfma_i32_16x16x64_i8 v[104:107], v[140:143], v[204:207], v[104:107]
	v_mfma_i32_16x16x64_i8 v[104:107], v[144:147], v[208:211], v[104:107]
	v_mfma_i32_16x16x64_i8 v[100:103], v[156:159], v[204:207], v[100:103]
	v_mfma_i32_16x16x64_i8 v[100:103], v[160:163], v[208:211], v[100:103]
	v_mfma_i32_16x16x64_i8 v[88:91], v[140:143], v[212:215], v[88:91]
	v_mfma_i32_16x16x64_i8 v[88:91], v[144:147], v[220:223], v[88:91]
	v_mfma_i32_16x16x64_i8 v[84:87], v[156:159], v[212:215], v[84:87]
	v_mfma_i32_16x16x64_i8 v[84:87], v[160:163], v[220:223], v[84:87]
	s_setprio 0
	s_barrier
; #define PG8_STAGE(bufoff, gbase, voff) do { _Pragma("unroll") for (int _i = 0; _i < 2; ++_i) \
;         __builtin_amdgcn_global_load_lds((const unsigned*)((const char*)(gbase) + (voff)[_i]), (PG8_LAS unsigned*)(lds + (bufoff) + ldsw + _i * 8192), 16, 0, 0); } while (0)
; #define PG8_LDA(dst, b, h) do { _Pragma("unroll") for (int m = 0; m < 4; ++m) _Pragma("unroll") for (int k = 0; k < 2; ++k) dst[m][k] = *(const PG8_LAS bf16x8*)(lds + PG8_SA(b, h) + aoff + m * 2048 + k * 1024); } while (0)
; #define PG8_WAIT_V(n) asm volatile("s_waitcnt vmcnt(" #n ")" ::: "memory")
; #define PG8_WAIT_L(n) asm volatile("s_waitcnt lgkmcnt(" #n ")" ::: "memory")
; #define PG8_BAR __builtin_amdgcn_s_barrier()
; template <class Epi, class Sched, bool ALIGN_EPI = false, bool SP2 = false, bool I8 = false>
; __device__ __forceinline__ void gemm_phase(PG8_LAS unsigned char* lds, const Gemm g, const Sched& S, const Epi& E) {
;     ...
;         for (int t = 0; t < nt; t += 2) {
;             const bool last = (t == nt - 2);
;             const char* a1 = cA + (size_t)(t + 1) * kstep;
;             const char* a2 = last ? nA : cA + (size_t)(t + 2) * kstep; const char* b2 = last ? nB : cB + (size_t)(t + 2) * kstep;
;             const char* a3 = a2 + kstep; const char* b3 = b2 + kstep;
;             if (last && has_next) S.a_ready(nxt);
;             if constexpr (SP2) {
;             PG8_LDB(B0, 0, 0); PG8_LDB(B1, 0, 1); PG8_SCHED; PG8_LDA(At, 0, 0); PG8_STAGE(PG8_SA(1, 1), a1 + hstep, voffA);
;             PG8_WAIT_V(8); PG8_WAIT_L(0); PG8_BAR; PG8_MMA(0, 0, At, B0); PG8_MMA(0, 1, At, B1); PG8_BAR; PG8_SCHED;
;             PG8_LDA(At, 0, 1); PG8_STAGE(PG8_SB(0, 0), b2, voffB); PG8_STAGE(PG8_SB(0, 1), b2 + hstep, voffB); PG8_STAGE(PG8_SA(0, 0), a2, voffA);
;             PG8_WAIT_V(8); PG8_WAIT_L(0); PG8_BAR; PG8_MMA(1, 0, At, B0); PG8_MMA(1, 1, At, B1); PG8_BAR; PG8_SCHED;
;             PG8_LDB(B0, 1, 0); PG8_LDB(B1, 1, 1); PG8_SCHED; PG8_LDA(At, 1, 0); PG8_STAGE(PG8_SA(0, 1), a2 + hstep, voffA);
;             PG8_WAIT_V(8); PG8_WAIT_L(0); PG8_BAR; PG8_MMA(0, 0, At, B0); PG8_MMA(0, 1, At, B1); PG8_BAR; PG8_SCHED;
;             PG8_LDA(At, 1, 1); PG8_STAGE(PG8_SB(1, 0), b3, voffB); PG8_STAGE(PG8_SB(1, 1), b3 + hstep, voffB); PG8_STAGE(PG8_SA(1, 0), a3, voffA);
;             PG8_WAIT_V(8); PG8_WAIT_L(0); PG8_BAR; PG8_MMA(1, 0, At, B0); PG8_MMA(1, 1, At, B1); PG8_BAR; PG8_SCHED;
	s_add_i32 s60, s87, s46
	v_lshl_add_u64 v[190:191], v[190:191], 0, s[84:85]
	s_mov_b32 m0, s60
	ds_read_b128 v[164:167], v219 offset:49152
	ds_read_b128 v[168:171], v219 offset:50176
	ds_read_b128 v[172:175], v219 offset:51200
	ds_read_b128 v[176:179], v219 offset:52224
	ds_read_b128 v[204:207], v219 offset:53248
	ds_read_b128 v[208:211], v219 offset:54272
	ds_read_b128 v[212:215], v219 offset:55296
	ds_read_b128 v[220:223], v219 offset:56320
	global_load_lds_dwordx4 v[190:191], off
	s_add_i32 m0, s60, 0x2000
	s_add_u32 s58, s58, 0x80080
	v_lshl_add_u64 v[190:191], v[224:225], 0, s[84:85]
	s_addc_u32 s59, s59, 0
	s_add_i32 s60, s96, s46
	global_load_lds_dwordx4 v[190:191], off
	v_lshl_add_u64 v[190:191], s[58:59], 0, v[2:3]
	s_mov_b32 m0, s60
	s_nop 0
	global_load_lds_dwordx4 v[190:191], off
	v_lshl_add_u64 v[190:191], s[58:59], 0, v[184:185]
	s_add_i32 m0, s60, 0x2000
	s_nop 0
	global_load_lds_dwordx4 v[190:191], off
	v_lshl_add_u64 v[190:191], v[226:227], 0, s[84:85]
	s_mov_b32 m0, s28
	s_nop 0
	global_load_lds_dwordx4 v[190:191], off
	v_lshl_add_u64 v[190:191], v[228:229], 0, s[84:85]
	s_mov_b32 m0, s77
	s_nop 0
	global_load_lds_dwordx4 v[190:191], off
	s_waitcnt vmcnt(8)
	s_waitcnt lgkmcnt(0)
	s_barrier
	s_setprio 1
	s_waitcnt lgkmcnt(0)
	v_mfma_i32_16x16x64_i8 v[80:83], v[52:55], v[164:167], v[80:83]
	v_mfma_i32_16x16x64_i8 v[80:83], v[56:59], v[168:171], v[80:83]
	v_mfma_i32_16x16x64_i8 v[76:79], v[68:71], v[164:167], v[76:79]
	v_mfma_i32_16x16x64_i8 v[76:79], v[72:75], v[168:171], v[76:79]
	v_mfma_i32_16x16x64_i8 v[64:67], v[52:55], v[172:175], v[64:67]
	v_mfma_i32_16x16x64_i8 v[64:67], v[56:59], v[176:179], v[64:67]
	v_mfma_i32_16x16x64_i8 v[60:63], v[68:71], v[172:175], v[60:63]
	v_mfma_i32_16x16x64_i8 v[60:63], v[72:75], v[176:179], v[60:63]
	v_mfma_i32_16x16x64_i8 v[48:51], v[52:55], v[204:207], v[48:51]
	v_mfma_i32_16x16x64_i8 v[48:51], v[56:59], v[208:211], v[48:51]
	v_mfma_i32_16x16x64_i8 v[44:47], v[68:71], v[204:207], v[44:47]
	v_mfma_i32_16x16x64_i8 v[44:47], v[72:75], v[208:211], v[44:47]
	v_mfma_i32_16x16x64_i8 v[16:19], v[52:55], v[212:215], v[16:19]
	v_mfma_i32_16x16x64_i8 v[16:19], v[56:59], v[220:223], v[16:19]
	v_mfma_i32_16x16x64_i8 v[12:15], v[68:71], v[212:215], v[12:15]
	v_mfma_i32_16x16x64_i8 v[12:15], v[72:75], v[220:223], v[12:15]
	s_setprio 0
	s_setprio 1
	v_mfma_i32_16x16x64_i8 v[28:31], v[140:143], v[164:167], v[28:31]
	v_mfma_i32_16x16x64_i8 v[72:75], v[144:147], v[168:171], v[28:31]
	v_mfma_i32_16x16x64_i8 v[28:31], v[156:159], v[164:167], v[32:35]
	v_mfma_i32_16x16x64_i8 v[68:71], v[160:163], v[168:171], v[28:31]
	v_mfma_i32_16x16x64_i8 v[28:31], v[140:143], v[172:175], v[36:39]
	v_mfma_i32_16x16x64_i8 v[56:59], v[144:147], v[176:179], v[28:31]
	v_mfma_i32_16x16x64_i8 v[28:31], v[156:159], v[172:175], v[40:43]
	v_mfma_i32_16x16x64_i8 v[52:55], v[160:163], v[176:179], v[28:31]
	v_mfma_i32_16x16x64_i8 v[24:27], v[140:143], v[204:207], v[24:27]
	v_mfma_i32_16x16x64_i8 v[24:27], v[144:147], v[208:211], v[24:27]
	v_mfma_i32_16x16x64_i8 v[20:23], v[156:159], v[204:207], v[20:23]
	v_mfma_i32_16x16x64_i8 v[20:23], v[160:163], v[208:211], v[20:23]
	v_mfma_i32_16x16x64_i8 v[8:11], v[140:143], v[212:215], v[8:11]
	v_mfma_i32_16x16x64_i8 v[8:11], v[144:147], v[220:223], v[8:11]
	v_mfma_i32_16x16x64_i8 v[4:7], v[156:159], v[212:215], v[4:7]
	v_mfma_i32_16x16x64_i8 v[4:7], v[160:163], v[220:223], v[4:7]
	s_setprio 0
	s_barrier
	s_add_i32 s86, s86, 2
	s_add_u32 s54, s54, 0x100
	s_addc_u32 s55, s55, 0
	s_add_u32 s45, s45, 0x100
	s_addc_u32 s49, s49, 0
	s_cmp_gt_u32 s86, 29
	s_cbranch_scc1 .Lkloop_exit_6
.LBB0_1843:
	s_add_u32 s58, s54, 0xfff80080
	s_addc_u32 s59, s55, -1
	s_add_i32 s87, 0, 0x10000
	s_cmp_eq_u32 s86, 28
	s_cselect_b32 s61, s11, s59
	s_cselect_b32 s60, s13, s58
	s_cselect_b32 s59, s34, s49
	s_cselect_b32 s58, s35, s45
	s_add_i32 vcc_lo, 0, 0x14000
	v_add_u32_e32 v40, s87, v217
	v_add_u32_e32 v160, vcc_lo, v217
	ds_read_b128 v[28:31], v40
	ds_read_b128 v[32:35], v40 offset:1024
	ds_read_b128 v[36:39], v40 offset:2048
	ds_read_b128 v[40:43], v40 offset:3072
	ds_read_b128 v[140:143], v160
	ds_read_b128 v[144:147], v160 offset:1024
	ds_read_b128 v[156:159], v160 offset:2048
	ds_read_b128 v[160:163], v160 offset:3072
	v_lshl_add_u64 v[190:191], s[54:55], 0, v[186:187]
	s_add_i32 m0, s65, 0xc000
	ds_read_b128 v[164:167], v219
	ds_read_b128 v[168:171], v219 offset:1024
	ds_read_b128 v[172:175], v219 offset:2048
	ds_read_b128 v[176:179], v219 offset:3072
	ds_read_b128 v[204:207], v219 offset:4096
	ds_read_b128 v[208:211], v219 offset:5120
	ds_read_b128 v[212:215], v219 offset:6144
	ds_read_b128 v[220:223], v219 offset:7168
	global_load_lds_dwordx4 v[190:191], off
	v_lshl_add_u64 v[190:191], s[54:55], 0, v[188:189]
	s_add_i32 m0, s65, 0xe000
	s_nop 0
	global_load_lds_dwordx4 v[190:191], off
	s_waitcnt vmcnt(8)
	s_waitcnt lgkmcnt(0)
	s_barrier
; #define PG8_STAGE(bufoff, gbase, voff) do { _Pragma("unroll") for (int _i = 0; _i < 2; ++_i) \
;         __builtin_amdgcn_global_load_lds((const unsigned*)((const char*)(gbase) + (voff)[_i]), (PG8_LAS unsigned*)(lds + (bufoff) + ldsw + _i * 8192), 16, 0, 0); } while (0)
; #define PG8_LDA(dst, b, h) do { _Pragma("unroll") for (int m = 0; m < 4; ++m) _Pragma("unroll") for (int k = 0; k < 2; ++k) dst[m][k] = *(const PG8_LAS bf16x8*)(lds + PG8_SA(b, h) + aoff + m * 2048 + k * 1024); } while (0)
; #define PG8_LDB(dst, b, h) do { _Pragma("unroll") for (int n = 0; n < 2; ++n) _Pragma("unroll") for (int k = 0; k < 2; ++k) dst[n][k] = *(const PG8_LAS bf16x8*)(lds + PG8_SB(b, h) + boff + n * 2048 + k * 1024); } while (0)
; #define PG8_WAIT_V(n) asm volatile("s_waitcnt vmcnt(" #n ")" ::: "memory")
; #define PG8_WAIT_L(n) asm volatile("s_waitcnt lgkmcnt(" #n ")" ::: "memory")
; #define PG8_BAR __builtin_amdgcn_s_barrier()
; #define PG8_SCHED __builtin_amdgcn_sched_barrier(0)
; template <class Epi, class Sched, bool ALIGN_EPI = false, bool SP2 = false, bool I8 = false>
; __device__ __forceinline__ void gemm_phase(PG8_LAS unsigned char* lds, const Gemm g, const Sched& S, const Epi& E) {
;     ...
;             PG8_LDB(B0, 0, 0); PG8_LDB(B1, 0, 1); PG8_SCHED; PG8_LDA(At, 0, 0); PG8_STAGE(PG8_SA(1, 1), a1 + hstep, voffA);
;             PG8_WAIT_V(8); PG8_WAIT_L(0); PG8_BAR; PG8_MMA(0, 0, At, B0); PG8_MMA(0, 1, At, B1); PG8_BAR; PG8_SCHED;
;             PG8_LDA(At, 0, 1); PG8_STAGE(PG8_SB(0, 0), b2, voffB); PG8_STAGE(PG8_SB(0, 1), b2 + hstep, voffB); PG8_STAGE(PG8_SA(0, 0), a2, voffA);
;             PG8_WAIT_V(8); PG8_WAIT_L(0); PG8_BAR; PG8_MMA(1, 0, At, B0); PG8_MMA(1, 1, At, B1); PG8_BAR; PG8_SCHED;
	s_setprio 1
	s_waitcnt lgkmcnt(0)
	v_mfma_i32_16x16x64_i8 v[152:155], v[28:31], v[164:167], v[152:155]
	v_mfma_i32_16x16x64_i8 v[152:155], v[32:35], v[168:171], v[152:155]
	v_mfma_i32_16x16x64_i8 v[148:151], v[36:39], v[164:167], v[148:151]
	v_mfma_i32_16x16x64_i8 v[148:151], v[40:43], v[168:171], v[148:151]
	v_mfma_i32_16x16x64_i8 v[128:131], v[28:31], v[172:175], v[128:131]
	v_mfma_i32_16x16x64_i8 v[128:131], v[32:35], v[176:179], v[128:131]
	v_mfma_i32_16x16x64_i8 v[124:127], v[36:39], v[172:175], v[124:127]
	v_mfma_i32_16x16x64_i8 v[124:127], v[40:43], v[176:179], v[124:127]
	v_mfma_i32_16x16x64_i8 v[112:115], v[28:31], v[204:207], v[112:115]
	v_mfma_i32_16x16x64_i8 v[112:115], v[32:35], v[208:211], v[112:115]
	v_mfma_i32_16x16x64_i8 v[108:111], v[36:39], v[204:207], v[108:111]
	v_mfma_i32_16x16x64_i8 v[108:111], v[40:43], v[208:211], v[108:111]
	v_mfma_i32_16x16x64_i8 v[96:99], v[28:31], v[212:215], v[96:99]
	v_mfma_i32_16x16x64_i8 v[96:99], v[32:35], v[220:223], v[96:99]
	v_mfma_i32_16x16x64_i8 v[92:95], v[36:39], v[212:215], v[92:95]
	v_mfma_i32_16x16x64_i8 v[92:95], v[40:43], v[220:223], v[92:95]
	s_setprio 0
	s_setprio 1
	v_mfma_i32_16x16x64_i8 v[136:139], v[140:143], v[164:167], v[136:139]
	v_mfma_i32_16x16x64_i8 v[136:139], v[144:147], v[168:171], v[136:139]
	v_mfma_i32_16x16x64_i8 v[132:135], v[156:159], v[164:167], v[132:135]
	v_mfma_i32_16x16x64_i8 v[132:135], v[160:163], v[168:171], v[132:135]
	v_mfma_i32_16x16x64_i8 v[120:123], v[140:143], v[172:175], v[120:123]
	v_mfma_i32_16x16x64_i8 v[120:123], v[144:147], v[176:179], v[120:123]
	v_mfma_i32_16x16x64_i8 v[116:119], v[156:159], v[172:175], v[116:119]
	v_mfma_i32_16x16x64_i8 v[116:119], v[160:163], v[176:179], v[116:119]
	v_mfma_i32_16x16x64_i8 v[104:107], v[140:143], v[204:207], v[104:107]
	v_mfma_i32_16x16x64_i8 v[104:107], v[144:147], v[208:211], v[104:107]
	v_mfma_i32_16x16x64_i8 v[100:103], v[156:159], v[204:207], v[100:103]
	v_mfma_i32_16x16x64_i8 v[100:103], v[160:163], v[208:211], v[100:103]
	v_mfma_i32_16x16x64_i8 v[88:91], v[140:143], v[212:215], v[88:91]
	v_mfma_i32_16x16x64_i8 v[88:91], v[144:147], v[220:223], v[88:91]
	v_mfma_i32_16x16x64_i8 v[84:87], v[156:159], v[212:215], v[84:87]
	v_mfma_i32_16x16x64_i8 v[84:87], v[160:163], v[220:223], v[84:87]
	s_setprio 0
	s_barrier
	s_add_i32 s87, s87, s46
	v_lshl_add_u64 v[190:191], s[58:59], 0, v[2:3]
	s_mov_b32 m0, s87
	ds_read_b128 v[164:167], v219 offset:16384
	ds_read_b128 v[168:171], v219 offset:17408
	ds_read_b128 v[172:175], v219 offset:18432
	ds_read_b128 v[176:179], v219 offset:19456
	ds_read_b128 v[204:207], v219 offset:20480
	ds_read_b128 v[208:211], v219 offset:21504
	ds_read_b128 v[212:215], v219 offset:22528
	ds_read_b128 v[220:223], v219 offset:23552
	global_load_lds_dwordx4 v[190:191], off
	s_add_i32 m0, s87, 0x2000
	s_add_u32 s96, s58, 0x80000
	v_lshl_add_u64 v[224:225], s[58:59], 0, v[184:185]
	s_addc_u32 s97, s59, 0
	s_add_i32 s87, vcc_lo, s46
	global_load_lds_dwordx4 v[224:225], off
	v_lshl_add_u64 v[226:227], s[96:97], 0, v[2:3]
	s_mov_b32 m0, s87
	v_lshl_add_u64 v[228:229], s[60:61], 0, v[182:183]
	global_load_lds_dwordx4 v[226:227], off
	v_lshl_add_u64 v[226:227], s[96:97], 0, v[184:185]
	s_add_i32 m0, s87, 0x2000
	s_nop 0
	global_load_lds_dwordx4 v[226:227], off
	v_lshl_add_u64 v[226:227], s[60:61], 0, v[180:181]
	s_mov_b32 m0, s65
	s_nop 0
	global_load_lds_dwordx4 v[226:227], off
	s_mov_b32 m0, s67
	s_nop 0
	global_load_lds_dwordx4 v[228:229], off
	s_waitcnt vmcnt(8)
	s_waitcnt lgkmcnt(0)
	s_barrier
	s_setprio 1
	s_waitcnt lgkmcnt(0)
	v_mfma_i32_16x16x64_i8 v[80:83], v[28:31], v[164:167], v[80:83]
	v_mfma_i32_16x16x64_i8 v[80:83], v[32:35], v[168:171], v[80:83]
	v_mfma_i32_16x16x64_i8 v[76:79], v[36:39], v[164:167], v[76:79]
	v_mfma_i32_16x16x64_i8 v[76:79], v[40:43], v[168:171], v[76:79]
	v_mfma_i32_16x16x64_i8 v[64:67], v[28:31], v[172:175], v[64:67]
	v_mfma_i32_16x16x64_i8 v[64:67], v[32:35], v[176:179], v[64:67]
	v_mfma_i32_16x16x64_i8 v[60:63], v[36:39], v[172:175], v[60:63]
	v_mfma_i32_16x16x64_i8 v[60:63], v[40:43], v[176:179], v[60:63]
	v_mfma_i32_16x16x64_i8 v[48:51], v[28:31], v[204:207], v[48:51]
	v_mfma_i32_16x16x64_i8 v[48:51], v[32:35], v[208:211], v[48:51]
	v_mfma_i32_16x16x64_i8 v[44:47], v[36:39], v[204:207], v[44:47]
	v_mfma_i32_16x16x64_i8 v[44:47], v[40:43], v[208:211], v[44:47]
	v_mfma_i32_16x16x64_i8 v[16:19], v[28:31], v[212:215], v[16:19]
	v_mfma_i32_16x16x64_i8 v[16:19], v[32:35], v[220:223], v[16:19]
	v_mfma_i32_16x16x64_i8 v[12:15], v[36:39], v[212:215], v[12:15]
	v_mfma_i32_16x16x64_i8 v[12:15], v[40:43], v[220:223], v[12:15]
	s_setprio 0
	s_setprio 1
	v_mfma_i32_16x16x64_i8 v[24:27], v[140:143], v[204:207], v[24:27]
	v_mfma_i32_16x16x64_i8 v[24:27], v[144:147], v[208:211], v[24:27]
	v_mfma_i32_16x16x64_i8 v[20:23], v[156:159], v[204:207], v[20:23]
	v_mfma_i32_16x16x64_i8 v[20:23], v[160:163], v[208:211], v[20:23]
	v_mfma_i32_16x16x64_i8 v[8:11], v[140:143], v[212:215], v[8:11]
	v_mfma_i32_16x16x64_i8 v[8:11], v[144:147], v[220:223], v[8:11]
	v_mfma_i32_16x16x64_i8 v[4:7], v[156:159], v[212:215], v[4:7]
	v_mfma_i32_16x16x64_i8 v[4:7], v[160:163], v[220:223], v[4:7]
	v_mfma_i32_16x16x64_i8 v[28:31], v[140:143], v[164:167], v[72:75]
	v_mfma_i32_16x16x64_i8 v[28:31], v[144:147], v[168:171], v[28:31]
	v_mfma_i32_16x16x64_i8 v[32:35], v[156:159], v[164:167], v[68:71]
	v_mfma_i32_16x16x64_i8 v[32:35], v[160:163], v[168:171], v[32:35]
	v_mfma_i32_16x16x64_i8 v[36:39], v[140:143], v[172:175], v[56:59]
	v_mfma_i32_16x16x64_i8 v[36:39], v[144:147], v[176:179], v[36:39]
	v_mfma_i32_16x16x64_i8 v[40:43], v[156:159], v[172:175], v[52:55]
	v_mfma_i32_16x16x64_i8 v[40:43], v[160:163], v[176:179], v[40:43]
	s_setprio 0
	s_barrier
; #define PG8_STAGE(bufoff, gbase, voff) do { _Pragma("unroll") for (int _i = 0; _i < 2; ++_i) \
;         __builtin_amdgcn_global_load_lds((const unsigned*)((const char*)(gbase) + (voff)[_i]), (PG8_LAS unsigned*)(lds + (bufoff) + ldsw + _i * 8192), 16, 0, 0); } while (0)
; #define PG8_LDA(dst, b, h) do { _Pragma("unroll") for (int m = 0; m < 4; ++m) _Pragma("unroll") for (int k = 0; k < 2; ++k) dst[m][k] = *(const PG8_LAS bf16x8*)(lds + PG8_SA(b, h) + aoff + m * 2048 + k * 1024); } while (0)
; #define PG8_LDB(dst, b, h) do { _Pragma("unroll") for (int n = 0; n < 2; ++n) _Pragma("unroll") for (int k = 0; k < 2; ++k) dst[n][k] = *(const PG8_LAS bf16x8*)(lds + PG8_SB(b, h) + boff + n * 2048 + k * 1024); } while (0)
; #define PG8_WAIT_V(n) asm volatile("s_waitcnt vmcnt(" #n ")" ::: "memory")
; #define PG8_WAIT_L(n) asm volatile("s_waitcnt lgkmcnt(" #n ")" ::: "memory")
; #define PG8_BAR __builtin_amdgcn_s_barrier()
; #define PG8_SCHED __builtin_amdgcn_sched_barrier(0)
; template <class Epi, class Sched, bool ALIGN_EPI = false, bool SP2 = false, bool I8 = false>
; __device__ __forceinline__ void gemm_phase(PG8_LAS unsigned char* lds, const Gemm g, const Sched& S, const Epi& E) {
;     ...
;         for (int t = 0; t < nt; t += 2) {
;             const bool last = (t == nt - 2);
;             const char* a1 = cA + (size_t)(t + 1) * kstep;
;             const char* a2 = last ? nA : cA + (size_t)(t + 2) * kstep; const char* b2 = last ? nB : cB + (size_t)(t + 2) * kstep;
;     ...
;             PG8_LDB(B0, 1, 0); PG8_LDB(B1, 1, 1); PG8_SCHED; PG8_LDA(At, 1, 0); PG8_STAGE(PG8_SA(0, 1), a2 + hstep, voffA);
;             PG8_WAIT_V(8); PG8_WAIT_L(0); PG8_BAR; PG8_MMA(0, 0, At, B0); PG8_MMA(0, 1, At, B1); PG8_BAR; PG8_SCHED;
;             PG8_LDA(At, 1, 1); PG8_STAGE(PG8_SB(1, 0), b3, voffB); PG8_STAGE(PG8_SB(1, 1), b3 + hstep, voffB); PG8_STAGE(PG8_SA(1, 0), a3, voffA);
;             PG8_WAIT_V(8); PG8_WAIT_L(0); PG8_BAR; PG8_MMA(1, 0, At, B0); PG8_MMA(1, 1, At, B1); PG8_BAR; PG8_SCHED;
	s_add_i32 s87, 0, 0x18000
	s_add_i32 s96, 0, 0x1c000
	v_add_u32_e32 v72, s87, v217
	v_add_u32_e32 v160, s96, v217
	ds_read_b128 v[52:55], v72
	ds_read_b128 v[56:59], v72 offset:1024
	ds_read_b128 v[68:71], v72 offset:2048
	ds_read_b128 v[72:75], v72 offset:3072
	ds_read_b128 v[140:143], v160
	ds_read_b128 v[144:147], v160 offset:1024
	ds_read_b128 v[156:159], v160 offset:2048
	ds_read_b128 v[160:163], v160 offset:3072
	s_add_u32 s60, s60, 0x80000
	s_addc_u32 s61, s61, 0
	s_mov_b32 m0, s72
	v_lshl_add_u64 v[240:241], s[60:61], 0, v[180:181]
	ds_read_b128 v[164:167], v219 offset:32768
	ds_read_b128 v[168:171], v219 offset:33792
	ds_read_b128 v[172:175], v219 offset:34816
	ds_read_b128 v[176:179], v219 offset:35840
	ds_read_b128 v[204:207], v219 offset:36864
	ds_read_b128 v[208:211], v219 offset:37888
	ds_read_b128 v[212:215], v219 offset:38912
	ds_read_b128 v[220:223], v219 offset:39936
	global_load_lds_dwordx4 v[240:241], off
	v_lshl_add_u64 v[240:241], s[60:61], 0, v[182:183]
	s_mov_b32 m0, s73
	s_nop 0
	global_load_lds_dwordx4 v[240:241], off
	s_waitcnt vmcnt(8)
	s_waitcnt lgkmcnt(0)
	s_barrier
	s_setprio 1
	s_waitcnt lgkmcnt(0)
	v_mfma_i32_16x16x64_i8 v[152:155], v[52:55], v[164:167], v[152:155]
	v_mfma_i32_16x16x64_i8 v[152:155], v[56:59], v[168:171], v[152:155]
	v_mfma_i32_16x16x64_i8 v[148:151], v[68:71], v[164:167], v[148:151]
	v_mfma_i32_16x16x64_i8 v[148:151], v[72:75], v[168:171], v[148:151]
	v_mfma_i32_16x16x64_i8 v[128:131], v[52:55], v[172:175], v[128:131]
	v_mfma_i32_16x16x64_i8 v[128:131], v[56:59], v[176:179], v[128:131]
	v_mfma_i32_16x16x64_i8 v[124:127], v[68:71], v[172:175], v[124:127]
	v_mfma_i32_16x16x64_i8 v[124:127], v[72:75], v[176:179], v[124:127]
	v_mfma_i32_16x16x64_i8 v[112:115], v[52:55], v[204:207], v[112:115]
	v_mfma_i32_16x16x64_i8 v[112:115], v[56:59], v[208:211], v[112:115]
	v_mfma_i32_16x16x64_i8 v[108:111], v[68:71], v[204:207], v[108:111]
	v_mfma_i32_16x16x64_i8 v[108:111], v[72:75], v[208:211], v[108:111]
	v_mfma_i32_16x16x64_i8 v[96:99], v[52:55], v[212:215], v[96:99]
	v_mfma_i32_16x16x64_i8 v[96:99], v[56:59], v[220:223], v[96:99]
	v_mfma_i32_16x16x64_i8 v[92:95], v[68:71], v[212:215], v[92:95]
	v_mfma_i32_16x16x64_i8 v[92:95], v[72:75], v[220:223], v[92:95]
	s_setprio 0
	s_setprio 1
	v_mfma_i32_16x16x64_i8 v[136:139], v[140:143], v[164:167], v[136:139]
	v_mfma_i32_16x16x64_i8 v[136:139], v[144:147], v[168:171], v[136:139]
	v_mfma_i32_16x16x64_i8 v[132:135], v[156:159], v[164:167], v[132:135]
	v_mfma_i32_16x16x64_i8 v[132:135], v[160:163], v[168:171], v[132:135]
	v_mfma_i32_16x16x64_i8 v[120:123], v[140:143], v[172:175], v[120:123]
	v_mfma_i32_16x16x64_i8 v[120:123], v[144:147], v[176:179], v[120:123]
	v_mfma_i32_16x16x64_i8 v[116:119], v[156:159], v[172:175], v[116:119]
	v_mfma_i32_16x16x64_i8 v[116:119], v[160:163], v[176:179], v[116:119]
	v_mfma_i32_16x16x64_i8 v[104:107], v[140:143], v[204:207], v[104:107]
	v_mfma_i32_16x16x64_i8 v[104:107], v[144:147], v[208:211], v[104:107]
	v_mfma_i32_16x16x64_i8 v[100:103], v[156:159], v[204:207], v[100:103]
	v_mfma_i32_16x16x64_i8 v[100:103], v[160:163], v[208:211], v[100:103]
	v_mfma_i32_16x16x64_i8 v[88:91], v[140:143], v[212:215], v[88:91]
	v_mfma_i32_16x16x64_i8 v[88:91], v[144:147], v[220:223], v[88:91]
	v_mfma_i32_16x16x64_i8 v[84:87], v[156:159], v[212:215], v[84:87]
	v_mfma_i32_16x16x64_i8 v[84:87], v[160:163], v[220:223], v[84:87]
	s_setprio 0
	s_barrier
	s_add_i32 s60, s87, s46
	v_lshl_add_u64 v[190:191], v[190:191], 0, s[84:85]
	s_mov_b32 m0, s60
	ds_read_b128 v[164:167], v219 offset:49152
	ds_read_b128 v[168:171], v219 offset:50176
	ds_read_b128 v[172:175], v219 offset:51200
	ds_read_b128 v[176:179], v219 offset:52224
	ds_read_b128 v[204:207], v219 offset:53248
	ds_read_b128 v[208:211], v219 offset:54272
	ds_read_b128 v[212:215], v219 offset:55296
	ds_read_b128 v[220:223], v219 offset:56320
	global_load_lds_dwordx4 v[190:191], off
	s_add_i32 m0, s60, 0x2000
	s_add_u32 s58, s58, 0x80080
	v_lshl_add_u64 v[190:191], v[224:225], 0, s[84:85]
	s_addc_u32 s59, s59, 0
	s_add_i32 s60, s96, s46
	global_load_lds_dwordx4 v[190:191], off
	v_lshl_add_u64 v[190:191], s[58:59], 0, v[2:3]
	s_mov_b32 m0, s60
	s_nop 0
	global_load_lds_dwordx4 v[190:191], off
	v_lshl_add_u64 v[190:191], s[58:59], 0, v[184:185]
	s_add_i32 m0, s60, 0x2000
	s_nop 0
	global_load_lds_dwordx4 v[190:191], off
	v_lshl_add_u64 v[190:191], v[226:227], 0, s[84:85]
	s_mov_b32 m0, s28
	s_nop 0
	global_load_lds_dwordx4 v[190:191], off
	v_lshl_add_u64 v[190:191], v[228:229], 0, s[84:85]
	s_mov_b32 m0, s77
	s_nop 0
	global_load_lds_dwordx4 v[190:191], off
	s_waitcnt vmcnt(8)
	s_waitcnt lgkmcnt(0)
	s_barrier
	s_setprio 1
	s_waitcnt lgkmcnt(0)
	v_mfma_i32_16x16x64_i8 v[80:83], v[52:55], v[164:167], v[80:83]
	v_mfma_i32_16x16x64_i8 v[80:83], v[56:59], v[168:171], v[80:83]
	v_mfma_i32_16x16x64_i8 v[76:79], v[68:71], v[164:167], v[76:79]
	v_mfma_i32_16x16x64_i8 v[76:79], v[72:75], v[168:171], v[76:79]
	v_mfma_i32_16x16x64_i8 v[64:67], v[52:55], v[172:175], v[64:67]
	v_mfma_i32_16x16x64_i8 v[64:67], v[56:59], v[176:179], v[64:67]
	v_mfma_i32_16x16x64_i8 v[60:63], v[68:71], v[172:175], v[60:63]
	v_mfma_i32_16x16x64_i8 v[60:63], v[72:75], v[176:179], v[60:63]
	v_mfma_i32_16x16x64_i8 v[48:51], v[52:55], v[204:207], v[48:51]
	v_mfma_i32_16x16x64_i8 v[48:51], v[56:59], v[208:211], v[48:51]
	v_mfma_i32_16x16x64_i8 v[44:47], v[68:71], v[204:207], v[44:47]
	v_mfma_i32_16x16x64_i8 v[44:47], v[72:75], v[208:211], v[44:47]
	v_mfma_i32_16x16x64_i8 v[16:19], v[52:55], v[212:215], v[16:19]
	v_mfma_i32_16x16x64_i8 v[16:19], v[56:59], v[220:223], v[16:19]
	v_mfma_i32_16x16x64_i8 v[12:15], v[68:71], v[212:215], v[12:15]
	v_mfma_i32_16x16x64_i8 v[12:15], v[72:75], v[220:223], v[12:15]
	s_setprio 0
	s_setprio 1
	v_mfma_i32_16x16x64_i8 v[28:31], v[140:143], v[164:167], v[28:31]
	v_mfma_i32_16x16x64_i8 v[72:75], v[144:147], v[168:171], v[28:31]
	v_mfma_i32_16x16x64_i8 v[28:31], v[156:159], v[164:167], v[32:35]
	v_mfma_i32_16x16x64_i8 v[68:71], v[160:163], v[168:171], v[28:31]
	v_mfma_i32_16x16x64_i8 v[28:31], v[140:143], v[172:175], v[36:39]
	v_mfma_i32_16x16x64_i8 v[56:59], v[144:147], v[176:179], v[28:31]
	v_mfma_i32_16x16x64_i8 v[28:31], v[156:159], v[172:175], v[40:43]
	v_mfma_i32_16x16x64_i8 v[52:55], v[160:163], v[176:179], v[28:31]
	v_mfma_i32_16x16x64_i8 v[24:27], v[140:143], v[204:207], v[24:27]
	v_mfma_i32_16x16x64_i8 v[24:27], v[144:147], v[208:211], v[24:27]
	v_mfma_i32_16x16x64_i8 v[20:23], v[156:159], v[204:207], v[20:23]
	v_mfma_i32_16x16x64_i8 v[20:23], v[160:163], v[208:211], v[20:23]
	v_mfma_i32_16x16x64_i8 v[8:11], v[140:143], v[212:215], v[8:11]
	v_mfma_i32_16x16x64_i8 v[8:11], v[144:147], v[220:223], v[8:11]
	v_mfma_i32_16x16x64_i8 v[4:7], v[156:159], v[212:215], v[4:7]
	v_mfma_i32_16x16x64_i8 v[4:7], v[160:163], v[220:223], v[4:7]
	s_setprio 0
	s_barrier
	s_add_i32 s86, s86, 2
	s_add_u32 s54, s54, 0x100
	s_addc_u32 s55, s55, 0
	s_add_u32 s45, s45, 0x100
	s_addc_u32 s49, s49, 0
	s_cmp_gt_u32 s86, 29
	s_cbranch_scc0 .LBB0_1843
